# speedup vs baseline: 1.0105x; 1.0105x over previous
; #define LAS __attribute__((address_space(3)))
; DEV int otid() { int t = (int)threadIdx.x; asm volatile("" : "+v"(t)); return t; }
; #define PG8_WAIT_V(n) asm volatile("s_waitcnt vmcnt(" #n ")" ::: "memory")
; template <class Epi>
; DEV void gemm_phase(LAS unsigned char* lds, const Gemm g, const StaticOrder& S, const Epi& E) {
;     const int tid = otid(), wid = __builtin_amdgcn_readfirstlane(tid >> 6), lane = tid & 63, wr = wid >> 2, wc = wid & 3, fr = lane & 15, fq = lane >> 4;
;     const int K = g.K, nt = K / BK;
;     unsigned voffA[2], voffB[2];
; #pragma unroll
;     for (int i = 0; i < 2; ++i) { int R, C; stage_rc(tid * 16 + i * 8192, R, C); const int Rb = Epi::PERM ? ((R & ~31) + perm32(R & 31)) : R;
;         voffA[i] = (unsigned)(R * K + C) * 2u; voffB[i] = (unsigned)(Rb * K + C) * 2u; }
;     const size_t kstep = (size_t)(BK * 2);
;     const size_t hstep = (size_t)HALF * K * 2;
;     const size_t tstep = 2 * hstep;
;     const unsigned ldsw = (unsigned)wid * 1024u;
;     const int aoff = lds_byte(wr * 64 + fr, fq * 8), boff = lds_byte(wc * 32 + fr, fq * 8);
;     ...
;     Unit cur, nxt; int ui = 0;
;     if (!S.next(0, cur)) return;
;     f32x4 acc[2][2][4][2];
; #pragma unroll
;     for (int a = 0; a < 2; ++a)
; #pragma unroll
;         for (int b = 0; b < 2; ++b)
; #pragma unroll
;             for (int m = 0; m < 4; ++m)
; #pragma unroll
;                 for (int n = 0; n < 2; ++n) acc[a][b][m][n] = (f32x4){0.f, 0.f, 0.f, 0.f};
;     bf16x8 At[4][2], B0[2][2], B1[2][2];
;     const char* cA = (const char*)g.A + (size_t)cur.pm * tstep; const char* cB = (const char*)g.Bt + (size_t)cur.pn * tstep;
;     PG8_STAGE(PG8_SB(0, 0), cB, voffB); PG8_STAGE(PG8_SA(0, 0), cA, voffA); PG8_STAGE(PG8_SB(0, 1), cB + hstep, voffB); PG8_STAGE(PG8_SA(0, 1), cA + hstep, voffA);
;     if (wr == 1) PG8_BAR;
;     PG8_WAIT_V(4); PG8_BAR;
;     PG8_STAGE(PG8_SB(1, 0), cB + kstep, voffB); PG8_STAGE(PG8_SA(1, 0), cA + kstep, voffA); PG8_STAGE(PG8_SB(1, 1), cB + hstep + kstep, voffB);
;     PG8_WAIT_V(6); PG8_BAR;
; DEV void run_resid_gemm(LAS unsigned char* lds, const u16* A, const u16* Bt, int K, const float* base, float* out, float scale, u16* xb, float* ssout, int bx, int G) {
;     const bool one = (G == 256);
;     LAS float* red = (LAS float*)(lds + pg8::STAGE_BYTES);
;     EpiResid E{base, out, scale, xb, ssout, (one && ssout) ? red : (LAS float*)nullptr};
.LBB0_49:
	v_readlane_b32 s0, v254, 23
	s_cmpk_eq_i32 s0, 0x100
	s_cselect_b64 s[10:11], -1, 0
	s_cmpk_lg_i32 s0, 0x100
	v_cndmask_b32_e64 v0, 0, 1, s[8:9]
	s_cselect_b64 s[12:13], -1, 0
	v_cmp_ne_u32_e64 s[0:1], 1, v0
	s_andn2_b64 vcc, exec, s[8:9]
	s_cbranch_vccnz .LBB0_107
	v_ashrrev_i32_e32 v1, 31, v8
	v_lshrrev_b32_e32 v1, 26, v1
	v_add_u32_e32 v1, v8, v1
	v_ashrrev_i32_e32 v9, 6, v1
	v_bfe_i32 v1, v8, 27, 1
	v_lshlrev_b32_e32 v0, 4, v8
	v_lshrrev_b32_e32 v1, 22, v1
	v_add_u32_e32 v1, v0, v1
	v_and_b32_e32 v1, 0xfffffc00, v1
	v_sub_u32_e32 v1, v0, v1
	v_lshrrev_b32_e32 v2, 4, v1
	v_bitop3_b32 v2, v2, v1, 32 bitop3:0x6c
	v_ashrrev_i32_e32 v1, 31, v1
	v_lshrrev_b32_e32 v1, 26, v1
	v_add_u32_e32 v1, v2, v1
	v_ashrrev_i32_e32 v10, 6, v1
	v_lshlrev_b32_e32 v3, 3, v9
	v_mul_i32_i24_e32 v4, 64, v10
	v_and_b32_e32 v3, -16, v3
	v_sub_u32_e32 v2, v2, v4
	v_add_u32_e32 v1, v10, v3
	v_lshlrev_b32_e32 v3, 5, v9
	v_ashrrev_i16_sdwa v2, v203, sext(v2) dst_sel:DWORD dst_unused:UNUSED_PAD src0_sel:DWORD src1_sel:BYTE_0
	v_and_b32_e32 v3, 32, v3
	v_bfe_i32 v11, v2, 0, 16
	v_and_b32_e32 v5, 3, v10
	s_mov_b32 s5, 0xfffe0
	v_add_lshl_u32 v3, v3, v11, 1
	v_add_u32_e32 v0, 0x2000, v0
	v_lshlrev_b32_e32 v2, 1, v1
	v_lshrrev_b32_e32 v4, 2, v1
	v_and_or_b32 v5, v1, s5, v5
	v_lshl_add_u32 v144, v1, 12, v3
	v_ashrrev_i32_e32 v1, 31, v0
	v_lshrrev_b32_e32 v1, 22, v1
	v_add_u32_e32 v1, v0, v1
	v_ashrrev_i32_e32 v12, 10, v1
	v_mul_i32_i24_e32 v1, 0x400, v12
	v_sub_u32_e32 v0, v0, v1
	v_and_b32_e32 v2, 24, v2
	v_and_b32_e32 v4, 4, v4
	v_lshrrev_b32_e32 v1, 4, v0
	v_or3_b32 v2, v5, v4, v2
	v_bitop3_b32 v0, v1, v0, 32 bitop3:0x6c
	v_lshl_add_u32 v160, v2, 12, v3
	v_ashrrev_i32_e32 v2, 31, v0
	v_lshrrev_b32_e32 v2, 26, v2
	v_lshlrev_b32_e32 v1, 3, v12
	v_add_u32_e32 v2, v0, v2
	v_and_b32_e32 v1, -16, v1
	v_ashrrev_i32_e32 v13, 6, v2
	s_ashr_i32 s4, s35, 6
	v_add_u32_e32 v1, v13, v1
	v_and_b32_e32 v2, 0xc0, v2
	v_and_b32_e32 v4, 3, v13
	s_ashr_i32 s25, s24, 31
	s_ashr_i32 s15, s14, 31
	v_sub_u32_e32 v0, v0, v2
	v_and_or_b32 v4, v1, s5, v4
	s_ashr_i32 s5, s35, 8
	s_lshl_b32 s36, s4, 10
	s_lshl_b64 s[6:7], s[24:25], 20
	s_lshl_b64 s[16:17], s[14:15], 20
	v_readlane_b32 s18, v250, 35
	v_ashrrev_i16_sdwa v0, v203, sext(v0) dst_sel:DWORD dst_unused:UNUSED_PAD src0_sel:DWORD src1_sel:BYTE_0
	v_readlane_b32 s19, v250, 36
	s_add_u32 s28, s18, s16
	v_lshlrev_b32_e32 v3, 5, v12
	v_bfe_i32 v14, v0, 0, 16
	v_lshlrev_b32_e32 v0, 1, v1
	v_lshrrev_b32_e32 v2, 2, v1
	s_addc_u32 s29, s19, s17
	s_add_i32 s37, s36, 0
	v_and_b32_e32 v3, 32, v3
	v_and_b32_e32 v0, 24, v0
	v_and_b32_e32 v2, 4, v2
	s_add_i32 m0, s37, 0x10000
	v_or3_b32 v0, v4, v2, v0
	v_add_lshl_u32 v2, v3, v14, 1
	global_load_lds_dwordx4 v160, s[28:29]
	s_add_i32 m0, s37, 0x12000
	v_readlane_b32 s16, v250, 13
	v_lshl_add_u32 v148, v0, 12, v2
	v_readlane_b32 s17, v250, 14
	s_add_u32 s26, s16, s6
	global_load_lds_dwordx4 v148, s[28:29]
	s_addc_u32 s27, s17, s7
	s_mov_b32 m0, s37
	s_add_i32 s38, s37, 0x2000
	v_lshl_add_u32 v146, v1, 12, v2
	global_load_lds_dwordx4 v144, s[26:27]
	s_mov_b32 m0, s38
	s_add_u32 s6, s28, 0x80000
	global_load_lds_dwordx4 v146, s[26:27]
	s_addc_u32 s7, s29, 0
	s_add_i32 m0, s37, 0x14000
	v_mov_b32_e32 v149, v161
	global_load_lds_dwordx4 v160, s[6:7]
	s_add_i32 m0, s37, 0x16000
	v_mov_b32_e32 v145, v161
	global_load_lds_dwordx4 v148, s[6:7]
	s_add_u32 s6, s26, 0x80000
	s_addc_u32 s7, s27, 0
	s_add_i32 s39, s37, 0x4000
	s_mov_b32 m0, s39
	s_add_i32 s40, s37, 0x6000
	global_load_lds_dwordx4 v144, s[6:7]
	s_mov_b32 m0, s40
	v_mov_b32_e32 v147, v161
	global_load_lds_dwordx4 v146, s[6:7]
	v_lshl_add_u64 v[6:7], s[28:29], 0, v[160:161]
	v_lshl_add_u64 v[4:5], s[28:29], 0, v[148:149]
	v_lshl_add_u64 v[2:3], s[26:27], 0, v[144:145]
	s_cmp_lg_u32 s5, 1
	v_lshl_add_u64 v[0:1], s[26:27], 0, v[146:147]
	s_cbranch_scc1 .LBB0_52
	s_barrier
	s_setprio 1

; #define PG8_STAGE(bufoff, gbase, voff) do { _Pragma("unroll") for (int _i = 0; _i < 2; ++_i) \
;         __builtin_amdgcn_global_load_lds((const unsigned*)((const char*)(gbase) + (voff)[_i]), (LAS unsigned*)(lds + (bufoff) + ldsw + _i * 8192), 16, 0, 0); } while (0)
; #define PG8_LDA(dst, b, h) do { _Pragma("unroll") for (int m = 0; m < 4; ++m) _Pragma("unroll") for (int k = 0; k < 2; ++k) dst[m][k] = *(const LAS bf16x8*)(lds + PG8_SA(b, h) + aoff + m * 2048 + k * 1024); } while (0)
; #define PG8_LDB(dst, b, h) do { _Pragma("unroll") for (int n = 0; n < 2; ++n) _Pragma("unroll") for (int k = 0; k < 2; ++k) dst[n][k] = *(const LAS bf16x8*)(lds + PG8_SB(b, h) + boff + n * 2048 + k * 1024); } while (0)
; #define PG8_MMA(ai, bj, At, Bt) do { __builtin_amdgcn_s_setprio(1); _Pragma("unroll") for (int m = 0; m < 4; ++m) _Pragma("unroll") for (int n = 0; n < 2; ++n) _Pragma("unroll") for (int k = 0; k < 2; ++k) \
;         acc[ai][bj][m][n] = __builtin_amdgcn_mfma_f32_16x16x32_bf16(Bt[n][k], At[m][k], acc[ai][bj][m][n], 0, 0, 0); __builtin_amdgcn_s_setprio(0); } while (0)
; #define PG8_WAIT_L(n) asm volatile("s_waitcnt lgkmcnt(" #n ")" ::: "memory")
; #define PG8_BAR __builtin_amdgcn_s_barrier()
; #define PG8_SCHED __builtin_amdgcn_sched_barrier(0)
; template <class Epi>
; DEV void gemm_phase(LAS unsigned char* lds, const Gemm g, const StaticOrder& S, const Epi& E) {
;     ...
;             PG8_LDB(B0, 0, 0); PG8_SCHED; PG8_LDA(At, 0, 0); PG8_STAGE(PG8_SA(1, 1), a1 + hstep, voffA);
;             PG8_WAIT_L(8); PG8_BAR; PG8_WAIT_L(0); PG8_MMA(0, 0, At, B0); PG8_BAR; PG8_SCHED;
;             PG8_LDB(B1, 0, 1); PG8_STAGE(PG8_SB(0, 0), b2, voffB);
;             PG8_BAR; PG8_WAIT_L(0); PG8_MMA(0, 1, At, B1); PG8_BAR;
;             PG8_LDA(At, 0, 1); PG8_STAGE(PG8_SA(0, 0), a2, voffA);
;             PG8_BAR; PG8_WAIT_L(0); PG8_MMA(1, 0, At, B0); PG8_BAR; PG8_SCHED;
.LBB0_61:
	s_add_u32 s28, s26, 0xfff80080
	s_addc_u32 s29, s27, -1
	s_add_i32 s49, 0, 0x10000
	v_add_u32_e32 v140, s49, v178
	ds_read_b128 v[128:131], v140
	ds_read_b128 v[132:135], v140 offset:1024
	ds_read_b128 v[136:139], v140 offset:2048
	ds_read_b128 v[140:143], v140 offset:3072
	s_cmp_eq_u32 s48, 28
	s_cselect_b32 s31, s15, s29
	s_cselect_b32 s30, s19, s28
	s_cselect_b32 s29, s17, s47
	s_cselect_b32 s28, s25, s46
	v_lshl_add_u64 v[158:159], s[26:27], 0, v[150:151]
	s_add_i32 m0, s37, 0xc000
	ds_read_b128 v[154:157], v181
	ds_read_b128 v[174:177], v181 offset:1024
	ds_read_b128 v[182:185], v181 offset:2048
	ds_read_b128 v[186:189], v181 offset:3072
	ds_read_b128 v[190:193], v181 offset:4096
	ds_read_b128 v[194:197], v181 offset:5120
	ds_read_b128 v[214:217], v181 offset:6144
	ds_read_b128 v[218:221], v181 offset:7168
	global_load_lds_dwordx4 v[158:159], off
	v_lshl_add_u64 v[158:159], s[26:27], 0, v[152:153]
	s_add_i32 m0, s37, 0xe000
	s_nop 0
	global_load_lds_dwordx4 v[158:159], off
	s_waitcnt lgkmcnt(8)
	s_barrier
	s_waitcnt lgkmcnt(0)
	v_mfma_f32_16x16x32_bf16 v[124:127], v[128:131], v[154:157], v[124:127]
	v_mfma_f32_16x16x32_bf16 v[120:123], v[136:139], v[154:157], v[120:123]
	v_mfma_f32_16x16x32_bf16 v[108:111], v[128:131], v[182:185], v[108:111]
	v_mfma_f32_16x16x32_bf16 v[104:107], v[136:139], v[182:185], v[104:107]
	v_mfma_f32_16x16x32_bf16 v[92:95], v[128:131], v[190:193], v[92:95]
	v_mfma_f32_16x16x32_bf16 v[88:91], v[136:139], v[190:193], v[88:91]
	v_mfma_f32_16x16x32_bf16 v[76:79], v[128:131], v[214:217], v[76:79]
	v_mfma_f32_16x16x32_bf16 v[72:75], v[136:139], v[214:217], v[72:75]
	v_mfma_f32_16x16x32_bf16 v[124:127], v[132:135], v[174:177], v[124:127]
	v_mfma_f32_16x16x32_bf16 v[120:123], v[140:143], v[174:177], v[120:123]
	v_mfma_f32_16x16x32_bf16 v[108:111], v[132:135], v[186:189], v[108:111]
	v_mfma_f32_16x16x32_bf16 v[104:107], v[140:143], v[186:189], v[104:107]
	v_mfma_f32_16x16x32_bf16 v[92:95], v[132:135], v[194:197], v[92:95]
	v_mfma_f32_16x16x32_bf16 v[88:91], v[140:143], v[194:197], v[88:91]
	v_mfma_f32_16x16x32_bf16 v[76:79], v[132:135], v[218:221], v[76:79]
	v_mfma_f32_16x16x32_bf16 v[72:75], v[140:143], v[218:221], v[72:75]
	s_barrier
	s_add_i32 s52, 0, 0x14000
	v_add_u32_e32 v158, s52, v178
	s_add_i32 s49, s49, s36
	ds_read_b128 v[222:225], v158
	ds_read_b128 v[226:229], v158 offset:1024
	ds_read_b128 v[230:233], v158 offset:2048
	ds_read_b128 v[234:237], v158 offset:3072
	v_lshl_add_u64 v[158:159], s[28:29], 0, v[160:161]
	s_mov_b32 m0, s49
	v_lshl_add_u64 v[238:239], s[28:29], 0, v[148:149]
	global_load_lds_dwordx4 v[158:159], off
	s_add_i32 m0, s49, 0x2000
	s_nop 0
	global_load_lds_dwordx4 v[238:239], off
	s_barrier
	s_waitcnt lgkmcnt(0)
	v_mfma_f32_16x16x32_bf16 v[116:119], v[222:225], v[154:157], v[116:119]
	v_mfma_f32_16x16x32_bf16 v[112:115], v[230:233], v[154:157], v[112:115]
	v_mfma_f32_16x16x32_bf16 v[100:103], v[222:225], v[182:185], v[100:103]
	v_mfma_f32_16x16x32_bf16 v[96:99], v[230:233], v[182:185], v[96:99]
	v_mfma_f32_16x16x32_bf16 v[84:87], v[222:225], v[190:193], v[84:87]
	v_mfma_f32_16x16x32_bf16 v[80:83], v[230:233], v[190:193], v[80:83]
	v_mfma_f32_16x16x32_bf16 v[68:71], v[222:225], v[214:217], v[68:71]
	v_mfma_f32_16x16x32_bf16 v[64:67], v[230:233], v[214:217], v[64:67]
	v_mfma_f32_16x16x32_bf16 v[116:119], v[226:229], v[174:177], v[116:119]
	v_mfma_f32_16x16x32_bf16 v[112:115], v[234:237], v[174:177], v[112:115]
	v_mfma_f32_16x16x32_bf16 v[100:103], v[226:229], v[186:189], v[100:103]
	v_mfma_f32_16x16x32_bf16 v[96:99], v[234:237], v[186:189], v[96:99]
	v_mfma_f32_16x16x32_bf16 v[84:87], v[226:229], v[194:197], v[84:87]
	v_mfma_f32_16x16x32_bf16 v[80:83], v[234:237], v[194:197], v[80:83]
	v_mfma_f32_16x16x32_bf16 v[68:71], v[226:229], v[218:221], v[68:71]
	v_mfma_f32_16x16x32_bf16 v[64:67], v[234:237], v[218:221], v[64:67]
	s_mov_b32 m0, s37
	v_lshl_add_u64 v[240:241], s[30:31], 0, v[144:145]
	s_barrier
	ds_read_b128 v[154:157], v181 offset:16384
	ds_read_b128 v[174:177], v181 offset:17408
	ds_read_b128 v[182:185], v181 offset:18432
	ds_read_b128 v[186:189], v181 offset:19456
	ds_read_b128 v[190:193], v181 offset:20480
	ds_read_b128 v[194:197], v181 offset:21504
	ds_read_b128 v[214:217], v181 offset:22528
	ds_read_b128 v[218:221], v181 offset:23552
	global_load_lds_dwordx4 v[240:241], off
	v_lshl_add_u64 v[242:243], s[30:31], 0, v[146:147]
	s_mov_b32 m0, s38
	s_nop 0
	global_load_lds_dwordx4 v[242:243], off
	s_barrier
	s_waitcnt lgkmcnt(0)
	v_mfma_f32_16x16x32_bf16 v[60:63], v[128:131], v[154:157], v[60:63]
	v_mfma_f32_16x16x32_bf16 v[56:59], v[136:139], v[154:157], v[56:59]
	v_mfma_f32_16x16x32_bf16 v[44:47], v[128:131], v[182:185], v[44:47]
	v_mfma_f32_16x16x32_bf16 v[40:43], v[136:139], v[182:185], v[40:43]
	v_mfma_f32_16x16x32_bf16 v[28:31], v[128:131], v[190:193], v[28:31]
	v_mfma_f32_16x16x32_bf16 v[24:27], v[136:139], v[190:193], v[24:27]
	v_mfma_f32_16x16x32_bf16 v[12:15], v[128:131], v[214:217], v[12:15]
	v_mfma_f32_16x16x32_bf16 v[8:11], v[136:139], v[214:217], v[8:11]
	v_mfma_f32_16x16x32_bf16 v[60:63], v[132:135], v[174:177], v[60:63]
	v_mfma_f32_16x16x32_bf16 v[56:59], v[140:143], v[174:177], v[56:59]
	v_mfma_f32_16x16x32_bf16 v[44:47], v[132:135], v[186:189], v[44:47]
	v_mfma_f32_16x16x32_bf16 v[40:43], v[140:143], v[186:189], v[40:43]
	v_mfma_f32_16x16x32_bf16 v[28:31], v[132:135], v[194:197], v[28:31]
	v_mfma_f32_16x16x32_bf16 v[24:27], v[140:143], v[194:197], v[24:27]
	v_mfma_f32_16x16x32_bf16 v[12:15], v[132:135], v[218:221], v[12:15]
	v_mfma_f32_16x16x32_bf16 v[8:11], v[140:143], v[218:221], v[8:11]
	s_barrier
; #define PG8_STAGE(bufoff, gbase, voff) do { _Pragma("unroll") for (int _i = 0; _i < 2; ++_i) \
;         __builtin_amdgcn_global_load_lds((const unsigned*)((const char*)(gbase) + (voff)[_i]), (LAS unsigned*)(lds + (bufoff) + ldsw + _i * 8192), 16, 0, 0); } while (0)
; #define PG8_LDA(dst, b, h) do { _Pragma("unroll") for (int m = 0; m < 4; ++m) _Pragma("unroll") for (int k = 0; k < 2; ++k) dst[m][k] = *(const LAS bf16x8*)(lds + PG8_SA(b, h) + aoff + m * 2048 + k * 1024); } while (0)
; #define PG8_LDB(dst, b, h) do { _Pragma("unroll") for (int n = 0; n < 2; ++n) _Pragma("unroll") for (int k = 0; k < 2; ++k) dst[n][k] = *(const LAS bf16x8*)(lds + PG8_SB(b, h) + boff + n * 2048 + k * 1024); } while (0)
; #define PG8_MMA(ai, bj, At, Bt) do { __builtin_amdgcn_s_setprio(1); _Pragma("unroll") for (int m = 0; m < 4; ++m) _Pragma("unroll") for (int n = 0; n < 2; ++n) _Pragma("unroll") for (int k = 0; k < 2; ++k) \
;         acc[ai][bj][m][n] = __builtin_amdgcn_mfma_f32_16x16x32_bf16(Bt[n][k], At[m][k], acc[ai][bj][m][n], 0, 0, 0); __builtin_amdgcn_s_setprio(0); } while (0)
; #define PG8_WAIT_V(n) asm volatile("s_waitcnt vmcnt(" #n ")" ::: "memory")
; #define PG8_WAIT_L(n) asm volatile("s_waitcnt lgkmcnt(" #n ")" ::: "memory")
; #define PG8_BAR __builtin_amdgcn_s_barrier()
; #define PG8_SCHED __builtin_amdgcn_sched_barrier(0)
; template <class Epi>
; DEV void gemm_phase(LAS unsigned char* lds, const Gemm g, const StaticOrder& S, const Epi& E) {
;     ...
;             PG8_BAR; PG8_WAIT_L(0); PG8_MMA(1, 0, At, B0); PG8_BAR; PG8_SCHED;
;             PG8_STAGE(PG8_SB(0, 1), b2 + hstep, voffB);
;             PG8_WAIT_V(6); PG8_BAR; PG8_MMA(1, 1, At, B1); PG8_BAR;
;             PG8_LDB(B0, 1, 0); PG8_SCHED; PG8_LDA(At, 1, 0); PG8_STAGE(PG8_SA(0, 1), a2 + hstep, voffA);
;             PG8_WAIT_L(8); PG8_BAR; PG8_WAIT_L(0); PG8_MMA(0, 0, At, B0); PG8_BAR; PG8_SCHED;
;             PG8_LDB(B1, 1, 1); PG8_STAGE(PG8_SB(1, 0), b3, voffB);
;             PG8_BAR; PG8_WAIT_L(0); PG8_MMA(0, 1, At, B1); PG8_BAR;
;             PG8_LDA(At, 1, 1); PG8_STAGE(PG8_SA(1, 0), a3, voffA);
	s_add_u32 s50, s28, 0x80000
	s_addc_u32 s51, s29, 0
	s_add_i32 s49, s52, s36
	v_lshl_add_u64 v[128:129], s[50:51], 0, v[160:161]
	s_mov_b32 m0, s49
	s_nop 0
	global_load_lds_dwordx4 v[128:129], off
	v_lshl_add_u64 v[128:129], s[50:51], 0, v[148:149]
	s_add_i32 m0, s49, 0x2000
	s_nop 0
	global_load_lds_dwordx4 v[128:129], off
	s_waitcnt vmcnt(6)
	s_barrier
	v_mfma_f32_16x16x32_bf16 v[52:55], v[222:225], v[154:157], v[52:55]
	v_mfma_f32_16x16x32_bf16 v[48:51], v[230:233], v[154:157], v[48:51]
	v_mfma_f32_16x16x32_bf16 v[36:39], v[222:225], v[182:185], v[36:39]
	v_mfma_f32_16x16x32_bf16 v[32:35], v[230:233], v[182:185], v[32:35]
	v_mfma_f32_16x16x32_bf16 v[20:23], v[222:225], v[190:193], v[20:23]
	v_mfma_f32_16x16x32_bf16 v[16:19], v[230:233], v[190:193], v[16:19]
	v_mfma_f32_16x16x32_bf16 v[4:7], v[222:225], v[214:217], v[4:7]
	v_mfma_f32_16x16x32_bf16 v[0:3], v[230:233], v[214:217], v[0:3]
	v_mfma_f32_16x16x32_bf16 v[52:55], v[226:229], v[174:177], v[52:55]
	v_mfma_f32_16x16x32_bf16 v[48:51], v[234:237], v[174:177], v[48:51]
	v_mfma_f32_16x16x32_bf16 v[36:39], v[226:229], v[186:189], v[36:39]
	v_mfma_f32_16x16x32_bf16 v[32:35], v[234:237], v[186:189], v[32:35]
	v_mfma_f32_16x16x32_bf16 v[20:23], v[226:229], v[194:197], v[20:23]
	v_mfma_f32_16x16x32_bf16 v[16:19], v[234:237], v[194:197], v[16:19]
	v_mfma_f32_16x16x32_bf16 v[4:7], v[226:229], v[218:221], v[4:7]
	v_mfma_f32_16x16x32_bf16 v[0:3], v[234:237], v[218:221], v[0:3]
	s_add_i32 s49, 0, 0x18000
	v_add_u32_e32 v140, s49, v178
	s_barrier
	ds_read_b128 v[128:131], v140
	ds_read_b128 v[132:135], v140 offset:1024
	ds_read_b128 v[136:139], v140 offset:2048
	ds_read_b128 v[140:143], v140 offset:3072
	s_add_u32 s30, s30, 0x80000
	s_addc_u32 s31, s31, 0
	s_mov_b32 m0, s39
	v_lshl_add_u64 v[222:223], s[30:31], 0, v[144:145]
	ds_read_b128 v[154:157], v181 offset:32768
	ds_read_b128 v[174:177], v181 offset:33792
	ds_read_b128 v[182:185], v181 offset:34816
	ds_read_b128 v[186:189], v181 offset:35840
	ds_read_b128 v[190:193], v181 offset:36864
	ds_read_b128 v[194:197], v181 offset:37888
	ds_read_b128 v[214:217], v181 offset:38912
	ds_read_b128 v[218:221], v181 offset:39936
	global_load_lds_dwordx4 v[222:223], off
	v_lshl_add_u64 v[222:223], s[30:31], 0, v[146:147]
	s_mov_b32 m0, s40
	s_nop 0
	global_load_lds_dwordx4 v[222:223], off
	s_waitcnt lgkmcnt(8)
	s_barrier
	s_waitcnt lgkmcnt(0)
	v_mfma_f32_16x16x32_bf16 v[124:127], v[128:131], v[154:157], v[124:127]
	v_mfma_f32_16x16x32_bf16 v[120:123], v[136:139], v[154:157], v[120:123]
	v_mfma_f32_16x16x32_bf16 v[108:111], v[128:131], v[182:185], v[108:111]
	v_mfma_f32_16x16x32_bf16 v[104:107], v[136:139], v[182:185], v[104:107]
	v_mfma_f32_16x16x32_bf16 v[92:95], v[128:131], v[190:193], v[92:95]
	v_mfma_f32_16x16x32_bf16 v[88:91], v[136:139], v[190:193], v[88:91]
	v_mfma_f32_16x16x32_bf16 v[76:79], v[128:131], v[214:217], v[76:79]
	v_mfma_f32_16x16x32_bf16 v[72:75], v[136:139], v[214:217], v[72:75]
	v_mfma_f32_16x16x32_bf16 v[124:127], v[132:135], v[174:177], v[124:127]
	v_mfma_f32_16x16x32_bf16 v[120:123], v[140:143], v[174:177], v[120:123]
	v_mfma_f32_16x16x32_bf16 v[108:111], v[132:135], v[186:189], v[108:111]
	v_mfma_f32_16x16x32_bf16 v[104:107], v[140:143], v[186:189], v[104:107]
	v_mfma_f32_16x16x32_bf16 v[92:95], v[132:135], v[194:197], v[92:95]
	v_mfma_f32_16x16x32_bf16 v[88:91], v[140:143], v[194:197], v[88:91]
	v_mfma_f32_16x16x32_bf16 v[76:79], v[132:135], v[218:221], v[76:79]
	v_mfma_f32_16x16x32_bf16 v[72:75], v[140:143], v[218:221], v[72:75]
	s_barrier
	s_add_i32 s30, 0, 0x1c000
	s_add_i32 s31, s49, s36
	v_add_u32_e32 v234, s30, v178
	v_lshl_add_u64 v[158:159], v[158:159], 0, s[2:3]
	s_mov_b32 m0, s31
	ds_read_b128 v[222:225], v234
	ds_read_b128 v[226:229], v234 offset:1024
	ds_read_b128 v[230:233], v234 offset:2048
	ds_read_b128 v[234:237], v234 offset:3072
	global_load_lds_dwordx4 v[158:159], off
	v_lshl_add_u64 v[158:159], v[238:239], 0, s[2:3]
	s_add_i32 m0, s31, 0x2000
	s_nop 0
	global_load_lds_dwordx4 v[158:159], off
	s_barrier
	s_waitcnt lgkmcnt(0)
	v_mfma_f32_16x16x32_bf16 v[116:119], v[222:225], v[154:157], v[116:119]
	v_mfma_f32_16x16x32_bf16 v[112:115], v[230:233], v[154:157], v[112:115]
	v_mfma_f32_16x16x32_bf16 v[100:103], v[222:225], v[182:185], v[100:103]
	v_mfma_f32_16x16x32_bf16 v[96:99], v[230:233], v[182:185], v[96:99]
	v_mfma_f32_16x16x32_bf16 v[84:87], v[222:225], v[190:193], v[84:87]
	v_mfma_f32_16x16x32_bf16 v[80:83], v[230:233], v[190:193], v[80:83]
	v_mfma_f32_16x16x32_bf16 v[68:71], v[222:225], v[214:217], v[68:71]
	v_mfma_f32_16x16x32_bf16 v[64:67], v[230:233], v[214:217], v[64:67]
	v_mfma_f32_16x16x32_bf16 v[116:119], v[226:229], v[174:177], v[116:119]
	v_mfma_f32_16x16x32_bf16 v[112:115], v[234:237], v[174:177], v[112:115]
	v_mfma_f32_16x16x32_bf16 v[100:103], v[226:229], v[186:189], v[100:103]
	v_mfma_f32_16x16x32_bf16 v[96:99], v[234:237], v[186:189], v[96:99]
	v_mfma_f32_16x16x32_bf16 v[84:87], v[226:229], v[194:197], v[84:87]
	v_mfma_f32_16x16x32_bf16 v[80:83], v[234:237], v[194:197], v[80:83]
	v_mfma_f32_16x16x32_bf16 v[68:71], v[226:229], v[218:221], v[68:71]
	v_mfma_f32_16x16x32_bf16 v[64:67], v[234:237], v[218:221], v[64:67]
	s_mov_b32 m0, s41
	v_lshl_add_u64 v[158:159], v[240:241], 0, s[2:3]
	s_barrier
	ds_read_b128 v[154:157], v181 offset:49152
	ds_read_b128 v[174:177], v181 offset:50176
	ds_read_b128 v[182:185], v181 offset:51200
	ds_read_b128 v[186:189], v181 offset:52224
	ds_read_b128 v[190:193], v181 offset:53248
	ds_read_b128 v[194:197], v181 offset:54272
	ds_read_b128 v[214:217], v181 offset:55296
	ds_read_b128 v[218:221], v181 offset:56320
	global_load_lds_dwordx4 v[158:159], off
	v_lshl_add_u64 v[158:159], v[242:243], 0, s[2:3]
	s_mov_b32 m0, s42
	s_nop 0
	global_load_lds_dwordx4 v[158:159], off
	s_barrier
; DEV bf16x8 pack8(f32x4 a, f32x4 b) { u32x4 w; w.x = cvt_pk_bf16(a[0], a[1]); w.y = cvt_pk_bf16(a[2], a[3]); w.z = cvt_pk_bf16(b[0], b[1]); w.w = cvt_pk_bf16(b[2], b[3]); return __builtin_bit_cast(bf16x8, w); }
; #define PG8_WAIT_V(n) asm volatile("s_waitcnt vmcnt(" #n ")" ::: "memory")
; #define PG8_WAIT_L(n) asm volatile("s_waitcnt lgkmcnt(" #n ")" ::: "memory")
; template <class Epi>
; DEV void gemm_phase(LAS unsigned char* lds, const Gemm g, const StaticOrder& S, const Epi& E) {
;     ...
;             PG8_LDA(At, 1, 1); PG8_STAGE(PG8_SA(1, 0), a3, voffA);
;             PG8_BAR; PG8_WAIT_L(0); PG8_MMA(1, 0, At, B0); PG8_BAR; PG8_SCHED;
;             PG8_STAGE(PG8_SB(1, 1), b3 + hstep, voffB);
;             PG8_WAIT_V(6); PG8_BAR; PG8_MMA(1, 1, At, B1); PG8_BAR;
;         }
;     DEV void operator()(AccRef acc, const pg8::Unit& u, int wr, int wc, int fr, int fq) const {
;         const int row0 = u.pm * 256 + wr * 64 + fr, col0 = u.pn * 256 + wc * 32 + 8 * fq;
; #pragma unroll
;         for (int am = 0; am < 4; ++am) { const int ai = am >> 1, m0 = (am & 1) * 2;
;             f32x4 bv[4][2][2];
; #pragma unroll
;             for (int m = m0; m < m0 + 2; ++m)
; #pragma unroll
;                 for (int bj = 0; bj < 2; ++bj)
; #pragma unroll
;                     for (int n = 0; n < 2; ++n) bv[m][bj][n] = *(const f32x4*)(base + (size_t)(row0 + ai * 128 + m * 16) * 2048 + col0 + bj * 128 + n * 4);
; #pragma unroll
;             for (int m = m0; m < m0 + 2; ++m) { const size_t off = (size_t)(row0 + ai * 128 + m * 16) * 2048 + col0; float sq = 0.f;
; #pragma unroll
;                 for (int bj = 0; bj < 2; ++bj) { const f32x4 o0 = bv[m][bj][0] + scale * acc[ai][bj][m][0], o1 = bv[m][bj][1] + scale * acc[ai][bj][m][1];
;                     *(f32x4*)(out + off + bj * 128) = o0; *(f32x4*)(out + off + bj * 128 + 4) = o1;
;                     if (xb) { *(u32x4*)(xb + off + bj * 128) = __builtin_bit_cast(u32x4, pack8(o0, o1));
;                         sq += (o0[0] * o0[0] + o0[1] * o0[1] + o0[2] * o0[2] + o0[3] * o0[3]) + (o1[0] * o1[0] + o1[1] * o1[1] + o1[2] * o1[2] + o1[3] * o1[3]); } }
;                 if (ssout) { sq += __shfl_xor(sq, 16); sq += __shfl_xor(sq, 32);
;                     if (fq == 0) { if (red) red[(ai * 128 + wr * 64 + m * 16 + fr) * 4 + wc] = sq; else atomicAdd(ssout + (size_t)(row0 + ai * 128 + m * 16) * 8 + u.pn, sq); } } }
	s_waitcnt lgkmcnt(0)
	v_mfma_f32_16x16x32_bf16 v[60:63], v[128:131], v[154:157], v[60:63]
	v_mfma_f32_16x16x32_bf16 v[56:59], v[136:139], v[154:157], v[56:59]
	v_mfma_f32_16x16x32_bf16 v[44:47], v[128:131], v[182:185], v[44:47]
	v_mfma_f32_16x16x32_bf16 v[40:43], v[136:139], v[182:185], v[40:43]
	v_mfma_f32_16x16x32_bf16 v[28:31], v[128:131], v[190:193], v[28:31]
	v_mfma_f32_16x16x32_bf16 v[24:27], v[136:139], v[190:193], v[24:27]
	v_mfma_f32_16x16x32_bf16 v[12:15], v[128:131], v[214:217], v[12:15]
	v_mfma_f32_16x16x32_bf16 v[8:11], v[136:139], v[214:217], v[8:11]
	v_mfma_f32_16x16x32_bf16 v[60:63], v[132:135], v[174:177], v[60:63]
	v_mfma_f32_16x16x32_bf16 v[56:59], v[140:143], v[174:177], v[56:59]
	v_mfma_f32_16x16x32_bf16 v[44:47], v[132:135], v[186:189], v[44:47]
	v_mfma_f32_16x16x32_bf16 v[40:43], v[140:143], v[186:189], v[40:43]
	v_mfma_f32_16x16x32_bf16 v[28:31], v[132:135], v[194:197], v[28:31]
	v_mfma_f32_16x16x32_bf16 v[24:27], v[140:143], v[194:197], v[24:27]
	v_mfma_f32_16x16x32_bf16 v[12:15], v[132:135], v[218:221], v[12:15]
	v_mfma_f32_16x16x32_bf16 v[8:11], v[140:143], v[218:221], v[8:11]
	s_barrier
	s_add_u32 s28, s28, 0x80080
	s_addc_u32 s29, s29, 0
	s_add_i32 s30, s30, s36
	v_lshl_add_u64 v[128:129], s[28:29], 0, v[160:161]
	s_mov_b32 m0, s30
	s_nop 0
	global_load_lds_dwordx4 v[128:129], off
	v_lshl_add_u64 v[128:129], s[28:29], 0, v[148:149]
	s_add_i32 m0, s30, 0x2000
	s_nop 0
	global_load_lds_dwordx4 v[128:129], off
	s_waitcnt vmcnt(6)
	s_barrier
	v_mfma_f32_16x16x32_bf16 v[52:55], v[222:225], v[154:157], v[52:55]
	v_mfma_f32_16x16x32_bf16 v[48:51], v[230:233], v[154:157], v[48:51]
	v_mfma_f32_16x16x32_bf16 v[36:39], v[222:225], v[182:185], v[36:39]
	v_mfma_f32_16x16x32_bf16 v[32:35], v[230:233], v[182:185], v[32:35]
	v_mfma_f32_16x16x32_bf16 v[20:23], v[222:225], v[190:193], v[20:23]
	v_mfma_f32_16x16x32_bf16 v[16:19], v[230:233], v[190:193], v[16:19]
	v_mfma_f32_16x16x32_bf16 v[4:7], v[222:225], v[214:217], v[4:7]
	v_mfma_f32_16x16x32_bf16 v[0:3], v[230:233], v[214:217], v[0:3]
	v_mfma_f32_16x16x32_bf16 v[52:55], v[226:229], v[174:177], v[52:55]
	v_mfma_f32_16x16x32_bf16 v[48:51], v[234:237], v[174:177], v[48:51]
	v_mfma_f32_16x16x32_bf16 v[36:39], v[226:229], v[186:189], v[36:39]
	v_mfma_f32_16x16x32_bf16 v[32:35], v[234:237], v[186:189], v[32:35]
	v_mfma_f32_16x16x32_bf16 v[20:23], v[226:229], v[194:197], v[20:23]
	v_mfma_f32_16x16x32_bf16 v[16:19], v[234:237], v[194:197], v[16:19]
	v_mfma_f32_16x16x32_bf16 v[4:7], v[226:229], v[218:221], v[4:7]
	v_mfma_f32_16x16x32_bf16 v[0:3], v[234:237], v[218:221], v[0:3]
	s_add_i32 s48, s48, 2
	s_add_u32 s26, s26, 0x100
	s_addc_u32 s27, s27, 0
	s_add_u32 s46, s46, 0x100
	s_addc_u32 s47, s47, 0
	s_cmp_gt_u32 s48, 29
	s_barrier
	s_cbranch_scc0 .LBB0_61
	v_lshl_add_u32 v156, s24, 8, v167
	v_lshl_or_b32 v154, s14, 8, v179
	v_readlane_b32 s24, v254, 16
	v_ashrrev_i32_e32 v155, 31, v154
	v_readlane_b32 s25, v254, 17
	v_ashrrev_i32_e32 v157, 31, v156
	v_lshlrev_b64 v[128:129], 13, v[156:157]
	v_lshl_add_u64 v[158:159], v[154:155], 2, s[24:25]
	v_lshl_add_u64 v[214:215], v[158:159], 0, v[128:129]
	global_load_dwordx4 v[182:185], v[214:215], off offset:16
	global_load_dwordx4 v[186:189], v[214:215], off
	global_load_dwordx4 v[190:193], v[214:215], off offset:528
	global_load_dwordx4 v[194:197], v[214:215], off offset:512
	v_or_b32_e32 v174, 16, v156
	v_ashrrev_i32_e32 v175, 31, v174
	v_lshlrev_b64 v[128:129], 13, v[174:175]
	v_lshl_add_u64 v[176:177], v[158:159], 0, v[128:129]
	global_load_dwordx4 v[136:139], v[176:177], off offset:16
	global_load_dwordx4 v[140:143], v[176:177], off
	global_load_dwordx4 v[128:131], v[176:177], off offset:528
	global_load_dwordx4 v[132:135], v[176:177], off offset:512
	v_lshlrev_b64 v[216:217], 11, v[156:157]
	v_readlane_b32 s24, v250, 9
	v_lshl_add_u64 v[216:217], v[216:217], 0, v[154:155]
	v_readlane_b32 s25, v250, 10
	v_cmp_lt_i32_e32 vcc, v208, v206
	s_ashr_i32 s15, s14, 31
	s_waitcnt vmcnt(0)
	v_pk_add_f32 v[120:121], v[120:121], v[182:183]
	v_pk_add_f32 v[126:127], v[126:127], v[188:189]
	v_pk_add_f32 v[124:125], v[124:125], v[186:187]
	v_pk_add_f32 v[122:123], v[122:123], v[184:185]
	global_store_dwordx4 v[214:215], v[124:127], off
	global_store_dwordx4 v[214:215], v[120:123], off offset:16
	v_cvt_pk_bf16_f32 v184, v120, v121
	v_cvt_pk_bf16_f32 v182, v124, v125
	v_mul_f32_e32 v121, v121, v121
	v_cvt_pk_bf16_f32 v183, v126, v127
	v_cvt_pk_bf16_f32 v185, v122, v123
	v_lshl_add_u64 v[186:187], v[216:217], 1, s[24:25]
	v_fmac_f32_e32 v121, v120, v120
	v_pk_add_f32 v[118:119], v[118:119], v[196:197]
	v_pk_add_f32 v[116:117], v[116:117], v[194:195]
	v_pk_add_f32 v[112:113], v[112:113], v[190:191]
	global_store_dwordx4 v[186:187], v[182:185], off
	v_mul_f32_e32 v125, v125, v125
	v_fmac_f32_e32 v121, v122, v122
	v_pk_add_f32 v[114:115], v[114:115], v[192:193]
	global_store_dwordx4 v[214:215], v[116:119], off offset:512
	global_store_dwordx4 v[214:215], v[112:115], off offset:528
	v_cvt_pk_bf16_f32 v120, v116, v117
	v_cvt_pk_bf16_f32 v122, v112, v113
	v_mul_f32_e32 v117, v117, v117
	v_mul_f32_e32 v113, v113, v113
	v_fmac_f32_e32 v125, v124, v124
	v_fmac_f32_e32 v117, v116, v116
	v_fmac_f32_e32 v113, v112, v112
	v_fmac_f32_e32 v125, v126, v126
	v_fmac_f32_e32 v117, v118, v118
	v_fmac_f32_e32 v113, v114, v114
	v_fmac_f32_e32 v125, v127, v127
	v_fmac_f32_e32 v121, v123, v123
	v_fmac_f32_e32 v117, v119, v119
	v_fmac_f32_e32 v113, v115, v115
	v_add_f32_e32 v124, v125, v121
	v_add_f32_e32 v112, v117, v113
	v_cndmask_b32_e32 v113, v204, v208, vcc
	v_cvt_pk_bf16_f32 v121, v118, v119
	v_add_f32_e32 v112, v124, v112
	v_lshlrev_b32_e32 v118, 2, v113
	ds_bpermute_b32 v113, v118, v112
	v_cmp_lt_i32_e32 vcc, v207, v206
	v_cvt_pk_bf16_f32 v123, v114, v115
	global_store_dwordx4 v[186:187], v[120:123], off offset:256
	s_waitcnt lgkmcnt(0)
	v_add_f32_e32 v112, v112, v113
	v_cndmask_b32_e32 v113, v204, v207, vcc
	v_lshlrev_b32_e32 v119, 2, v113
	ds_bpermute_b32 v113, v119, v112
	s_and_saveexec_b64 s[24:25], s[6:7]
	s_cbranch_execz .LBB0_67
	s_waitcnt lgkmcnt(0)
	v_add_f32_e32 v112, v112, v113
	s_mov_b64 s[26:27], -1
	s_and_b64 vcc, exec, s[12:13]
	s_cbranch_vccz .LBB0_65
	v_readlane_b32 s26, v250, 37
	v_lshlrev_b64 v[114:115], 5, v[156:157]
	v_readlane_b32 s27, v250, 38
	s_nop 1
	v_lshl_add_u64 v[114:115], s[26:27], 0, v[114:115]
	v_lshl_add_u64 v[114:115], s[14:15], 2, v[114:115]
	global_atomic_add_f32 v[114:115], v112, off
	s_mov_b64 s[26:27], 0

; #define PG8_STAGE(bufoff, gbase, voff) do { _Pragma("unroll") for (int _i = 0; _i < 2; ++_i) \
;         __builtin_amdgcn_global_load_lds((const unsigned*)((const char*)(gbase) + (voff)[_i]), (LAS unsigned*)(lds + (bufoff) + ldsw + _i * 8192), 16, 0, 0); } while (0)
; #define PG8_BAR __builtin_amdgcn_s_barrier()
; template <class Epi>
; DEV void gemm_phase(LAS unsigned char* lds, const Gemm g, const StaticOrder& S, const Epi& E) {
;     ...
;     for (int i = 0; i < 2; ++i) { int R, C; stage_rc(tid * 16 + i * 8192, R, C); const int Rb = Epi::PERM ? ((R & ~31) + perm32(R & 31)) : R;
;         voffA[i] = (unsigned)(R * K + C) * 2u; voffB[i] = (unsigned)(Rb * K + C) * 2u; }
;     const size_t kstep = (size_t)(BK * 2);
;     const size_t hstep = (size_t)HALF * K * 2;
;     const size_t tstep = 2 * hstep;
;     const unsigned ldsw = (unsigned)wid * 1024u;
;     const int aoff = lds_byte(wr * 64 + fr, fq * 8), boff = lds_byte(wc * 32 + fr, fq * 8);
;     ...
;     const char* cA = (const char*)g.A + (size_t)cur.pm * tstep; const char* cB = (const char*)g.Bt + (size_t)cur.pn * tstep;
;     PG8_STAGE(PG8_SB(0, 0), cB, voffB); PG8_STAGE(PG8_SA(0, 0), cA, voffA); PG8_STAGE(PG8_SB(0, 1), cB + hstep, voffB); PG8_STAGE(PG8_SA(0, 1), cA + hstep, voffA);
;     if (wr == 1) PG8_BAR;
.LBB0_144:
	s_andn2_b64 vcc, exec, s[0:1]
	s_cbranch_vccnz .LBB0_212
	s_waitcnt lgkmcnt(0)
	v_ashrrev_i32_e32 v1, 31, v8
	v_lshrrev_b32_e32 v1, 26, v1
	v_add_u32_e32 v1, v8, v1
	v_ashrrev_i32_e32 v9, 6, v1
	v_bfe_i32 v1, v8, 27, 1
	v_lshlrev_b32_e32 v0, 4, v8
	v_lshrrev_b32_e32 v1, 22, v1
	v_add_u32_e32 v1, v0, v1
	v_and_b32_e32 v1, 0xfffffc00, v1
	v_sub_u32_e32 v1, v0, v1
	v_lshrrev_b32_e32 v2, 4, v1
	v_bitop3_b32 v2, v2, v1, 32 bitop3:0x6c
	v_ashrrev_i32_e32 v1, 31, v1
	v_lshrrev_b32_e32 v1, 26, v1
	v_add_u32_e32 v1, v2, v1
	v_ashrrev_i32_e32 v10, 6, v1
	v_mul_i32_i24_e32 v4, 64, v10
	v_sub_u32_e32 v2, v2, v4
	v_lshlrev_b32_e32 v3, 3, v9
	v_lshlrev_b32_e32 v1, 5, v9
	v_ashrrev_i16_sdwa v2, v203, sext(v2) dst_sel:DWORD dst_unused:UNUSED_PAD src0_sel:DWORD src1_sel:BYTE_0
	v_and_b32_e32 v3, 0xffff0, v3
	v_and_b32_e32 v1, 32, v1
	v_bfe_i32 v11, v2, 0, 16
	v_add_u32_e32 v1, v1, v11
	v_add_lshl_u32 v2, v10, v3, 12
	v_add_u32_e32 v0, 0x2000, v0
	v_lshl_add_u32 v160, v1, 1, v2
	v_ashrrev_i32_e32 v1, 31, v0
	v_lshrrev_b32_e32 v1, 22, v1
	v_add_u32_e32 v1, v0, v1
	v_ashrrev_i32_e32 v12, 10, v1
	v_mul_i32_i24_e32 v1, 0x400, v12
	v_sub_u32_e32 v0, v0, v1
	v_lshrrev_b32_e32 v1, 4, v0
	v_bitop3_b32 v0, v1, v0, 32 bitop3:0x6c
	v_ashrrev_i32_e32 v2, 31, v0
	v_lshrrev_b32_e32 v2, 26, v2
	s_ashr_i32 s0, s25, 6
	v_add_u32_e32 v2, v0, v2
	s_ashr_i32 s5, s4, 31
	s_ashr_i32 s17, s16, 31
	v_ashrrev_i32_e32 v13, 6, v2
	v_and_b32_e32 v2, 0xc0, v2
	s_ashr_i32 s1, s25, 8
	s_lshl_b32 s26, s0, 10
	s_lshl_b64 s[6:7], s[4:5], 20
	s_lshl_b64 s[8:9], s[16:17], 20
	v_readlane_b32 s10, v250, 49
	v_sub_u32_e32 v0, v0, v2
	v_readlane_b32 s11, v250, 50
	s_add_u32 s20, s10, s8
	v_lshlrev_b32_e32 v1, 3, v12
	v_lshlrev_b32_e32 v3, 5, v12
	v_ashrrev_i16_sdwa v0, v203, sext(v0) dst_sel:DWORD dst_unused:UNUSED_PAD src0_sel:DWORD src1_sel:BYTE_0
	s_addc_u32 s21, s11, s9
	s_add_i32 s17, s26, 0
	v_and_b32_e32 v1, 0xffff0, v1
	v_and_b32_e32 v3, 32, v3
	v_bfe_i32 v14, v0, 0, 16
	s_add_i32 m0, s17, 0x10000
	v_add_u32_e32 v0, v3, v14
	v_add_lshl_u32 v1, v13, v1, 12
	global_load_lds_dwordx4 v160, s[20:21]
	s_add_i32 m0, s17, 0x12000
	v_readlane_b32 s8, v250, 9
	v_lshl_add_u32 v144, v0, 1, v1
	v_readlane_b32 s9, v250, 10
	s_add_u32 s18, s8, s6
	global_load_lds_dwordx4 v144, s[20:21]
	s_addc_u32 s19, s9, s7
	s_mov_b32 m0, s17
	s_add_i32 s27, s17, 0x2000
	global_load_lds_dwordx4 v160, s[18:19]
	s_mov_b32 m0, s27
	s_add_u32 s6, s20, 0x80000
	global_load_lds_dwordx4 v144, s[18:19]
	s_addc_u32 s7, s21, 0
	s_add_i32 m0, s17, 0x14000
	v_mov_b32_e32 v145, v161
	global_load_lds_dwordx4 v160, s[6:7]
	s_add_i32 m0, s17, 0x16000
	v_lshl_add_u64 v[6:7], s[20:21], 0, v[160:161]
	global_load_lds_dwordx4 v144, s[6:7]
	s_add_u32 s6, s18, 0x80000
	s_addc_u32 s7, s19, 0
	s_add_i32 s28, s17, 0x4000
	s_mov_b32 m0, s28
	s_add_i32 s29, s17, 0x6000
	global_load_lds_dwordx4 v160, s[6:7]
	s_mov_b32 m0, s29
	v_lshl_add_u64 v[4:5], s[20:21], 0, v[144:145]
	global_load_lds_dwordx4 v144, s[6:7]
	v_lshl_add_u64 v[2:3], s[18:19], 0, v[160:161]
	s_cmp_lg_u32 s1, 1
	v_lshl_add_u64 v[0:1], s[18:19], 0, v[144:145]
	s_cbranch_scc1 .LBB0_147
	s_barrier
	s_setprio 1

; #define PG8_STAGE(bufoff, gbase, voff) do { _Pragma("unroll") for (int _i = 0; _i < 2; ++_i) \
;         __builtin_amdgcn_global_load_lds((const unsigned*)((const char*)(gbase) + (voff)[_i]), (LAS unsigned*)(lds + (bufoff) + ldsw + _i * 8192), 16, 0, 0); } while (0)
; #define PG8_LDA(dst, b, h) do { _Pragma("unroll") for (int m = 0; m < 4; ++m) _Pragma("unroll") for (int k = 0; k < 2; ++k) dst[m][k] = *(const LAS bf16x8*)(lds + PG8_SA(b, h) + aoff + m * 2048 + k * 1024); } while (0)
; #define PG8_LDB(dst, b, h) do { _Pragma("unroll") for (int n = 0; n < 2; ++n) _Pragma("unroll") for (int k = 0; k < 2; ++k) dst[n][k] = *(const LAS bf16x8*)(lds + PG8_SB(b, h) + boff + n * 2048 + k * 1024); } while (0)
; #define PG8_MMA(ai, bj, At, Bt) do { __builtin_amdgcn_s_setprio(1); _Pragma("unroll") for (int m = 0; m < 4; ++m) _Pragma("unroll") for (int n = 0; n < 2; ++n) _Pragma("unroll") for (int k = 0; k < 2; ++k) \
;         acc[ai][bj][m][n] = __builtin_amdgcn_mfma_f32_16x16x32_bf16(Bt[n][k], At[m][k], acc[ai][bj][m][n], 0, 0, 0); __builtin_amdgcn_s_setprio(0); } while (0)
; #define PG8_WAIT_L(n) asm volatile("s_waitcnt lgkmcnt(" #n ")" ::: "memory")
; #define PG8_BAR __builtin_amdgcn_s_barrier()
; #define PG8_SCHED __builtin_amdgcn_sched_barrier(0)
; template <class Epi>
; DEV void gemm_phase(LAS unsigned char* lds, const Gemm g, const StaticOrder& S, const Epi& E) {
;     ...
;             PG8_LDB(B0, 0, 0); PG8_SCHED; PG8_LDA(At, 0, 0); PG8_STAGE(PG8_SA(1, 1), a1 + hstep, voffA);
;             PG8_WAIT_L(8); PG8_BAR; PG8_WAIT_L(0); PG8_MMA(0, 0, At, B0); PG8_BAR; PG8_SCHED;
;             PG8_LDB(B1, 0, 1); PG8_STAGE(PG8_SB(0, 0), b2, voffB);
;             PG8_BAR; PG8_WAIT_L(0); PG8_MMA(0, 1, At, B1); PG8_BAR;
;             PG8_LDA(At, 0, 1); PG8_STAGE(PG8_SA(0, 0), a2, voffA);
;             PG8_BAR; PG8_WAIT_L(0); PG8_MMA(1, 0, At, B0); PG8_BAR; PG8_SCHED;
.LBB0_152:
	s_add_u32 s20, s18, 0xfff80080
	s_addc_u32 s21, s19, -1
	s_add_i32 s41, 0, 0x10000
	v_add_u32_e32 v140, s41, v176
	ds_read_b128 v[128:131], v140
	ds_read_b128 v[132:135], v140 offset:1024
	ds_read_b128 v[136:139], v140 offset:2048
	ds_read_b128 v[140:143], v140 offset:3072
	s_cmp_eq_u32 s40, 28
	s_cselect_b32 s23, s5, s21
	s_cselect_b32 s22, s11, s20
	s_cselect_b32 s21, s9, s39
	s_cselect_b32 s20, s37, s38
	v_lshl_add_u64 v[158:159], s[18:19], 0, v[154:155]
	s_add_i32 m0, s17, 0xc000
	ds_read_b128 v[180:183], v178
	ds_read_b128 v[184:187], v178 offset:1024
	ds_read_b128 v[188:191], v178 offset:2048
	ds_read_b128 v[192:195], v178 offset:3072
	ds_read_b128 v[214:217], v178 offset:4096
	ds_read_b128 v[218:221], v178 offset:5120
	ds_read_b128 v[222:225], v178 offset:6144
	ds_read_b128 v[226:229], v178 offset:7168
	global_load_lds_dwordx4 v[158:159], off
	v_lshl_add_u64 v[158:159], s[18:19], 0, v[156:157]
	s_add_i32 m0, s17, 0xe000
	s_nop 0
	global_load_lds_dwordx4 v[158:159], off
	s_waitcnt lgkmcnt(8)
	s_barrier
	s_waitcnt lgkmcnt(0)
	v_mfma_f32_16x16x32_bf16 v[124:127], v[128:131], v[180:183], v[124:127]
	v_mfma_f32_16x16x32_bf16 v[120:123], v[136:139], v[180:183], v[120:123]
	v_mfma_f32_16x16x32_bf16 v[108:111], v[128:131], v[188:191], v[108:111]
	v_mfma_f32_16x16x32_bf16 v[104:107], v[136:139], v[188:191], v[104:107]
	v_mfma_f32_16x16x32_bf16 v[92:95], v[128:131], v[214:217], v[92:95]
	v_mfma_f32_16x16x32_bf16 v[88:91], v[136:139], v[214:217], v[88:91]
	v_mfma_f32_16x16x32_bf16 v[76:79], v[128:131], v[222:225], v[76:79]
	v_mfma_f32_16x16x32_bf16 v[72:75], v[136:139], v[222:225], v[72:75]
	v_mfma_f32_16x16x32_bf16 v[124:127], v[132:135], v[184:187], v[124:127]
	v_mfma_f32_16x16x32_bf16 v[120:123], v[140:143], v[184:187], v[120:123]
	v_mfma_f32_16x16x32_bf16 v[108:111], v[132:135], v[192:195], v[108:111]
	v_mfma_f32_16x16x32_bf16 v[104:107], v[140:143], v[192:195], v[104:107]
	v_mfma_f32_16x16x32_bf16 v[92:95], v[132:135], v[218:221], v[92:95]
	v_mfma_f32_16x16x32_bf16 v[88:91], v[140:143], v[218:221], v[88:91]
	v_mfma_f32_16x16x32_bf16 v[76:79], v[132:135], v[226:229], v[76:79]
	v_mfma_f32_16x16x32_bf16 v[72:75], v[140:143], v[226:229], v[72:75]
	s_barrier
	s_add_i32 s44, 0, 0x14000
	v_add_u32_e32 v158, s44, v176
	s_add_i32 s41, s41, s26
	ds_read_b128 v[230:233], v158
	ds_read_b128 v[234:237], v158 offset:1024
	ds_read_b128 v[238:241], v158 offset:2048
	ds_read_b128 v[242:245], v158 offset:3072
	v_lshl_add_u64 v[158:159], s[20:21], 0, v[160:161]
	s_mov_b32 m0, s41
	v_lshl_add_u64 v[174:175], s[20:21], 0, v[144:145]
	global_load_lds_dwordx4 v[158:159], off
	s_add_i32 m0, s41, 0x2000
	s_nop 0
	global_load_lds_dwordx4 v[174:175], off
	s_barrier
	s_waitcnt lgkmcnt(0)
	v_mfma_f32_16x16x32_bf16 v[116:119], v[230:233], v[180:183], v[116:119]
	v_mfma_f32_16x16x32_bf16 v[112:115], v[238:241], v[180:183], v[112:115]
	v_mfma_f32_16x16x32_bf16 v[100:103], v[230:233], v[188:191], v[100:103]
	v_mfma_f32_16x16x32_bf16 v[96:99], v[238:241], v[188:191], v[96:99]
	v_mfma_f32_16x16x32_bf16 v[84:87], v[230:233], v[214:217], v[84:87]
	v_mfma_f32_16x16x32_bf16 v[80:83], v[238:241], v[214:217], v[80:83]
	v_mfma_f32_16x16x32_bf16 v[68:71], v[230:233], v[222:225], v[68:71]
	v_mfma_f32_16x16x32_bf16 v[64:67], v[238:241], v[222:225], v[64:67]
	v_mfma_f32_16x16x32_bf16 v[116:119], v[234:237], v[184:187], v[116:119]
	v_mfma_f32_16x16x32_bf16 v[112:115], v[242:245], v[184:187], v[112:115]
	v_mfma_f32_16x16x32_bf16 v[100:103], v[234:237], v[192:195], v[100:103]
	v_mfma_f32_16x16x32_bf16 v[96:99], v[242:245], v[192:195], v[96:99]
	v_mfma_f32_16x16x32_bf16 v[84:87], v[234:237], v[218:221], v[84:87]
	v_mfma_f32_16x16x32_bf16 v[80:83], v[242:245], v[218:221], v[80:83]
	v_mfma_f32_16x16x32_bf16 v[68:71], v[234:237], v[226:229], v[68:71]
	v_mfma_f32_16x16x32_bf16 v[64:67], v[242:245], v[226:229], v[64:67]
	s_mov_b32 m0, s17
	v_lshl_add_u64 v[196:197], s[22:23], 0, v[160:161]
	s_barrier
	ds_read_b128 v[180:183], v178 offset:16384
	ds_read_b128 v[184:187], v178 offset:17408
	ds_read_b128 v[188:191], v178 offset:18432
	ds_read_b128 v[192:195], v178 offset:19456
	ds_read_b128 v[214:217], v178 offset:20480
	ds_read_b128 v[218:221], v178 offset:21504
	ds_read_b128 v[222:225], v178 offset:22528
	ds_read_b128 v[226:229], v178 offset:23552
	global_load_lds_dwordx4 v[196:197], off
	v_lshl_add_u64 v[246:247], s[22:23], 0, v[144:145]
	s_mov_b32 m0, s27
	s_nop 0
	global_load_lds_dwordx4 v[246:247], off
	s_barrier
	s_waitcnt lgkmcnt(0)
	v_mfma_f32_16x16x32_bf16 v[60:63], v[128:131], v[180:183], v[60:63]
	v_mfma_f32_16x16x32_bf16 v[56:59], v[136:139], v[180:183], v[56:59]
	v_mfma_f32_16x16x32_bf16 v[44:47], v[128:131], v[188:191], v[44:47]
	v_mfma_f32_16x16x32_bf16 v[40:43], v[136:139], v[188:191], v[40:43]
	v_mfma_f32_16x16x32_bf16 v[28:31], v[128:131], v[214:217], v[28:31]
	v_mfma_f32_16x16x32_bf16 v[24:27], v[136:139], v[214:217], v[24:27]
	v_mfma_f32_16x16x32_bf16 v[12:15], v[128:131], v[222:225], v[12:15]
	v_mfma_f32_16x16x32_bf16 v[8:11], v[136:139], v[222:225], v[8:11]
	v_mfma_f32_16x16x32_bf16 v[60:63], v[132:135], v[184:187], v[60:63]
	v_mfma_f32_16x16x32_bf16 v[56:59], v[140:143], v[184:187], v[56:59]
	v_mfma_f32_16x16x32_bf16 v[44:47], v[132:135], v[192:195], v[44:47]
	v_mfma_f32_16x16x32_bf16 v[40:43], v[140:143], v[192:195], v[40:43]
	v_mfma_f32_16x16x32_bf16 v[28:31], v[132:135], v[218:221], v[28:31]
	v_mfma_f32_16x16x32_bf16 v[24:27], v[140:143], v[218:221], v[24:27]
	v_mfma_f32_16x16x32_bf16 v[12:15], v[132:135], v[226:229], v[12:15]
	v_mfma_f32_16x16x32_bf16 v[8:11], v[140:143], v[226:229], v[8:11]
	s_barrier
; #define PG8_STAGE(bufoff, gbase, voff) do { _Pragma("unroll") for (int _i = 0; _i < 2; ++_i) \
;         __builtin_amdgcn_global_load_lds((const unsigned*)((const char*)(gbase) + (voff)[_i]), (LAS unsigned*)(lds + (bufoff) + ldsw + _i * 8192), 16, 0, 0); } while (0)
; #define PG8_LDA(dst, b, h) do { _Pragma("unroll") for (int m = 0; m < 4; ++m) _Pragma("unroll") for (int k = 0; k < 2; ++k) dst[m][k] = *(const LAS bf16x8*)(lds + PG8_SA(b, h) + aoff + m * 2048 + k * 1024); } while (0)
; #define PG8_LDB(dst, b, h) do { _Pragma("unroll") for (int n = 0; n < 2; ++n) _Pragma("unroll") for (int k = 0; k < 2; ++k) dst[n][k] = *(const LAS bf16x8*)(lds + PG8_SB(b, h) + boff + n * 2048 + k * 1024); } while (0)
; #define PG8_MMA(ai, bj, At, Bt) do { __builtin_amdgcn_s_setprio(1); _Pragma("unroll") for (int m = 0; m < 4; ++m) _Pragma("unroll") for (int n = 0; n < 2; ++n) _Pragma("unroll") for (int k = 0; k < 2; ++k) \
;         acc[ai][bj][m][n] = __builtin_amdgcn_mfma_f32_16x16x32_bf16(Bt[n][k], At[m][k], acc[ai][bj][m][n], 0, 0, 0); __builtin_amdgcn_s_setprio(0); } while (0)
; #define PG8_WAIT_V(n) asm volatile("s_waitcnt vmcnt(" #n ")" ::: "memory")
; #define PG8_WAIT_L(n) asm volatile("s_waitcnt lgkmcnt(" #n ")" ::: "memory")
; #define PG8_BAR __builtin_amdgcn_s_barrier()
; #define PG8_SCHED __builtin_amdgcn_sched_barrier(0)
; template <class Epi>
; DEV void gemm_phase(LAS unsigned char* lds, const Gemm g, const StaticOrder& S, const Epi& E) {
;     ...
;             PG8_STAGE(PG8_SB(0, 1), b2 + hstep, voffB);
;             PG8_WAIT_V(6); PG8_BAR; PG8_MMA(1, 1, At, B1); PG8_BAR;
;             PG8_LDB(B0, 1, 0); PG8_SCHED; PG8_LDA(At, 1, 0); PG8_STAGE(PG8_SA(0, 1), a2 + hstep, voffA);
;             PG8_WAIT_L(8); PG8_BAR; PG8_WAIT_L(0); PG8_MMA(0, 0, At, B0); PG8_BAR; PG8_SCHED;
;             PG8_LDB(B1, 1, 1); PG8_STAGE(PG8_SB(1, 0), b3, voffB);
;             PG8_BAR; PG8_WAIT_L(0); PG8_MMA(0, 1, At, B1); PG8_BAR;
	s_add_u32 s42, s20, 0x80000
	s_addc_u32 s43, s21, 0
	s_add_i32 s41, s44, s26
	v_lshl_add_u64 v[128:129], s[42:43], 0, v[160:161]
	s_mov_b32 m0, s41
	s_nop 0
	global_load_lds_dwordx4 v[128:129], off
	v_lshl_add_u64 v[128:129], s[42:43], 0, v[144:145]
	s_add_i32 m0, s41, 0x2000
	s_nop 0
	global_load_lds_dwordx4 v[128:129], off
	s_waitcnt vmcnt(6)
	s_barrier
	v_mfma_f32_16x16x32_bf16 v[52:55], v[230:233], v[180:183], v[52:55]
	v_mfma_f32_16x16x32_bf16 v[48:51], v[238:241], v[180:183], v[48:51]
	v_mfma_f32_16x16x32_bf16 v[36:39], v[230:233], v[188:191], v[36:39]
	v_mfma_f32_16x16x32_bf16 v[32:35], v[238:241], v[188:191], v[32:35]
	v_mfma_f32_16x16x32_bf16 v[20:23], v[230:233], v[214:217], v[20:23]
	v_mfma_f32_16x16x32_bf16 v[16:19], v[238:241], v[214:217], v[16:19]
	v_mfma_f32_16x16x32_bf16 v[4:7], v[230:233], v[222:225], v[4:7]
	v_mfma_f32_16x16x32_bf16 v[0:3], v[238:241], v[222:225], v[0:3]
	v_mfma_f32_16x16x32_bf16 v[52:55], v[234:237], v[184:187], v[52:55]
	v_mfma_f32_16x16x32_bf16 v[48:51], v[242:245], v[184:187], v[48:51]
	v_mfma_f32_16x16x32_bf16 v[36:39], v[234:237], v[192:195], v[36:39]
	v_mfma_f32_16x16x32_bf16 v[32:35], v[242:245], v[192:195], v[32:35]
	v_mfma_f32_16x16x32_bf16 v[20:23], v[234:237], v[218:221], v[20:23]
	v_mfma_f32_16x16x32_bf16 v[16:19], v[242:245], v[218:221], v[16:19]
	v_mfma_f32_16x16x32_bf16 v[4:7], v[234:237], v[226:229], v[4:7]
	v_mfma_f32_16x16x32_bf16 v[0:3], v[242:245], v[226:229], v[0:3]
	s_add_i32 s41, 0, 0x18000
	v_add_u32_e32 v140, s41, v176
	s_barrier
	ds_read_b128 v[128:131], v140
	ds_read_b128 v[132:135], v140 offset:1024
	ds_read_b128 v[136:139], v140 offset:2048
	ds_read_b128 v[140:143], v140 offset:3072
	s_add_u32 s22, s22, 0x80000
	s_addc_u32 s23, s23, 0
	s_mov_b32 m0, s28
	v_lshl_add_u64 v[230:231], s[22:23], 0, v[160:161]
	ds_read_b128 v[180:183], v178 offset:32768
	ds_read_b128 v[184:187], v178 offset:33792
	ds_read_b128 v[188:191], v178 offset:34816
	ds_read_b128 v[192:195], v178 offset:35840
	ds_read_b128 v[214:217], v178 offset:36864
	ds_read_b128 v[218:221], v178 offset:37888
	ds_read_b128 v[222:225], v178 offset:38912
	ds_read_b128 v[226:229], v178 offset:39936
	global_load_lds_dwordx4 v[230:231], off
	v_lshl_add_u64 v[230:231], s[22:23], 0, v[144:145]
	s_mov_b32 m0, s29
	s_nop 0
	global_load_lds_dwordx4 v[230:231], off
	s_waitcnt lgkmcnt(8)
	s_barrier
	s_waitcnt lgkmcnt(0)
	v_mfma_f32_16x16x32_bf16 v[124:127], v[128:131], v[180:183], v[124:127]
	v_mfma_f32_16x16x32_bf16 v[120:123], v[136:139], v[180:183], v[120:123]
	v_mfma_f32_16x16x32_bf16 v[108:111], v[128:131], v[188:191], v[108:111]
	v_mfma_f32_16x16x32_bf16 v[104:107], v[136:139], v[188:191], v[104:107]
	v_mfma_f32_16x16x32_bf16 v[92:95], v[128:131], v[214:217], v[92:95]
	v_mfma_f32_16x16x32_bf16 v[88:91], v[136:139], v[214:217], v[88:91]
	v_mfma_f32_16x16x32_bf16 v[76:79], v[128:131], v[222:225], v[76:79]
	v_mfma_f32_16x16x32_bf16 v[72:75], v[136:139], v[222:225], v[72:75]
	v_mfma_f32_16x16x32_bf16 v[124:127], v[132:135], v[184:187], v[124:127]
	v_mfma_f32_16x16x32_bf16 v[120:123], v[140:143], v[184:187], v[120:123]
	v_mfma_f32_16x16x32_bf16 v[108:111], v[132:135], v[192:195], v[108:111]
	v_mfma_f32_16x16x32_bf16 v[104:107], v[140:143], v[192:195], v[104:107]
	v_mfma_f32_16x16x32_bf16 v[92:95], v[132:135], v[218:221], v[92:95]
	v_mfma_f32_16x16x32_bf16 v[88:91], v[140:143], v[218:221], v[88:91]
	v_mfma_f32_16x16x32_bf16 v[76:79], v[132:135], v[226:229], v[76:79]
	v_mfma_f32_16x16x32_bf16 v[72:75], v[140:143], v[226:229], v[72:75]
	s_barrier
	s_add_i32 s22, 0, 0x1c000
	s_add_i32 s23, s41, s26
	v_add_u32_e32 v179, s22, v176
	v_lshl_add_u64 v[158:159], v[158:159], 0, s[2:3]
	s_mov_b32 m0, s23
	ds_read_b128 v[230:233], v179
	ds_read_b128 v[234:237], v179 offset:1024
	ds_read_b128 v[238:241], v179 offset:2048
	ds_read_b128 v[242:245], v179 offset:3072
	global_load_lds_dwordx4 v[158:159], off
	v_lshl_add_u64 v[158:159], v[174:175], 0, s[2:3]
	s_add_i32 m0, s23, 0x2000
	s_nop 0
	global_load_lds_dwordx4 v[158:159], off
	s_barrier
	s_waitcnt lgkmcnt(0)
	v_mfma_f32_16x16x32_bf16 v[116:119], v[230:233], v[180:183], v[116:119]
	v_mfma_f32_16x16x32_bf16 v[112:115], v[238:241], v[180:183], v[112:115]
	v_mfma_f32_16x16x32_bf16 v[100:103], v[230:233], v[188:191], v[100:103]
	v_mfma_f32_16x16x32_bf16 v[96:99], v[238:241], v[188:191], v[96:99]
	v_mfma_f32_16x16x32_bf16 v[84:87], v[230:233], v[214:217], v[84:87]
	v_mfma_f32_16x16x32_bf16 v[80:83], v[238:241], v[214:217], v[80:83]
	v_mfma_f32_16x16x32_bf16 v[68:71], v[230:233], v[222:225], v[68:71]
	v_mfma_f32_16x16x32_bf16 v[64:67], v[238:241], v[222:225], v[64:67]
	v_mfma_f32_16x16x32_bf16 v[116:119], v[234:237], v[184:187], v[116:119]
	v_mfma_f32_16x16x32_bf16 v[112:115], v[242:245], v[184:187], v[112:115]
	v_mfma_f32_16x16x32_bf16 v[100:103], v[234:237], v[192:195], v[100:103]
	v_mfma_f32_16x16x32_bf16 v[96:99], v[242:245], v[192:195], v[96:99]
	v_mfma_f32_16x16x32_bf16 v[84:87], v[234:237], v[218:221], v[84:87]
	v_mfma_f32_16x16x32_bf16 v[80:83], v[242:245], v[218:221], v[80:83]
	v_mfma_f32_16x16x32_bf16 v[68:71], v[234:237], v[226:229], v[68:71]
	v_mfma_f32_16x16x32_bf16 v[64:67], v[242:245], v[226:229], v[64:67]
	s_mov_b32 m0, s30
	v_lshl_add_u64 v[158:159], v[196:197], 0, s[2:3]
	s_barrier
; #define PG8_STAGE(bufoff, gbase, voff) do { _Pragma("unroll") for (int _i = 0; _i < 2; ++_i) \
;         __builtin_amdgcn_global_load_lds((const unsigned*)((const char*)(gbase) + (voff)[_i]), (LAS unsigned*)(lds + (bufoff) + ldsw + _i * 8192), 16, 0, 0); } while (0)
; #define PG8_LDA(dst, b, h) do { _Pragma("unroll") for (int m = 0; m < 4; ++m) _Pragma("unroll") for (int k = 0; k < 2; ++k) dst[m][k] = *(const LAS bf16x8*)(lds + PG8_SA(b, h) + aoff + m * 2048 + k * 1024); } while (0)
; #define PG8_MMA(ai, bj, At, Bt) do { __builtin_amdgcn_s_setprio(1); _Pragma("unroll") for (int m = 0; m < 4; ++m) _Pragma("unroll") for (int n = 0; n < 2; ++n) _Pragma("unroll") for (int k = 0; k < 2; ++k) \
;         acc[ai][bj][m][n] = __builtin_amdgcn_mfma_f32_16x16x32_bf16(Bt[n][k], At[m][k], acc[ai][bj][m][n], 0, 0, 0); __builtin_amdgcn_s_setprio(0); } while (0)
; #define PG8_WAIT_V(n) asm volatile("s_waitcnt vmcnt(" #n ")" ::: "memory")
; #define PG8_WAIT_L(n) asm volatile("s_waitcnt lgkmcnt(" #n ")" ::: "memory")
; #define PG8_BAR __builtin_amdgcn_s_barrier()
; #define PG8_SCHED __builtin_amdgcn_sched_barrier(0)
; template <class Epi>
; DEV void gemm_phase(LAS unsigned char* lds, const Gemm g, const StaticOrder& S, const Epi& E) {
;     ...
;             PG8_LDA(At, 1, 1); PG8_STAGE(PG8_SA(1, 0), a3, voffA);
;             PG8_BAR; PG8_WAIT_L(0); PG8_MMA(1, 0, At, B0); PG8_BAR; PG8_SCHED;
;             PG8_STAGE(PG8_SB(1, 1), b3 + hstep, voffB);
;             PG8_WAIT_V(6); PG8_BAR; PG8_MMA(1, 1, At, B1); PG8_BAR;
;     DEV void operator()(AccRef acc, const pg8::Unit& u, int wr, int wc, int fr, int fq) const {
;         const int row0 = u.pm * 256 + wr * 64 + fr, col0 = u.pn * 256 + wc * 32 + 4 * fq;
;         const bool rope = (u.pn < 9) && ((wc & 1) == 0);
; #pragma unroll
;         for (int ai = 0; ai < 2; ++ai)
; #pragma unroll
;             for (int m = 0; m < 4; ++m) { const int row = row0 + ai * 128 + m * 16; u16* rowp = O + (size_t)row * 2560 + col0; const float rs = rowscale(ss, row);
;                 f32x4 cs = (f32x4){1.f, 1.f, 1.f, 1.f}, sn = (f32x4){0.f, 0.f, 0.f, 0.f};
;                 if (rope) { cs = *(const f32x4*)(cosT + row * 8 + 4 * (fq & 1)); sn = *(const f32x4*)(sinT + row * 8 + 4 * (fq & 1)); }
	ds_read_b128 v[180:183], v178 offset:49152
	ds_read_b128 v[184:187], v178 offset:50176
	ds_read_b128 v[188:191], v178 offset:51200
	ds_read_b128 v[192:195], v178 offset:52224
	ds_read_b128 v[214:217], v178 offset:53248
	ds_read_b128 v[218:221], v178 offset:54272
	ds_read_b128 v[222:225], v178 offset:55296
	ds_read_b128 v[226:229], v178 offset:56320
	global_load_lds_dwordx4 v[158:159], off
	v_lshl_add_u64 v[158:159], v[246:247], 0, s[2:3]
	s_mov_b32 m0, s31
	s_nop 0
	global_load_lds_dwordx4 v[158:159], off
	s_barrier
	s_waitcnt lgkmcnt(0)
	v_mfma_f32_16x16x32_bf16 v[60:63], v[128:131], v[180:183], v[60:63]
	v_mfma_f32_16x16x32_bf16 v[56:59], v[136:139], v[180:183], v[56:59]
	v_mfma_f32_16x16x32_bf16 v[44:47], v[128:131], v[188:191], v[44:47]
	v_mfma_f32_16x16x32_bf16 v[40:43], v[136:139], v[188:191], v[40:43]
	v_mfma_f32_16x16x32_bf16 v[28:31], v[128:131], v[214:217], v[28:31]
	v_mfma_f32_16x16x32_bf16 v[24:27], v[136:139], v[214:217], v[24:27]
	v_mfma_f32_16x16x32_bf16 v[12:15], v[128:131], v[222:225], v[12:15]
	v_mfma_f32_16x16x32_bf16 v[8:11], v[136:139], v[222:225], v[8:11]
	v_mfma_f32_16x16x32_bf16 v[60:63], v[132:135], v[184:187], v[60:63]
	v_mfma_f32_16x16x32_bf16 v[56:59], v[140:143], v[184:187], v[56:59]
	v_mfma_f32_16x16x32_bf16 v[44:47], v[132:135], v[192:195], v[44:47]
	v_mfma_f32_16x16x32_bf16 v[40:43], v[140:143], v[192:195], v[40:43]
	v_mfma_f32_16x16x32_bf16 v[28:31], v[132:135], v[218:221], v[28:31]
	v_mfma_f32_16x16x32_bf16 v[24:27], v[140:143], v[218:221], v[24:27]
	v_mfma_f32_16x16x32_bf16 v[12:15], v[132:135], v[226:229], v[12:15]
	v_mfma_f32_16x16x32_bf16 v[8:11], v[140:143], v[226:229], v[8:11]
	s_barrier
	s_add_u32 s20, s20, 0x80080
	s_addc_u32 s21, s21, 0
	s_add_i32 s22, s22, s26
	v_lshl_add_u64 v[128:129], s[20:21], 0, v[160:161]
	s_mov_b32 m0, s22
	s_nop 0
	global_load_lds_dwordx4 v[128:129], off
	v_lshl_add_u64 v[128:129], s[20:21], 0, v[144:145]
	s_add_i32 m0, s22, 0x2000
	s_nop 0
	global_load_lds_dwordx4 v[128:129], off
	s_waitcnt vmcnt(6)
	s_barrier
	v_mfma_f32_16x16x32_bf16 v[52:55], v[230:233], v[180:183], v[52:55]
	v_mfma_f32_16x16x32_bf16 v[48:51], v[238:241], v[180:183], v[48:51]
	v_mfma_f32_16x16x32_bf16 v[36:39], v[230:233], v[188:191], v[36:39]
	v_mfma_f32_16x16x32_bf16 v[32:35], v[238:241], v[188:191], v[32:35]
	v_mfma_f32_16x16x32_bf16 v[20:23], v[230:233], v[214:217], v[20:23]
	v_mfma_f32_16x16x32_bf16 v[16:19], v[238:241], v[214:217], v[16:19]
	v_mfma_f32_16x16x32_bf16 v[4:7], v[230:233], v[222:225], v[4:7]
	v_mfma_f32_16x16x32_bf16 v[0:3], v[238:241], v[222:225], v[0:3]
	v_mfma_f32_16x16x32_bf16 v[52:55], v[234:237], v[184:187], v[52:55]
	v_mfma_f32_16x16x32_bf16 v[48:51], v[242:245], v[184:187], v[48:51]
	v_mfma_f32_16x16x32_bf16 v[36:39], v[234:237], v[192:195], v[36:39]
	v_mfma_f32_16x16x32_bf16 v[32:35], v[242:245], v[192:195], v[32:35]
	v_mfma_f32_16x16x32_bf16 v[20:23], v[234:237], v[218:221], v[20:23]
	v_mfma_f32_16x16x32_bf16 v[16:19], v[242:245], v[218:221], v[16:19]
	v_mfma_f32_16x16x32_bf16 v[4:7], v[234:237], v[226:229], v[4:7]
	v_mfma_f32_16x16x32_bf16 v[0:3], v[242:245], v[226:229], v[0:3]
	s_add_i32 s40, s40, 2
	s_add_u32 s18, s18, 0x100
	s_addc_u32 s19, s19, 0
	s_add_u32 s38, s38, 0x100
	s_addc_u32 s39, s39, 0
	s_cmp_gt_u32 s40, 29
	s_barrier
	s_cbranch_scc0 .LBB0_152
	v_lshl_add_u32 v174, s4, 8, v167
	v_ashrrev_i32_e32 v175, 31, v174
	v_readlane_b32 s20, v250, 47
	v_lshlrev_b64 v[128:129], 5, v[174:175]
	v_readlane_b32 s21, v250, 48
	s_cmp_lt_i32 s16, 9
	s_cselect_b64 s[4:5], -1, 0
	v_lshl_add_u64 v[128:129], s[20:21], 0, v[128:129]
	global_load_dwordx4 v[136:139], v[128:129], off offset:16
	global_load_dwordx4 v[140:143], v[128:129], off
	s_and_b64 s[18:19], s[6:7], s[4:5]
	v_cndmask_b32_e64 v128, 0, 1, s[18:19]
	v_cmp_ne_u32_e64 s[4:5], 1, v128
	s_andn2_b64 vcc, exec, s[18:19]
	s_cbranch_vccnz .LBB0_155
	v_lshlrev_b32_e32 v128, 3, v174
	v_ashrrev_i32_e32 v129, 31, v128
	v_lshlrev_b64 v[128:129], 2, v[128:129]
	v_lshl_add_u64 v[130:131], v[152:153], 0, v[128:129]
	v_lshl_add_u64 v[132:133], v[150:151], 0, v[128:129]
	global_load_dwordx4 v[128:131], v[130:131], off
	s_nop 0
	global_load_dwordx4 v[132:135], v[132:133], off
	s_branch .LBB0_156

; #define LAS __attribute__((address_space(3)))
; #define PG8_STAGE(bufoff, gbase, voff) do { _Pragma("unroll") for (int _i = 0; _i < 2; ++_i) \
;         __builtin_amdgcn_global_load_lds((const unsigned*)((const char*)(gbase) + (voff)[_i]), (LAS unsigned*)(lds + (bufoff) + ldsw + _i * 8192), 16, 0, 0); } while (0)
; #define PG8_WAIT_V(n) asm volatile("s_waitcnt vmcnt(" #n ")" ::: "memory")
; #define PG8_BAR __builtin_amdgcn_s_barrier()
; template <class Epi>
; DEV void gemm_phase(LAS unsigned char* lds, const Gemm g, const StaticOrder& S, const Epi& E) {
;     ...
;     const char* cA = (const char*)g.A + (size_t)cur.pm * tstep; const char* cB = (const char*)g.Bt + (size_t)cur.pn * tstep;
;     PG8_STAGE(PG8_SB(0, 0), cB, voffB); PG8_STAGE(PG8_SA(0, 0), cA, voffA); PG8_STAGE(PG8_SB(0, 1), cB + hstep, voffB); PG8_STAGE(PG8_SA(0, 1), cA + hstep, voffA);
;     if (wr == 1) PG8_BAR;
;     PG8_WAIT_V(4); PG8_BAR;
;     PG8_STAGE(PG8_SB(1, 0), cB + kstep, voffB); PG8_STAGE(PG8_SA(1, 0), cA + kstep, voffA); PG8_STAGE(PG8_SB(1, 1), cB + hstep + kstep, voffB);
;     PG8_WAIT_V(6); PG8_BAR;
; DEV void run_resid_gemm(LAS unsigned char* lds, const u16* A, const u16* Bt, int K, const float* base, float* out, float scale, u16* xb, float* ssout, int bx, int G) {
;     ...
;     EpiResid E{base, out, scale, xb, ssout, (one && ssout) ? red : (LAS float*)nullptr};
;     run_gemm(lds, A, Bt, 8192, 2048, K, E, bx);
.LBB0_248:
	v_readlane_b32 s0, v254, 26
	v_readlane_b32 s1, v254, 27
	s_and_b64 s[0:1], s[0:1], exec
	s_mov_b32 s0, 0x1c0000
	s_cselect_b32 s0, s0, 0xc0000
	v_readlane_b32 s4, v254, 18
	v_readlane_b32 s5, v254, 19
	s_add_u32 s12, s4, s0
	s_addc_u32 s13, s5, 0
	v_readlane_b32 s0, v254, 23
	s_cmpk_eq_i32 s0, 0x100
	s_cselect_b64 s[14:15], -1, 0
	s_cmpk_lg_i32 s0, 0x100
	v_cndmask_b32_e64 v0, 0, 1, s[10:11]
	s_cselect_b64 s[16:17], -1, 0
	v_cmp_ne_u32_e64 s[0:1], 1, v0
	s_andn2_b64 vcc, exec, s[10:11]
	s_cbranch_vccnz .LBB0_306
	s_waitcnt lgkmcnt(0)
	v_ashrrev_i32_e32 v1, 31, v8
	v_lshrrev_b32_e32 v1, 26, v1
	v_add_u32_e32 v1, v8, v1
	v_ashrrev_i32_e32 v9, 6, v1
	v_bfe_i32 v1, v8, 27, 1
	v_lshlrev_b32_e32 v0, 4, v8
	v_lshrrev_b32_e32 v1, 22, v1
	v_add_u32_e32 v1, v0, v1
	v_and_b32_e32 v1, 0xfffffc00, v1
	v_sub_u32_e32 v1, v0, v1
	v_lshrrev_b32_e32 v2, 4, v1
	v_bitop3_b32 v2, v2, v1, 32 bitop3:0x6c
	v_ashrrev_i32_e32 v1, 31, v1
	v_lshrrev_b32_e32 v1, 26, v1
	v_add_u32_e32 v1, v2, v1
	v_ashrrev_i32_e32 v10, 6, v1
	v_lshlrev_b32_e32 v3, 3, v9
	v_mul_i32_i24_e32 v4, 64, v10
	v_readlane_b32 s4, v254, 26
	v_and_b32_e32 v3, -16, v3
	v_sub_u32_e32 v2, v2, v4
	v_readlane_b32 s5, v254, 27
	v_add_u32_e32 v1, v10, v3
	v_lshlrev_b32_e32 v3, 5, v9
	v_ashrrev_i16_sdwa v2, v203, sext(v2) dst_sel:DWORD dst_unused:UNUSED_PAD src0_sel:DWORD src1_sel:BYTE_0
	s_and_b64 s[4:5], s[4:5], exec
	v_and_b32_e32 v3, 32, v3
	v_bfe_i32 v11, v2, 0, 16
	v_and_b32_e32 v5, 3, v10
	s_mov_b32 s5, 0x3fffe0
	v_add_lshl_u32 v3, v3, v11, 1
	v_add_u32_e32 v0, 0x2000, v0
	v_lshlrev_b32_e32 v2, 1, v1
	v_lshrrev_b32_e32 v4, 2, v1
	v_and_or_b32 v5, v1, s5, v5
	v_lshl_add_u32 v144, v1, 10, v3
	v_ashrrev_i32_e32 v1, 31, v0
	v_lshrrev_b32_e32 v1, 22, v1
	v_add_u32_e32 v1, v0, v1
	v_ashrrev_i32_e32 v12, 10, v1
	v_mul_i32_i24_e32 v1, 0x400, v12
	v_sub_u32_e32 v0, v0, v1
	v_and_b32_e32 v2, 24, v2
	v_and_b32_e32 v4, 4, v4
	v_lshrrev_b32_e32 v1, 4, v0
	v_or3_b32 v2, v5, v4, v2
	v_bitop3_b32 v0, v1, v0, 32 bitop3:0x6c
	v_lshl_add_u32 v160, v2, 10, v3
	v_ashrrev_i32_e32 v2, 31, v0
	v_lshrrev_b32_e32 v2, 26, v2
	s_cselect_b32 s4, 0x200000, 0
	v_readlane_b32 s6, v250, 15
	v_lshlrev_b32_e32 v1, 3, v12
	v_add_u32_e32 v2, v0, v2
	v_readlane_b32 s7, v250, 16
	s_add_u32 s40, s6, s4
	v_and_b32_e32 v1, -16, v1
	v_ashrrev_i32_e32 v13, 6, v2
	s_addc_u32 s41, s7, 0
	s_ashr_i32 s4, s39, 6
	v_add_u32_e32 v1, v13, v1
	v_and_b32_e32 v2, 0xc0, v2
	v_and_b32_e32 v4, 3, v13
	s_ashr_i32 s29, s28, 31
	s_ashr_i32 s19, s18, 31
	v_sub_u32_e32 v0, v0, v2
	v_and_or_b32 v4, v1, s5, v4
	s_ashr_i32 s5, s39, 8
	s_lshl_b32 s42, s4, 10
	s_lshl_b64 s[6:7], s[28:29], 18
	s_lshl_b64 s[20:21], s[18:19], 18
	v_ashrrev_i16_sdwa v0, v203, sext(v0) dst_sel:DWORD dst_unused:UNUSED_PAD src0_sel:DWORD src1_sel:BYTE_0
	s_add_u32 s34, s40, s20
	v_lshlrev_b32_e32 v3, 5, v12
	v_bfe_i32 v14, v0, 0, 16
	v_lshlrev_b32_e32 v0, 1, v1
	v_lshrrev_b32_e32 v2, 2, v1
	s_addc_u32 s35, s41, s21
	s_add_i32 s43, s42, 0
	v_and_b32_e32 v3, 32, v3
	v_and_b32_e32 v0, 24, v0
	v_and_b32_e32 v2, 4, v2
	s_add_i32 m0, s43, 0x10000
	v_or3_b32 v0, v4, v2, v0
	v_add_lshl_u32 v2, v3, v14, 1
	global_load_lds_dwordx4 v160, s[34:35]
	s_add_i32 m0, s43, 0x12000
	v_readlane_b32 s20, v250, 13
	v_lshl_add_u32 v148, v0, 10, v2
	v_readlane_b32 s21, v250, 14
	s_add_u32 s30, s20, s6
	global_load_lds_dwordx4 v148, s[34:35]
	s_addc_u32 s31, s21, s7
	s_mov_b32 m0, s43
	s_add_i32 s44, s43, 0x2000
	v_lshl_add_u32 v146, v1, 10, v2
	global_load_lds_dwordx4 v144, s[30:31]
	s_mov_b32 m0, s44
	s_add_u32 s6, s34, 0x20000
	global_load_lds_dwordx4 v146, s[30:31]
	s_addc_u32 s7, s35, 0
	s_add_i32 m0, s43, 0x14000
	v_mov_b32_e32 v149, v161
	global_load_lds_dwordx4 v160, s[6:7]
	s_add_i32 m0, s43, 0x16000
	v_mov_b32_e32 v145, v161
	global_load_lds_dwordx4 v148, s[6:7]
	s_add_u32 s6, s30, 0x20000
	s_addc_u32 s7, s31, 0
	s_add_i32 s45, s43, 0x4000
	s_mov_b32 m0, s45
	s_add_i32 s46, s43, 0x6000
	global_load_lds_dwordx4 v144, s[6:7]
	s_mov_b32 m0, s46
	v_mov_b32_e32 v147, v161
	global_load_lds_dwordx4 v146, s[6:7]
	v_lshl_add_u64 v[6:7], s[34:35], 0, v[160:161]
	v_lshl_add_u64 v[4:5], s[34:35], 0, v[148:149]
	v_lshl_add_u64 v[2:3], s[30:31], 0, v[144:145]
	s_cmp_lg_u32 s5, 1
	v_lshl_add_u64 v[0:1], s[30:31], 0, v[146:147]
	s_cbranch_scc1 .LBB0_251
	s_barrier
	s_setprio 1

; #define PG8_STAGE(bufoff, gbase, voff) do { _Pragma("unroll") for (int _i = 0; _i < 2; ++_i) \
;         __builtin_amdgcn_global_load_lds((const unsigned*)((const char*)(gbase) + (voff)[_i]), (LAS unsigned*)(lds + (bufoff) + ldsw + _i * 8192), 16, 0, 0); } while (0)
; #define PG8_LDA(dst, b, h) do { _Pragma("unroll") for (int m = 0; m < 4; ++m) _Pragma("unroll") for (int k = 0; k < 2; ++k) dst[m][k] = *(const LAS bf16x8*)(lds + PG8_SA(b, h) + aoff + m * 2048 + k * 1024); } while (0)
; #define PG8_LDB(dst, b, h) do { _Pragma("unroll") for (int n = 0; n < 2; ++n) _Pragma("unroll") for (int k = 0; k < 2; ++k) dst[n][k] = *(const LAS bf16x8*)(lds + PG8_SB(b, h) + boff + n * 2048 + k * 1024); } while (0)
; #define PG8_MMA(ai, bj, At, Bt) do { __builtin_amdgcn_s_setprio(1); _Pragma("unroll") for (int m = 0; m < 4; ++m) _Pragma("unroll") for (int n = 0; n < 2; ++n) _Pragma("unroll") for (int k = 0; k < 2; ++k) \
;         acc[ai][bj][m][n] = __builtin_amdgcn_mfma_f32_16x16x32_bf16(Bt[n][k], At[m][k], acc[ai][bj][m][n], 0, 0, 0); __builtin_amdgcn_s_setprio(0); } while (0)
; #define PG8_WAIT_L(n) asm volatile("s_waitcnt lgkmcnt(" #n ")" ::: "memory")
; #define PG8_BAR __builtin_amdgcn_s_barrier()
; #define PG8_SCHED __builtin_amdgcn_sched_barrier(0)
; template <class Epi>
; DEV void gemm_phase(LAS unsigned char* lds, const Gemm g, const StaticOrder& S, const Epi& E) {
;     ...
;             PG8_LDB(B0, 0, 0); PG8_SCHED; PG8_LDA(At, 0, 0); PG8_STAGE(PG8_SA(1, 1), a1 + hstep, voffA);
;             PG8_WAIT_L(8); PG8_BAR; PG8_WAIT_L(0); PG8_MMA(0, 0, At, B0); PG8_BAR; PG8_SCHED;
;             PG8_LDB(B1, 0, 1); PG8_STAGE(PG8_SB(0, 0), b2, voffB);
;             PG8_BAR; PG8_WAIT_L(0); PG8_MMA(0, 1, At, B1); PG8_BAR;
;             PG8_LDA(At, 0, 1); PG8_STAGE(PG8_SA(0, 0), a2, voffA);
;             PG8_BAR; PG8_WAIT_L(0); PG8_MMA(1, 0, At, B0); PG8_BAR; PG8_SCHED;
.LBB0_260:
	s_add_u32 s34, s30, 0xfffe0080
	s_addc_u32 s35, s31, -1
	s_add_i32 s55, 0, 0x10000
	v_add_u32_e32 v140, s55, v178
	ds_read_b128 v[128:131], v140
	ds_read_b128 v[132:135], v140 offset:1024
	ds_read_b128 v[136:139], v140 offset:2048
	ds_read_b128 v[140:143], v140 offset:3072
	s_cmp_eq_u32 s54, 4
	s_cselect_b32 s37, s19, s35
	s_cselect_b32 s36, s23, s34
	s_cselect_b32 s35, s21, s53
	s_cselect_b32 s34, s29, s52
	v_lshl_add_u64 v[158:159], s[30:31], 0, v[150:151]
	s_add_i32 m0, s43, 0xc000
	ds_read_b128 v[154:157], v181
	ds_read_b128 v[174:177], v181 offset:1024
	ds_read_b128 v[182:185], v181 offset:2048
	ds_read_b128 v[186:189], v181 offset:3072
	ds_read_b128 v[190:193], v181 offset:4096
	ds_read_b128 v[194:197], v181 offset:5120
	ds_read_b128 v[214:217], v181 offset:6144
	ds_read_b128 v[218:221], v181 offset:7168
	global_load_lds_dwordx4 v[158:159], off
	v_lshl_add_u64 v[158:159], s[30:31], 0, v[152:153]
	s_add_i32 m0, s43, 0xe000
	s_nop 0
	global_load_lds_dwordx4 v[158:159], off
	s_waitcnt lgkmcnt(8)
	s_barrier
	s_waitcnt lgkmcnt(0)
	v_mfma_f32_16x16x32_bf16 v[124:127], v[128:131], v[154:157], v[124:127]
	v_mfma_f32_16x16x32_bf16 v[120:123], v[136:139], v[154:157], v[120:123]
	v_mfma_f32_16x16x32_bf16 v[108:111], v[128:131], v[182:185], v[108:111]
	v_mfma_f32_16x16x32_bf16 v[104:107], v[136:139], v[182:185], v[104:107]
	v_mfma_f32_16x16x32_bf16 v[92:95], v[128:131], v[190:193], v[92:95]
	v_mfma_f32_16x16x32_bf16 v[88:91], v[136:139], v[190:193], v[88:91]
	v_mfma_f32_16x16x32_bf16 v[76:79], v[128:131], v[214:217], v[76:79]
	v_mfma_f32_16x16x32_bf16 v[72:75], v[136:139], v[214:217], v[72:75]
	v_mfma_f32_16x16x32_bf16 v[124:127], v[132:135], v[174:177], v[124:127]
	v_mfma_f32_16x16x32_bf16 v[120:123], v[140:143], v[174:177], v[120:123]
	v_mfma_f32_16x16x32_bf16 v[108:111], v[132:135], v[186:189], v[108:111]
	v_mfma_f32_16x16x32_bf16 v[104:107], v[140:143], v[186:189], v[104:107]
	v_mfma_f32_16x16x32_bf16 v[92:95], v[132:135], v[194:197], v[92:95]
	v_mfma_f32_16x16x32_bf16 v[88:91], v[140:143], v[194:197], v[88:91]
	v_mfma_f32_16x16x32_bf16 v[76:79], v[132:135], v[218:221], v[76:79]
	v_mfma_f32_16x16x32_bf16 v[72:75], v[140:143], v[218:221], v[72:75]
	s_barrier
	s_add_i32 s58, 0, 0x14000
	v_add_u32_e32 v158, s58, v178
	s_add_i32 s55, s55, s42
	ds_read_b128 v[222:225], v158
	ds_read_b128 v[226:229], v158 offset:1024
	ds_read_b128 v[230:233], v158 offset:2048
	ds_read_b128 v[234:237], v158 offset:3072
	v_lshl_add_u64 v[158:159], s[34:35], 0, v[160:161]
	s_mov_b32 m0, s55
	v_lshl_add_u64 v[238:239], s[34:35], 0, v[148:149]
	global_load_lds_dwordx4 v[158:159], off
	s_add_i32 m0, s55, 0x2000
	s_nop 0
	global_load_lds_dwordx4 v[238:239], off
	s_barrier
	s_waitcnt lgkmcnt(0)
	v_mfma_f32_16x16x32_bf16 v[116:119], v[222:225], v[154:157], v[116:119]
	v_mfma_f32_16x16x32_bf16 v[112:115], v[230:233], v[154:157], v[112:115]
	v_mfma_f32_16x16x32_bf16 v[100:103], v[222:225], v[182:185], v[100:103]
	v_mfma_f32_16x16x32_bf16 v[96:99], v[230:233], v[182:185], v[96:99]
	v_mfma_f32_16x16x32_bf16 v[84:87], v[222:225], v[190:193], v[84:87]
	v_mfma_f32_16x16x32_bf16 v[80:83], v[230:233], v[190:193], v[80:83]
	v_mfma_f32_16x16x32_bf16 v[68:71], v[222:225], v[214:217], v[68:71]
	v_mfma_f32_16x16x32_bf16 v[64:67], v[230:233], v[214:217], v[64:67]
	v_mfma_f32_16x16x32_bf16 v[116:119], v[226:229], v[174:177], v[116:119]
	v_mfma_f32_16x16x32_bf16 v[112:115], v[234:237], v[174:177], v[112:115]
	v_mfma_f32_16x16x32_bf16 v[100:103], v[226:229], v[186:189], v[100:103]
	v_mfma_f32_16x16x32_bf16 v[96:99], v[234:237], v[186:189], v[96:99]
	v_mfma_f32_16x16x32_bf16 v[84:87], v[226:229], v[194:197], v[84:87]
	v_mfma_f32_16x16x32_bf16 v[80:83], v[234:237], v[194:197], v[80:83]
	v_mfma_f32_16x16x32_bf16 v[68:71], v[226:229], v[218:221], v[68:71]
	v_mfma_f32_16x16x32_bf16 v[64:67], v[234:237], v[218:221], v[64:67]
	s_mov_b32 m0, s43
	v_lshl_add_u64 v[240:241], s[36:37], 0, v[144:145]
	s_barrier
	ds_read_b128 v[154:157], v181 offset:16384
	ds_read_b128 v[174:177], v181 offset:17408
	ds_read_b128 v[182:185], v181 offset:18432
	ds_read_b128 v[186:189], v181 offset:19456
	ds_read_b128 v[190:193], v181 offset:20480
	ds_read_b128 v[194:197], v181 offset:21504
	ds_read_b128 v[214:217], v181 offset:22528
	ds_read_b128 v[218:221], v181 offset:23552
	global_load_lds_dwordx4 v[240:241], off
	v_lshl_add_u64 v[242:243], s[36:37], 0, v[146:147]
	s_mov_b32 m0, s44
	s_nop 0
	global_load_lds_dwordx4 v[242:243], off
	s_barrier
	s_waitcnt lgkmcnt(0)
	v_mfma_f32_16x16x32_bf16 v[60:63], v[128:131], v[154:157], v[60:63]
	v_mfma_f32_16x16x32_bf16 v[56:59], v[136:139], v[154:157], v[56:59]
	v_mfma_f32_16x16x32_bf16 v[44:47], v[128:131], v[182:185], v[44:47]
	v_mfma_f32_16x16x32_bf16 v[40:43], v[136:139], v[182:185], v[40:43]
	v_mfma_f32_16x16x32_bf16 v[28:31], v[128:131], v[190:193], v[28:31]
	v_mfma_f32_16x16x32_bf16 v[24:27], v[136:139], v[190:193], v[24:27]
	v_mfma_f32_16x16x32_bf16 v[12:15], v[128:131], v[214:217], v[12:15]
	v_mfma_f32_16x16x32_bf16 v[8:11], v[136:139], v[214:217], v[8:11]
	v_mfma_f32_16x16x32_bf16 v[60:63], v[132:135], v[174:177], v[60:63]
	v_mfma_f32_16x16x32_bf16 v[56:59], v[140:143], v[174:177], v[56:59]
	v_mfma_f32_16x16x32_bf16 v[44:47], v[132:135], v[186:189], v[44:47]
	v_mfma_f32_16x16x32_bf16 v[40:43], v[140:143], v[186:189], v[40:43]
	v_mfma_f32_16x16x32_bf16 v[28:31], v[132:135], v[194:197], v[28:31]
	v_mfma_f32_16x16x32_bf16 v[24:27], v[140:143], v[194:197], v[24:27]
	v_mfma_f32_16x16x32_bf16 v[12:15], v[132:135], v[218:221], v[12:15]
	v_mfma_f32_16x16x32_bf16 v[8:11], v[140:143], v[218:221], v[8:11]
	s_barrier
; #define PG8_STAGE(bufoff, gbase, voff) do { _Pragma("unroll") for (int _i = 0; _i < 2; ++_i) \
;         __builtin_amdgcn_global_load_lds((const unsigned*)((const char*)(gbase) + (voff)[_i]), (LAS unsigned*)(lds + (bufoff) + ldsw + _i * 8192), 16, 0, 0); } while (0)
; #define PG8_LDA(dst, b, h) do { _Pragma("unroll") for (int m = 0; m < 4; ++m) _Pragma("unroll") for (int k = 0; k < 2; ++k) dst[m][k] = *(const LAS bf16x8*)(lds + PG8_SA(b, h) + aoff + m * 2048 + k * 1024); } while (0)
; #define PG8_LDB(dst, b, h) do { _Pragma("unroll") for (int n = 0; n < 2; ++n) _Pragma("unroll") for (int k = 0; k < 2; ++k) dst[n][k] = *(const LAS bf16x8*)(lds + PG8_SB(b, h) + boff + n * 2048 + k * 1024); } while (0)
; #define PG8_MMA(ai, bj, At, Bt) do { __builtin_amdgcn_s_setprio(1); _Pragma("unroll") for (int m = 0; m < 4; ++m) _Pragma("unroll") for (int n = 0; n < 2; ++n) _Pragma("unroll") for (int k = 0; k < 2; ++k) \
;         acc[ai][bj][m][n] = __builtin_amdgcn_mfma_f32_16x16x32_bf16(Bt[n][k], At[m][k], acc[ai][bj][m][n], 0, 0, 0); __builtin_amdgcn_s_setprio(0); } while (0)
; #define PG8_WAIT_V(n) asm volatile("s_waitcnt vmcnt(" #n ")" ::: "memory")
; #define PG8_WAIT_L(n) asm volatile("s_waitcnt lgkmcnt(" #n ")" ::: "memory")
; #define PG8_BAR __builtin_amdgcn_s_barrier()
; #define PG8_SCHED __builtin_amdgcn_sched_barrier(0)
; template <class Epi>
; DEV void gemm_phase(LAS unsigned char* lds, const Gemm g, const StaticOrder& S, const Epi& E) {
;     ...
;             PG8_STAGE(PG8_SB(0, 1), b2 + hstep, voffB);
;             PG8_WAIT_V(6); PG8_BAR; PG8_MMA(1, 1, At, B1); PG8_BAR;
;             PG8_LDB(B0, 1, 0); PG8_SCHED; PG8_LDA(At, 1, 0); PG8_STAGE(PG8_SA(0, 1), a2 + hstep, voffA);
;             PG8_WAIT_L(8); PG8_BAR; PG8_WAIT_L(0); PG8_MMA(0, 0, At, B0); PG8_BAR; PG8_SCHED;
;             PG8_LDB(B1, 1, 1); PG8_STAGE(PG8_SB(1, 0), b3, voffB);
;             PG8_BAR; PG8_WAIT_L(0); PG8_MMA(0, 1, At, B1); PG8_BAR;
	s_add_u32 s56, s34, 0x20000
	s_addc_u32 s57, s35, 0
	s_add_i32 s55, s58, s42
	v_lshl_add_u64 v[128:129], s[56:57], 0, v[160:161]
	s_mov_b32 m0, s55
	s_nop 0
	global_load_lds_dwordx4 v[128:129], off
	v_lshl_add_u64 v[128:129], s[56:57], 0, v[148:149]
	s_add_i32 m0, s55, 0x2000
	s_nop 0
	global_load_lds_dwordx4 v[128:129], off
	s_waitcnt vmcnt(6)
	s_barrier
	v_mfma_f32_16x16x32_bf16 v[52:55], v[222:225], v[154:157], v[52:55]
	v_mfma_f32_16x16x32_bf16 v[48:51], v[230:233], v[154:157], v[48:51]
	v_mfma_f32_16x16x32_bf16 v[36:39], v[222:225], v[182:185], v[36:39]
	v_mfma_f32_16x16x32_bf16 v[32:35], v[230:233], v[182:185], v[32:35]
	v_mfma_f32_16x16x32_bf16 v[20:23], v[222:225], v[190:193], v[20:23]
	v_mfma_f32_16x16x32_bf16 v[16:19], v[230:233], v[190:193], v[16:19]
	v_mfma_f32_16x16x32_bf16 v[4:7], v[222:225], v[214:217], v[4:7]
	v_mfma_f32_16x16x32_bf16 v[0:3], v[230:233], v[214:217], v[0:3]
	v_mfma_f32_16x16x32_bf16 v[52:55], v[226:229], v[174:177], v[52:55]
	v_mfma_f32_16x16x32_bf16 v[48:51], v[234:237], v[174:177], v[48:51]
	v_mfma_f32_16x16x32_bf16 v[36:39], v[226:229], v[186:189], v[36:39]
	v_mfma_f32_16x16x32_bf16 v[32:35], v[234:237], v[186:189], v[32:35]
	v_mfma_f32_16x16x32_bf16 v[20:23], v[226:229], v[194:197], v[20:23]
	v_mfma_f32_16x16x32_bf16 v[16:19], v[234:237], v[194:197], v[16:19]
	v_mfma_f32_16x16x32_bf16 v[4:7], v[226:229], v[218:221], v[4:7]
	v_mfma_f32_16x16x32_bf16 v[0:3], v[234:237], v[218:221], v[0:3]
	s_add_i32 s55, 0, 0x18000
	v_add_u32_e32 v140, s55, v178
	s_barrier
	ds_read_b128 v[128:131], v140
	ds_read_b128 v[132:135], v140 offset:1024
	ds_read_b128 v[136:139], v140 offset:2048
	ds_read_b128 v[140:143], v140 offset:3072
	s_add_u32 s36, s36, 0x20000
	s_addc_u32 s37, s37, 0
	s_mov_b32 m0, s45
	v_lshl_add_u64 v[222:223], s[36:37], 0, v[144:145]
	ds_read_b128 v[154:157], v181 offset:32768
	ds_read_b128 v[174:177], v181 offset:33792
	ds_read_b128 v[182:185], v181 offset:34816
	ds_read_b128 v[186:189], v181 offset:35840
	ds_read_b128 v[190:193], v181 offset:36864
	ds_read_b128 v[194:197], v181 offset:37888
	ds_read_b128 v[214:217], v181 offset:38912
	ds_read_b128 v[218:221], v181 offset:39936
	global_load_lds_dwordx4 v[222:223], off
	v_lshl_add_u64 v[222:223], s[36:37], 0, v[146:147]
	s_mov_b32 m0, s46
	s_nop 0
	global_load_lds_dwordx4 v[222:223], off
	s_waitcnt lgkmcnt(8)
	s_barrier
	s_waitcnt lgkmcnt(0)
	v_mfma_f32_16x16x32_bf16 v[124:127], v[128:131], v[154:157], v[124:127]
	v_mfma_f32_16x16x32_bf16 v[120:123], v[136:139], v[154:157], v[120:123]
	v_mfma_f32_16x16x32_bf16 v[108:111], v[128:131], v[182:185], v[108:111]
	v_mfma_f32_16x16x32_bf16 v[104:107], v[136:139], v[182:185], v[104:107]
	v_mfma_f32_16x16x32_bf16 v[92:95], v[128:131], v[190:193], v[92:95]
	v_mfma_f32_16x16x32_bf16 v[88:91], v[136:139], v[190:193], v[88:91]
	v_mfma_f32_16x16x32_bf16 v[76:79], v[128:131], v[214:217], v[76:79]
	v_mfma_f32_16x16x32_bf16 v[72:75], v[136:139], v[214:217], v[72:75]
	v_mfma_f32_16x16x32_bf16 v[124:127], v[132:135], v[174:177], v[124:127]
	v_mfma_f32_16x16x32_bf16 v[120:123], v[140:143], v[174:177], v[120:123]
	v_mfma_f32_16x16x32_bf16 v[108:111], v[132:135], v[186:189], v[108:111]
	v_mfma_f32_16x16x32_bf16 v[104:107], v[140:143], v[186:189], v[104:107]
	v_mfma_f32_16x16x32_bf16 v[92:95], v[132:135], v[194:197], v[92:95]
	v_mfma_f32_16x16x32_bf16 v[88:91], v[140:143], v[194:197], v[88:91]
	v_mfma_f32_16x16x32_bf16 v[76:79], v[132:135], v[218:221], v[76:79]
	v_mfma_f32_16x16x32_bf16 v[72:75], v[140:143], v[218:221], v[72:75]
	s_barrier
	s_add_i32 s36, 0, 0x1c000
	s_add_i32 s37, s55, s42
	v_add_u32_e32 v234, s36, v178
	v_lshl_add_u64 v[158:159], v[158:159], 0, s[2:3]
	s_mov_b32 m0, s37
	ds_read_b128 v[222:225], v234
	ds_read_b128 v[226:229], v234 offset:1024
	ds_read_b128 v[230:233], v234 offset:2048
	ds_read_b128 v[234:237], v234 offset:3072
	global_load_lds_dwordx4 v[158:159], off
	v_lshl_add_u64 v[158:159], v[238:239], 0, s[2:3]
	s_add_i32 m0, s37, 0x2000
	s_nop 0
	global_load_lds_dwordx4 v[158:159], off
	s_barrier
	s_waitcnt lgkmcnt(0)
	v_mfma_f32_16x16x32_bf16 v[116:119], v[222:225], v[154:157], v[116:119]
	v_mfma_f32_16x16x32_bf16 v[112:115], v[230:233], v[154:157], v[112:115]
	v_mfma_f32_16x16x32_bf16 v[100:103], v[222:225], v[182:185], v[100:103]
	v_mfma_f32_16x16x32_bf16 v[96:99], v[230:233], v[182:185], v[96:99]
	v_mfma_f32_16x16x32_bf16 v[84:87], v[222:225], v[190:193], v[84:87]
	v_mfma_f32_16x16x32_bf16 v[80:83], v[230:233], v[190:193], v[80:83]
	v_mfma_f32_16x16x32_bf16 v[68:71], v[222:225], v[214:217], v[68:71]
	v_mfma_f32_16x16x32_bf16 v[64:67], v[230:233], v[214:217], v[64:67]
	v_mfma_f32_16x16x32_bf16 v[116:119], v[226:229], v[174:177], v[116:119]
	v_mfma_f32_16x16x32_bf16 v[112:115], v[234:237], v[174:177], v[112:115]
	v_mfma_f32_16x16x32_bf16 v[100:103], v[226:229], v[186:189], v[100:103]
	v_mfma_f32_16x16x32_bf16 v[96:99], v[234:237], v[186:189], v[96:99]
	v_mfma_f32_16x16x32_bf16 v[84:87], v[226:229], v[194:197], v[84:87]
	v_mfma_f32_16x16x32_bf16 v[80:83], v[234:237], v[194:197], v[80:83]
	v_mfma_f32_16x16x32_bf16 v[68:71], v[226:229], v[218:221], v[68:71]
	v_mfma_f32_16x16x32_bf16 v[64:67], v[234:237], v[218:221], v[64:67]
	s_mov_b32 m0, s47
	v_lshl_add_u64 v[158:159], v[240:241], 0, s[2:3]
	s_barrier
	ds_read_b128 v[154:157], v181 offset:49152
	ds_read_b128 v[174:177], v181 offset:50176
	ds_read_b128 v[182:185], v181 offset:51200
	ds_read_b128 v[186:189], v181 offset:52224
	ds_read_b128 v[190:193], v181 offset:53248
	ds_read_b128 v[194:197], v181 offset:54272
	ds_read_b128 v[214:217], v181 offset:55296
	ds_read_b128 v[218:221], v181 offset:56320
	global_load_lds_dwordx4 v[158:159], off
	v_lshl_add_u64 v[158:159], v[242:243], 0, s[2:3]
	s_mov_b32 m0, s48
	s_nop 0
	global_load_lds_dwordx4 v[158:159], off
	s_barrier
; DEV bf16x8 pack8(f32x4 a, f32x4 b) { u32x4 w; w.x = cvt_pk_bf16(a[0], a[1]); w.y = cvt_pk_bf16(a[2], a[3]); w.z = cvt_pk_bf16(b[0], b[1]); w.w = cvt_pk_bf16(b[2], b[3]); return __builtin_bit_cast(bf16x8, w); }
; #define PG8_WAIT_V(n) asm volatile("s_waitcnt vmcnt(" #n ")" ::: "memory")
; #define PG8_WAIT_L(n) asm volatile("s_waitcnt lgkmcnt(" #n ")" ::: "memory")
; template <class Epi>
; DEV void gemm_phase(LAS unsigned char* lds, const Gemm g, const StaticOrder& S, const Epi& E) {
;     ...
;             PG8_LDA(At, 1, 1); PG8_STAGE(PG8_SA(1, 0), a3, voffA);
;             PG8_BAR; PG8_WAIT_L(0); PG8_MMA(1, 0, At, B0); PG8_BAR; PG8_SCHED;
;             PG8_STAGE(PG8_SB(1, 1), b3 + hstep, voffB);
;             PG8_WAIT_V(6); PG8_BAR; PG8_MMA(1, 1, At, B1); PG8_BAR;
;     DEV void operator()(AccRef acc, const pg8::Unit& u, int wr, int wc, int fr, int fq) const {
;         const int row0 = u.pm * 256 + wr * 64 + fr, col0 = u.pn * 256 + wc * 32 + 8 * fq;
; #pragma unroll
;         for (int am = 0; am < 4; ++am) { const int ai = am >> 1, m0 = (am & 1) * 2;
;             f32x4 bv[4][2][2];
; #pragma unroll
;             for (int m = m0; m < m0 + 2; ++m)
; #pragma unroll
;                 for (int bj = 0; bj < 2; ++bj)
; #pragma unroll
;                     for (int n = 0; n < 2; ++n) bv[m][bj][n] = *(const f32x4*)(base + (size_t)(row0 + ai * 128 + m * 16) * 2048 + col0 + bj * 128 + n * 4);
; #pragma unroll
;             for (int m = m0; m < m0 + 2; ++m) { const size_t off = (size_t)(row0 + ai * 128 + m * 16) * 2048 + col0; float sq = 0.f;
; #pragma unroll
;                 for (int bj = 0; bj < 2; ++bj) { const f32x4 o0 = bv[m][bj][0] + scale * acc[ai][bj][m][0], o1 = bv[m][bj][1] + scale * acc[ai][bj][m][1];
;                     *(f32x4*)(out + off + bj * 128) = o0; *(f32x4*)(out + off + bj * 128 + 4) = o1;
;                     if (xb) { *(u32x4*)(xb + off + bj * 128) = __builtin_bit_cast(u32x4, pack8(o0, o1));
;                         sq += (o0[0] * o0[0] + o0[1] * o0[1] + o0[2] * o0[2] + o0[3] * o0[3]) + (o1[0] * o1[0] + o1[1] * o1[1] + o1[2] * o1[2] + o1[3] * o1[3]); } }
;                 if (ssout) { sq += __shfl_xor(sq, 16); sq += __shfl_xor(sq, 32);
;                     if (fq == 0) { if (red) red[(ai * 128 + wr * 64 + m * 16 + fr) * 4 + wc] = sq; else atomicAdd(ssout + (size_t)(row0 + ai * 128 + m * 16) * 8 + u.pn, sq); } } }
	s_waitcnt lgkmcnt(0)
	v_mfma_f32_16x16x32_bf16 v[60:63], v[128:131], v[154:157], v[60:63]
	v_mfma_f32_16x16x32_bf16 v[56:59], v[136:139], v[154:157], v[56:59]
	v_mfma_f32_16x16x32_bf16 v[44:47], v[128:131], v[182:185], v[44:47]
	v_mfma_f32_16x16x32_bf16 v[40:43], v[136:139], v[182:185], v[40:43]
	v_mfma_f32_16x16x32_bf16 v[28:31], v[128:131], v[190:193], v[28:31]
	v_mfma_f32_16x16x32_bf16 v[24:27], v[136:139], v[190:193], v[24:27]
	v_mfma_f32_16x16x32_bf16 v[12:15], v[128:131], v[214:217], v[12:15]
	v_mfma_f32_16x16x32_bf16 v[8:11], v[136:139], v[214:217], v[8:11]
	v_mfma_f32_16x16x32_bf16 v[60:63], v[132:135], v[174:177], v[60:63]
	v_mfma_f32_16x16x32_bf16 v[56:59], v[140:143], v[174:177], v[56:59]
	v_mfma_f32_16x16x32_bf16 v[44:47], v[132:135], v[186:189], v[44:47]
	v_mfma_f32_16x16x32_bf16 v[40:43], v[140:143], v[186:189], v[40:43]
	v_mfma_f32_16x16x32_bf16 v[28:31], v[132:135], v[194:197], v[28:31]
	v_mfma_f32_16x16x32_bf16 v[24:27], v[140:143], v[194:197], v[24:27]
	v_mfma_f32_16x16x32_bf16 v[12:15], v[132:135], v[218:221], v[12:15]
	v_mfma_f32_16x16x32_bf16 v[8:11], v[140:143], v[218:221], v[8:11]
	s_barrier
	s_add_u32 s34, s34, 0x20080
	s_addc_u32 s35, s35, 0
	s_add_i32 s36, s36, s42
	v_lshl_add_u64 v[128:129], s[34:35], 0, v[160:161]
	s_mov_b32 m0, s36
	s_nop 0
	global_load_lds_dwordx4 v[128:129], off
	v_lshl_add_u64 v[128:129], s[34:35], 0, v[148:149]
	s_add_i32 m0, s36, 0x2000
	s_nop 0
	global_load_lds_dwordx4 v[128:129], off
	s_waitcnt vmcnt(6)
	s_barrier
	v_mfma_f32_16x16x32_bf16 v[52:55], v[222:225], v[154:157], v[52:55]
	v_mfma_f32_16x16x32_bf16 v[48:51], v[230:233], v[154:157], v[48:51]
	v_mfma_f32_16x16x32_bf16 v[36:39], v[222:225], v[182:185], v[36:39]
	v_mfma_f32_16x16x32_bf16 v[32:35], v[230:233], v[182:185], v[32:35]
	v_mfma_f32_16x16x32_bf16 v[20:23], v[222:225], v[190:193], v[20:23]
	v_mfma_f32_16x16x32_bf16 v[16:19], v[230:233], v[190:193], v[16:19]
	v_mfma_f32_16x16x32_bf16 v[4:7], v[222:225], v[214:217], v[4:7]
	v_mfma_f32_16x16x32_bf16 v[0:3], v[230:233], v[214:217], v[0:3]
	v_mfma_f32_16x16x32_bf16 v[52:55], v[226:229], v[174:177], v[52:55]
	v_mfma_f32_16x16x32_bf16 v[48:51], v[234:237], v[174:177], v[48:51]
	v_mfma_f32_16x16x32_bf16 v[36:39], v[226:229], v[186:189], v[36:39]
	v_mfma_f32_16x16x32_bf16 v[32:35], v[234:237], v[186:189], v[32:35]
	v_mfma_f32_16x16x32_bf16 v[20:23], v[226:229], v[194:197], v[20:23]
	v_mfma_f32_16x16x32_bf16 v[16:19], v[234:237], v[194:197], v[16:19]
	v_mfma_f32_16x16x32_bf16 v[4:7], v[226:229], v[218:221], v[4:7]
	v_mfma_f32_16x16x32_bf16 v[0:3], v[234:237], v[218:221], v[0:3]
	s_add_i32 s54, s54, 2
	s_add_u32 s30, s30, 0x100
	s_addc_u32 s31, s31, 0
	s_add_u32 s52, s52, 0x100
	s_addc_u32 s53, s53, 0
	s_cmp_gt_u32 s54, 5
	s_barrier
	s_cbranch_scc0 .LBB0_260
	v_lshl_add_u32 v156, s28, 8, v167
	v_lshl_or_b32 v154, s18, 8, v179
	v_readlane_b32 s28, v254, 16
	v_ashrrev_i32_e32 v155, 31, v154
	v_readlane_b32 s29, v254, 17
	v_ashrrev_i32_e32 v157, 31, v156
	v_lshlrev_b64 v[128:129], 13, v[156:157]
	v_lshl_add_u64 v[158:159], v[154:155], 2, s[28:29]
	v_lshl_add_u64 v[214:215], v[158:159], 0, v[128:129]
	global_load_dwordx4 v[182:185], v[214:215], off offset:16
	global_load_dwordx4 v[186:189], v[214:215], off
	global_load_dwordx4 v[190:193], v[214:215], off offset:528
	global_load_dwordx4 v[194:197], v[214:215], off offset:512
	v_or_b32_e32 v174, 16, v156
	v_ashrrev_i32_e32 v175, 31, v174
	v_lshlrev_b64 v[128:129], 13, v[174:175]
	v_lshl_add_u64 v[176:177], v[158:159], 0, v[128:129]
	global_load_dwordx4 v[136:139], v[176:177], off offset:16
	global_load_dwordx4 v[140:143], v[176:177], off
	global_load_dwordx4 v[128:131], v[176:177], off offset:528
	global_load_dwordx4 v[132:135], v[176:177], off offset:512
	v_lshlrev_b64 v[216:217], 11, v[156:157]
	v_readlane_b32 s28, v250, 9
	v_lshl_add_u64 v[216:217], v[216:217], 0, v[154:155]
	v_readlane_b32 s29, v250, 10
	v_cmp_lt_i32_e32 vcc, v208, v206
	s_ashr_i32 s19, s18, 31
	s_waitcnt vmcnt(0)
	v_pk_add_f32 v[120:121], v[120:121], v[182:183]
	v_pk_add_f32 v[126:127], v[126:127], v[188:189]
	v_pk_add_f32 v[124:125], v[124:125], v[186:187]
	v_pk_add_f32 v[122:123], v[122:123], v[184:185]
	global_store_dwordx4 v[214:215], v[124:127], off
	global_store_dwordx4 v[214:215], v[120:123], off offset:16
	v_cvt_pk_bf16_f32 v184, v120, v121
	v_cvt_pk_bf16_f32 v182, v124, v125
	v_mul_f32_e32 v121, v121, v121
	v_cvt_pk_bf16_f32 v183, v126, v127
	v_cvt_pk_bf16_f32 v185, v122, v123
	v_lshl_add_u64 v[186:187], v[216:217], 1, s[28:29]
	v_fmac_f32_e32 v121, v120, v120
	v_pk_add_f32 v[118:119], v[118:119], v[196:197]
	v_pk_add_f32 v[116:117], v[116:117], v[194:195]
	v_pk_add_f32 v[112:113], v[112:113], v[190:191]
	global_store_dwordx4 v[186:187], v[182:185], off
	v_mul_f32_e32 v125, v125, v125
	v_fmac_f32_e32 v121, v122, v122
	v_pk_add_f32 v[114:115], v[114:115], v[192:193]
	global_store_dwordx4 v[214:215], v[116:119], off offset:512
	global_store_dwordx4 v[214:215], v[112:115], off offset:528
	v_cvt_pk_bf16_f32 v120, v116, v117
	v_cvt_pk_bf16_f32 v122, v112, v113
	v_mul_f32_e32 v117, v117, v117
	v_mul_f32_e32 v113, v113, v113
	v_fmac_f32_e32 v125, v124, v124
	v_fmac_f32_e32 v117, v116, v116
	v_fmac_f32_e32 v113, v112, v112
	v_fmac_f32_e32 v125, v126, v126
	v_fmac_f32_e32 v117, v118, v118
	v_fmac_f32_e32 v113, v114, v114
	v_fmac_f32_e32 v125, v127, v127
	v_fmac_f32_e32 v121, v123, v123
	v_fmac_f32_e32 v117, v119, v119
	v_fmac_f32_e32 v113, v115, v115
	v_add_f32_e32 v124, v125, v121
	v_add_f32_e32 v112, v117, v113
	v_cndmask_b32_e32 v113, v204, v208, vcc
	v_cvt_pk_bf16_f32 v121, v118, v119
	v_add_f32_e32 v112, v124, v112
	v_lshlrev_b32_e32 v118, 2, v113
	ds_bpermute_b32 v113, v118, v112
	v_cmp_lt_i32_e32 vcc, v207, v206
	v_cvt_pk_bf16_f32 v123, v114, v115
	global_store_dwordx4 v[186:187], v[120:123], off offset:256
	s_waitcnt lgkmcnt(0)
	v_add_f32_e32 v112, v112, v113
	v_cndmask_b32_e32 v113, v204, v207, vcc
	v_lshlrev_b32_e32 v119, 2, v113
	ds_bpermute_b32 v113, v119, v112
	s_and_saveexec_b64 s[28:29], s[6:7]
	s_cbranch_execz .LBB0_266
	s_waitcnt lgkmcnt(0)
	v_add_f32_e32 v112, v112, v113
	s_mov_b64 s[30:31], -1
	s_and_b64 vcc, exec, s[16:17]
	s_cbranch_vccz .LBB0_264
	v_lshlrev_b64 v[114:115], 5, v[156:157]
	v_lshl_add_u64 v[114:115], s[12:13], 0, v[114:115]
	v_lshl_add_u64 v[114:115], s[18:19], 2, v[114:115]
	global_atomic_add_f32 v[114:115], v112, off
	s_mov_b64 s[30:31], 0

; #define PG8_STAGE(bufoff, gbase, voff) do { _Pragma("unroll") for (int _i = 0; _i < 2; ++_i) \
;         __builtin_amdgcn_global_load_lds((const unsigned*)((const char*)(gbase) + (voff)[_i]), (LAS unsigned*)(lds + (bufoff) + ldsw + _i * 8192), 16, 0, 0); } while (0)
; #define PG8_WAIT_V(n) asm volatile("s_waitcnt vmcnt(" #n ")" ::: "memory")
; #define PG8_BAR __builtin_amdgcn_s_barrier()
; template <class Epi>
; DEV void gemm_phase(LAS unsigned char* lds, const Gemm g, const StaticOrder& S, const Epi& E) {
;     ...
;     const char* cA = (const char*)g.A + (size_t)cur.pm * tstep; const char* cB = (const char*)g.Bt + (size_t)cur.pn * tstep;
;     PG8_STAGE(PG8_SB(0, 0), cB, voffB); PG8_STAGE(PG8_SA(0, 0), cA, voffA); PG8_STAGE(PG8_SB(0, 1), cB + hstep, voffB); PG8_STAGE(PG8_SA(0, 1), cA + hstep, voffA);
;     if (wr == 1) PG8_BAR;
;     PG8_WAIT_V(4); PG8_BAR;
;     PG8_STAGE(PG8_SB(1, 0), cB + kstep, voffB); PG8_STAGE(PG8_SA(1, 0), cA + kstep, voffA); PG8_STAGE(PG8_SB(1, 1), cB + hstep + kstep, voffB);
;     PG8_WAIT_V(6); PG8_BAR;
; DEV void run_phase(const P& p, int ph, LAS unsigned char* lds) {
;     ...
;         { EpiBf16 E{QX, 512, SS + (size_t)(4 * L + 2) * 65536}; run_gemm(lds, XB, (const u16*)(ws + O_WXQ) + (size_t)L * 512 * 2048, 8192, 512, 2048, E, bx); }
.LBB0_334:
	s_waitcnt lgkmcnt(0)
	v_ashrrev_i32_e32 v1, 31, v14
	v_lshrrev_b32_e32 v1, 26, v1
	v_add_u32_e32 v1, v14, v1
	v_ashrrev_i32_e32 v8, 6, v1
	v_bfe_i32 v1, v14, 27, 1
	v_lshlrev_b32_e32 v0, 4, v14
	v_lshrrev_b32_e32 v1, 22, v1
	v_add_u32_e32 v1, v0, v1
	v_and_b32_e32 v1, 0xfffffc00, v1
	v_sub_u32_e32 v1, v0, v1
	v_lshrrev_b32_e32 v2, 4, v1
	v_bitop3_b32 v2, v2, v1, 32 bitop3:0x6c
	v_ashrrev_i32_e32 v1, 31, v1
	v_readlane_b32 s0, v254, 26
	v_lshrrev_b32_e32 v1, 26, v1
	s_ashr_i32 s5, s5, 3
	v_readlane_b32 s1, v254, 27
	v_add_u32_e32 v1, v2, v1
	s_and_b64 s[0:1], s[0:1], exec
	v_ashrrev_i32_e32 v9, 6, v1
	s_cselect_b32 s0, 0x200000, 0
	v_readlane_b32 s6, v250, 19
	v_mul_i32_i24_e32 v4, 64, v9
	v_readlane_b32 s7, v250, 20
	s_add_u32 s27, s6, s0
	v_sub_u32_e32 v2, v2, v4
	s_addc_u32 s28, s7, 0
	v_lshlrev_b32_e32 v3, 3, v8
	v_lshlrev_b32_e32 v1, 5, v8
	v_ashrrev_i16_sdwa v2, v203, sext(v2) dst_sel:DWORD dst_unused:UNUSED_PAD src0_sel:DWORD src1_sel:BYTE_0
	s_add_i32 s0, s4, s5
	v_and_b32_e32 v3, 0xffff0, v3
	v_and_b32_e32 v1, 32, v1
	v_bfe_i32 v10, v2, 0, 16
	s_ashr_i32 s1, s0, 31
	v_add_u32_e32 v1, v1, v10
	v_add_lshl_u32 v2, v9, v3, 12
	v_add_u32_e32 v0, 0x2000, v0
	s_lshr_b32 s1, s1, 28
	v_lshl_add_u32 v160, v1, 1, v2
	v_ashrrev_i32_e32 v1, 31, v0
	s_add_i32 s1, s0, s1
	v_lshrrev_b32_e32 v1, 22, v1
	s_ashr_i32 s4, s1, 4
	s_and_b32 s1, s1, -16
	v_add_u32_e32 v1, v0, v1
	s_sub_i32 s0, s0, s1
	v_ashrrev_i32_e32 v11, 10, v1
	s_bfe_i32 s1, s0, 0x80000
	v_mul_i32_i24_e32 v1, 0x400, v11
	s_bfe_u32 s1, s1, 0x3000c
	v_sub_u32_e32 v0, v0, v1
	s_add_i32 s1, s0, s1
	v_lshrrev_b32_e32 v1, 4, v0
	s_lshl_b32 s5, s4, 3
	s_bfe_i32 s4, s1, 0x80000
	s_and_b32 s1, s1, 0xf8
	v_bitop3_b32 v0, v1, v0, 32 bitop3:0x6c
	s_sub_i32 s0, s0, s1
	v_ashrrev_i32_e32 v2, 31, v0
	s_sext_i32_i16 s4, s4
	s_sext_i32_i8 s0, s0
	v_lshrrev_b32_e32 v2, 26, v2
	s_lshr_b32 s4, s4, 3
	s_add_i32 s0, s5, s0
	v_add_u32_e32 v2, v0, v2
	s_ashr_i32 s7, s25, 6
	s_ashr_i32 s1, s0, 31
	s_bfe_i64 s[12:13], s[4:5], 0x100000
	s_ashr_i32 s6, s25, 8
	v_ashrrev_i32_e32 v12, 6, v2
	v_and_b32_e32 v2, 0xc0, v2
	s_lshl_b32 s29, s7, 10
	s_lshl_b64 s[10:11], s[0:1], 20
	s_lshl_b64 s[12:13], s[12:13], 20
	v_sub_u32_e32 v0, v0, v2
	s_add_u32 s20, s27, s12
	v_lshlrev_b32_e32 v1, 3, v11
	v_lshlrev_b32_e32 v3, 5, v11
	v_ashrrev_i16_sdwa v0, v203, sext(v0) dst_sel:DWORD dst_unused:UNUSED_PAD src0_sel:DWORD src1_sel:BYTE_0
	s_addc_u32 s21, s28, s13
	s_add_i32 s30, s29, 0
	v_and_b32_e32 v1, 0xffff0, v1
	v_and_b32_e32 v3, 32, v3
	v_bfe_i32 v13, v0, 0, 16
	s_add_i32 m0, s30, 0x10000
	v_add_u32_e32 v0, v3, v13
	v_add_lshl_u32 v1, v12, v1, 12
	global_load_lds_dwordx4 v160, s[20:21]
	s_add_i32 m0, s30, 0x12000
	v_readlane_b32 s12, v250, 9
	v_lshl_add_u32 v136, v0, 1, v1
	v_readlane_b32 s13, v250, 10
	s_add_u32 s18, s12, s10
	global_load_lds_dwordx4 v136, s[20:21]
	s_addc_u32 s19, s13, s11
	s_mov_b32 m0, s30
	s_add_i32 s31, s30, 0x2000
	global_load_lds_dwordx4 v160, s[18:19]
	s_mov_b32 m0, s31
	s_add_u32 s10, s20, 0x80000
	global_load_lds_dwordx4 v136, s[18:19]
	s_addc_u32 s11, s21, 0
	s_add_i32 m0, s30, 0x14000
	v_mov_b32_e32 v137, v161
	global_load_lds_dwordx4 v160, s[10:11]
	s_add_i32 m0, s30, 0x16000
	v_lshl_add_u64 v[6:7], s[20:21], 0, v[160:161]
	global_load_lds_dwordx4 v136, s[10:11]
	s_add_u32 s10, s18, 0x80000
	s_addc_u32 s11, s19, 0
	s_add_i32 s34, s30, 0x4000
	s_mov_b32 m0, s34
	s_add_i32 s35, s30, 0x6000
	global_load_lds_dwordx4 v160, s[10:11]
	s_mov_b32 m0, s35
	v_lshl_add_u64 v[4:5], s[20:21], 0, v[136:137]
	global_load_lds_dwordx4 v136, s[10:11]
	v_lshl_add_u64 v[2:3], s[18:19], 0, v[160:161]
	s_cmp_lg_u32 s6, 1
	v_lshl_add_u64 v[0:1], s[18:19], 0, v[136:137]
	s_cbranch_scc1 .LBB0_336
	s_barrier
	s_setprio 1

; #define PG8_STAGE(bufoff, gbase, voff) do { _Pragma("unroll") for (int _i = 0; _i < 2; ++_i) \
;         __builtin_amdgcn_global_load_lds((const unsigned*)((const char*)(gbase) + (voff)[_i]), (LAS unsigned*)(lds + (bufoff) + ldsw + _i * 8192), 16, 0, 0); } while (0)
; #define PG8_LDA(dst, b, h) do { _Pragma("unroll") for (int m = 0; m < 4; ++m) _Pragma("unroll") for (int k = 0; k < 2; ++k) dst[m][k] = *(const LAS bf16x8*)(lds + PG8_SA(b, h) + aoff + m * 2048 + k * 1024); } while (0)
; #define PG8_LDB(dst, b, h) do { _Pragma("unroll") for (int n = 0; n < 2; ++n) _Pragma("unroll") for (int k = 0; k < 2; ++k) dst[n][k] = *(const LAS bf16x8*)(lds + PG8_SB(b, h) + boff + n * 2048 + k * 1024); } while (0)
; #define PG8_MMA(ai, bj, At, Bt) do { __builtin_amdgcn_s_setprio(1); _Pragma("unroll") for (int m = 0; m < 4; ++m) _Pragma("unroll") for (int n = 0; n < 2; ++n) _Pragma("unroll") for (int k = 0; k < 2; ++k) \
;         acc[ai][bj][m][n] = __builtin_amdgcn_mfma_f32_16x16x32_bf16(Bt[n][k], At[m][k], acc[ai][bj][m][n], 0, 0, 0); __builtin_amdgcn_s_setprio(0); } while (0)
; #define PG8_WAIT_L(n) asm volatile("s_waitcnt lgkmcnt(" #n ")" ::: "memory")
; #define PG8_BAR __builtin_amdgcn_s_barrier()
; #define PG8_SCHED __builtin_amdgcn_sched_barrier(0)
; template <class Epi>
; DEV void gemm_phase(LAS unsigned char* lds, const Gemm g, const StaticOrder& S, const Epi& E) {
;     ...
;             PG8_LDB(B0, 0, 0); PG8_SCHED; PG8_LDA(At, 0, 0); PG8_STAGE(PG8_SA(1, 1), a1 + hstep, voffA);
;             PG8_WAIT_L(8); PG8_BAR; PG8_WAIT_L(0); PG8_MMA(0, 0, At, B0); PG8_BAR; PG8_SCHED;
;             PG8_LDB(B1, 0, 1); PG8_STAGE(PG8_SB(0, 0), b2, voffB);
;             PG8_BAR; PG8_WAIT_L(0); PG8_MMA(0, 1, At, B1); PG8_BAR;
;             PG8_LDA(At, 0, 1); PG8_STAGE(PG8_SA(0, 0), a2, voffA);
;             PG8_BAR; PG8_WAIT_L(0); PG8_MMA(1, 0, At, B0); PG8_BAR; PG8_SCHED;
.LBB0_344:
	s_add_u32 s20, s18, 0xfff80080
	s_addc_u32 s21, s19, -1
	s_add_i32 s45, 0, 0x10000
	v_add_u32_e32 v146, s45, v149
	ds_read_b128 v[128:131], v146
	ds_read_b128 v[132:135], v146 offset:1024
	ds_read_b128 v[142:145], v146 offset:2048
	ds_read_b128 v[150:153], v146 offset:3072
	s_cmp_eq_u32 s44, 28
	s_cselect_b32 s23, s1, s21
	s_cselect_b32 s22, s13, s20
	s_cselect_b32 s21, s11, s43
	s_cselect_b32 s20, s41, s42
	v_lshl_add_u64 v[154:155], s[18:19], 0, v[138:139]
	s_add_i32 m0, s30, 0xc000
	ds_read_b128 v[174:177], v159
	ds_read_b128 v[178:181], v159 offset:1024
	ds_read_b128 v[182:185], v159 offset:2048
	ds_read_b128 v[186:189], v159 offset:3072
	ds_read_b128 v[190:193], v159 offset:4096
	ds_read_b128 v[194:197], v159 offset:5120
	ds_read_b128 v[214:217], v159 offset:6144
	ds_read_b128 v[218:221], v159 offset:7168
	global_load_lds_dwordx4 v[154:155], off
	v_lshl_add_u64 v[154:155], s[18:19], 0, v[140:141]
	s_add_i32 m0, s30, 0xe000
	s_nop 0
	global_load_lds_dwordx4 v[154:155], off
	s_waitcnt lgkmcnt(8)
	s_barrier
	s_waitcnt lgkmcnt(0)
	v_mfma_f32_16x16x32_bf16 v[124:127], v[128:131], v[174:177], v[124:127]
	v_mfma_f32_16x16x32_bf16 v[120:123], v[142:145], v[174:177], v[120:123]
	v_mfma_f32_16x16x32_bf16 v[116:119], v[128:131], v[182:185], v[116:119]
	v_mfma_f32_16x16x32_bf16 v[108:111], v[142:145], v[182:185], v[108:111]
	v_mfma_f32_16x16x32_bf16 v[100:103], v[128:131], v[190:193], v[100:103]
	v_mfma_f32_16x16x32_bf16 v[92:95], v[142:145], v[190:193], v[92:95]
	v_mfma_f32_16x16x32_bf16 v[84:87], v[128:131], v[214:217], v[84:87]
	v_mfma_f32_16x16x32_bf16 v[76:79], v[142:145], v[214:217], v[76:79]
	v_mfma_f32_16x16x32_bf16 v[124:127], v[132:135], v[178:181], v[124:127]
	v_mfma_f32_16x16x32_bf16 v[120:123], v[150:153], v[178:181], v[120:123]
	v_mfma_f32_16x16x32_bf16 v[116:119], v[132:135], v[186:189], v[116:119]
	v_mfma_f32_16x16x32_bf16 v[108:111], v[150:153], v[186:189], v[108:111]
	v_mfma_f32_16x16x32_bf16 v[100:103], v[132:135], v[194:197], v[100:103]
	v_mfma_f32_16x16x32_bf16 v[92:95], v[150:153], v[194:197], v[92:95]
	v_mfma_f32_16x16x32_bf16 v[84:87], v[132:135], v[218:221], v[84:87]
	v_mfma_f32_16x16x32_bf16 v[76:79], v[150:153], v[218:221], v[76:79]
	s_barrier
	s_add_i32 s48, 0, 0x14000
	s_add_i32 s45, s45, s29
	v_add_u32_e32 v146, s48, v149
	v_lshl_add_u64 v[154:155], s[20:21], 0, v[160:161]
	s_mov_b32 m0, s45
	ds_read_b128 v[222:225], v146
	ds_read_b128 v[226:229], v146 offset:1024
	ds_read_b128 v[230:233], v146 offset:2048
	ds_read_b128 v[234:237], v146 offset:3072
	global_load_lds_dwordx4 v[154:155], off
	v_lshl_add_u64 v[238:239], s[20:21], 0, v[136:137]
	s_add_i32 m0, s45, 0x2000
	s_nop 0
	global_load_lds_dwordx4 v[238:239], off
	s_barrier
	s_waitcnt lgkmcnt(0)
	v_mfma_f32_16x16x32_bf16 v[112:115], v[222:225], v[174:177], v[112:115]
	v_mfma_f32_16x16x32_bf16 v[104:107], v[230:233], v[174:177], v[104:107]
	v_mfma_f32_16x16x32_bf16 v[96:99], v[222:225], v[182:185], v[96:99]
	v_mfma_f32_16x16x32_bf16 v[88:91], v[230:233], v[182:185], v[88:91]
	v_mfma_f32_16x16x32_bf16 v[80:83], v[222:225], v[190:193], v[80:83]
	v_mfma_f32_16x16x32_bf16 v[72:75], v[230:233], v[190:193], v[72:75]
	v_mfma_f32_16x16x32_bf16 v[68:71], v[222:225], v[214:217], v[68:71]
	v_mfma_f32_16x16x32_bf16 v[64:67], v[230:233], v[214:217], v[64:67]
	v_mfma_f32_16x16x32_bf16 v[112:115], v[226:229], v[178:181], v[112:115]
	v_mfma_f32_16x16x32_bf16 v[104:107], v[234:237], v[178:181], v[104:107]
	v_mfma_f32_16x16x32_bf16 v[96:99], v[226:229], v[186:189], v[96:99]
	v_mfma_f32_16x16x32_bf16 v[88:91], v[234:237], v[186:189], v[88:91]
	v_mfma_f32_16x16x32_bf16 v[80:83], v[226:229], v[194:197], v[80:83]
	v_mfma_f32_16x16x32_bf16 v[72:75], v[234:237], v[194:197], v[72:75]
	v_mfma_f32_16x16x32_bf16 v[68:71], v[226:229], v[218:221], v[68:71]
	v_mfma_f32_16x16x32_bf16 v[64:67], v[234:237], v[218:221], v[64:67]
	s_mov_b32 m0, s30
	v_lshl_add_u64 v[240:241], s[22:23], 0, v[160:161]
	s_barrier
	ds_read_b128 v[174:177], v159 offset:16384
	ds_read_b128 v[178:181], v159 offset:17408
	ds_read_b128 v[182:185], v159 offset:18432
	ds_read_b128 v[186:189], v159 offset:19456
	ds_read_b128 v[190:193], v159 offset:20480
	ds_read_b128 v[194:197], v159 offset:21504
	ds_read_b128 v[214:217], v159 offset:22528
	ds_read_b128 v[218:221], v159 offset:23552
	global_load_lds_dwordx4 v[240:241], off
	v_lshl_add_u64 v[242:243], s[22:23], 0, v[136:137]
	s_mov_b32 m0, s31
	s_nop 0
	global_load_lds_dwordx4 v[242:243], off
	s_barrier
	s_waitcnt lgkmcnt(0)
	v_mfma_f32_16x16x32_bf16 v[60:63], v[128:131], v[174:177], v[60:63]
	v_mfma_f32_16x16x32_bf16 v[56:59], v[142:145], v[174:177], v[56:59]
	v_mfma_f32_16x16x32_bf16 v[52:55], v[128:131], v[182:185], v[52:55]
	v_mfma_f32_16x16x32_bf16 v[44:47], v[142:145], v[182:185], v[44:47]
	v_mfma_f32_16x16x32_bf16 v[36:39], v[128:131], v[190:193], v[36:39]
	v_mfma_f32_16x16x32_bf16 v[28:31], v[142:145], v[190:193], v[28:31]
	v_mfma_f32_16x16x32_bf16 v[20:23], v[128:131], v[214:217], v[20:23]
	v_mfma_f32_16x16x32_bf16 v[12:15], v[142:145], v[214:217], v[12:15]
	v_mfma_f32_16x16x32_bf16 v[60:63], v[132:135], v[178:181], v[60:63]
	v_mfma_f32_16x16x32_bf16 v[56:59], v[150:153], v[178:181], v[56:59]
	v_mfma_f32_16x16x32_bf16 v[52:55], v[132:135], v[186:189], v[52:55]
	v_mfma_f32_16x16x32_bf16 v[44:47], v[150:153], v[186:189], v[44:47]
	v_mfma_f32_16x16x32_bf16 v[36:39], v[132:135], v[194:197], v[36:39]
	v_mfma_f32_16x16x32_bf16 v[28:31], v[150:153], v[194:197], v[28:31]
	v_mfma_f32_16x16x32_bf16 v[20:23], v[132:135], v[218:221], v[20:23]
	v_mfma_f32_16x16x32_bf16 v[12:15], v[150:153], v[218:221], v[12:15]
	s_barrier
; #define PG8_STAGE(bufoff, gbase, voff) do { _Pragma("unroll") for (int _i = 0; _i < 2; ++_i) \
;         __builtin_amdgcn_global_load_lds((const unsigned*)((const char*)(gbase) + (voff)[_i]), (LAS unsigned*)(lds + (bufoff) + ldsw + _i * 8192), 16, 0, 0); } while (0)
; #define PG8_LDA(dst, b, h) do { _Pragma("unroll") for (int m = 0; m < 4; ++m) _Pragma("unroll") for (int k = 0; k < 2; ++k) dst[m][k] = *(const LAS bf16x8*)(lds + PG8_SA(b, h) + aoff + m * 2048 + k * 1024); } while (0)
; #define PG8_LDB(dst, b, h) do { _Pragma("unroll") for (int n = 0; n < 2; ++n) _Pragma("unroll") for (int k = 0; k < 2; ++k) dst[n][k] = *(const LAS bf16x8*)(lds + PG8_SB(b, h) + boff + n * 2048 + k * 1024); } while (0)
; #define PG8_MMA(ai, bj, At, Bt) do { __builtin_amdgcn_s_setprio(1); _Pragma("unroll") for (int m = 0; m < 4; ++m) _Pragma("unroll") for (int n = 0; n < 2; ++n) _Pragma("unroll") for (int k = 0; k < 2; ++k) \
;         acc[ai][bj][m][n] = __builtin_amdgcn_mfma_f32_16x16x32_bf16(Bt[n][k], At[m][k], acc[ai][bj][m][n], 0, 0, 0); __builtin_amdgcn_s_setprio(0); } while (0)
; #define PG8_WAIT_V(n) asm volatile("s_waitcnt vmcnt(" #n ")" ::: "memory")
; #define PG8_WAIT_L(n) asm volatile("s_waitcnt lgkmcnt(" #n ")" ::: "memory")
; #define PG8_BAR __builtin_amdgcn_s_barrier()
; #define PG8_SCHED __builtin_amdgcn_sched_barrier(0)
; template <class Epi>
; DEV void gemm_phase(LAS unsigned char* lds, const Gemm g, const StaticOrder& S, const Epi& E) {
;     ...
;             PG8_STAGE(PG8_SB(0, 1), b2 + hstep, voffB);
;             PG8_WAIT_V(6); PG8_BAR; PG8_MMA(1, 1, At, B1); PG8_BAR;
;             PG8_LDB(B0, 1, 0); PG8_SCHED; PG8_LDA(At, 1, 0); PG8_STAGE(PG8_SA(0, 1), a2 + hstep, voffA);
;             PG8_WAIT_L(8); PG8_BAR; PG8_WAIT_L(0); PG8_MMA(0, 0, At, B0); PG8_BAR; PG8_SCHED;
;             PG8_LDB(B1, 1, 1); PG8_STAGE(PG8_SB(1, 0), b3, voffB);
;             PG8_BAR; PG8_WAIT_L(0); PG8_MMA(0, 1, At, B1); PG8_BAR;
	s_add_u32 s46, s20, 0x80000
	s_addc_u32 s47, s21, 0
	s_add_i32 s45, s48, s29
	v_lshl_add_u64 v[128:129], s[46:47], 0, v[160:161]
	s_mov_b32 m0, s45
	s_nop 0
	global_load_lds_dwordx4 v[128:129], off
	v_lshl_add_u64 v[128:129], s[46:47], 0, v[136:137]
	s_add_i32 m0, s45, 0x2000
	s_nop 0
	global_load_lds_dwordx4 v[128:129], off
	s_waitcnt vmcnt(6)
	s_barrier
	v_mfma_f32_16x16x32_bf16 v[48:51], v[222:225], v[174:177], v[48:51]
	v_mfma_f32_16x16x32_bf16 v[40:43], v[230:233], v[174:177], v[40:43]
	v_mfma_f32_16x16x32_bf16 v[32:35], v[222:225], v[182:185], v[32:35]
	v_mfma_f32_16x16x32_bf16 v[24:27], v[230:233], v[182:185], v[24:27]
	v_mfma_f32_16x16x32_bf16 v[16:19], v[222:225], v[190:193], v[16:19]
	v_mfma_f32_16x16x32_bf16 v[8:11], v[230:233], v[190:193], v[8:11]
	v_mfma_f32_16x16x32_bf16 v[4:7], v[222:225], v[214:217], v[4:7]
	v_mfma_f32_16x16x32_bf16 v[0:3], v[230:233], v[214:217], v[0:3]
	v_mfma_f32_16x16x32_bf16 v[48:51], v[226:229], v[178:181], v[48:51]
	v_mfma_f32_16x16x32_bf16 v[40:43], v[234:237], v[178:181], v[40:43]
	v_mfma_f32_16x16x32_bf16 v[32:35], v[226:229], v[186:189], v[32:35]
	v_mfma_f32_16x16x32_bf16 v[24:27], v[234:237], v[186:189], v[24:27]
	v_mfma_f32_16x16x32_bf16 v[16:19], v[226:229], v[194:197], v[16:19]
	v_mfma_f32_16x16x32_bf16 v[8:11], v[234:237], v[194:197], v[8:11]
	v_mfma_f32_16x16x32_bf16 v[4:7], v[226:229], v[218:221], v[4:7]
	v_mfma_f32_16x16x32_bf16 v[0:3], v[234:237], v[218:221], v[0:3]
	s_add_i32 s45, 0, 0x18000
	v_add_u32_e32 v146, s45, v149
	s_barrier
	ds_read_b128 v[128:131], v146
	ds_read_b128 v[132:135], v146 offset:1024
	ds_read_b128 v[142:145], v146 offset:2048
	ds_read_b128 v[150:153], v146 offset:3072
	s_add_u32 s22, s22, 0x80000
	s_addc_u32 s23, s23, 0
	s_mov_b32 m0, s34
	v_lshl_add_u64 v[222:223], s[22:23], 0, v[160:161]
	ds_read_b128 v[174:177], v159 offset:32768
	ds_read_b128 v[178:181], v159 offset:33792
	ds_read_b128 v[182:185], v159 offset:34816
	ds_read_b128 v[186:189], v159 offset:35840
	ds_read_b128 v[190:193], v159 offset:36864
	ds_read_b128 v[194:197], v159 offset:37888
	ds_read_b128 v[214:217], v159 offset:38912
	ds_read_b128 v[218:221], v159 offset:39936
	global_load_lds_dwordx4 v[222:223], off
	v_lshl_add_u64 v[222:223], s[22:23], 0, v[136:137]
	s_mov_b32 m0, s35
	s_nop 0
	global_load_lds_dwordx4 v[222:223], off
	s_waitcnt lgkmcnt(8)
	s_barrier
	s_waitcnt lgkmcnt(0)
	v_mfma_f32_16x16x32_bf16 v[124:127], v[128:131], v[174:177], v[124:127]
	v_mfma_f32_16x16x32_bf16 v[120:123], v[142:145], v[174:177], v[120:123]
	v_mfma_f32_16x16x32_bf16 v[116:119], v[128:131], v[182:185], v[116:119]
	v_mfma_f32_16x16x32_bf16 v[108:111], v[142:145], v[182:185], v[108:111]
	v_mfma_f32_16x16x32_bf16 v[100:103], v[128:131], v[190:193], v[100:103]
	v_mfma_f32_16x16x32_bf16 v[92:95], v[142:145], v[190:193], v[92:95]
	v_mfma_f32_16x16x32_bf16 v[84:87], v[128:131], v[214:217], v[84:87]
	v_mfma_f32_16x16x32_bf16 v[76:79], v[142:145], v[214:217], v[76:79]
	v_mfma_f32_16x16x32_bf16 v[124:127], v[132:135], v[178:181], v[124:127]
	v_mfma_f32_16x16x32_bf16 v[120:123], v[150:153], v[178:181], v[120:123]
	v_mfma_f32_16x16x32_bf16 v[116:119], v[132:135], v[186:189], v[116:119]
	v_mfma_f32_16x16x32_bf16 v[108:111], v[150:153], v[186:189], v[108:111]
	v_mfma_f32_16x16x32_bf16 v[100:103], v[132:135], v[194:197], v[100:103]
	v_mfma_f32_16x16x32_bf16 v[92:95], v[150:153], v[194:197], v[92:95]
	v_mfma_f32_16x16x32_bf16 v[84:87], v[132:135], v[218:221], v[84:87]
	v_mfma_f32_16x16x32_bf16 v[76:79], v[150:153], v[218:221], v[76:79]
	s_barrier
	s_add_i32 s22, 0, 0x1c000
	s_add_i32 s23, s45, s29
	v_add_u32_e32 v146, s22, v149
	v_lshl_add_u64 v[154:155], v[154:155], 0, s[2:3]
	s_mov_b32 m0, s23
	ds_read_b128 v[222:225], v146
	ds_read_b128 v[226:229], v146 offset:1024
	ds_read_b128 v[230:233], v146 offset:2048
	ds_read_b128 v[234:237], v146 offset:3072
	global_load_lds_dwordx4 v[154:155], off
	v_lshl_add_u64 v[154:155], v[238:239], 0, s[2:3]
	s_add_i32 m0, s23, 0x2000
	s_nop 0
	global_load_lds_dwordx4 v[154:155], off
	s_barrier
	s_waitcnt lgkmcnt(0)
	v_mfma_f32_16x16x32_bf16 v[112:115], v[222:225], v[174:177], v[112:115]
	v_mfma_f32_16x16x32_bf16 v[104:107], v[230:233], v[174:177], v[104:107]
	v_mfma_f32_16x16x32_bf16 v[96:99], v[222:225], v[182:185], v[96:99]
	v_mfma_f32_16x16x32_bf16 v[88:91], v[230:233], v[182:185], v[88:91]
	v_mfma_f32_16x16x32_bf16 v[80:83], v[222:225], v[190:193], v[80:83]
	v_mfma_f32_16x16x32_bf16 v[72:75], v[230:233], v[190:193], v[72:75]
	v_mfma_f32_16x16x32_bf16 v[68:71], v[222:225], v[214:217], v[68:71]
	v_mfma_f32_16x16x32_bf16 v[64:67], v[230:233], v[214:217], v[64:67]
	v_mfma_f32_16x16x32_bf16 v[112:115], v[226:229], v[178:181], v[112:115]
	v_mfma_f32_16x16x32_bf16 v[104:107], v[234:237], v[178:181], v[104:107]
	v_mfma_f32_16x16x32_bf16 v[96:99], v[226:229], v[186:189], v[96:99]
	v_mfma_f32_16x16x32_bf16 v[88:91], v[234:237], v[186:189], v[88:91]
	v_mfma_f32_16x16x32_bf16 v[80:83], v[226:229], v[194:197], v[80:83]
	v_mfma_f32_16x16x32_bf16 v[72:75], v[234:237], v[194:197], v[72:75]
	v_mfma_f32_16x16x32_bf16 v[68:71], v[226:229], v[218:221], v[68:71]
	v_mfma_f32_16x16x32_bf16 v[64:67], v[234:237], v[218:221], v[64:67]
	s_mov_b32 m0, s37
	v_lshl_add_u64 v[154:155], v[240:241], 0, s[2:3]
	s_barrier
	ds_read_b128 v[174:177], v159 offset:49152
	ds_read_b128 v[178:181], v159 offset:50176
	ds_read_b128 v[182:185], v159 offset:51200
	ds_read_b128 v[186:189], v159 offset:52224
	ds_read_b128 v[190:193], v159 offset:53248
	ds_read_b128 v[194:197], v159 offset:54272
	ds_read_b128 v[214:217], v159 offset:55296
	ds_read_b128 v[218:221], v159 offset:56320
	global_load_lds_dwordx4 v[154:155], off
	v_lshl_add_u64 v[154:155], v[242:243], 0, s[2:3]
	s_mov_b32 m0, s38
	s_nop 0
	global_load_lds_dwordx4 v[154:155], off
	s_barrier
; #define PG8_STAGE(bufoff, gbase, voff) do { _Pragma("unroll") for (int _i = 0; _i < 2; ++_i) \
;         __builtin_amdgcn_global_load_lds((const unsigned*)((const char*)(gbase) + (voff)[_i]), (LAS unsigned*)(lds + (bufoff) + ldsw + _i * 8192), 16, 0, 0); } while (0)
; #define PG8_LDA(dst, b, h) do { _Pragma("unroll") for (int m = 0; m < 4; ++m) _Pragma("unroll") for (int k = 0; k < 2; ++k) dst[m][k] = *(const LAS bf16x8*)(lds + PG8_SA(b, h) + aoff + m * 2048 + k * 1024); } while (0)
; #define PG8_MMA(ai, bj, At, Bt) do { __builtin_amdgcn_s_setprio(1); _Pragma("unroll") for (int m = 0; m < 4; ++m) _Pragma("unroll") for (int n = 0; n < 2; ++n) _Pragma("unroll") for (int k = 0; k < 2; ++k) \
;         acc[ai][bj][m][n] = __builtin_amdgcn_mfma_f32_16x16x32_bf16(Bt[n][k], At[m][k], acc[ai][bj][m][n], 0, 0, 0); __builtin_amdgcn_s_setprio(0); } while (0)
; #define PG8_WAIT_V(n) asm volatile("s_waitcnt vmcnt(" #n ")" ::: "memory")
; #define PG8_WAIT_L(n) asm volatile("s_waitcnt lgkmcnt(" #n ")" ::: "memory")
; #define PG8_BAR __builtin_amdgcn_s_barrier()
; #define PG8_SCHED __builtin_amdgcn_sched_barrier(0)
; template <class Epi>
; DEV void gemm_phase(LAS unsigned char* lds, const Gemm g, const StaticOrder& S, const Epi& E) {
;     ...
;             PG8_LDA(At, 1, 1); PG8_STAGE(PG8_SA(1, 0), a3, voffA);
;             PG8_BAR; PG8_WAIT_L(0); PG8_MMA(1, 0, At, B0); PG8_BAR; PG8_SCHED;
;             PG8_STAGE(PG8_SB(1, 1), b3 + hstep, voffB);
;             PG8_WAIT_V(6); PG8_BAR; PG8_MMA(1, 1, At, B1); PG8_BAR;
; DEV float rowscale(const float* ss, int row) { const f32x4 a = *(const f32x4*)(ss + (size_t)row * 8), b = *(const f32x4*)(ss + (size_t)row * 8 + 4);
;     return rsqrtf(((a[0] + a[1]) + (a[2] + a[3]) + (b[0] + b[1]) + (b[2] + b[3])) * (1.0f / 2048.0f) + EPS); }
; template <int ACT, bool PERM>
; DEV void store_bf16_tile(AccRef acc, u16* O, int ld, int row0, int col0, const float* ss) {
;     float rsv[2][4];
; #pragma unroll
;     for (int ai = 0; ai < 2; ++ai)
; #pragma unroll
;         for (int m = 0; m < 4; ++m) rsv[ai][m] = ss ? rowscale(ss, row0 + ai * 128 + m * 16) : 1.0f;
; #pragma unroll
;     for (int ai = 0; ai < 2; ++ai)
; #pragma unroll
;         for (int m = 0; m < 4; ++m) { u16* rowp = O + (size_t)(row0 + ai * 128 + m * 16) * ld + col0; const float rs = rsv[ai][m];
	s_waitcnt lgkmcnt(0)
	v_mfma_f32_16x16x32_bf16 v[60:63], v[128:131], v[174:177], v[60:63]
	v_mfma_f32_16x16x32_bf16 v[56:59], v[142:145], v[174:177], v[56:59]
	v_mfma_f32_16x16x32_bf16 v[52:55], v[128:131], v[182:185], v[52:55]
	v_mfma_f32_16x16x32_bf16 v[44:47], v[142:145], v[182:185], v[44:47]
	v_mfma_f32_16x16x32_bf16 v[36:39], v[128:131], v[190:193], v[36:39]
	v_mfma_f32_16x16x32_bf16 v[28:31], v[142:145], v[190:193], v[28:31]
	v_mfma_f32_16x16x32_bf16 v[20:23], v[128:131], v[214:217], v[20:23]
	v_mfma_f32_16x16x32_bf16 v[12:15], v[142:145], v[214:217], v[12:15]
	v_mfma_f32_16x16x32_bf16 v[60:63], v[132:135], v[178:181], v[60:63]
	v_mfma_f32_16x16x32_bf16 v[56:59], v[150:153], v[178:181], v[56:59]
	v_mfma_f32_16x16x32_bf16 v[52:55], v[132:135], v[186:189], v[52:55]
	v_mfma_f32_16x16x32_bf16 v[44:47], v[150:153], v[186:189], v[44:47]
	v_mfma_f32_16x16x32_bf16 v[36:39], v[132:135], v[194:197], v[36:39]
	v_mfma_f32_16x16x32_bf16 v[28:31], v[150:153], v[194:197], v[28:31]
	v_mfma_f32_16x16x32_bf16 v[20:23], v[132:135], v[218:221], v[20:23]
	v_mfma_f32_16x16x32_bf16 v[12:15], v[150:153], v[218:221], v[12:15]
	s_barrier
	s_add_u32 s20, s20, 0x80080
	s_addc_u32 s21, s21, 0
	s_add_i32 s22, s22, s29
	v_lshl_add_u64 v[128:129], s[20:21], 0, v[160:161]
	s_mov_b32 m0, s22
	s_nop 0
	global_load_lds_dwordx4 v[128:129], off
	v_lshl_add_u64 v[128:129], s[20:21], 0, v[136:137]
	s_add_i32 m0, s22, 0x2000
	s_nop 0
	global_load_lds_dwordx4 v[128:129], off
	s_waitcnt vmcnt(6)
	s_barrier
	v_mfma_f32_16x16x32_bf16 v[48:51], v[222:225], v[174:177], v[48:51]
	v_mfma_f32_16x16x32_bf16 v[40:43], v[230:233], v[174:177], v[40:43]
	v_mfma_f32_16x16x32_bf16 v[32:35], v[222:225], v[182:185], v[32:35]
	v_mfma_f32_16x16x32_bf16 v[24:27], v[230:233], v[182:185], v[24:27]
	v_mfma_f32_16x16x32_bf16 v[16:19], v[222:225], v[190:193], v[16:19]
	v_mfma_f32_16x16x32_bf16 v[8:11], v[230:233], v[190:193], v[8:11]
	v_mfma_f32_16x16x32_bf16 v[4:7], v[222:225], v[214:217], v[4:7]
	v_mfma_f32_16x16x32_bf16 v[0:3], v[230:233], v[214:217], v[0:3]
	v_mfma_f32_16x16x32_bf16 v[48:51], v[226:229], v[178:181], v[48:51]
	v_mfma_f32_16x16x32_bf16 v[40:43], v[234:237], v[178:181], v[40:43]
	v_mfma_f32_16x16x32_bf16 v[32:35], v[226:229], v[186:189], v[32:35]
	v_mfma_f32_16x16x32_bf16 v[24:27], v[234:237], v[186:189], v[24:27]
	v_mfma_f32_16x16x32_bf16 v[16:19], v[226:229], v[194:197], v[16:19]
	v_mfma_f32_16x16x32_bf16 v[8:11], v[234:237], v[194:197], v[8:11]
	v_mfma_f32_16x16x32_bf16 v[4:7], v[226:229], v[218:221], v[4:7]
	v_mfma_f32_16x16x32_bf16 v[0:3], v[234:237], v[218:221], v[0:3]
	s_add_i32 s44, s44, 2
	s_add_u32 s18, s18, 0x100
	s_addc_u32 s19, s19, 0
	s_add_u32 s42, s42, 0x100
	s_addc_u32 s43, s43, 0
	s_cmp_gt_u32 s44, 29
	s_barrier
	s_cbranch_scc0 .LBB0_344
	v_lshl_add_u32 v142, s0, 8, v147
	v_ashrrev_i32_e32 v143, 31, v142
	v_lshlrev_b64 v[128:129], 5, v[142:143]
	v_lshl_add_u64 v[132:133], s[4:5], 0, v[128:129]
	global_load_dwordx4 v[128:131], v[132:133], off offset:16
	s_nop 0
	global_load_dwordx4 v[132:135], v[132:133], off
	s_mov_b32 s0, 0x3727c5ac
	s_mov_b32 s18, 0x3a000000
	s_mov_b32 s11, 0x800000
	s_mov_b64 s[20:21], s[16:17]
	s_waitcnt vmcnt(0)
	v_mov_b32_e32 v144, v133
	v_mov_b32_e32 v145, v134
	v_mov_b32_e32 v133, v135
	v_pk_add_f32 v[150:151], v[144:145], v[132:133]
	v_or_b32_e32 v144, 16, v142
	v_mov_b32_e32 v132, v130
	v_mov_b32_e32 v133, v128
	v_mov_b32_e32 v128, v131
	v_ashrrev_i32_e32 v145, 31, v144
	v_pk_add_f32 v[152:153], v[132:133], v[128:129]
	v_lshlrev_b64 v[128:129], 5, v[144:145]
	v_lshl_add_u64 v[132:133], s[4:5], 0, v[128:129]
	global_load_dwordx4 v[128:131], v[132:133], off offset:16
	s_nop 0
	global_load_dwordx4 v[132:135], v[132:133], off
	s_waitcnt vmcnt(0)
	v_mov_b32_e32 v154, v133
	v_mov_b32_e32 v155, v134
	v_mov_b32_e32 v133, v135
	v_pk_add_f32 v[132:133], v[154:155], v[132:133]
	v_mov_b32_e32 v134, v130
	v_mov_b32_e32 v135, v128
	v_mov_b32_e32 v128, v131
	v_pk_add_f32 v[128:129], v[134:135], v[128:129]
	v_mov_b32_e32 v130, v132
	v_mov_b32_e32 v131, v150
	v_mov_b32_e32 v150, v133
	v_pk_add_f32 v[130:131], v[130:131], v[150:151]
	v_mov_b32_e32 v132, v129
	v_mov_b32_e32 v133, v153
	v_pk_add_f32 v[130:131], v[130:131], v[132:133]
	v_mov_b32_e32 v129, v152
	v_pk_add_f32 v[128:129], v[128:129], v[130:131]
	v_mov_b64_e32 v[150:151], s[0:1]
	v_pk_fma_f32 v[128:129], v[128:129], s[18:19], v[150:151] op_sel_hi:[1,0,0]
	v_or_b32_e32 v152, 32, v142
	v_mul_f32_e32 v130, 0x4b800000, v129
	v_cmp_gt_f32_e64 s[0:1], s11, v129
	v_cmp_gt_f32_e32 vcc, s11, v128
	v_ashrrev_i32_e32 v153, 31, v152
	v_cndmask_b32_e64 v129, v129, v130, s[0:1]
	v_rsq_f32_e32 v129, v129
	s_nop 0
	v_mul_f32_e32 v130, 0x45800000, v129
	v_cndmask_b32_e64 v148, v129, v130, s[0:1]
	v_mul_f32_e32 v129, 0x4b800000, v128
	v_cndmask_b32_e32 v128, v128, v129, vcc
	v_rsq_f32_e32 v128, v128
	v_pk_mul_f32 v[106:107], v[106:107], v[148:149] op_sel_hi:[1,0]
	v_pk_mul_f32 v[104:105], v[104:105], v[148:149] op_sel_hi:[1,0]
	v_pk_mul_f32 v[114:115], v[114:115], v[148:149] op_sel_hi:[1,0]
	v_mul_f32_e32 v129, 0x45800000, v128
	v_cndmask_b32_e32 v146, v128, v129, vcc
	v_lshlrev_b64 v[128:129], 5, v[152:153]
	v_lshl_add_u64 v[132:133], s[4:5], 0, v[128:129]
	global_load_dwordx4 v[128:131], v[132:133], off offset:16
	s_nop 0
	global_load_dwordx4 v[132:135], v[132:133], off
	v_cvt_pk_bf16_f32 v104, v104, v105
	v_cvt_pk_bf16_f32 v105, v106, v107
	v_pk_mul_f32 v[90:91], v[90:91], v[146:147] op_sel_hi:[1,0]
	v_pk_mul_f32 v[88:89], v[88:89], v[146:147] op_sel_hi:[1,0]
	v_pk_mul_f32 v[112:113], v[112:113], v[148:149] op_sel_hi:[1,0]
	v_cvt_pk_bf16_f32 v88, v88, v89
	v_cvt_pk_bf16_f32 v89, v90, v91
	v_pk_mul_f32 v[98:99], v[98:99], v[146:147] op_sel_hi:[1,0]
	v_pk_mul_f32 v[96:97], v[96:97], v[146:147] op_sel_hi:[1,0]
	v_cvt_pk_bf16_f32 v112, v112, v113
	v_cvt_pk_bf16_f32 v113, v114, v115
	v_cvt_pk_bf16_f32 v96, v96, v97
	v_cvt_pk_bf16_f32 v97, v98, v99
	v_pk_mul_f32 v[126:127], v[126:127], v[148:149] op_sel_hi:[1,0]
	v_pk_mul_f32 v[124:125], v[124:125], v[148:149] op_sel_hi:[1,0]
	v_pk_mul_f32 v[122:123], v[122:123], v[148:149] op_sel_hi:[1,0]
	v_pk_mul_f32 v[120:121], v[120:121], v[148:149] op_sel_hi:[1,0]
	v_pk_mul_f32 v[106:107], v[118:119], v[146:147] op_sel_hi:[1,0]
	v_pk_mul_f32 v[110:111], v[110:111], v[146:147] op_sel_hi:[1,0]
	v_pk_mul_f32 v[108:109], v[108:109], v[146:147] op_sel_hi:[1,0]
	v_cvt_pk_bf16_f32 v124, v124, v125
	v_cvt_pk_bf16_f32 v125, v126, v127
	v_cvt_pk_bf16_f32 v120, v120, v121
	v_cvt_pk_bf16_f32 v121, v122, v123
	s_waitcnt vmcnt(0)
; DEV bf16x8 pack8(f32x4 a, f32x4 b) { u32x4 w; w.x = cvt_pk_bf16(a[0], a[1]); w.y = cvt_pk_bf16(a[2], a[3]); w.z = cvt_pk_bf16(b[0], b[1]); w.w = cvt_pk_bf16(b[2], b[3]); return __builtin_bit_cast(bf16x8, w); }
; DEV u32x2 pack4(f32x4 a) { u32x2 w; w.x = cvt_pk_bf16(a[0], a[1]); w.y = cvt_pk_bf16(a[2], a[3]); return w; }
; DEV f32x4 gelu4(f32x4 v) { f32x2 a = gelu_pk((f32x2){v[0], v[1]}), b = gelu_pk((f32x2){v[2], v[3]}); return (f32x4){a.x, a.y, b.x, b.y}; }
; DEV float rowscale(const float* ss, int row) { const f32x4 a = *(const f32x4*)(ss + (size_t)row * 8), b = *(const f32x4*)(ss + (size_t)row * 8 + 4);
;     return rsqrtf(((a[0] + a[1]) + (a[2] + a[3]) + (b[0] + b[1]) + (b[2] + b[3])) * (1.0f / 2048.0f) + EPS); }
; template <int ACT, bool PERM>
; DEV void store_bf16_tile(AccRef acc, u16* O, int ld, int row0, int col0, const float* ss) {
;     float rsv[2][4];
; #pragma unroll
;     for (int ai = 0; ai < 2; ++ai)
; #pragma unroll
;         for (int m = 0; m < 4; ++m) rsv[ai][m] = ss ? rowscale(ss, row0 + ai * 128 + m * 16) : 1.0f;
; #pragma unroll
;     for (int ai = 0; ai < 2; ++ai)
; #pragma unroll
;         for (int m = 0; m < 4; ++m) { u16* rowp = O + (size_t)(row0 + ai * 128 + m * 16) * ld + col0; const float rs = rsv[ai][m];
; #pragma unroll
;             for (int bj = 0; bj < 2; ++bj) { f32x4 v0 = acc[ai][bj][m][0] * rs, v1 = acc[ai][bj][m][1] * rs; if (ACT == 1) { v0 = gelu4(v0); v1 = gelu4(v1); }
;                 if (PERM) *(u32x4*)(rowp + bj * 128) = __builtin_bit_cast(u32x4, pack8(v0, v1));
;                 else { *(u32x2*)(rowp + bj * 128) = pack4(v0); *(u32x2*)(rowp + bj * 128 + 16) = pack4(v1); } } }
	v_mov_b32_e32 v154, v133
	v_mov_b32_e32 v155, v134
	v_mov_b32_e32 v133, v135
	v_pk_add_f32 v[174:175], v[154:155], v[132:133]
	v_or_b32_e32 v154, 48, v142
	v_mov_b32_e32 v132, v130
	v_mov_b32_e32 v133, v128
	v_mov_b32_e32 v128, v131
	v_ashrrev_i32_e32 v155, 31, v154
	v_pk_add_f32 v[176:177], v[132:133], v[128:129]
	v_lshlrev_b64 v[128:129], 5, v[154:155]
	v_lshl_add_u64 v[132:133], s[4:5], 0, v[128:129]
	global_load_dwordx4 v[128:131], v[132:133], off offset:16
	s_nop 0
	global_load_dwordx4 v[132:135], v[132:133], off
	s_waitcnt vmcnt(0)
	v_mov_b32_e32 v178, v133
	v_mov_b32_e32 v179, v134
	v_mov_b32_e32 v133, v135
	v_pk_add_f32 v[132:133], v[178:179], v[132:133]
	v_mov_b32_e32 v134, v130
	v_mov_b32_e32 v135, v128
	v_mov_b32_e32 v128, v131
	v_pk_add_f32 v[128:129], v[134:135], v[128:129]
	v_mov_b32_e32 v130, v132
	v_mov_b32_e32 v131, v174
	v_mov_b32_e32 v174, v133
	v_pk_add_f32 v[130:131], v[130:131], v[174:175]
	v_mov_b32_e32 v132, v129
	v_mov_b32_e32 v133, v177
	v_pk_add_f32 v[130:131], v[130:131], v[132:133]
	v_mov_b32_e32 v129, v176
	v_pk_add_f32 v[128:129], v[128:129], v[130:131]
	v_add_u32_e32 v174, 0x80, v142
	v_pk_fma_f32 v[128:129], v[128:129], s[18:19], v[150:151] op_sel_hi:[1,0,0]
	v_ashrrev_i32_e32 v175, 31, v174
	v_mul_f32_e32 v130, 0x4b800000, v129
	v_cmp_gt_f32_e64 s[0:1], s11, v129
	v_cmp_gt_f32_e32 vcc, s11, v128
	s_nop 0
	v_cndmask_b32_e64 v129, v129, v130, s[0:1]
	v_rsq_f32_e32 v129, v129
	s_nop 0
	v_mul_f32_e32 v130, 0x45800000, v129
	v_cndmask_b32_e64 v158, v129, v130, s[0:1]
	v_mul_f32_e32 v129, 0x4b800000, v128
	v_cndmask_b32_e32 v128, v128, v129, vcc
	v_rsq_f32_e32 v128, v128
	v_pk_mul_f32 v[74:75], v[74:75], v[158:159] op_sel_hi:[1,0]
	v_pk_mul_f32 v[72:73], v[72:73], v[158:159] op_sel_hi:[1,0]
	v_pk_mul_f32 v[82:83], v[82:83], v[158:159] op_sel_hi:[1,0]
	v_mul_f32_e32 v129, 0x45800000, v128
	v_cndmask_b32_e32 v156, v128, v129, vcc
	v_lshlrev_b64 v[128:129], 5, v[174:175]
	v_lshl_add_u64 v[132:133], s[4:5], 0, v[128:129]
	global_load_dwordx4 v[128:131], v[132:133], off offset:16
	s_nop 0
	global_load_dwordx4 v[132:135], v[132:133], off
	v_cvt_pk_bf16_f32 v72, v72, v73
	v_cvt_pk_bf16_f32 v73, v74, v75
	v_pk_mul_f32 v[66:67], v[66:67], v[156:157] op_sel_hi:[1,0]
	v_pk_mul_f32 v[64:65], v[64:65], v[156:157] op_sel_hi:[1,0]
	v_pk_mul_f32 v[80:81], v[80:81], v[158:159] op_sel_hi:[1,0]
	v_cvt_pk_bf16_f32 v64, v64, v65
	v_cvt_pk_bf16_f32 v65, v66, v67
	v_cvt_pk_bf16_f32 v80, v80, v81
	v_cvt_pk_bf16_f32 v81, v82, v83
	v_pk_mul_f32 v[90:91], v[102:103], v[158:159] op_sel_hi:[1,0]
	v_pk_mul_f32 v[94:95], v[94:95], v[158:159] op_sel_hi:[1,0]
	v_pk_mul_f32 v[92:93], v[92:93], v[158:159] op_sel_hi:[1,0]
	v_pk_mul_f32 v[74:75], v[86:87], v[156:157] op_sel_hi:[1,0]
	v_pk_mul_f32 v[78:79], v[78:79], v[156:157] op_sel_hi:[1,0]
	v_pk_mul_f32 v[76:77], v[76:77], v[156:157] op_sel_hi:[1,0]
	v_pk_mul_f32 v[70:71], v[70:71], v[156:157] op_sel_hi:[1,0]
	v_pk_mul_f32 v[68:69], v[68:69], v[156:157] op_sel_hi:[1,0]
	s_waitcnt vmcnt(0)
	v_mov_b32_e32 v176, v133
	v_mov_b32_e32 v177, v134
	v_mov_b32_e32 v133, v135
	v_pk_add_f32 v[178:179], v[176:177], v[132:133]
	v_add_u32_e32 v176, 0x90, v142
	v_mov_b32_e32 v132, v130
	v_mov_b32_e32 v133, v128
	v_mov_b32_e32 v128, v131
	v_ashrrev_i32_e32 v177, 31, v176
	v_pk_add_f32 v[180:181], v[132:133], v[128:129]
	v_lshlrev_b64 v[128:129], 5, v[176:177]
	v_lshl_add_u64 v[132:133], s[4:5], 0, v[128:129]
	global_load_dwordx4 v[128:131], v[132:133], off offset:16
	s_nop 0
	global_load_dwordx4 v[132:135], v[132:133], off
	v_cvt_pk_bf16_f32 v68, v68, v69
	v_cvt_pk_bf16_f32 v69, v70, v71
	s_waitcnt vmcnt(0)
	v_mov_b32_e32 v182, v133
	v_mov_b32_e32 v183, v134
	v_mov_b32_e32 v133, v135
	v_pk_add_f32 v[132:133], v[182:183], v[132:133]
	v_mov_b32_e32 v134, v130
	v_mov_b32_e32 v135, v128
	v_mov_b32_e32 v128, v131
	v_pk_add_f32 v[128:129], v[134:135], v[128:129]
	v_mov_b32_e32 v130, v132
	v_mov_b32_e32 v131, v178
	v_mov_b32_e32 v178, v133
	v_pk_add_f32 v[130:131], v[130:131], v[178:179]
	v_mov_b32_e32 v132, v129
	v_mov_b32_e32 v133, v181
	v_pk_add_f32 v[130:131], v[130:131], v[132:133]
	v_mov_b32_e32 v129, v180
	v_pk_add_f32 v[128:129], v[128:129], v[130:131]
	v_add_u32_e32 v182, 0xa0, v142
	v_pk_fma_f32 v[128:129], v[128:129], s[18:19], v[150:151] op_sel_hi:[1,0,0]
	v_ashrrev_i32_e32 v183, 31, v182
	v_mul_f32_e32 v130, 0x4b800000, v129
	v_cmp_gt_f32_e64 s[0:1], s11, v129
	v_cmp_gt_f32_e32 vcc, s11, v128
	s_nop 0
	v_cndmask_b32_e64 v129, v129, v130, s[0:1]
	v_rsq_f32_e32 v129, v129
	s_nop 0
	v_mul_f32_e32 v130, 0x45800000, v129
	v_cndmask_b32_e64 v180, v129, v130, s[0:1]
	v_mul_f32_e32 v129, 0x4b800000, v128
	v_cndmask_b32_e32 v128, v128, v129, vcc
	v_rsq_f32_e32 v128, v128
	v_pk_mul_f32 v[42:43], v[42:43], v[180:181] op_sel_hi:[1,0]
	v_pk_mul_f32 v[40:41], v[40:41], v[180:181] op_sel_hi:[1,0]
	v_pk_mul_f32 v[50:51], v[50:51], v[180:181] op_sel_hi:[1,0]
	v_mul_f32_e32 v129, 0x45800000, v128
	v_cndmask_b32_e32 v178, v128, v129, vcc
	v_lshlrev_b64 v[128:129], 5, v[182:183]
	v_lshl_add_u64 v[132:133], s[4:5], 0, v[128:129]
	global_load_dwordx4 v[128:131], v[132:133], off offset:16
	s_nop 0
	global_load_dwordx4 v[132:135], v[132:133], off
	v_cvt_pk_bf16_f32 v40, v40, v41
	v_cvt_pk_bf16_f32 v41, v42, v43
	v_pk_mul_f32 v[26:27], v[26:27], v[178:179] op_sel_hi:[1,0]
	v_pk_mul_f32 v[24:25], v[24:25], v[178:179] op_sel_hi:[1,0]
	v_pk_mul_f32 v[48:49], v[48:49], v[180:181] op_sel_hi:[1,0]
	v_cvt_pk_bf16_f32 v24, v24, v25
	v_cvt_pk_bf16_f32 v25, v26, v27
	v_pk_mul_f32 v[34:35], v[34:35], v[178:179] op_sel_hi:[1,0]
	v_pk_mul_f32 v[32:33], v[32:33], v[178:179] op_sel_hi:[1,0]
	v_cvt_pk_bf16_f32 v48, v48, v49
	v_cvt_pk_bf16_f32 v49, v50, v51
	v_cvt_pk_bf16_f32 v32, v32, v33
	v_cvt_pk_bf16_f32 v33, v34, v35
	v_pk_mul_f32 v[62:63], v[62:63], v[180:181] op_sel_hi:[1,0]
	v_pk_mul_f32 v[60:61], v[60:61], v[180:181] op_sel_hi:[1,0]
	v_pk_mul_f32 v[58:59], v[58:59], v[180:181] op_sel_hi:[1,0]
	v_pk_mul_f32 v[56:57], v[56:57], v[180:181] op_sel_hi:[1,0]
	v_pk_mul_f32 v[42:43], v[54:55], v[178:179] op_sel_hi:[1,0]
	v_pk_mul_f32 v[46:47], v[46:47], v[178:179] op_sel_hi:[1,0]
	v_pk_mul_f32 v[44:45], v[44:45], v[178:179] op_sel_hi:[1,0]
	v_cvt_pk_bf16_f32 v60, v60, v61
	v_cvt_pk_bf16_f32 v61, v62, v63
	v_cvt_pk_bf16_f32 v56, v56, v57
	v_cvt_pk_bf16_f32 v57, v58, v59
	s_waitcnt vmcnt(0)
; DEV bf16x8 pack8(f32x4 a, f32x4 b) { u32x4 w; w.x = cvt_pk_bf16(a[0], a[1]); w.y = cvt_pk_bf16(a[2], a[3]); w.z = cvt_pk_bf16(b[0], b[1]); w.w = cvt_pk_bf16(b[2], b[3]); return __builtin_bit_cast(bf16x8, w); }
; DEV u32x2 pack4(f32x4 a) { u32x2 w; w.x = cvt_pk_bf16(a[0], a[1]); w.y = cvt_pk_bf16(a[2], a[3]); return w; }
; DEV f32x4 gelu4(f32x4 v) { f32x2 a = gelu_pk((f32x2){v[0], v[1]}), b = gelu_pk((f32x2){v[2], v[3]}); return (f32x4){a.x, a.y, b.x, b.y}; }
; #define PG8_WAIT_V(n) asm volatile("s_waitcnt vmcnt(" #n ")" ::: "memory")
; #define PG8_BAR __builtin_amdgcn_s_barrier()
; template <class Epi>
; DEV void gemm_phase(LAS unsigned char* lds, const Gemm g, const StaticOrder& S, const Epi& E) {
;     ...
;         E(acc, cur, wr, wc, fr, fq);
;         if (!has_next) break;
; #pragma unroll
;         for (int a = 0; a < 2; ++a)
; #pragma unroll
;             for (int b = 0; b < 2; ++b)
; #pragma unroll
;                 for (int m = 0; m < 4; ++m)
; #pragma unroll
;                     for (int n = 0; n < 2; ++n) acc[a][b][m][n] = (f32x4){0.f, 0.f, 0.f, 0.f};
;         cur = nxt; cA = nA; cB = nB; ++ui;
;     }
;     PG8_WAIT_V(0);
;     if (wr == 0) PG8_BAR;
;     PG8_BAR;
; template <int ACT, bool PERM>
; DEV void store_bf16_tile(AccRef acc, u16* O, int ld, int row0, int col0, const float* ss) {
;     float rsv[2][4];
; #pragma unroll
;     for (int ai = 0; ai < 2; ++ai)
; #pragma unroll
;         for (int m = 0; m < 4; ++m) rsv[ai][m] = ss ? rowscale(ss, row0 + ai * 128 + m * 16) : 1.0f;
; #pragma unroll
;     for (int ai = 0; ai < 2; ++ai)
; #pragma unroll
;         for (int m = 0; m < 4; ++m) { u16* rowp = O + (size_t)(row0 + ai * 128 + m * 16) * ld + col0; const float rs = rsv[ai][m];
; #pragma unroll
;             for (int bj = 0; bj < 2; ++bj) { f32x4 v0 = acc[ai][bj][m][0] * rs, v1 = acc[ai][bj][m][1] * rs; if (ACT == 1) { v0 = gelu4(v0); v1 = gelu4(v1); }
;                 if (PERM) *(u32x4*)(rowp + bj * 128) = __builtin_bit_cast(u32x4, pack8(v0, v1));
;                 else { *(u32x2*)(rowp + bj * 128) = pack4(v0); *(u32x2*)(rowp + bj * 128 + 16) = pack4(v1); } } }
	v_mov_b32_e32 v184, v133
	v_mov_b32_e32 v185, v134
	v_mov_b32_e32 v133, v135
	v_pk_add_f32 v[188:189], v[184:185], v[132:133]
	v_add_u32_e32 v184, 0xb0, v142
	v_mov_b32_e32 v132, v130
	v_mov_b32_e32 v133, v128
	v_mov_b32_e32 v128, v131
	v_ashrrev_i32_e32 v185, 31, v184
	v_pk_add_f32 v[186:187], v[132:133], v[128:129]
	v_lshlrev_b64 v[128:129], 5, v[184:185]
	v_lshl_add_u64 v[132:133], s[4:5], 0, v[128:129]
	global_load_dwordx4 v[128:131], v[132:133], off offset:16
	s_nop 0
	global_load_dwordx4 v[132:135], v[132:133], off
	s_waitcnt vmcnt(0)
	v_mov_b32_e32 v190, v133
	v_mov_b32_e32 v191, v134
	v_mov_b32_e32 v133, v135
	v_pk_add_f32 v[132:133], v[190:191], v[132:133]
	v_mov_b32_e32 v134, v130
	v_mov_b32_e32 v135, v128
	v_mov_b32_e32 v128, v131
	v_pk_add_f32 v[128:129], v[134:135], v[128:129]
	v_mov_b32_e32 v130, v132
	v_mov_b32_e32 v131, v188
	v_mov_b32_e32 v188, v133
	v_pk_add_f32 v[130:131], v[130:131], v[188:189]
	v_mov_b32_e32 v132, v129
	v_mov_b32_e32 v133, v187
	v_pk_add_f32 v[130:131], v[130:131], v[132:133]
	v_mov_b32_e32 v129, v186
	v_pk_add_f32 v[128:129], v[128:129], v[130:131]
	v_lshl_or_b32 v132, s40, 8, v157
	v_pk_fma_f32 v[128:129], v[128:129], s[18:19], v[150:151] op_sel_hi:[1,0,0]
	v_ashrrev_i32_e32 v133, 31, v132
	v_mul_f32_e32 v130, 0x4b800000, v129
	v_cmp_gt_f32_e64 s[0:1], s11, v129
	v_lshlrev_b64 v[134:135], 10, v[142:143]
	v_cmp_gt_f32_e32 vcc, s11, v128
	v_cndmask_b32_e64 v129, v129, v130, s[0:1]
	v_rsq_f32_e32 v129, v129
	s_mov_b32 s40, s10
	s_mov_b64 s[18:19], s[14:15]
	v_mul_f32_e32 v130, 0x45800000, v129
	v_cndmask_b32_e64 v130, v129, v130, s[0:1]
	v_readlane_b32 s0, v250, 11
	v_readlane_b32 s1, v250, 12
	v_mul_f32_e32 v129, 0x4b800000, v128
	v_cndmask_b32_e32 v128, v128, v129, vcc
	v_lshl_add_u64 v[132:133], v[132:133], 1, s[0:1]
	v_lshl_add_u64 v[134:135], v[132:133], 0, v[134:135]
	global_store_dwordx2 v[134:135], v[104:105], off offset:288
	v_lshlrev_b64 v[104:105], 10, v[144:145]
	v_lshl_add_u64 v[104:105], v[132:133], 0, v[104:105]
	global_store_dwordx2 v[104:105], v[88:89], off offset:288
	v_lshlrev_b64 v[88:89], 10, v[152:153]
	v_lshl_add_u64 v[88:89], v[132:133], 0, v[88:89]
	global_store_dwordx2 v[88:89], v[72:73], off offset:288
	v_lshlrev_b64 v[72:73], 10, v[154:155]
	v_lshl_add_u64 v[72:73], v[132:133], 0, v[72:73]
	v_rsq_f32_e32 v128, v128
	global_store_dwordx2 v[72:73], v[64:65], off offset:288
	v_lshlrev_b64 v[64:65], 10, v[174:175]
	v_lshl_add_u64 v[64:65], v[132:133], 0, v[64:65]
	global_store_dwordx2 v[64:65], v[40:41], off offset:288
	v_lshlrev_b64 v[40:41], 10, v[176:177]
	v_lshl_add_u64 v[40:41], v[132:133], 0, v[40:41]
	v_mul_f32_e32 v129, 0x45800000, v128
	global_store_dwordx2 v[40:41], v[24:25], off offset:288
	v_lshlrev_b64 v[24:25], 10, v[182:183]
	v_pk_mul_f32 v[18:19], v[18:19], v[130:131] op_sel_hi:[1,0]
	v_pk_mul_f32 v[16:17], v[16:17], v[130:131] op_sel_hi:[1,0]
	v_pk_mul_f32 v[10:11], v[10:11], v[130:131] op_sel_hi:[1,0]
	v_pk_mul_f32 v[8:9], v[8:9], v[130:131] op_sel_hi:[1,0]
	v_cndmask_b32_e32 v128, v128, v129, vcc
	v_lshl_add_u64 v[24:25], v[132:133], 0, v[24:25]
	v_cvt_pk_bf16_f32 v16, v16, v17
	v_cvt_pk_bf16_f32 v17, v18, v19
	v_cvt_pk_bf16_f32 v8, v8, v9
	v_cvt_pk_bf16_f32 v9, v10, v11
	global_store_dwordx2 v[134:135], v[112:113], off offset:256
	v_pk_mul_f32 v[112:113], v[116:117], v[146:147] op_sel_hi:[1,0]
	global_store_dwordx2 v[104:105], v[96:97], off offset:256
	v_pk_mul_f32 v[96:97], v[100:101], v[158:159] op_sel_hi:[1,0]
	global_store_dwordx2 v[88:89], v[80:81], off offset:256
	v_pk_mul_f32 v[80:81], v[84:85], v[156:157] op_sel_hi:[1,0]
	global_store_dwordx2 v[64:65], v[48:49], off offset:256
	v_pk_mul_f32 v[48:49], v[52:53], v[178:179] op_sel_hi:[1,0]
	global_store_dwordx2 v[40:41], v[32:33], off offset:256
	v_pk_mul_f32 v[26:27], v[38:39], v[130:131] op_sel_hi:[1,0]
	v_pk_mul_f32 v[32:33], v[36:37], v[130:131] op_sel_hi:[1,0]
	v_pk_mul_f32 v[30:31], v[30:31], v[130:131] op_sel_hi:[1,0]
	v_pk_mul_f32 v[28:29], v[28:29], v[130:131] op_sel_hi:[1,0]
	global_store_dwordx2 v[24:25], v[16:17], off offset:256
	global_store_dwordx2 v[24:25], v[8:9], off offset:288
	v_lshlrev_b64 v[8:9], 10, v[184:185]
	v_pk_mul_f32 v[10:11], v[22:23], v[128:129] op_sel_hi:[1,0]
	v_pk_mul_f32 v[16:17], v[20:21], v[128:129] op_sel_hi:[1,0]
	v_pk_mul_f32 v[14:15], v[14:15], v[128:129] op_sel_hi:[1,0]
	v_pk_mul_f32 v[12:13], v[12:13], v[128:129] op_sel_hi:[1,0]
	v_pk_mul_f32 v[6:7], v[6:7], v[128:129] op_sel_hi:[1,0]
	v_pk_mul_f32 v[4:5], v[4:5], v[128:129] op_sel_hi:[1,0]
	v_pk_mul_f32 v[2:3], v[2:3], v[128:129] op_sel_hi:[1,0]
	v_pk_mul_f32 v[0:1], v[0:1], v[128:129] op_sel_hi:[1,0]
	v_cvt_pk_bf16_f32 v112, v112, v113
	v_cvt_pk_bf16_f32 v113, v106, v107
	v_cvt_pk_bf16_f32 v106, v108, v109
	v_cvt_pk_bf16_f32 v107, v110, v111
	v_cvt_pk_bf16_f32 v96, v96, v97
	v_cvt_pk_bf16_f32 v97, v90, v91
	v_cvt_pk_bf16_f32 v90, v92, v93
	v_cvt_pk_bf16_f32 v91, v94, v95
	v_cvt_pk_bf16_f32 v80, v80, v81
	v_cvt_pk_bf16_f32 v81, v74, v75
	v_cvt_pk_bf16_f32 v74, v76, v77
	v_cvt_pk_bf16_f32 v75, v78, v79
	v_cvt_pk_bf16_f32 v48, v48, v49
	v_cvt_pk_bf16_f32 v49, v42, v43
	v_cvt_pk_bf16_f32 v42, v44, v45
	v_cvt_pk_bf16_f32 v43, v46, v47
	v_cvt_pk_bf16_f32 v32, v32, v33
	v_cvt_pk_bf16_f32 v33, v26, v27
	v_cvt_pk_bf16_f32 v26, v28, v29
	v_cvt_pk_bf16_f32 v27, v30, v31
	v_lshl_add_u64 v[8:9], v[132:133], 0, v[8:9]
	v_cvt_pk_bf16_f32 v16, v16, v17
	v_cvt_pk_bf16_f32 v17, v10, v11
	v_cvt_pk_bf16_f32 v10, v12, v13
	v_cvt_pk_bf16_f32 v11, v14, v15
	v_cvt_pk_bf16_f32 v4, v4, v5
	v_cvt_pk_bf16_f32 v5, v6, v7
	v_cvt_pk_bf16_f32 v0, v0, v1
	v_cvt_pk_bf16_f32 v1, v2, v3
	s_and_b64 vcc, exec, s[6:7]
	s_mov_b32 s0, s12
	global_store_dwordx2 v[134:135], v[124:125], off
	global_store_dwordx2 v[134:135], v[120:121], off offset:32
	global_store_dwordx2 v[104:105], v[112:113], off
	global_store_dwordx2 v[104:105], v[106:107], off offset:32
	global_store_dwordx2 v[88:89], v[96:97], off
	global_store_dwordx2 v[88:89], v[90:91], off offset:32
	global_store_dwordx2 v[72:73], v[80:81], off
	global_store_dwordx2 v[72:73], v[74:75], off offset:32
	global_store_dwordx2 v[72:73], v[68:69], off offset:256
	global_store_dwordx2 v[64:65], v[60:61], off
	global_store_dwordx2 v[64:65], v[56:57], off offset:32
	global_store_dwordx2 v[40:41], v[48:49], off
	global_store_dwordx2 v[40:41], v[42:43], off offset:32
	global_store_dwordx2 v[24:25], v[32:33], off
	global_store_dwordx2 v[24:25], v[26:27], off offset:32
	global_store_dwordx2 v[8:9], v[16:17], off
	global_store_dwordx2 v[8:9], v[10:11], off offset:32
	global_store_dwordx2 v[8:9], v[4:5], off offset:256
	global_store_dwordx2 v[8:9], v[0:1], off offset:288
	s_cbranch_vccz .LBB0_337
	s_waitcnt vmcnt(0)
	s_cmpk_gt_u32 s25, 0xff
	s_cbranch_scc1 .LBB0_348
	s_barrier

; #define PG8_STAGE(bufoff, gbase, voff) do { _Pragma("unroll") for (int _i = 0; _i < 2; ++_i) \
;         __builtin_amdgcn_global_load_lds((const unsigned*)((const char*)(gbase) + (voff)[_i]), (LAS unsigned*)(lds + (bufoff) + ldsw + _i * 8192), 16, 0, 0); } while (0)
; #define PG8_WAIT_V(n) asm volatile("s_waitcnt vmcnt(" #n ")" ::: "memory")
; #define PG8_BAR __builtin_amdgcn_s_barrier()
;     DEV bool next(int i, Unit& u) const {
;         const long L = (long)i * G + c; if (L >= nwg) return false;
;         int wgid = (int)L; { const int q = nwg / NXCD, r = nwg % NXCD, xcd = wgid % NXCD, off = wgid / NXCD; wgid = (xcd < r ? xcd * (q + 1) : r * (q + 1) + (xcd - r) * q) + off; }
;         const int nig = WGM * nN, gid = wgid / nig, fm = gid * WGM, gsz = (nM - fm) < WGM ? (nM - fm) : WGM;
;         u.pm = fm + ((wgid % nig) % gsz); u.pn = (wgid % nig) / gsz; return true;
;     }
; template <class Epi>
; DEV void gemm_phase(LAS unsigned char* lds, const Gemm g, const StaticOrder& S, const Epi& E) {
;     ...
;     const char* cA = (const char*)g.A + (size_t)cur.pm * tstep; const char* cB = (const char*)g.Bt + (size_t)cur.pn * tstep;
;     PG8_STAGE(PG8_SB(0, 0), cB, voffB); PG8_STAGE(PG8_SA(0, 0), cA, voffA); PG8_STAGE(PG8_SB(0, 1), cB + hstep, voffB); PG8_STAGE(PG8_SA(0, 1), cA + hstep, voffA);
;     if (wr == 1) PG8_BAR;
;     PG8_WAIT_V(4); PG8_BAR;
;     PG8_STAGE(PG8_SB(1, 0), cB + kstep, voffB); PG8_STAGE(PG8_SA(1, 0), cA + kstep, voffA); PG8_STAGE(PG8_SB(1, 1), cB + hstep + kstep, voffB);
;     PG8_WAIT_V(6); PG8_BAR;
; DEV void run_phase(const P& p, int ph, LAS unsigned char* lds) {
;     ...
;             for (int l = 0; l < 2; ++l) { EpiBf16 E{(u16*)(ws + O_KVX) + (size_t)l * 256 * 1024, 1024, nullptr};
;                 const int first = (64 + 4 * l) % G;
;                 run_gemm(lds, (const u16*)(ws + O_MEMN) + (size_t)l * 256 * 2048, (const u16*)(ws + O_WXKV) + (size_t)l * 1024 * 2048, 256, 1024, 2048, E, (bx + G - first) % G); }
.LBB0_355:
	s_lshl_b32 s10, s72, 2
	s_or_b32 s10, s10, 64
	s_mul_hi_u32 s11, s10, s4
	s_mul_i32 s11, s11, s30
	s_sub_i32 s10, s10, s11
	s_sub_i32 s11, s10, s30
	s_cmp_ge_u32 s10, s30
	s_cselect_b32 s10, s11, s10
	s_sub_i32 s11, s10, s30
	s_cmp_ge_u32 s10, s30
	s_cselect_b32 s10, s11, s10
	s_sub_i32 s10, s31, s10
	s_ashr_i32 s11, s10, 31
	s_abs_i32 s10, s10
	s_mul_hi_u32 s12, s10, s4
	s_mul_i32 s12, s12, s30
	s_sub_i32 s10, s10, s12
	s_sub_i32 s12, s10, s30
	s_cmp_ge_u32 s10, s30
	s_cselect_b32 s10, s12, s10
	s_sub_i32 s12, s10, s30
	s_cmp_ge_u32 s10, s30
	s_cselect_b32 s10, s12, s10
	s_xor_b32 s10, s10, s11
	s_sub_i32 s34, s10, s11
	v_readlane_b32 s10, v250, 1
	s_mov_b32 s35, s10
	v_mov_b32_e32 v14, v198
	s_cmp_gt_i32 s34, 3
	v_readfirstlane_b32 s36, v14
	v_readlane_b32 s11, v250, 2
	s_cbranch_scc1 .LBB0_354
	v_lshlrev_b32_e32 v0, 4, v14
	s_waitcnt lgkmcnt(0)
	v_add_u32_e32 v1, 0x2000, v0
	v_ashrrev_i32_e32 v2, 31, v1
	v_lshrrev_b32_e32 v2, 22, v2
	v_add_u32_e32 v2, v1, v2
	v_ashrrev_i32_e32 v8, 10, v2
	v_mul_i32_i24_e32 v3, 0x400, v8
	v_sub_u32_e32 v1, v1, v3
	v_lshrrev_b32_e32 v3, 4, v1
	v_bitop3_b32 v1, v3, v1, 32 bitop3:0x6c
	v_ashrrev_i32_e32 v3, 31, v1
	v_lshrrev_b32_e32 v3, 26, v3
	v_add_u32_e32 v3, v1, v3
	v_ashrrev_i32_e32 v9, 6, v3
	v_and_b32_e32 v3, 0xc0, v3
	v_sub_u32_e32 v1, v1, v3
	s_lshl_b64 s[10:11], s[72:73], 20
	v_readlane_b32 s12, v250, 21
	v_lshlrev_b32_e32 v2, 5, v8
	v_ashrrev_i16_sdwa v1, v203, sext(v1) dst_sel:DWORD dst_unused:UNUSED_PAD src0_sel:DWORD src1_sel:BYTE_0
	s_add_u32 s37, s12, s10
	v_readlane_b32 s10, v250, 22
	v_and_b32_e32 v2, 32, v2
	v_bfe_i32 v10, v1, 0, 16
	s_addc_u32 s38, s10, s11
	s_lshl_b64 s[10:11], s[72:73], 22
	v_readlane_b32 s12, v250, 23
	v_add_u32_e32 v1, v2, v10
	v_lshlrev_b32_e32 v2, 3, v8
	v_readlane_b32 s13, v250, 24
	s_add_u32 s39, s12, s10
	v_and_b32_e32 v2, 0xffff0, v2
	s_addc_u32 s40, s13, s11
	v_add_lshl_u32 v2, v9, v2, 12
	s_ashr_i32 s42, s34, 31
	v_lshl_add_u32 v128, v1, 1, v2
	v_bfe_i32 v2, v14, 27, 1
	s_lshr_b32 s10, s42, 29
	v_lshrrev_b32_e32 v2, 22, v2
	s_add_i32 s10, s34, s10
	v_add_u32_e32 v2, v0, v2
	s_ashr_i32 s11, s10, 3
	s_and_b32 s10, s10, -8
	v_and_b32_e32 v2, 0xfffffc00, v2
	s_sub_i32 s10, s34, s10
	v_sub_u32_e32 v0, v0, v2
	s_add_i32 s10, s10, s11
	v_lshrrev_b32_e32 v2, 4, v0
	s_ashr_i32 s11, s10, 31
	v_bitop3_b32 v2, v2, v0, 32 bitop3:0x6c
	v_ashrrev_i32_e32 v0, 31, v0
	s_lshr_b32 s11, s11, 27
	v_lshrrev_b32_e32 v0, 26, v0
	s_add_i32 s11, s10, s11
	v_ashrrev_i32_e32 v1, 31, v14
	v_add_u32_e32 v0, v2, v0
	s_ashr_i32 s11, s11, 5
	v_lshrrev_b32_e32 v1, 26, v1
	v_ashrrev_i32_e32 v12, 6, v0
	s_lshl_b32 s12, s11, 3
	v_add_u32_e32 v1, v14, v1
	v_mul_i32_i24_e32 v0, 64, v12
	s_sub_i32 s13, 1, s12
	s_lshl_b32 s11, s11, 5
	v_ashrrev_i32_e32 v11, 6, v1
	v_sub_u32_e32 v0, v2, v0
	s_min_u32 s13, s13, 8
	s_sub_i32 s16, s10, s11
	v_lshlrev_b32_e32 v1, 5, v11
	v_ashrrev_i16_sdwa v0, v203, sext(v0) dst_sel:DWORD dst_unused:UNUSED_PAD src0_sel:DWORD src1_sel:BYTE_0
	s_sext_i32_i8 s10, s16
	v_cvt_f32_ubyte0_e32 v3, s13
	v_and_b32_e32 v1, 32, v1
	v_bfe_i32 v13, v0, 0, 16
	v_cvt_f32_i32_e32 v2, s10
	v_rcp_iflag_f32_e32 v4, v3
	v_add_u32_e32 v0, v1, v13
	v_lshlrev_b32_e32 v1, 3, v11
	v_and_b32_e32 v1, 0xffff0, v1
	v_add_lshl_u32 v1, v12, v1, 12
	v_lshl_add_u32 v160, v0, 1, v1
	v_mul_f32_e32 v0, v2, v4
	v_trunc_f32_e32 v0, v0
	v_fma_f32 v1, -v0, v3, v2
	v_cvt_i32_f32_e32 v0, v0
	s_ashr_i32 s14, s36, 6
	s_ashr_i32 s10, s10, 30
	s_ashr_i32 s15, s36, 8
	s_lshl_b32 s41, s14, 10
	s_or_b32 s17, s10, 1
	v_cmp_ge_f32_e64 s[10:11], |v1|, v3
	s_and_b64 s[10:11], s[10:11], exec
	s_cselect_b32 s10, s17, 0
	v_readfirstlane_b32 s11, v0
	s_add_i32 s10, s11, s10
	s_mul_i32 s11, s10, s13
	s_sub_i32 s11, s16, s11
	s_sext_i32_i8 s11, s11
	s_add_i32 s12, s12, s11
	s_ashr_i32 s13, s12, 31
	s_bfe_i64 s[18:19], s[10:11], 0x80000
	s_lshl_b64 s[16:17], s[12:13], 20
	s_lshl_b64 s[18:19], s[18:19], 20
	s_add_u32 s26, s39, s18
	s_addc_u32 s27, s40, s19
	s_add_i32 s13, s41, 0
	s_add_i32 m0, s13, 0x10000
	v_mov_b32_e32 v129, v161
	global_load_lds_dwordx4 v160, s[26:27]
	s_add_i32 m0, s13, 0x12000
	s_add_u32 s24, s37, s16
	global_load_lds_dwordx4 v128, s[26:27]
	s_addc_u32 s25, s38, s17
	s_mov_b32 m0, s13
	s_add_i32 s43, s13, 0x2000
	global_load_lds_dwordx4 v160, s[24:25]
	s_mov_b32 m0, s43
	s_add_u32 s16, s26, 0x80000
	global_load_lds_dwordx4 v128, s[24:25]
	s_addc_u32 s17, s27, 0
	s_add_i32 m0, s13, 0x14000
	v_lshl_add_u64 v[6:7], s[26:27], 0, v[160:161]
	global_load_lds_dwordx4 v160, s[16:17]
	s_add_i32 m0, s13, 0x16000
	v_lshl_add_u64 v[4:5], s[26:27], 0, v[128:129]
	global_load_lds_dwordx4 v128, s[16:17]
	s_add_u32 s16, s24, 0x80000
	s_addc_u32 s17, s25, 0
	s_add_i32 s44, s13, 0x4000
	s_mov_b32 m0, s44
	s_add_i32 s45, s13, 0x6000
	global_load_lds_dwordx4 v160, s[16:17]
	s_mov_b32 m0, s45
	v_lshl_add_u64 v[2:3], s[24:25], 0, v[160:161]
	global_load_lds_dwordx4 v128, s[16:17]
	s_cmp_lg_u32 s15, 1
	v_lshl_add_u64 v[0:1], s[24:25], 0, v[128:129]
	s_cbranch_scc1 .LBB0_358
	s_barrier
	s_setprio 1

; #define PG8_STAGE(bufoff, gbase, voff) do { _Pragma("unroll") for (int _i = 0; _i < 2; ++_i) \
;         __builtin_amdgcn_global_load_lds((const unsigned*)((const char*)(gbase) + (voff)[_i]), (LAS unsigned*)(lds + (bufoff) + ldsw + _i * 8192), 16, 0, 0); } while (0)
; #define PG8_LDA(dst, b, h) do { _Pragma("unroll") for (int m = 0; m < 4; ++m) _Pragma("unroll") for (int k = 0; k < 2; ++k) dst[m][k] = *(const LAS bf16x8*)(lds + PG8_SA(b, h) + aoff + m * 2048 + k * 1024); } while (0)
; #define PG8_LDB(dst, b, h) do { _Pragma("unroll") for (int n = 0; n < 2; ++n) _Pragma("unroll") for (int k = 0; k < 2; ++k) dst[n][k] = *(const LAS bf16x8*)(lds + PG8_SB(b, h) + boff + n * 2048 + k * 1024); } while (0)
; #define PG8_MMA(ai, bj, At, Bt) do { __builtin_amdgcn_s_setprio(1); _Pragma("unroll") for (int m = 0; m < 4; ++m) _Pragma("unroll") for (int n = 0; n < 2; ++n) _Pragma("unroll") for (int k = 0; k < 2; ++k) \
;         acc[ai][bj][m][n] = __builtin_amdgcn_mfma_f32_16x16x32_bf16(Bt[n][k], At[m][k], acc[ai][bj][m][n], 0, 0, 0); __builtin_amdgcn_s_setprio(0); } while (0)
; #define PG8_WAIT_L(n) asm volatile("s_waitcnt lgkmcnt(" #n ")" ::: "memory")
; #define PG8_BAR __builtin_amdgcn_s_barrier()
; #define PG8_SCHED __builtin_amdgcn_sched_barrier(0)
; template <class Epi>
; DEV void gemm_phase(LAS unsigned char* lds, const Gemm g, const StaticOrder& S, const Epi& E) {
;     ...
;             PG8_LDB(B0, 0, 0); PG8_SCHED; PG8_LDA(At, 0, 0); PG8_STAGE(PG8_SA(1, 1), a1 + hstep, voffA);
;             PG8_WAIT_L(8); PG8_BAR; PG8_WAIT_L(0); PG8_MMA(0, 0, At, B0); PG8_BAR; PG8_SCHED;
;             PG8_LDB(B1, 0, 1); PG8_STAGE(PG8_SB(0, 0), b2, voffB);
;             PG8_BAR; PG8_WAIT_L(0); PG8_MMA(0, 1, At, B1); PG8_BAR;
;             PG8_LDA(At, 0, 1); PG8_STAGE(PG8_SA(0, 0), a2, voffA);
;             PG8_BAR; PG8_WAIT_L(0); PG8_MMA(1, 0, At, B0); PG8_BAR; PG8_SCHED;
.LBB0_362:
	s_add_u32 s26, s24, 0xfff80080
	s_addc_u32 s27, s25, -1
	s_add_i32 s56, 0, 0x10000
	v_add_u32_e32 v150, s56, v135
	ds_read_b128 v[138:141], v150
	ds_read_b128 v[142:145], v150 offset:1024
	ds_read_b128 v[146:149], v150 offset:2048
	ds_read_b128 v[150:153], v150 offset:3072
	s_cmp_eq_u32 s55, 28
	s_cselect_b32 s29, s19, s27
	s_cselect_b32 s28, s51, s26
	s_cselect_b32 s27, s17, s54
	s_cselect_b32 s26, s52, s53
	v_lshl_add_u64 v[158:159], s[24:25], 0, v[130:131]
	s_add_i32 m0, s13, 0xc000
	ds_read_b128 v[154:157], v137
	ds_read_b128 v[174:177], v137 offset:1024
	ds_read_b128 v[178:181], v137 offset:2048
	ds_read_b128 v[182:185], v137 offset:3072
	ds_read_b128 v[186:189], v137 offset:4096
	ds_read_b128 v[190:193], v137 offset:5120
	ds_read_b128 v[194:197], v137 offset:6144
	ds_read_b128 v[214:217], v137 offset:7168
	global_load_lds_dwordx4 v[158:159], off
	v_lshl_add_u64 v[158:159], s[24:25], 0, v[132:133]
	s_add_i32 m0, s13, 0xe000
	s_nop 0
	global_load_lds_dwordx4 v[158:159], off
	s_waitcnt lgkmcnt(8)
	s_barrier
	s_waitcnt lgkmcnt(0)
	v_mfma_f32_16x16x32_bf16 v[124:127], v[138:141], v[154:157], v[124:127]
	v_mfma_f32_16x16x32_bf16 v[120:123], v[146:149], v[154:157], v[120:123]
	v_mfma_f32_16x16x32_bf16 v[116:119], v[138:141], v[178:181], v[116:119]
	v_mfma_f32_16x16x32_bf16 v[108:111], v[146:149], v[178:181], v[108:111]
	v_mfma_f32_16x16x32_bf16 v[100:103], v[138:141], v[186:189], v[100:103]
	v_mfma_f32_16x16x32_bf16 v[92:95], v[146:149], v[186:189], v[92:95]
	v_mfma_f32_16x16x32_bf16 v[84:87], v[138:141], v[194:197], v[84:87]
	v_mfma_f32_16x16x32_bf16 v[76:79], v[146:149], v[194:197], v[76:79]
	v_mfma_f32_16x16x32_bf16 v[124:127], v[142:145], v[174:177], v[124:127]
	v_mfma_f32_16x16x32_bf16 v[120:123], v[150:153], v[174:177], v[120:123]
	v_mfma_f32_16x16x32_bf16 v[116:119], v[142:145], v[182:185], v[116:119]
	v_mfma_f32_16x16x32_bf16 v[108:111], v[150:153], v[182:185], v[108:111]
	v_mfma_f32_16x16x32_bf16 v[100:103], v[142:145], v[190:193], v[100:103]
	v_mfma_f32_16x16x32_bf16 v[92:95], v[150:153], v[190:193], v[92:95]
	v_mfma_f32_16x16x32_bf16 v[84:87], v[142:145], v[214:217], v[84:87]
	v_mfma_f32_16x16x32_bf16 v[76:79], v[150:153], v[214:217], v[76:79]
	s_barrier
	s_add_i32 s58, 0, 0x14000
	v_add_u32_e32 v158, s58, v135
	s_add_i32 s56, s56, s41
	ds_read_b128 v[218:221], v158
	ds_read_b128 v[222:225], v158 offset:1024
	ds_read_b128 v[226:229], v158 offset:2048
	ds_read_b128 v[230:233], v158 offset:3072
	v_lshl_add_u64 v[158:159], s[26:27], 0, v[160:161]
	s_mov_b32 m0, s56
	v_lshl_add_u64 v[234:235], s[26:27], 0, v[128:129]
	global_load_lds_dwordx4 v[158:159], off
	s_add_i32 m0, s56, 0x2000
	s_nop 0
	global_load_lds_dwordx4 v[234:235], off
	s_barrier
	s_waitcnt lgkmcnt(0)
	v_mfma_f32_16x16x32_bf16 v[112:115], v[218:221], v[154:157], v[112:115]
	v_mfma_f32_16x16x32_bf16 v[104:107], v[226:229], v[154:157], v[104:107]
	v_mfma_f32_16x16x32_bf16 v[96:99], v[218:221], v[178:181], v[96:99]
	v_mfma_f32_16x16x32_bf16 v[88:91], v[226:229], v[178:181], v[88:91]
	v_mfma_f32_16x16x32_bf16 v[80:83], v[218:221], v[186:189], v[80:83]
	v_mfma_f32_16x16x32_bf16 v[72:75], v[226:229], v[186:189], v[72:75]
	v_mfma_f32_16x16x32_bf16 v[68:71], v[218:221], v[194:197], v[68:71]
	v_mfma_f32_16x16x32_bf16 v[64:67], v[226:229], v[194:197], v[64:67]
	v_mfma_f32_16x16x32_bf16 v[112:115], v[222:225], v[174:177], v[112:115]
	v_mfma_f32_16x16x32_bf16 v[104:107], v[230:233], v[174:177], v[104:107]
	v_mfma_f32_16x16x32_bf16 v[96:99], v[222:225], v[182:185], v[96:99]
	v_mfma_f32_16x16x32_bf16 v[88:91], v[230:233], v[182:185], v[88:91]
	v_mfma_f32_16x16x32_bf16 v[80:83], v[222:225], v[190:193], v[80:83]
	v_mfma_f32_16x16x32_bf16 v[72:75], v[230:233], v[190:193], v[72:75]
	v_mfma_f32_16x16x32_bf16 v[68:71], v[222:225], v[214:217], v[68:71]
	v_mfma_f32_16x16x32_bf16 v[64:67], v[230:233], v[214:217], v[64:67]
	s_mov_b32 m0, s13
	v_lshl_add_u64 v[236:237], s[28:29], 0, v[160:161]
	s_barrier
	ds_read_b128 v[154:157], v137 offset:16384
	ds_read_b128 v[174:177], v137 offset:17408
	ds_read_b128 v[178:181], v137 offset:18432
	ds_read_b128 v[182:185], v137 offset:19456
	ds_read_b128 v[186:189], v137 offset:20480
	ds_read_b128 v[190:193], v137 offset:21504
	ds_read_b128 v[194:197], v137 offset:22528
	ds_read_b128 v[214:217], v137 offset:23552
	global_load_lds_dwordx4 v[236:237], off
	v_lshl_add_u64 v[238:239], s[28:29], 0, v[128:129]
	s_mov_b32 m0, s43
	s_nop 0
	global_load_lds_dwordx4 v[238:239], off
	s_barrier
	s_waitcnt lgkmcnt(0)
	v_mfma_f32_16x16x32_bf16 v[60:63], v[138:141], v[154:157], v[60:63]
	v_mfma_f32_16x16x32_bf16 v[56:59], v[146:149], v[154:157], v[56:59]
	v_mfma_f32_16x16x32_bf16 v[52:55], v[138:141], v[178:181], v[52:55]
	v_mfma_f32_16x16x32_bf16 v[44:47], v[146:149], v[178:181], v[44:47]
	v_mfma_f32_16x16x32_bf16 v[36:39], v[138:141], v[186:189], v[36:39]
	v_mfma_f32_16x16x32_bf16 v[28:31], v[146:149], v[186:189], v[28:31]
	v_mfma_f32_16x16x32_bf16 v[20:23], v[138:141], v[194:197], v[20:23]
	v_mfma_f32_16x16x32_bf16 v[12:15], v[146:149], v[194:197], v[12:15]
	v_mfma_f32_16x16x32_bf16 v[60:63], v[142:145], v[174:177], v[60:63]
	v_mfma_f32_16x16x32_bf16 v[56:59], v[150:153], v[174:177], v[56:59]
	v_mfma_f32_16x16x32_bf16 v[52:55], v[142:145], v[182:185], v[52:55]
	v_mfma_f32_16x16x32_bf16 v[44:47], v[150:153], v[182:185], v[44:47]
	v_mfma_f32_16x16x32_bf16 v[36:39], v[142:145], v[190:193], v[36:39]
	v_mfma_f32_16x16x32_bf16 v[28:31], v[150:153], v[190:193], v[28:31]
	v_mfma_f32_16x16x32_bf16 v[20:23], v[142:145], v[214:217], v[20:23]
	v_mfma_f32_16x16x32_bf16 v[12:15], v[150:153], v[214:217], v[12:15]
	s_barrier
; #define PG8_STAGE(bufoff, gbase, voff) do { _Pragma("unroll") for (int _i = 0; _i < 2; ++_i) \
;         __builtin_amdgcn_global_load_lds((const unsigned*)((const char*)(gbase) + (voff)[_i]), (LAS unsigned*)(lds + (bufoff) + ldsw + _i * 8192), 16, 0, 0); } while (0)
; #define PG8_LDA(dst, b, h) do { _Pragma("unroll") for (int m = 0; m < 4; ++m) _Pragma("unroll") for (int k = 0; k < 2; ++k) dst[m][k] = *(const LAS bf16x8*)(lds + PG8_SA(b, h) + aoff + m * 2048 + k * 1024); } while (0)
; #define PG8_LDB(dst, b, h) do { _Pragma("unroll") for (int n = 0; n < 2; ++n) _Pragma("unroll") for (int k = 0; k < 2; ++k) dst[n][k] = *(const LAS bf16x8*)(lds + PG8_SB(b, h) + boff + n * 2048 + k * 1024); } while (0)
; #define PG8_MMA(ai, bj, At, Bt) do { __builtin_amdgcn_s_setprio(1); _Pragma("unroll") for (int m = 0; m < 4; ++m) _Pragma("unroll") for (int n = 0; n < 2; ++n) _Pragma("unroll") for (int k = 0; k < 2; ++k) \
;         acc[ai][bj][m][n] = __builtin_amdgcn_mfma_f32_16x16x32_bf16(Bt[n][k], At[m][k], acc[ai][bj][m][n], 0, 0, 0); __builtin_amdgcn_s_setprio(0); } while (0)
; #define PG8_WAIT_V(n) asm volatile("s_waitcnt vmcnt(" #n ")" ::: "memory")
; #define PG8_WAIT_L(n) asm volatile("s_waitcnt lgkmcnt(" #n ")" ::: "memory")
; #define PG8_BAR __builtin_amdgcn_s_barrier()
; #define PG8_SCHED __builtin_amdgcn_sched_barrier(0)
; template <class Epi>
; DEV void gemm_phase(LAS unsigned char* lds, const Gemm g, const StaticOrder& S, const Epi& E) {
;     ...
;             PG8_STAGE(PG8_SB(0, 1), b2 + hstep, voffB);
;             PG8_WAIT_V(6); PG8_BAR; PG8_MMA(1, 1, At, B1); PG8_BAR;
;             PG8_LDB(B0, 1, 0); PG8_SCHED; PG8_LDA(At, 1, 0); PG8_STAGE(PG8_SA(0, 1), a2 + hstep, voffA);
;             PG8_WAIT_L(8); PG8_BAR; PG8_WAIT_L(0); PG8_MMA(0, 0, At, B0); PG8_BAR; PG8_SCHED;
;             PG8_LDB(B1, 1, 1); PG8_STAGE(PG8_SB(1, 0), b3, voffB);
;             PG8_BAR; PG8_WAIT_L(0); PG8_MMA(0, 1, At, B1); PG8_BAR;
	s_add_u32 s56, s26, 0x80000
	s_addc_u32 s57, s27, 0
	s_add_i32 s58, s58, s41
	v_lshl_add_u64 v[138:139], s[56:57], 0, v[160:161]
	s_mov_b32 m0, s58
	s_nop 0
	global_load_lds_dwordx4 v[138:139], off
	v_lshl_add_u64 v[138:139], s[56:57], 0, v[128:129]
	s_add_i32 m0, s58, 0x2000
	s_nop 0
	global_load_lds_dwordx4 v[138:139], off
	s_waitcnt vmcnt(6)
	s_barrier
	v_mfma_f32_16x16x32_bf16 v[48:51], v[218:221], v[154:157], v[48:51]
	v_mfma_f32_16x16x32_bf16 v[40:43], v[226:229], v[154:157], v[40:43]
	v_mfma_f32_16x16x32_bf16 v[32:35], v[218:221], v[178:181], v[32:35]
	v_mfma_f32_16x16x32_bf16 v[24:27], v[226:229], v[178:181], v[24:27]
	v_mfma_f32_16x16x32_bf16 v[16:19], v[218:221], v[186:189], v[16:19]
	v_mfma_f32_16x16x32_bf16 v[8:11], v[226:229], v[186:189], v[8:11]
	v_mfma_f32_16x16x32_bf16 v[4:7], v[218:221], v[194:197], v[4:7]
	v_mfma_f32_16x16x32_bf16 v[0:3], v[226:229], v[194:197], v[0:3]
	v_mfma_f32_16x16x32_bf16 v[48:51], v[222:225], v[174:177], v[48:51]
	v_mfma_f32_16x16x32_bf16 v[40:43], v[230:233], v[174:177], v[40:43]
	v_mfma_f32_16x16x32_bf16 v[32:35], v[222:225], v[182:185], v[32:35]
	v_mfma_f32_16x16x32_bf16 v[24:27], v[230:233], v[182:185], v[24:27]
	v_mfma_f32_16x16x32_bf16 v[16:19], v[222:225], v[190:193], v[16:19]
	v_mfma_f32_16x16x32_bf16 v[8:11], v[230:233], v[190:193], v[8:11]
	v_mfma_f32_16x16x32_bf16 v[4:7], v[222:225], v[214:217], v[4:7]
	v_mfma_f32_16x16x32_bf16 v[0:3], v[230:233], v[214:217], v[0:3]
	s_add_i32 s56, 0, 0x18000
	v_add_u32_e32 v150, s56, v135
	s_barrier
	ds_read_b128 v[138:141], v150
	ds_read_b128 v[142:145], v150 offset:1024
	ds_read_b128 v[146:149], v150 offset:2048
	ds_read_b128 v[150:153], v150 offset:3072
	s_add_u32 s28, s28, 0x80000
	s_addc_u32 s29, s29, 0
	s_mov_b32 m0, s44
	v_lshl_add_u64 v[218:219], s[28:29], 0, v[160:161]
	ds_read_b128 v[154:157], v137 offset:32768
	ds_read_b128 v[174:177], v137 offset:33792
	ds_read_b128 v[178:181], v137 offset:34816
	ds_read_b128 v[182:185], v137 offset:35840
	ds_read_b128 v[186:189], v137 offset:36864
	ds_read_b128 v[190:193], v137 offset:37888
	ds_read_b128 v[194:197], v137 offset:38912
	ds_read_b128 v[214:217], v137 offset:39936
	global_load_lds_dwordx4 v[218:219], off
	v_lshl_add_u64 v[218:219], s[28:29], 0, v[128:129]
	s_mov_b32 m0, s45
	s_nop 0
	global_load_lds_dwordx4 v[218:219], off
	s_waitcnt lgkmcnt(8)
	s_barrier
	s_waitcnt lgkmcnt(0)
	v_mfma_f32_16x16x32_bf16 v[124:127], v[138:141], v[154:157], v[124:127]
	v_mfma_f32_16x16x32_bf16 v[120:123], v[146:149], v[154:157], v[120:123]
	v_mfma_f32_16x16x32_bf16 v[116:119], v[138:141], v[178:181], v[116:119]
	v_mfma_f32_16x16x32_bf16 v[108:111], v[146:149], v[178:181], v[108:111]
	v_mfma_f32_16x16x32_bf16 v[100:103], v[138:141], v[186:189], v[100:103]
	v_mfma_f32_16x16x32_bf16 v[92:95], v[146:149], v[186:189], v[92:95]
	v_mfma_f32_16x16x32_bf16 v[84:87], v[138:141], v[194:197], v[84:87]
	v_mfma_f32_16x16x32_bf16 v[76:79], v[146:149], v[194:197], v[76:79]
	v_mfma_f32_16x16x32_bf16 v[124:127], v[142:145], v[174:177], v[124:127]
	v_mfma_f32_16x16x32_bf16 v[120:123], v[150:153], v[174:177], v[120:123]
	v_mfma_f32_16x16x32_bf16 v[116:119], v[142:145], v[182:185], v[116:119]
	v_mfma_f32_16x16x32_bf16 v[108:111], v[150:153], v[182:185], v[108:111]
	v_mfma_f32_16x16x32_bf16 v[100:103], v[142:145], v[190:193], v[100:103]
	v_mfma_f32_16x16x32_bf16 v[92:95], v[150:153], v[190:193], v[92:95]
	v_mfma_f32_16x16x32_bf16 v[84:87], v[142:145], v[214:217], v[84:87]
	v_mfma_f32_16x16x32_bf16 v[76:79], v[150:153], v[214:217], v[76:79]
	s_barrier
	s_add_i32 s28, 0, 0x1c000
	s_add_i32 s29, s56, s41
	v_add_u32_e32 v167, s28, v135
	v_lshl_add_u64 v[158:159], v[158:159], 0, s[2:3]
	s_mov_b32 m0, s29
	ds_read_b128 v[218:221], v167
	ds_read_b128 v[222:225], v167 offset:1024
	ds_read_b128 v[226:229], v167 offset:2048
	ds_read_b128 v[230:233], v167 offset:3072
	global_load_lds_dwordx4 v[158:159], off
	v_lshl_add_u64 v[158:159], v[234:235], 0, s[2:3]
	s_add_i32 m0, s29, 0x2000
	s_nop 0
	global_load_lds_dwordx4 v[158:159], off
	s_barrier
	s_waitcnt lgkmcnt(0)
	v_mfma_f32_16x16x32_bf16 v[112:115], v[218:221], v[154:157], v[112:115]
	v_mfma_f32_16x16x32_bf16 v[104:107], v[226:229], v[154:157], v[104:107]
	v_mfma_f32_16x16x32_bf16 v[96:99], v[218:221], v[178:181], v[96:99]
	v_mfma_f32_16x16x32_bf16 v[88:91], v[226:229], v[178:181], v[88:91]
	v_mfma_f32_16x16x32_bf16 v[80:83], v[218:221], v[186:189], v[80:83]
	v_mfma_f32_16x16x32_bf16 v[72:75], v[226:229], v[186:189], v[72:75]
	v_mfma_f32_16x16x32_bf16 v[68:71], v[218:221], v[194:197], v[68:71]
	v_mfma_f32_16x16x32_bf16 v[64:67], v[226:229], v[194:197], v[64:67]
	v_mfma_f32_16x16x32_bf16 v[112:115], v[222:225], v[174:177], v[112:115]
	v_mfma_f32_16x16x32_bf16 v[104:107], v[230:233], v[174:177], v[104:107]
	v_mfma_f32_16x16x32_bf16 v[96:99], v[222:225], v[182:185], v[96:99]
	v_mfma_f32_16x16x32_bf16 v[88:91], v[230:233], v[182:185], v[88:91]
	v_mfma_f32_16x16x32_bf16 v[80:83], v[222:225], v[190:193], v[80:83]
	v_mfma_f32_16x16x32_bf16 v[72:75], v[230:233], v[190:193], v[72:75]
	v_mfma_f32_16x16x32_bf16 v[68:71], v[222:225], v[214:217], v[68:71]
	v_mfma_f32_16x16x32_bf16 v[64:67], v[230:233], v[214:217], v[64:67]
	s_mov_b32 m0, s46
	v_lshl_add_u64 v[158:159], v[236:237], 0, s[2:3]
	s_barrier
	ds_read_b128 v[154:157], v137 offset:49152
	ds_read_b128 v[174:177], v137 offset:50176
	ds_read_b128 v[178:181], v137 offset:51200
	ds_read_b128 v[182:185], v137 offset:52224
	ds_read_b128 v[186:189], v137 offset:53248
	ds_read_b128 v[190:193], v137 offset:54272
	ds_read_b128 v[194:197], v137 offset:55296
	ds_read_b128 v[214:217], v137 offset:56320
	global_load_lds_dwordx4 v[158:159], off
	v_lshl_add_u64 v[158:159], v[238:239], 0, s[2:3]
	s_mov_b32 m0, s47
	s_nop 0
	global_load_lds_dwordx4 v[158:159], off
	s_barrier
; #define PG8_STAGE(bufoff, gbase, voff) do { _Pragma("unroll") for (int _i = 0; _i < 2; ++_i) \
;         __builtin_amdgcn_global_load_lds((const unsigned*)((const char*)(gbase) + (voff)[_i]), (LAS unsigned*)(lds + (bufoff) + ldsw + _i * 8192), 16, 0, 0); } while (0)
; #define PG8_LDA(dst, b, h) do { _Pragma("unroll") for (int m = 0; m < 4; ++m) _Pragma("unroll") for (int k = 0; k < 2; ++k) dst[m][k] = *(const LAS bf16x8*)(lds + PG8_SA(b, h) + aoff + m * 2048 + k * 1024); } while (0)
; #define PG8_MMA(ai, bj, At, Bt) do { __builtin_amdgcn_s_setprio(1); _Pragma("unroll") for (int m = 0; m < 4; ++m) _Pragma("unroll") for (int n = 0; n < 2; ++n) _Pragma("unroll") for (int k = 0; k < 2; ++k) \
;         acc[ai][bj][m][n] = __builtin_amdgcn_mfma_f32_16x16x32_bf16(Bt[n][k], At[m][k], acc[ai][bj][m][n], 0, 0, 0); __builtin_amdgcn_s_setprio(0); } while (0)
; #define PG8_WAIT_V(n) asm volatile("s_waitcnt vmcnt(" #n ")" ::: "memory")
; #define PG8_WAIT_L(n) asm volatile("s_waitcnt lgkmcnt(" #n ")" ::: "memory")
; #define PG8_BAR __builtin_amdgcn_s_barrier()
; #define PG8_SCHED __builtin_amdgcn_sched_barrier(0)
; template <class Epi>
; DEV void gemm_phase(LAS unsigned char* lds, const Gemm g, const StaticOrder& S, const Epi& E) {
;     ...
;             PG8_LDA(At, 1, 1); PG8_STAGE(PG8_SA(1, 0), a3, voffA);
;             PG8_BAR; PG8_WAIT_L(0); PG8_MMA(1, 0, At, B0); PG8_BAR; PG8_SCHED;
;             PG8_STAGE(PG8_SB(1, 1), b3 + hstep, voffB);
;             PG8_WAIT_V(6); PG8_BAR; PG8_MMA(1, 1, At, B1); PG8_BAR;
	s_waitcnt lgkmcnt(0)
	v_mfma_f32_16x16x32_bf16 v[60:63], v[138:141], v[154:157], v[60:63]
	v_mfma_f32_16x16x32_bf16 v[56:59], v[146:149], v[154:157], v[56:59]
	v_mfma_f32_16x16x32_bf16 v[52:55], v[138:141], v[178:181], v[52:55]
	v_mfma_f32_16x16x32_bf16 v[44:47], v[146:149], v[178:181], v[44:47]
	v_mfma_f32_16x16x32_bf16 v[36:39], v[138:141], v[186:189], v[36:39]
	v_mfma_f32_16x16x32_bf16 v[28:31], v[146:149], v[186:189], v[28:31]
	v_mfma_f32_16x16x32_bf16 v[20:23], v[138:141], v[194:197], v[20:23]
	v_mfma_f32_16x16x32_bf16 v[12:15], v[146:149], v[194:197], v[12:15]
	v_mfma_f32_16x16x32_bf16 v[60:63], v[142:145], v[174:177], v[60:63]
	v_mfma_f32_16x16x32_bf16 v[56:59], v[150:153], v[174:177], v[56:59]
	v_mfma_f32_16x16x32_bf16 v[52:55], v[142:145], v[182:185], v[52:55]
	v_mfma_f32_16x16x32_bf16 v[44:47], v[150:153], v[182:185], v[44:47]
	v_mfma_f32_16x16x32_bf16 v[36:39], v[142:145], v[190:193], v[36:39]
	v_mfma_f32_16x16x32_bf16 v[28:31], v[150:153], v[190:193], v[28:31]
	v_mfma_f32_16x16x32_bf16 v[20:23], v[142:145], v[214:217], v[20:23]
	v_mfma_f32_16x16x32_bf16 v[12:15], v[150:153], v[214:217], v[12:15]
	s_barrier
	s_add_u32 s26, s26, 0x80080
	s_addc_u32 s27, s27, 0
	s_add_i32 s28, s28, s41
	v_lshl_add_u64 v[138:139], s[26:27], 0, v[160:161]
	s_mov_b32 m0, s28
	s_nop 0
	global_load_lds_dwordx4 v[138:139], off
	v_lshl_add_u64 v[138:139], s[26:27], 0, v[128:129]
	s_add_i32 m0, s28, 0x2000
	s_nop 0
	global_load_lds_dwordx4 v[138:139], off
	s_waitcnt vmcnt(6)
	s_barrier
	v_mfma_f32_16x16x32_bf16 v[48:51], v[218:221], v[154:157], v[48:51]
	v_mfma_f32_16x16x32_bf16 v[40:43], v[226:229], v[154:157], v[40:43]
	v_mfma_f32_16x16x32_bf16 v[32:35], v[218:221], v[178:181], v[32:35]
	v_mfma_f32_16x16x32_bf16 v[24:27], v[226:229], v[178:181], v[24:27]
	v_mfma_f32_16x16x32_bf16 v[16:19], v[218:221], v[186:189], v[16:19]
	v_mfma_f32_16x16x32_bf16 v[8:11], v[226:229], v[186:189], v[8:11]
	v_mfma_f32_16x16x32_bf16 v[4:7], v[218:221], v[194:197], v[4:7]
	v_mfma_f32_16x16x32_bf16 v[0:3], v[226:229], v[194:197], v[0:3]
	v_mfma_f32_16x16x32_bf16 v[48:51], v[222:225], v[174:177], v[48:51]
	v_mfma_f32_16x16x32_bf16 v[40:43], v[230:233], v[174:177], v[40:43]
	v_mfma_f32_16x16x32_bf16 v[32:35], v[222:225], v[182:185], v[32:35]
	v_mfma_f32_16x16x32_bf16 v[24:27], v[230:233], v[182:185], v[24:27]
	v_mfma_f32_16x16x32_bf16 v[16:19], v[222:225], v[190:193], v[16:19]
	v_mfma_f32_16x16x32_bf16 v[8:11], v[230:233], v[190:193], v[8:11]
	v_mfma_f32_16x16x32_bf16 v[4:7], v[222:225], v[214:217], v[4:7]
	v_mfma_f32_16x16x32_bf16 v[0:3], v[230:233], v[214:217], v[0:3]
	s_add_i32 s55, s55, 2
	s_add_u32 s24, s24, 0x100
	s_addc_u32 s25, s25, 0
	s_add_u32 s53, s53, 0x100
	s_addc_u32 s54, s54, 0
	s_cmp_gt_u32 s55, 29
	s_barrier
	s_cbranch_scc0 .LBB0_362
; DEV bf16x8 pack8(f32x4 a, f32x4 b) { u32x4 w; w.x = cvt_pk_bf16(a[0], a[1]); w.y = cvt_pk_bf16(a[2], a[3]); w.z = cvt_pk_bf16(b[0], b[1]); w.w = cvt_pk_bf16(b[2], b[3]); return __builtin_bit_cast(bf16x8, w); }
; DEV u32x2 pack4(f32x4 a) { u32x2 w; w.x = cvt_pk_bf16(a[0], a[1]); w.y = cvt_pk_bf16(a[2], a[3]); return w; }
; DEV f32x4 gelu4(f32x4 v) { f32x2 a = gelu_pk((f32x2){v[0], v[1]}), b = gelu_pk((f32x2){v[2], v[3]}); return (f32x4){a.x, a.y, b.x, b.y}; }
; template <int ACT, bool PERM>
; DEV void store_bf16_tile(AccRef acc, u16* O, int ld, int row0, int col0, const float* ss) {
;     ...
;         for (int m = 0; m < 4; ++m) { u16* rowp = O + (size_t)(row0 + ai * 128 + m * 16) * ld + col0; const float rs = rsv[ai][m];
; #pragma unroll
;             for (int bj = 0; bj < 2; ++bj) { f32x4 v0 = acc[ai][bj][m][0] * rs, v1 = acc[ai][bj][m][1] * rs; if (ACT == 1) { v0 = gelu4(v0); v1 = gelu4(v1); }
;                 if (PERM) *(u32x4*)(rowp + bj * 128) = __builtin_bit_cast(u32x4, pack8(v0, v1));
;                 else { *(u32x2*)(rowp + bj * 128) = pack4(v0); *(u32x2*)(rowp + bj * 128 + 16) = pack4(v1); } } }
	v_lshl_add_u32 v138, s12, 8, v134
	v_lshl_or_b32 v140, s50, 8, v136
	v_ashrrev_i32_e32 v141, 31, v140
	v_ashrrev_i32_e32 v139, 31, v138
	v_lshl_add_u64 v[140:141], v[140:141], 1, s[10:11]
	v_lshlrev_b64 v[142:143], 11, v[138:139]
	v_lshl_add_u64 v[142:143], v[140:141], 0, v[142:143]
	v_cvt_pk_bf16_f32 v104, v104, v105
	v_cvt_pk_bf16_f32 v105, v106, v107
	global_store_dwordx2 v[142:143], v[104:105], off offset:288
	v_or_b32_e32 v104, 16, v138
	v_ashrrev_i32_e32 v105, 31, v104
	v_lshlrev_b64 v[104:105], 11, v[104:105]
	v_lshl_add_u64 v[104:105], v[140:141], 0, v[104:105]
	v_cvt_pk_bf16_f32 v88, v88, v89
	v_cvt_pk_bf16_f32 v89, v90, v91
	global_store_dwordx2 v[104:105], v[88:89], off offset:288
	v_or_b32_e32 v88, 32, v138
	v_ashrrev_i32_e32 v89, 31, v88
	v_lshlrev_b64 v[88:89], 11, v[88:89]
	v_lshl_add_u64 v[88:89], v[140:141], 0, v[88:89]
	v_cvt_pk_bf16_f32 v72, v72, v73
	v_cvt_pk_bf16_f32 v73, v74, v75
	global_store_dwordx2 v[88:89], v[72:73], off offset:288
	v_or_b32_e32 v72, 48, v138
	v_ashrrev_i32_e32 v73, 31, v72
	v_lshlrev_b64 v[72:73], 11, v[72:73]
	s_mov_b32 s12, 0x40000
	v_lshl_add_u64 v[72:73], v[140:141], 0, v[72:73]
	v_cvt_pk_bf16_f32 v64, v64, v65
	v_cvt_pk_bf16_f32 v65, v66, v67
	s_mov_b64 s[24:25], 0x40000
	v_cvt_pk_bf16_f32 v60, v60, v61
	v_cvt_pk_bf16_f32 v61, v62, v63
	v_add_co_u32_e32 v62, vcc, s12, v142
	global_store_dwordx2 v[72:73], v[64:65], off offset:288
	v_lshl_add_u64 v[64:65], v[142:143], 0, s[24:25]
	v_addc_co_u32_e32 v63, vcc, 0, v143, vcc
	v_cvt_pk_bf16_f32 v48, v48, v49
	v_cvt_pk_bf16_f32 v49, v50, v51
	s_mov_b32 s12, 0x48000
	global_store_dwordx2 v[64:65], v[48:49], off offset:256
	v_cvt_pk_bf16_f32 v40, v40, v41
	v_cvt_pk_bf16_f32 v41, v42, v43
	s_mov_b64 s[24:25], 0x48000
	v_add_co_u32_e32 v48, vcc, s12, v142
	global_store_dwordx2 v[64:65], v[40:41], off offset:288
	v_lshl_add_u64 v[40:41], v[142:143], 0, s[24:25]
	v_addc_co_u32_e32 v49, vcc, 0, v143, vcc
	v_cvt_pk_bf16_f32 v32, v32, v33
	v_cvt_pk_bf16_f32 v33, v34, v35
	s_mov_b32 s12, 0x50000
	global_store_dwordx2 v[40:41], v[32:33], off offset:256
	v_cvt_pk_bf16_f32 v24, v24, v25
	v_cvt_pk_bf16_f32 v25, v26, v27
	s_mov_b64 s[24:25], 0x50000
	v_add_co_u32_e32 v32, vcc, s12, v142
	global_store_dwordx2 v[40:41], v[24:25], off offset:288
	v_lshl_add_u64 v[24:25], v[142:143], 0, s[24:25]
	v_addc_co_u32_e32 v33, vcc, 0, v143, vcc
	v_cvt_pk_bf16_f32 v16, v16, v17
	v_cvt_pk_bf16_f32 v17, v18, v19
	global_store_dwordx2 v[24:25], v[16:17], off offset:256
	v_add_co_u32_e32 v16, vcc, s59, v142
	v_cvt_pk_bf16_f32 v106, v116, v117
	v_cvt_pk_bf16_f32 v107, v118, v119
	v_cvt_pk_bf16_f32 v90, v100, v101
	v_cvt_pk_bf16_f32 v91, v102, v103
	v_cvt_pk_bf16_f32 v74, v84, v85
	v_cvt_pk_bf16_f32 v75, v86, v87
	v_cvt_pk_bf16_f32 v42, v52, v53
	v_cvt_pk_bf16_f32 v43, v54, v55
	v_cvt_pk_bf16_f32 v26, v36, v37
	v_cvt_pk_bf16_f32 v27, v38, v39
	v_cvt_pk_bf16_f32 v8, v8, v9
	v_cvt_pk_bf16_f32 v9, v10, v11
	s_mov_b64 s[24:25], 0x58000
	v_cvt_pk_bf16_f32 v10, v20, v21
	v_cvt_pk_bf16_f32 v11, v22, v23
	v_addc_co_u32_e32 v17, vcc, 0, v143, vcc
	v_cvt_pk_bf16_f32 v124, v124, v125
	v_cvt_pk_bf16_f32 v125, v126, v127
	v_cvt_pk_bf16_f32 v120, v120, v121
	v_cvt_pk_bf16_f32 v121, v122, v123
	v_cvt_pk_bf16_f32 v112, v112, v113
	v_cvt_pk_bf16_f32 v113, v114, v115
	global_store_dwordx2 v[104:105], v[106:107], off
	v_cvt_pk_bf16_f32 v106, v108, v109
	v_cvt_pk_bf16_f32 v107, v110, v111
	v_cvt_pk_bf16_f32 v96, v96, v97
	v_cvt_pk_bf16_f32 v97, v98, v99
	global_store_dwordx2 v[88:89], v[90:91], off
	v_cvt_pk_bf16_f32 v90, v92, v93
	v_cvt_pk_bf16_f32 v91, v94, v95
	v_cvt_pk_bf16_f32 v80, v80, v81
	v_cvt_pk_bf16_f32 v81, v82, v83
	global_store_dwordx2 v[72:73], v[74:75], off
	v_cvt_pk_bf16_f32 v74, v76, v77
	v_cvt_pk_bf16_f32 v75, v78, v79
	v_cvt_pk_bf16_f32 v68, v68, v69
	v_cvt_pk_bf16_f32 v69, v70, v71
	v_cvt_pk_bf16_f32 v56, v56, v57
	v_cvt_pk_bf16_f32 v57, v58, v59
	global_store_dwordx2 v[48:49], v[42:43], off
	v_cvt_pk_bf16_f32 v42, v44, v45
	v_cvt_pk_bf16_f32 v43, v46, v47
	global_store_dwordx2 v[32:33], v[26:27], off
	v_cvt_pk_bf16_f32 v26, v28, v29
	v_cvt_pk_bf16_f32 v27, v30, v31
	global_store_dwordx2 v[24:25], v[8:9], off offset:288
	v_lshl_add_u64 v[8:9], v[142:143], 0, s[24:25]
	global_store_dwordx2 v[16:17], v[10:11], off
	v_cvt_pk_bf16_f32 v10, v12, v13
	v_cvt_pk_bf16_f32 v11, v14, v15
	v_cvt_pk_bf16_f32 v4, v4, v5
	v_cvt_pk_bf16_f32 v5, v6, v7
	v_cvt_pk_bf16_f32 v0, v0, v1
	v_cvt_pk_bf16_f32 v1, v2, v3
	s_and_b64 vcc, exec, s[14:15]
	s_mov_b32 s50, s16
	s_mov_b32 s12, s18
	s_mov_b64 s[26:27], s[22:23]
	s_mov_b64 s[24:25], s[20:21]
	global_store_dwordx2 v[142:143], v[124:125], off
	global_store_dwordx2 v[142:143], v[120:121], off offset:32
	global_store_dwordx2 v[142:143], v[112:113], off offset:256
	global_store_dwordx2 v[104:105], v[106:107], off offset:32
	global_store_dwordx2 v[104:105], v[96:97], off offset:256
	global_store_dwordx2 v[88:89], v[90:91], off offset:32
	global_store_dwordx2 v[88:89], v[80:81], off offset:256
	global_store_dwordx2 v[72:73], v[74:75], off offset:32
	global_store_dwordx2 v[72:73], v[68:69], off offset:256
	global_store_dwordx2 v[62:63], v[60:61], off
	global_store_dwordx2 v[64:65], v[56:57], off offset:32
	global_store_dwordx2 v[40:41], v[42:43], off offset:32
	global_store_dwordx2 v[24:25], v[26:27], off offset:32
	global_store_dwordx2 v[8:9], v[10:11], off offset:32
	global_store_dwordx2 v[8:9], v[4:5], off offset:256
	global_store_dwordx2 v[8:9], v[0:1], off offset:288
	s_cbranch_vccz .LBB0_359
	s_waitcnt vmcnt(0)
	s_cmpk_gt_u32 s36, 0xff
	s_cbranch_scc1 .LBB0_353
	s_barrier
	s_branch .LBB0_353

; #define LAS __attribute__((address_space(3)))
; #define PG8_STAGE(bufoff, gbase, voff) do { _Pragma("unroll") for (int _i = 0; _i < 2; ++_i) \
;         __builtin_amdgcn_global_load_lds((const unsigned*)((const char*)(gbase) + (voff)[_i]), (LAS unsigned*)(lds + (bufoff) + ldsw + _i * 8192), 16, 0, 0); } while (0)
; #define PG8_WAIT_V(n) asm volatile("s_waitcnt vmcnt(" #n ")" ::: "memory")
; #define PG8_BAR __builtin_amdgcn_s_barrier()
; template <class Epi>
; DEV void gemm_phase(LAS unsigned char* lds, const Gemm g, const StaticOrder& S, const Epi& E) {
;     ...
;     const char* cA = (const char*)g.A + (size_t)cur.pm * tstep; const char* cB = (const char*)g.Bt + (size_t)cur.pn * tstep;
;     PG8_STAGE(PG8_SB(0, 0), cB, voffB); PG8_STAGE(PG8_SA(0, 0), cA, voffA); PG8_STAGE(PG8_SB(0, 1), cB + hstep, voffB); PG8_STAGE(PG8_SA(0, 1), cA + hstep, voffA);
;     if (wr == 1) PG8_BAR;
;     PG8_WAIT_V(4); PG8_BAR;
;     PG8_STAGE(PG8_SB(1, 0), cB + kstep, voffB); PG8_STAGE(PG8_SA(1, 0), cA + kstep, voffA); PG8_STAGE(PG8_SB(1, 1), cB + hstep + kstep, voffB);
;     PG8_WAIT_V(6); PG8_BAR;
; DEV void run_resid_gemm(LAS unsigned char* lds, const u16* A, const u16* Bt, int K, const float* base, float* out, float scale, u16* xb, float* ssout, int bx, int G) {
;     ...
;     EpiResid E{base, out, scale, xb, ssout, (one && ssout) ? red : (LAS float*)nullptr};
;     run_gemm(lds, A, Bt, 8192, 2048, K, E, bx);
.LBB0_392:
	v_readlane_b32 s0, v254, 23
	s_cmpk_eq_i32 s0, 0x100
	s_cselect_b64 s[10:11], -1, 0
	s_cmpk_lg_i32 s0, 0x100
	v_cndmask_b32_e64 v0, 0, 1, s[8:9]
	s_cselect_b64 s[12:13], -1, 0
	v_cmp_ne_u32_e64 s[0:1], 1, v0
	s_andn2_b64 vcc, exec, s[8:9]
	s_cbranch_vccnz .LBB0_450
	s_waitcnt lgkmcnt(0)
	v_ashrrev_i32_e32 v1, 31, v8
	v_lshrrev_b32_e32 v1, 26, v1
	v_add_u32_e32 v1, v8, v1
	v_ashrrev_i32_e32 v9, 6, v1
	v_bfe_i32 v1, v8, 27, 1
	v_lshlrev_b32_e32 v0, 4, v8
	v_lshrrev_b32_e32 v1, 22, v1
	v_add_u32_e32 v1, v0, v1
	v_and_b32_e32 v1, 0xfffffc00, v1
	v_sub_u32_e32 v1, v0, v1
	v_lshrrev_b32_e32 v2, 4, v1
	v_bitop3_b32 v2, v2, v1, 32 bitop3:0x6c
	v_ashrrev_i32_e32 v1, 31, v1
	v_lshrrev_b32_e32 v1, 26, v1
	v_add_u32_e32 v1, v2, v1
	v_ashrrev_i32_e32 v10, 6, v1
	v_lshlrev_b32_e32 v3, 3, v9
	v_mul_i32_i24_e32 v4, 64, v10
	v_and_b32_e32 v3, -16, v3
	v_sub_u32_e32 v2, v2, v4
	v_add_u32_e32 v1, v10, v3
	v_lshlrev_b32_e32 v3, 5, v9
	v_ashrrev_i16_sdwa v2, v203, sext(v2) dst_sel:DWORD dst_unused:UNUSED_PAD src0_sel:DWORD src1_sel:BYTE_0
	v_and_b32_e32 v3, 32, v3
	v_bfe_i32 v11, v2, 0, 16
	v_and_b32_e32 v5, 3, v10
	s_mov_b32 s5, 0x7ffe0
	v_add_lshl_u32 v3, v3, v11, 1
	v_add_u32_e32 v0, 0x2000, v0
	v_lshlrev_b32_e32 v2, 1, v1
	v_lshrrev_b32_e32 v4, 2, v1
	v_and_or_b32 v5, v1, s5, v5
	v_lshl_add_u32 v144, v1, 13, v3
	v_ashrrev_i32_e32 v1, 31, v0
	v_lshrrev_b32_e32 v1, 22, v1
	v_add_u32_e32 v1, v0, v1
	v_ashrrev_i32_e32 v12, 10, v1
	v_mul_i32_i24_e32 v1, 0x400, v12
	v_sub_u32_e32 v0, v0, v1
	v_and_b32_e32 v2, 24, v2
	v_and_b32_e32 v4, 4, v4
	v_lshrrev_b32_e32 v1, 4, v0
	v_or3_b32 v2, v5, v4, v2
	v_bitop3_b32 v0, v1, v0, 32 bitop3:0x6c
	v_lshl_add_u32 v160, v2, 13, v3
	v_ashrrev_i32_e32 v2, 31, v0
	v_lshrrev_b32_e32 v2, 26, v2
	v_lshlrev_b32_e32 v1, 3, v12
	v_add_u32_e32 v2, v0, v2
	v_and_b32_e32 v1, -16, v1
	v_ashrrev_i32_e32 v13, 6, v2
	s_ashr_i32 s4, s35, 6
	v_add_u32_e32 v1, v13, v1
	v_and_b32_e32 v2, 0xc0, v2
	v_and_b32_e32 v4, 3, v13
	s_ashr_i32 s25, s24, 31
	s_ashr_i32 s15, s14, 31
	v_sub_u32_e32 v0, v0, v2
	v_and_or_b32 v4, v1, s5, v4
	s_ashr_i32 s5, s35, 8
	s_lshl_b32 s36, s4, 10
	s_lshl_b64 s[6:7], s[24:25], 21
	s_lshl_b64 s[16:17], s[14:15], 21
	v_readlane_b32 s18, v250, 57
	v_ashrrev_i16_sdwa v0, v203, sext(v0) dst_sel:DWORD dst_unused:UNUSED_PAD src0_sel:DWORD src1_sel:BYTE_0
	v_readlane_b32 s19, v250, 58
	s_add_u32 s28, s18, s16
	v_lshlrev_b32_e32 v3, 5, v12
	v_bfe_i32 v14, v0, 0, 16
	v_lshlrev_b32_e32 v0, 1, v1
	v_lshrrev_b32_e32 v2, 2, v1
	s_addc_u32 s29, s19, s17
	s_add_i32 s37, s36, 0
	v_and_b32_e32 v3, 32, v3
	v_and_b32_e32 v0, 24, v0
	v_and_b32_e32 v2, 4, v2
	s_add_i32 m0, s37, 0x10000
	v_or3_b32 v0, v4, v2, v0
	v_add_lshl_u32 v2, v3, v14, 1
	global_load_lds_dwordx4 v160, s[28:29]
	s_add_i32 m0, s37, 0x12000
	v_readlane_b32 s16, v250, 13
	v_lshl_add_u32 v148, v0, 13, v2
	v_readlane_b32 s17, v250, 14
	s_add_u32 s26, s16, s6
	global_load_lds_dwordx4 v148, s[28:29]
	s_addc_u32 s27, s17, s7
	s_mov_b32 m0, s37
	s_add_i32 s38, s37, 0x2000
	v_lshl_add_u32 v146, v1, 13, v2
	global_load_lds_dwordx4 v144, s[26:27]
	s_mov_b32 m0, s38
	s_add_u32 s6, s28, 0x100000
	global_load_lds_dwordx4 v146, s[26:27]
	s_addc_u32 s7, s29, 0
	s_add_i32 m0, s37, 0x14000
	v_mov_b32_e32 v149, v161
	global_load_lds_dwordx4 v160, s[6:7]
	s_add_i32 m0, s37, 0x16000
	v_mov_b32_e32 v145, v161
	global_load_lds_dwordx4 v148, s[6:7]
	s_add_u32 s6, s26, 0x100000
	s_addc_u32 s7, s27, 0
	s_add_i32 s39, s37, 0x4000
	s_mov_b32 m0, s39
	s_add_i32 s40, s37, 0x6000
	global_load_lds_dwordx4 v144, s[6:7]
	s_mov_b32 m0, s40
	v_mov_b32_e32 v147, v161
	global_load_lds_dwordx4 v146, s[6:7]
	v_lshl_add_u64 v[6:7], s[28:29], 0, v[160:161]
	v_lshl_add_u64 v[4:5], s[28:29], 0, v[148:149]
	v_lshl_add_u64 v[2:3], s[26:27], 0, v[144:145]
	s_cmp_lg_u32 s5, 1
	v_lshl_add_u64 v[0:1], s[26:27], 0, v[146:147]
	s_cbranch_scc1 .LBB0_395
	s_barrier
	s_setprio 1

; #define PG8_STAGE(bufoff, gbase, voff) do { _Pragma("unroll") for (int _i = 0; _i < 2; ++_i) \
;         __builtin_amdgcn_global_load_lds((const unsigned*)((const char*)(gbase) + (voff)[_i]), (LAS unsigned*)(lds + (bufoff) + ldsw + _i * 8192), 16, 0, 0); } while (0)
; #define PG8_LDA(dst, b, h) do { _Pragma("unroll") for (int m = 0; m < 4; ++m) _Pragma("unroll") for (int k = 0; k < 2; ++k) dst[m][k] = *(const LAS bf16x8*)(lds + PG8_SA(b, h) + aoff + m * 2048 + k * 1024); } while (0)
; #define PG8_LDB(dst, b, h) do { _Pragma("unroll") for (int n = 0; n < 2; ++n) _Pragma("unroll") for (int k = 0; k < 2; ++k) dst[n][k] = *(const LAS bf16x8*)(lds + PG8_SB(b, h) + boff + n * 2048 + k * 1024); } while (0)
; #define PG8_MMA(ai, bj, At, Bt) do { __builtin_amdgcn_s_setprio(1); _Pragma("unroll") for (int m = 0; m < 4; ++m) _Pragma("unroll") for (int n = 0; n < 2; ++n) _Pragma("unroll") for (int k = 0; k < 2; ++k) \
;         acc[ai][bj][m][n] = __builtin_amdgcn_mfma_f32_16x16x32_bf16(Bt[n][k], At[m][k], acc[ai][bj][m][n], 0, 0, 0); __builtin_amdgcn_s_setprio(0); } while (0)
; #define PG8_WAIT_L(n) asm volatile("s_waitcnt lgkmcnt(" #n ")" ::: "memory")
; #define PG8_BAR __builtin_amdgcn_s_barrier()
; #define PG8_SCHED __builtin_amdgcn_sched_barrier(0)
; template <class Epi>
; DEV void gemm_phase(LAS unsigned char* lds, const Gemm g, const StaticOrder& S, const Epi& E) {
;     ...
;             PG8_LDB(B0, 0, 0); PG8_SCHED; PG8_LDA(At, 0, 0); PG8_STAGE(PG8_SA(1, 1), a1 + hstep, voffA);
;             PG8_WAIT_L(8); PG8_BAR; PG8_WAIT_L(0); PG8_MMA(0, 0, At, B0); PG8_BAR; PG8_SCHED;
;             PG8_LDB(B1, 0, 1); PG8_STAGE(PG8_SB(0, 0), b2, voffB);
;             PG8_BAR; PG8_WAIT_L(0); PG8_MMA(0, 1, At, B1); PG8_BAR;
;             PG8_LDA(At, 0, 1); PG8_STAGE(PG8_SA(0, 0), a2, voffA);
;             PG8_BAR; PG8_WAIT_L(0); PG8_MMA(1, 0, At, B0); PG8_BAR; PG8_SCHED;
.LBB0_404:
	s_add_u32 s28, s26, 0xfff00080
	s_addc_u32 s29, s27, -1
	s_add_i32 s49, 0, 0x10000
	v_add_u32_e32 v140, s49, v178
	ds_read_b128 v[128:131], v140
	ds_read_b128 v[132:135], v140 offset:1024
	ds_read_b128 v[136:139], v140 offset:2048
	ds_read_b128 v[140:143], v140 offset:3072
	s_cmp_eq_u32 s48, 60
	s_cselect_b32 s31, s15, s29
	s_cselect_b32 s30, s19, s28
	s_cselect_b32 s29, s17, s47
	s_cselect_b32 s28, s25, s46
	v_lshl_add_u64 v[158:159], s[26:27], 0, v[150:151]
	s_add_i32 m0, s37, 0xc000
	ds_read_b128 v[154:157], v181
	ds_read_b128 v[174:177], v181 offset:1024
	ds_read_b128 v[182:185], v181 offset:2048
	ds_read_b128 v[186:189], v181 offset:3072
	ds_read_b128 v[190:193], v181 offset:4096
	ds_read_b128 v[194:197], v181 offset:5120
	ds_read_b128 v[214:217], v181 offset:6144
	ds_read_b128 v[218:221], v181 offset:7168
	global_load_lds_dwordx4 v[158:159], off
	v_lshl_add_u64 v[158:159], s[26:27], 0, v[152:153]
	s_add_i32 m0, s37, 0xe000
	s_nop 0
	global_load_lds_dwordx4 v[158:159], off
	s_waitcnt lgkmcnt(8)
	s_barrier
	s_waitcnt lgkmcnt(0)
	v_mfma_f32_16x16x32_bf16 v[124:127], v[128:131], v[154:157], v[124:127]
	v_mfma_f32_16x16x32_bf16 v[120:123], v[136:139], v[154:157], v[120:123]
	v_mfma_f32_16x16x32_bf16 v[108:111], v[128:131], v[182:185], v[108:111]
	v_mfma_f32_16x16x32_bf16 v[104:107], v[136:139], v[182:185], v[104:107]
	v_mfma_f32_16x16x32_bf16 v[92:95], v[128:131], v[190:193], v[92:95]
	v_mfma_f32_16x16x32_bf16 v[88:91], v[136:139], v[190:193], v[88:91]
	v_mfma_f32_16x16x32_bf16 v[76:79], v[128:131], v[214:217], v[76:79]
	v_mfma_f32_16x16x32_bf16 v[72:75], v[136:139], v[214:217], v[72:75]
	v_mfma_f32_16x16x32_bf16 v[124:127], v[132:135], v[174:177], v[124:127]
	v_mfma_f32_16x16x32_bf16 v[120:123], v[140:143], v[174:177], v[120:123]
	v_mfma_f32_16x16x32_bf16 v[108:111], v[132:135], v[186:189], v[108:111]
	v_mfma_f32_16x16x32_bf16 v[104:107], v[140:143], v[186:189], v[104:107]
	v_mfma_f32_16x16x32_bf16 v[92:95], v[132:135], v[194:197], v[92:95]
	v_mfma_f32_16x16x32_bf16 v[88:91], v[140:143], v[194:197], v[88:91]
	v_mfma_f32_16x16x32_bf16 v[76:79], v[132:135], v[218:221], v[76:79]
	v_mfma_f32_16x16x32_bf16 v[72:75], v[140:143], v[218:221], v[72:75]
	s_barrier
	s_add_i32 s52, 0, 0x14000
	v_add_u32_e32 v158, s52, v178
	s_add_i32 s49, s49, s36
	ds_read_b128 v[222:225], v158
	ds_read_b128 v[226:229], v158 offset:1024
	ds_read_b128 v[230:233], v158 offset:2048
	ds_read_b128 v[234:237], v158 offset:3072
	v_lshl_add_u64 v[158:159], s[28:29], 0, v[160:161]
	s_mov_b32 m0, s49
	v_lshl_add_u64 v[238:239], s[28:29], 0, v[148:149]
	global_load_lds_dwordx4 v[158:159], off
	s_add_i32 m0, s49, 0x2000
	s_nop 0
	global_load_lds_dwordx4 v[238:239], off
	s_barrier
	s_waitcnt lgkmcnt(0)
	v_mfma_f32_16x16x32_bf16 v[116:119], v[222:225], v[154:157], v[116:119]
	v_mfma_f32_16x16x32_bf16 v[112:115], v[230:233], v[154:157], v[112:115]
	v_mfma_f32_16x16x32_bf16 v[100:103], v[222:225], v[182:185], v[100:103]
	v_mfma_f32_16x16x32_bf16 v[96:99], v[230:233], v[182:185], v[96:99]
	v_mfma_f32_16x16x32_bf16 v[84:87], v[222:225], v[190:193], v[84:87]
	v_mfma_f32_16x16x32_bf16 v[80:83], v[230:233], v[190:193], v[80:83]
	v_mfma_f32_16x16x32_bf16 v[68:71], v[222:225], v[214:217], v[68:71]
	v_mfma_f32_16x16x32_bf16 v[64:67], v[230:233], v[214:217], v[64:67]
	v_mfma_f32_16x16x32_bf16 v[116:119], v[226:229], v[174:177], v[116:119]
	v_mfma_f32_16x16x32_bf16 v[112:115], v[234:237], v[174:177], v[112:115]
	v_mfma_f32_16x16x32_bf16 v[100:103], v[226:229], v[186:189], v[100:103]
	v_mfma_f32_16x16x32_bf16 v[96:99], v[234:237], v[186:189], v[96:99]
	v_mfma_f32_16x16x32_bf16 v[84:87], v[226:229], v[194:197], v[84:87]
	v_mfma_f32_16x16x32_bf16 v[80:83], v[234:237], v[194:197], v[80:83]
	v_mfma_f32_16x16x32_bf16 v[68:71], v[226:229], v[218:221], v[68:71]
	v_mfma_f32_16x16x32_bf16 v[64:67], v[234:237], v[218:221], v[64:67]
	s_mov_b32 m0, s37
	v_lshl_add_u64 v[240:241], s[30:31], 0, v[144:145]
	s_barrier
	ds_read_b128 v[154:157], v181 offset:16384
	ds_read_b128 v[174:177], v181 offset:17408
	ds_read_b128 v[182:185], v181 offset:18432
	ds_read_b128 v[186:189], v181 offset:19456
	ds_read_b128 v[190:193], v181 offset:20480
	ds_read_b128 v[194:197], v181 offset:21504
	ds_read_b128 v[214:217], v181 offset:22528
	ds_read_b128 v[218:221], v181 offset:23552
	global_load_lds_dwordx4 v[240:241], off
	v_lshl_add_u64 v[242:243], s[30:31], 0, v[146:147]
	s_mov_b32 m0, s38
	s_nop 0
	global_load_lds_dwordx4 v[242:243], off
	s_barrier
	s_waitcnt lgkmcnt(0)
	v_mfma_f32_16x16x32_bf16 v[60:63], v[128:131], v[154:157], v[60:63]
	v_mfma_f32_16x16x32_bf16 v[56:59], v[136:139], v[154:157], v[56:59]
	v_mfma_f32_16x16x32_bf16 v[44:47], v[128:131], v[182:185], v[44:47]
	v_mfma_f32_16x16x32_bf16 v[40:43], v[136:139], v[182:185], v[40:43]
	v_mfma_f32_16x16x32_bf16 v[28:31], v[128:131], v[190:193], v[28:31]
	v_mfma_f32_16x16x32_bf16 v[24:27], v[136:139], v[190:193], v[24:27]
	v_mfma_f32_16x16x32_bf16 v[12:15], v[128:131], v[214:217], v[12:15]
	v_mfma_f32_16x16x32_bf16 v[8:11], v[136:139], v[214:217], v[8:11]
	v_mfma_f32_16x16x32_bf16 v[60:63], v[132:135], v[174:177], v[60:63]
	v_mfma_f32_16x16x32_bf16 v[56:59], v[140:143], v[174:177], v[56:59]
	v_mfma_f32_16x16x32_bf16 v[44:47], v[132:135], v[186:189], v[44:47]
	v_mfma_f32_16x16x32_bf16 v[40:43], v[140:143], v[186:189], v[40:43]
	v_mfma_f32_16x16x32_bf16 v[28:31], v[132:135], v[194:197], v[28:31]
	v_mfma_f32_16x16x32_bf16 v[24:27], v[140:143], v[194:197], v[24:27]
	v_mfma_f32_16x16x32_bf16 v[12:15], v[132:135], v[218:221], v[12:15]
	v_mfma_f32_16x16x32_bf16 v[8:11], v[140:143], v[218:221], v[8:11]
	s_barrier
; #define PG8_STAGE(bufoff, gbase, voff) do { _Pragma("unroll") for (int _i = 0; _i < 2; ++_i) \
;         __builtin_amdgcn_global_load_lds((const unsigned*)((const char*)(gbase) + (voff)[_i]), (LAS unsigned*)(lds + (bufoff) + ldsw + _i * 8192), 16, 0, 0); } while (0)
; #define PG8_LDA(dst, b, h) do { _Pragma("unroll") for (int m = 0; m < 4; ++m) _Pragma("unroll") for (int k = 0; k < 2; ++k) dst[m][k] = *(const LAS bf16x8*)(lds + PG8_SA(b, h) + aoff + m * 2048 + k * 1024); } while (0)
; #define PG8_LDB(dst, b, h) do { _Pragma("unroll") for (int n = 0; n < 2; ++n) _Pragma("unroll") for (int k = 0; k < 2; ++k) dst[n][k] = *(const LAS bf16x8*)(lds + PG8_SB(b, h) + boff + n * 2048 + k * 1024); } while (0)
; #define PG8_MMA(ai, bj, At, Bt) do { __builtin_amdgcn_s_setprio(1); _Pragma("unroll") for (int m = 0; m < 4; ++m) _Pragma("unroll") for (int n = 0; n < 2; ++n) _Pragma("unroll") for (int k = 0; k < 2; ++k) \
;         acc[ai][bj][m][n] = __builtin_amdgcn_mfma_f32_16x16x32_bf16(Bt[n][k], At[m][k], acc[ai][bj][m][n], 0, 0, 0); __builtin_amdgcn_s_setprio(0); } while (0)
; #define PG8_WAIT_V(n) asm volatile("s_waitcnt vmcnt(" #n ")" ::: "memory")
; #define PG8_WAIT_L(n) asm volatile("s_waitcnt lgkmcnt(" #n ")" ::: "memory")
; #define PG8_BAR __builtin_amdgcn_s_barrier()
; #define PG8_SCHED __builtin_amdgcn_sched_barrier(0)
; template <class Epi>
; DEV void gemm_phase(LAS unsigned char* lds, const Gemm g, const StaticOrder& S, const Epi& E) {
;     ...
;             PG8_STAGE(PG8_SB(0, 1), b2 + hstep, voffB);
;             PG8_WAIT_V(6); PG8_BAR; PG8_MMA(1, 1, At, B1); PG8_BAR;
;             PG8_LDB(B0, 1, 0); PG8_SCHED; PG8_LDA(At, 1, 0); PG8_STAGE(PG8_SA(0, 1), a2 + hstep, voffA);
;             PG8_WAIT_L(8); PG8_BAR; PG8_WAIT_L(0); PG8_MMA(0, 0, At, B0); PG8_BAR; PG8_SCHED;
;             PG8_LDB(B1, 1, 1); PG8_STAGE(PG8_SB(1, 0), b3, voffB);
;             PG8_BAR; PG8_WAIT_L(0); PG8_MMA(0, 1, At, B1); PG8_BAR;
	s_add_u32 s50, s28, 0x100000
	s_addc_u32 s51, s29, 0
	s_add_i32 s49, s52, s36
	v_lshl_add_u64 v[128:129], s[50:51], 0, v[160:161]
	s_mov_b32 m0, s49
	s_nop 0
	global_load_lds_dwordx4 v[128:129], off
	v_lshl_add_u64 v[128:129], s[50:51], 0, v[148:149]
	s_add_i32 m0, s49, 0x2000
	s_nop 0
	global_load_lds_dwordx4 v[128:129], off
	s_waitcnt vmcnt(6)
	s_barrier
	v_mfma_f32_16x16x32_bf16 v[52:55], v[222:225], v[154:157], v[52:55]
	v_mfma_f32_16x16x32_bf16 v[48:51], v[230:233], v[154:157], v[48:51]
	v_mfma_f32_16x16x32_bf16 v[36:39], v[222:225], v[182:185], v[36:39]
	v_mfma_f32_16x16x32_bf16 v[32:35], v[230:233], v[182:185], v[32:35]
	v_mfma_f32_16x16x32_bf16 v[20:23], v[222:225], v[190:193], v[20:23]
	v_mfma_f32_16x16x32_bf16 v[16:19], v[230:233], v[190:193], v[16:19]
	v_mfma_f32_16x16x32_bf16 v[4:7], v[222:225], v[214:217], v[4:7]
	v_mfma_f32_16x16x32_bf16 v[0:3], v[230:233], v[214:217], v[0:3]
	v_mfma_f32_16x16x32_bf16 v[52:55], v[226:229], v[174:177], v[52:55]
	v_mfma_f32_16x16x32_bf16 v[48:51], v[234:237], v[174:177], v[48:51]
	v_mfma_f32_16x16x32_bf16 v[36:39], v[226:229], v[186:189], v[36:39]
	v_mfma_f32_16x16x32_bf16 v[32:35], v[234:237], v[186:189], v[32:35]
	v_mfma_f32_16x16x32_bf16 v[20:23], v[226:229], v[194:197], v[20:23]
	v_mfma_f32_16x16x32_bf16 v[16:19], v[234:237], v[194:197], v[16:19]
	v_mfma_f32_16x16x32_bf16 v[4:7], v[226:229], v[218:221], v[4:7]
	v_mfma_f32_16x16x32_bf16 v[0:3], v[234:237], v[218:221], v[0:3]
	s_add_i32 s49, 0, 0x18000
	v_add_u32_e32 v140, s49, v178
	s_barrier
	ds_read_b128 v[128:131], v140
	ds_read_b128 v[132:135], v140 offset:1024
	ds_read_b128 v[136:139], v140 offset:2048
	ds_read_b128 v[140:143], v140 offset:3072
	s_add_u32 s30, s30, 0x100000
	s_addc_u32 s31, s31, 0
	s_mov_b32 m0, s39
	v_lshl_add_u64 v[222:223], s[30:31], 0, v[144:145]
	ds_read_b128 v[154:157], v181 offset:32768
	ds_read_b128 v[174:177], v181 offset:33792
	ds_read_b128 v[182:185], v181 offset:34816
	ds_read_b128 v[186:189], v181 offset:35840
	ds_read_b128 v[190:193], v181 offset:36864
	ds_read_b128 v[194:197], v181 offset:37888
	ds_read_b128 v[214:217], v181 offset:38912
	ds_read_b128 v[218:221], v181 offset:39936
	global_load_lds_dwordx4 v[222:223], off
	v_lshl_add_u64 v[222:223], s[30:31], 0, v[146:147]
	s_mov_b32 m0, s40
	s_nop 0
	global_load_lds_dwordx4 v[222:223], off
	s_waitcnt lgkmcnt(8)
	s_barrier
	s_waitcnt lgkmcnt(0)
	v_mfma_f32_16x16x32_bf16 v[124:127], v[128:131], v[154:157], v[124:127]
	v_mfma_f32_16x16x32_bf16 v[120:123], v[136:139], v[154:157], v[120:123]
	v_mfma_f32_16x16x32_bf16 v[108:111], v[128:131], v[182:185], v[108:111]
	v_mfma_f32_16x16x32_bf16 v[104:107], v[136:139], v[182:185], v[104:107]
	v_mfma_f32_16x16x32_bf16 v[92:95], v[128:131], v[190:193], v[92:95]
	v_mfma_f32_16x16x32_bf16 v[88:91], v[136:139], v[190:193], v[88:91]
	v_mfma_f32_16x16x32_bf16 v[76:79], v[128:131], v[214:217], v[76:79]
	v_mfma_f32_16x16x32_bf16 v[72:75], v[136:139], v[214:217], v[72:75]
	v_mfma_f32_16x16x32_bf16 v[124:127], v[132:135], v[174:177], v[124:127]
	v_mfma_f32_16x16x32_bf16 v[120:123], v[140:143], v[174:177], v[120:123]
	v_mfma_f32_16x16x32_bf16 v[108:111], v[132:135], v[186:189], v[108:111]
	v_mfma_f32_16x16x32_bf16 v[104:107], v[140:143], v[186:189], v[104:107]
	v_mfma_f32_16x16x32_bf16 v[92:95], v[132:135], v[194:197], v[92:95]
	v_mfma_f32_16x16x32_bf16 v[88:91], v[140:143], v[194:197], v[88:91]
	v_mfma_f32_16x16x32_bf16 v[76:79], v[132:135], v[218:221], v[76:79]
	v_mfma_f32_16x16x32_bf16 v[72:75], v[140:143], v[218:221], v[72:75]
	s_barrier
	s_add_i32 s30, 0, 0x1c000
	s_add_i32 s31, s49, s36
	v_add_u32_e32 v234, s30, v178
	v_lshl_add_u64 v[158:159], v[158:159], 0, s[2:3]
	s_mov_b32 m0, s31
	ds_read_b128 v[222:225], v234
	ds_read_b128 v[226:229], v234 offset:1024
	ds_read_b128 v[230:233], v234 offset:2048
	ds_read_b128 v[234:237], v234 offset:3072
	global_load_lds_dwordx4 v[158:159], off
	v_lshl_add_u64 v[158:159], v[238:239], 0, s[2:3]
	s_add_i32 m0, s31, 0x2000
	s_nop 0
	global_load_lds_dwordx4 v[158:159], off
	s_barrier
	s_waitcnt lgkmcnt(0)
	v_mfma_f32_16x16x32_bf16 v[116:119], v[222:225], v[154:157], v[116:119]
	v_mfma_f32_16x16x32_bf16 v[112:115], v[230:233], v[154:157], v[112:115]
	v_mfma_f32_16x16x32_bf16 v[100:103], v[222:225], v[182:185], v[100:103]
	v_mfma_f32_16x16x32_bf16 v[96:99], v[230:233], v[182:185], v[96:99]
	v_mfma_f32_16x16x32_bf16 v[84:87], v[222:225], v[190:193], v[84:87]
	v_mfma_f32_16x16x32_bf16 v[80:83], v[230:233], v[190:193], v[80:83]
	v_mfma_f32_16x16x32_bf16 v[68:71], v[222:225], v[214:217], v[68:71]
	v_mfma_f32_16x16x32_bf16 v[64:67], v[230:233], v[214:217], v[64:67]
	v_mfma_f32_16x16x32_bf16 v[116:119], v[226:229], v[174:177], v[116:119]
	v_mfma_f32_16x16x32_bf16 v[112:115], v[234:237], v[174:177], v[112:115]
	v_mfma_f32_16x16x32_bf16 v[100:103], v[226:229], v[186:189], v[100:103]
	v_mfma_f32_16x16x32_bf16 v[96:99], v[234:237], v[186:189], v[96:99]
	v_mfma_f32_16x16x32_bf16 v[84:87], v[226:229], v[194:197], v[84:87]
	v_mfma_f32_16x16x32_bf16 v[80:83], v[234:237], v[194:197], v[80:83]
	v_mfma_f32_16x16x32_bf16 v[68:71], v[226:229], v[218:221], v[68:71]
	v_mfma_f32_16x16x32_bf16 v[64:67], v[234:237], v[218:221], v[64:67]
	s_mov_b32 m0, s41
	v_lshl_add_u64 v[158:159], v[240:241], 0, s[2:3]
	s_barrier
	ds_read_b128 v[154:157], v181 offset:49152
	ds_read_b128 v[174:177], v181 offset:50176
	ds_read_b128 v[182:185], v181 offset:51200
	ds_read_b128 v[186:189], v181 offset:52224
	ds_read_b128 v[190:193], v181 offset:53248
	ds_read_b128 v[194:197], v181 offset:54272
	ds_read_b128 v[214:217], v181 offset:55296
	ds_read_b128 v[218:221], v181 offset:56320
	global_load_lds_dwordx4 v[158:159], off
	v_lshl_add_u64 v[158:159], v[242:243], 0, s[2:3]
	s_mov_b32 m0, s42
	s_nop 0
	global_load_lds_dwordx4 v[158:159], off
	s_barrier
; DEV bf16x8 pack8(f32x4 a, f32x4 b) { u32x4 w; w.x = cvt_pk_bf16(a[0], a[1]); w.y = cvt_pk_bf16(a[2], a[3]); w.z = cvt_pk_bf16(b[0], b[1]); w.w = cvt_pk_bf16(b[2], b[3]); return __builtin_bit_cast(bf16x8, w); }
; #define PG8_WAIT_V(n) asm volatile("s_waitcnt vmcnt(" #n ")" ::: "memory")
; #define PG8_WAIT_L(n) asm volatile("s_waitcnt lgkmcnt(" #n ")" ::: "memory")
; template <class Epi>
; DEV void gemm_phase(LAS unsigned char* lds, const Gemm g, const StaticOrder& S, const Epi& E) {
;     ...
;             PG8_LDA(At, 1, 1); PG8_STAGE(PG8_SA(1, 0), a3, voffA);
;             PG8_BAR; PG8_WAIT_L(0); PG8_MMA(1, 0, At, B0); PG8_BAR; PG8_SCHED;
;             PG8_STAGE(PG8_SB(1, 1), b3 + hstep, voffB);
;             PG8_WAIT_V(6); PG8_BAR; PG8_MMA(1, 1, At, B1); PG8_BAR;
;     DEV void operator()(AccRef acc, const pg8::Unit& u, int wr, int wc, int fr, int fq) const {
;         const int row0 = u.pm * 256 + wr * 64 + fr, col0 = u.pn * 256 + wc * 32 + 8 * fq;
; #pragma unroll
;         for (int am = 0; am < 4; ++am) { const int ai = am >> 1, m0 = (am & 1) * 2;
;             f32x4 bv[4][2][2];
; #pragma unroll
;             for (int m = m0; m < m0 + 2; ++m)
; #pragma unroll
;                 for (int bj = 0; bj < 2; ++bj)
; #pragma unroll
;                     for (int n = 0; n < 2; ++n) bv[m][bj][n] = *(const f32x4*)(base + (size_t)(row0 + ai * 128 + m * 16) * 2048 + col0 + bj * 128 + n * 4);
; #pragma unroll
;             for (int m = m0; m < m0 + 2; ++m) { const size_t off = (size_t)(row0 + ai * 128 + m * 16) * 2048 + col0; float sq = 0.f;
; #pragma unroll
;                 for (int bj = 0; bj < 2; ++bj) { const f32x4 o0 = bv[m][bj][0] + scale * acc[ai][bj][m][0], o1 = bv[m][bj][1] + scale * acc[ai][bj][m][1];
;                     *(f32x4*)(out + off + bj * 128) = o0; *(f32x4*)(out + off + bj * 128 + 4) = o1;
;                     if (xb) { *(u32x4*)(xb + off + bj * 128) = __builtin_bit_cast(u32x4, pack8(o0, o1));
;                         sq += (o0[0] * o0[0] + o0[1] * o0[1] + o0[2] * o0[2] + o0[3] * o0[3]) + (o1[0] * o1[0] + o1[1] * o1[1] + o1[2] * o1[2] + o1[3] * o1[3]); } }
;                 if (ssout) { sq += __shfl_xor(sq, 16); sq += __shfl_xor(sq, 32);
;                     if (fq == 0) { if (red) red[(ai * 128 + wr * 64 + m * 16 + fr) * 4 + wc] = sq; else atomicAdd(ssout + (size_t)(row0 + ai * 128 + m * 16) * 8 + u.pn, sq); } } }
	s_waitcnt lgkmcnt(0)
	v_mfma_f32_16x16x32_bf16 v[60:63], v[128:131], v[154:157], v[60:63]
	v_mfma_f32_16x16x32_bf16 v[56:59], v[136:139], v[154:157], v[56:59]
	v_mfma_f32_16x16x32_bf16 v[44:47], v[128:131], v[182:185], v[44:47]
	v_mfma_f32_16x16x32_bf16 v[40:43], v[136:139], v[182:185], v[40:43]
	v_mfma_f32_16x16x32_bf16 v[28:31], v[128:131], v[190:193], v[28:31]
	v_mfma_f32_16x16x32_bf16 v[24:27], v[136:139], v[190:193], v[24:27]
	v_mfma_f32_16x16x32_bf16 v[12:15], v[128:131], v[214:217], v[12:15]
	v_mfma_f32_16x16x32_bf16 v[8:11], v[136:139], v[214:217], v[8:11]
	v_mfma_f32_16x16x32_bf16 v[60:63], v[132:135], v[174:177], v[60:63]
	v_mfma_f32_16x16x32_bf16 v[56:59], v[140:143], v[174:177], v[56:59]
	v_mfma_f32_16x16x32_bf16 v[44:47], v[132:135], v[186:189], v[44:47]
	v_mfma_f32_16x16x32_bf16 v[40:43], v[140:143], v[186:189], v[40:43]
	v_mfma_f32_16x16x32_bf16 v[28:31], v[132:135], v[194:197], v[28:31]
	v_mfma_f32_16x16x32_bf16 v[24:27], v[140:143], v[194:197], v[24:27]
	v_mfma_f32_16x16x32_bf16 v[12:15], v[132:135], v[218:221], v[12:15]
	v_mfma_f32_16x16x32_bf16 v[8:11], v[140:143], v[218:221], v[8:11]
	s_barrier
	s_add_u32 s28, s28, 0x100080
	s_addc_u32 s29, s29, 0
	s_add_i32 s30, s30, s36
	v_lshl_add_u64 v[128:129], s[28:29], 0, v[160:161]
	s_mov_b32 m0, s30
	s_nop 0
	global_load_lds_dwordx4 v[128:129], off
	v_lshl_add_u64 v[128:129], s[28:29], 0, v[148:149]
	s_add_i32 m0, s30, 0x2000
	s_nop 0
	global_load_lds_dwordx4 v[128:129], off
	s_waitcnt vmcnt(6)
	s_barrier
	v_mfma_f32_16x16x32_bf16 v[52:55], v[222:225], v[154:157], v[52:55]
	v_mfma_f32_16x16x32_bf16 v[48:51], v[230:233], v[154:157], v[48:51]
	v_mfma_f32_16x16x32_bf16 v[36:39], v[222:225], v[182:185], v[36:39]
	v_mfma_f32_16x16x32_bf16 v[32:35], v[230:233], v[182:185], v[32:35]
	v_mfma_f32_16x16x32_bf16 v[20:23], v[222:225], v[190:193], v[20:23]
	v_mfma_f32_16x16x32_bf16 v[16:19], v[230:233], v[190:193], v[16:19]
	v_mfma_f32_16x16x32_bf16 v[4:7], v[222:225], v[214:217], v[4:7]
	v_mfma_f32_16x16x32_bf16 v[0:3], v[230:233], v[214:217], v[0:3]
	v_mfma_f32_16x16x32_bf16 v[52:55], v[226:229], v[174:177], v[52:55]
	v_mfma_f32_16x16x32_bf16 v[48:51], v[234:237], v[174:177], v[48:51]
	v_mfma_f32_16x16x32_bf16 v[36:39], v[226:229], v[186:189], v[36:39]
	v_mfma_f32_16x16x32_bf16 v[32:35], v[234:237], v[186:189], v[32:35]
	v_mfma_f32_16x16x32_bf16 v[20:23], v[226:229], v[194:197], v[20:23]
	v_mfma_f32_16x16x32_bf16 v[16:19], v[234:237], v[194:197], v[16:19]
	v_mfma_f32_16x16x32_bf16 v[4:7], v[226:229], v[218:221], v[4:7]
	v_mfma_f32_16x16x32_bf16 v[0:3], v[234:237], v[218:221], v[0:3]
	s_add_i32 s48, s48, 2
	s_add_u32 s26, s26, 0x100
	s_addc_u32 s27, s27, 0
	s_add_u32 s46, s46, 0x100
	s_addc_u32 s47, s47, 0
	s_cmp_gt_u32 s48, 61
	s_barrier
	s_cbranch_scc0 .LBB0_404
	v_lshl_add_u32 v156, s24, 8, v167
	v_lshl_or_b32 v154, s14, 8, v179
	v_readlane_b32 s24, v254, 16
	v_ashrrev_i32_e32 v155, 31, v154
	v_readlane_b32 s25, v254, 17
	v_ashrrev_i32_e32 v157, 31, v156
	v_lshlrev_b64 v[128:129], 13, v[156:157]
	v_lshl_add_u64 v[158:159], v[154:155], 2, s[24:25]
	v_lshl_add_u64 v[214:215], v[158:159], 0, v[128:129]
	global_load_dwordx4 v[182:185], v[214:215], off offset:16
	global_load_dwordx4 v[186:189], v[214:215], off
	global_load_dwordx4 v[190:193], v[214:215], off offset:528
	global_load_dwordx4 v[194:197], v[214:215], off offset:512
	v_or_b32_e32 v174, 16, v156
	v_ashrrev_i32_e32 v175, 31, v174
	v_lshlrev_b64 v[128:129], 13, v[174:175]
	v_lshl_add_u64 v[176:177], v[158:159], 0, v[128:129]
	global_load_dwordx4 v[136:139], v[176:177], off offset:16
	global_load_dwordx4 v[140:143], v[176:177], off
	global_load_dwordx4 v[128:131], v[176:177], off offset:528
	global_load_dwordx4 v[132:135], v[176:177], off offset:512
	v_lshlrev_b64 v[216:217], 11, v[156:157]
	v_readlane_b32 s24, v250, 9
	v_lshl_add_u64 v[216:217], v[216:217], 0, v[154:155]
	v_readlane_b32 s25, v250, 10
	v_cmp_lt_i32_e32 vcc, v208, v206
	s_ashr_i32 s15, s14, 31
	s_waitcnt vmcnt(0)
	v_pk_add_f32 v[120:121], v[120:121], v[182:183]
	v_pk_add_f32 v[126:127], v[126:127], v[188:189]
	v_pk_add_f32 v[124:125], v[124:125], v[186:187]
	v_pk_add_f32 v[122:123], v[122:123], v[184:185]
	global_store_dwordx4 v[214:215], v[124:127], off
	global_store_dwordx4 v[214:215], v[120:123], off offset:16
	v_cvt_pk_bf16_f32 v184, v120, v121
	v_cvt_pk_bf16_f32 v182, v124, v125
	v_mul_f32_e32 v121, v121, v121
	v_cvt_pk_bf16_f32 v183, v126, v127
	v_cvt_pk_bf16_f32 v185, v122, v123
	v_lshl_add_u64 v[186:187], v[216:217], 1, s[24:25]
	v_fmac_f32_e32 v121, v120, v120
	v_pk_add_f32 v[118:119], v[118:119], v[196:197]
	v_pk_add_f32 v[116:117], v[116:117], v[194:195]
	v_pk_add_f32 v[112:113], v[112:113], v[190:191]
	global_store_dwordx4 v[186:187], v[182:185], off
	v_mul_f32_e32 v125, v125, v125
	v_fmac_f32_e32 v121, v122, v122
	v_pk_add_f32 v[114:115], v[114:115], v[192:193]
	global_store_dwordx4 v[214:215], v[116:119], off offset:512
	global_store_dwordx4 v[214:215], v[112:115], off offset:528
	v_cvt_pk_bf16_f32 v120, v116, v117
	v_cvt_pk_bf16_f32 v122, v112, v113
	v_mul_f32_e32 v117, v117, v117
	v_mul_f32_e32 v113, v113, v113
	v_fmac_f32_e32 v125, v124, v124
	v_fmac_f32_e32 v117, v116, v116
	v_fmac_f32_e32 v113, v112, v112
	v_fmac_f32_e32 v125, v126, v126
	v_fmac_f32_e32 v117, v118, v118
	v_fmac_f32_e32 v113, v114, v114
	v_fmac_f32_e32 v125, v127, v127
	v_fmac_f32_e32 v121, v123, v123
	v_fmac_f32_e32 v117, v119, v119
	v_fmac_f32_e32 v113, v115, v115
	v_add_f32_e32 v124, v125, v121
	v_add_f32_e32 v112, v117, v113
	v_cndmask_b32_e32 v113, v204, v208, vcc
	v_cvt_pk_bf16_f32 v121, v118, v119
	v_add_f32_e32 v112, v124, v112
	v_lshlrev_b32_e32 v118, 2, v113
	ds_bpermute_b32 v113, v118, v112
	v_cmp_lt_i32_e32 vcc, v207, v206
	v_cvt_pk_bf16_f32 v123, v114, v115
	global_store_dwordx4 v[186:187], v[120:123], off offset:256
	s_waitcnt lgkmcnt(0)
	v_add_f32_e32 v112, v112, v113
	v_cndmask_b32_e32 v113, v204, v207, vcc
	v_lshlrev_b32_e32 v119, 2, v113
	ds_bpermute_b32 v113, v119, v112
	s_and_saveexec_b64 s[24:25], s[6:7]
	s_cbranch_execz .LBB0_410
	s_waitcnt lgkmcnt(0)
	v_add_f32_e32 v112, v112, v113
	s_mov_b64 s[26:27], -1
	s_and_b64 vcc, exec, s[12:13]
	s_cbranch_vccz .LBB0_408
	v_readlane_b32 s26, v250, 59
	v_lshlrev_b64 v[114:115], 5, v[156:157]
	v_readlane_b32 s27, v250, 60
	s_nop 1
	v_lshl_add_u64 v[114:115], s[26:27], 0, v[114:115]
	v_lshl_add_u64 v[114:115], s[14:15], 2, v[114:115]
	global_atomic_add_f32 v[114:115], v112, off
	s_mov_b64 s[26:27], 0

; DEV int otid() { int t = (int)threadIdx.x; asm volatile("" : "+v"(t)); return t; }
;     DEV bool next(int i, Unit& u) const {
;         const long L = (long)i * G + c; if (L >= nwg) return false;
;         int wgid = (int)L; { const int q = nwg / NXCD, r = nwg % NXCD, xcd = wgid % NXCD, off = wgid / NXCD; wgid = (xcd < r ? xcd * (q + 1) : r * (q + 1) + (xcd - r) * q) + off; }
;         const int nig = WGM * nN, gid = wgid / nig, fm = gid * WGM, gsz = (nM - fm) < WGM ? (nM - fm) : WGM;
;         u.pm = fm + ((wgid % nig) % gsz); u.pn = (wgid % nig) / gsz; return true;
; template <class Epi>
; DEV void gemm_phase(LAS unsigned char* lds, const Gemm g, const StaticOrder& S, const Epi& E) {
;     const int tid = otid(), wid = __builtin_amdgcn_readfirstlane(tid >> 6), lane = tid & 63, wr = wid >> 2, wc = wid & 3, fr = lane & 15, fq = lane >> 4;
;     const int K = g.K, nt = K / BK;
;     unsigned voffA[2], voffB[2];
; #pragma unroll
;     for (int i = 0; i < 2; ++i) { int R, C; stage_rc(tid * 16 + i * 8192, R, C); const int Rb = Epi::PERM ? ((R & ~31) + perm32(R & 31)) : R;
;         voffA[i] = (unsigned)(R * K + C) * 2u; voffB[i] = (unsigned)(Rb * K + C) * 2u; }
;     const size_t kstep = (size_t)(BK * 2);
;     const size_t hstep = (size_t)HALF * K * 2;
;     const size_t tstep = 2 * hstep;
;     const unsigned ldsw = (unsigned)wid * 1024u;
;     const int aoff = lds_byte(wr * 64 + fr, fq * 8), boff = lds_byte(wc * 32 + fr, fq * 8);
;     ...
;     Unit cur, nxt; int ui = 0;
;     if (!S.next(0, cur)) return;
;     f32x4 acc[2][2][4][2];
; #pragma unroll
;     for (int a = 0; a < 2; ++a)
; #pragma unroll
;         for (int b = 0; b < 2; ++b)
; #pragma unroll
;             for (int m = 0; m < 4; ++m)
; #pragma unroll
;                 for (int n = 0; n < 2; ++n) acc[a][b][m][n] = (f32x4){0.f, 0.f, 0.f, 0.f};
;     bf16x8 At[4][2], B0[2][2], B1[2][2];
;     const char* cA = (const char*)g.A + (size_t)cur.pm * tstep; const char* cB = (const char*)g.Bt + (size_t)cur.pn * tstep;
;     PG8_STAGE(PG8_SB(0, 0), cB, voffB); PG8_STAGE(PG8_SA(0, 0), cA, voffA); PG8_STAGE(PG8_SB(0, 1), cB + hstep, voffB); PG8_STAGE(PG8_SA(0, 1), cA + hstep, voffA);
;     if (wr == 1) PG8_BAR;
;     PG8_WAIT_V(4); PG8_BAR;
;     PG8_STAGE(PG8_SB(1, 0), cB + kstep, voffB); PG8_STAGE(PG8_SA(1, 0), cA + kstep, voffA); PG8_STAGE(PG8_SB(1, 1), cB + hstep + kstep, voffB);
;     PG8_WAIT_V(6); PG8_BAR;
.LBB0_579:
	s_andn2_b64 vcc, exec, s[0:1]
	s_cbranch_vccnz .LBB0_630
	v_readlane_b32 s0, v250, 1
	s_mov_b32 s20, s0
	v_mov_b32_e32 v10, v198
	v_readlane_b32 s7, v254, 20
	s_cmpk_gt_i32 s7, 0x49f
	v_readfirstlane_b32 s21, v10
	v_readlane_b32 s1, v250, 2
	s_cbranch_scc1 .LBB0_606
	v_lshlrev_b32_e32 v0, 4, v10
	s_waitcnt lgkmcnt(0)
	v_add_u32_e32 v1, 0x2000, v0
	v_ashrrev_i32_e32 v2, 31, v1
	v_lshrrev_b32_e32 v2, 22, v2
	v_add_u32_e32 v2, v1, v2
	v_ashrrev_i32_e32 v8, 10, v2
	v_mul_i32_i24_e32 v2, 0x400, v8
	v_sub_u32_e32 v1, v1, v2
	v_lshrrev_b32_e32 v2, 4, v1
	v_bitop3_b32 v1, v2, v1, 32 bitop3:0x6c
	v_ashrrev_i32_e32 v2, 31, v1
	v_lshrrev_b32_e32 v2, 26, v2
	v_add_u32_e32 v2, v1, v2
	v_lshlrev_b32_e32 v3, 3, v8
	v_ashrrev_i32_e32 v9, 6, v2
	v_and_b32_e32 v3, -16, v3
	v_add_u32_e32 v3, v9, v3
	v_and_b32_e32 v4, 3, v9
	s_mov_b32 s0, 0xfffe0
	v_lshrrev_b32_e32 v5, 2, v3
	v_lshlrev_b32_e32 v6, 1, v3
	v_and_b32_e32 v2, 0xc0, v2
	v_and_or_b32 v4, v3, s0, v4
	v_and_b32_e32 v5, 4, v5
	v_and_b32_e32 v6, 24, v6
	v_sub_u32_e32 v1, v1, v2
	v_or3_b32 v4, v4, v5, v6
	v_lshlrev_b32_e32 v5, 5, v8
	v_ashrrev_i16_sdwa v1, v203, sext(v1) dst_sel:DWORD dst_unused:UNUSED_PAD src0_sel:DWORD src1_sel:BYTE_0
	v_and_b32_e32 v5, 32, v5
	v_bfe_i32 v11, v1, 0, 16
	v_add_lshl_u32 v1, v5, v11, 1
	v_lshl_add_u32 v136, v4, 12, v1
	v_lshl_add_u32 v138, v3, 12, v1
	v_bfe_i32 v1, v10, 27, 1
	v_lshrrev_b32_e32 v1, 22, v1
	v_add_u32_e32 v1, v0, v1
	v_and_b32_e32 v1, 0xfffffc00, v1
	v_sub_u32_e32 v0, v0, v1
	v_lshrrev_b32_e32 v1, 4, v0
	v_bitop3_b32 v1, v1, v0, 32 bitop3:0x6c
	v_ashrrev_i32_e32 v0, 31, v0
	v_lshrrev_b32_e32 v0, 26, v0
	v_add_u32_e32 v0, v1, v0
	v_ashrrev_i32_e32 v12, 6, v0
	v_ashrrev_i32_e32 v0, 31, v10
	v_lshrrev_b32_e32 v0, 26, v0
	v_add_u32_e32 v0, v10, v0
	v_ashrrev_i32_e32 v13, 6, v0
	v_lshlrev_b32_e32 v0, 3, v13
	v_and_b32_e32 v0, -16, v0
	v_add_u32_e32 v0, v12, v0
	v_and_b32_e32 v2, 3, v12
	s_ashr_i32 s23, s7, 31
	v_and_or_b32 v2, v0, s0, v2
	s_lshr_b32 s0, s23, 29
	s_add_i32 s0, s7, s0
	s_ashr_i32 s6, s21, 6
	s_ashr_i32 s1, s0, 3
	s_and_b32 s0, s0, -8
	s_ashr_i32 s5, s21, 8
	s_lshl_b32 s22, s6, 10
	s_sub_i32 s0, s7, s0
	s_cmp_lt_i32 s0, 0
	s_movk_i32 s4, 0x95
	s_cselect_b32 s4, s4, 0x94
	s_mul_i32 s0, s4, s0
	s_add_i32 s0, s0, s1
	s_mul_hi_i32 s1, s0, 0xdd67c8a7
	s_add_i32 s1, s1, s0
	s_lshr_b32 s4, s1, 31
	s_ashr_i32 s1, s1, 8
	s_add_i32 s1, s1, s4
	s_lshl_b32 s7, s1, 3
	s_mulk_i32 s1, 0x128
	s_sub_i32 s0, s0, s1
	s_sext_i32_i16 s1, s0
	s_bfe_u32 s1, s1, 0x3001c
	s_add_i32 s1, s0, s1
	s_sext_i32_i16 s4, s1
	s_and_b32 s1, s1, 0xfff8
	v_lshrrev_b32_e32 v3, 2, v0
	v_lshlrev_b32_e32 v4, 1, v0
	s_sub_i32 s0, s0, s1
	v_and_b32_e32 v3, 4, v3
	v_and_b32_e32 v4, 24, v4
	s_sext_i32_i16 s0, s0
	v_or3_b32 v2, v2, v3, v4
	v_mul_i32_i24_e32 v4, 64, v12
	s_lshr_b32 s4, s4, 3
	s_add_i32 s0, s7, s0
	v_sub_u32_e32 v1, v1, v4
	s_ashr_i32 s1, s0, 31
	s_bfe_i64 s[10:11], s[4:5], 0x100000
	v_lshlrev_b32_e32 v3, 5, v13
	v_ashrrev_i16_sdwa v1, v203, sext(v1) dst_sel:DWORD dst_unused:UNUSED_PAD src0_sel:DWORD src1_sel:BYTE_0
	s_lshl_b64 s[8:9], s[0:1], 20
	s_lshl_b64 s[10:11], s[10:11], 20
	v_readlane_b32 s12, v251, 41
	v_and_b32_e32 v3, 32, v3
	v_bfe_i32 v14, v1, 0, 16
	v_readlane_b32 s13, v251, 42
	s_add_u32 s16, s12, s10
	v_add_lshl_u32 v1, v3, v14, 1
	s_addc_u32 s17, s13, s11
	s_add_i32 s24, s22, 0
	v_lshl_add_u32 v140, v2, 12, v1
	s_add_i32 m0, s24, 0x10000
	v_readlane_b32 s10, v250, 9
	global_load_lds_dwordx4 v140, s[16:17]
	s_add_i32 m0, s24, 0x12000
	v_readlane_b32 s11, v250, 10
	s_add_u32 s14, s10, s8
	v_lshl_add_u32 v142, v0, 12, v1
	global_load_lds_dwordx4 v136, s[16:17]
	s_addc_u32 s15, s11, s9
	s_mov_b32 m0, s24
	s_add_i32 s25, s24, 0x2000
	global_load_lds_dwordx4 v142, s[14:15]
	s_mov_b32 m0, s25
	s_add_u32 s8, s16, 0x80000
	global_load_lds_dwordx4 v138, s[14:15]
	s_addc_u32 s9, s17, 0
	s_add_i32 m0, s24, 0x14000
	v_mov_b32_e32 v141, v161
	global_load_lds_dwordx4 v140, s[8:9]
	s_add_i32 m0, s24, 0x16000
	v_mov_b32_e32 v137, v161
	global_load_lds_dwordx4 v136, s[8:9]
	s_add_u32 s8, s14, 0x80000
	s_addc_u32 s9, s15, 0
	s_add_i32 s26, s24, 0x4000
	s_mov_b32 m0, s26
	s_add_i32 s27, s24, 0x6000
	global_load_lds_dwordx4 v142, s[8:9]
	s_mov_b32 m0, s27
	v_mov_b32_e32 v143, v161
	global_load_lds_dwordx4 v138, s[8:9]
	v_mov_b32_e32 v139, v161
	v_lshl_add_u64 v[6:7], s[16:17], 0, v[140:141]
	v_lshl_add_u64 v[4:5], s[16:17], 0, v[136:137]
	v_lshl_add_u64 v[2:3], s[14:15], 0, v[142:143]
	s_cmp_lg_u32 s5, 1
	v_lshl_add_u64 v[0:1], s[14:15], 0, v[138:139]
	s_cbranch_scc1 .LBB0_583
	s_barrier
	s_setprio 1

; #define PG8_STAGE(bufoff, gbase, voff) do { _Pragma("unroll") for (int _i = 0; _i < 2; ++_i) \
;         __builtin_amdgcn_global_load_lds((const unsigned*)((const char*)(gbase) + (voff)[_i]), (LAS unsigned*)(lds + (bufoff) + ldsw + _i * 8192), 16, 0, 0); } while (0)
; #define PG8_LDA(dst, b, h) do { _Pragma("unroll") for (int m = 0; m < 4; ++m) _Pragma("unroll") for (int k = 0; k < 2; ++k) dst[m][k] = *(const LAS bf16x8*)(lds + PG8_SA(b, h) + aoff + m * 2048 + k * 1024); } while (0)
; #define PG8_LDB(dst, b, h) do { _Pragma("unroll") for (int n = 0; n < 2; ++n) _Pragma("unroll") for (int k = 0; k < 2; ++k) dst[n][k] = *(const LAS bf16x8*)(lds + PG8_SB(b, h) + boff + n * 2048 + k * 1024); } while (0)
; #define PG8_MMA(ai, bj, At, Bt) do { __builtin_amdgcn_s_setprio(1); _Pragma("unroll") for (int m = 0; m < 4; ++m) _Pragma("unroll") for (int n = 0; n < 2; ++n) _Pragma("unroll") for (int k = 0; k < 2; ++k) \
;         acc[ai][bj][m][n] = __builtin_amdgcn_mfma_f32_16x16x32_bf16(Bt[n][k], At[m][k], acc[ai][bj][m][n], 0, 0, 0); __builtin_amdgcn_s_setprio(0); } while (0)
; #define PG8_WAIT_V(n) asm volatile("s_waitcnt vmcnt(" #n ")" ::: "memory")
; #define PG8_WAIT_L(n) asm volatile("s_waitcnt lgkmcnt(" #n ")" ::: "memory")
; #define PG8_BAR __builtin_amdgcn_s_barrier()
; template <class Epi>
; DEV void gemm_phase(LAS unsigned char* lds, const Gemm g, const StaticOrder& S, const Epi& E) {
;     ...
;         for (int t = 0; t < nt; t += 2) {
;             const bool last = (t == nt - 2);
;             const char* a1 = cA + (size_t)(t + 1) * kstep;
;             const char* a2 = last ? nA : cA + (size_t)(t + 2) * kstep; const char* b2 = last ? nB : cB + (size_t)(t + 2) * kstep;
;             const char* a3 = a2 + kstep; const char* b3 = b2 + kstep;
;             PG8_LDB(B0, 0, 0); PG8_SCHED; PG8_LDA(At, 0, 0); PG8_STAGE(PG8_SA(1, 1), a1 + hstep, voffA);
;             PG8_WAIT_L(8); PG8_BAR; PG8_WAIT_L(0); PG8_MMA(0, 0, At, B0); PG8_BAR; PG8_SCHED;
;             PG8_LDB(B1, 0, 1); PG8_STAGE(PG8_SB(0, 0), b2, voffB);
;             PG8_BAR; PG8_WAIT_L(0); PG8_MMA(0, 1, At, B1); PG8_BAR;
;             PG8_LDA(At, 0, 1); PG8_STAGE(PG8_SA(0, 0), a2, voffA);
;             PG8_BAR; PG8_WAIT_L(0); PG8_MMA(1, 0, At, B0); PG8_BAR; PG8_SCHED;
;             PG8_STAGE(PG8_SB(0, 1), b2 + hstep, voffB);
;             PG8_WAIT_V(6); PG8_BAR; PG8_MMA(1, 1, At, B1); PG8_BAR;
.LBB0_588:
	s_add_u32 s16, s14, 0xfff80080
	s_addc_u32 s17, s15, -1
	s_add_i32 s41, 0, 0x10000
	v_add_u32_e32 v154, s41, v167
	ds_read_b128 v[128:131], v154
	ds_read_b128 v[132:135], v154 offset:1024
	ds_read_b128 v[150:153], v154 offset:2048
	ds_read_b128 v[174:177], v154 offset:3072
	s_cmp_eq_u32 s40, 28
	s_cselect_b32 s19, s1, s17
	s_cselect_b32 s18, s9, s16
	s_cselect_b32 s17, s7, s37
	s_cselect_b32 s16, s35, s36
	v_lshl_add_u64 v[154:155], s[14:15], 0, v[146:147]
	s_add_i32 m0, s24, 0xc000
	ds_read_b128 v[182:185], v219
	ds_read_b128 v[190:193], v219 offset:1024
	ds_read_b128 v[194:197], v219 offset:2048
	ds_read_b128 v[220:223], v219 offset:3072
	ds_read_b128 v[224:227], v219 offset:4096
	ds_read_b128 v[228:231], v219 offset:5120
	ds_read_b128 v[232:235], v219 offset:6144
	ds_read_b128 v[236:239], v219 offset:7168
	global_load_lds_dwordx4 v[154:155], off
	v_lshl_add_u64 v[154:155], s[14:15], 0, v[148:149]
	s_add_i32 m0, s24, 0xe000
	s_nop 0
	global_load_lds_dwordx4 v[154:155], off
	s_waitcnt lgkmcnt(8)
	s_barrier
	s_waitcnt lgkmcnt(0)
	v_mfma_f32_16x16x32_bf16 v[124:127], v[128:131], v[182:185], v[124:127]
	v_mfma_f32_16x16x32_bf16 v[120:123], v[150:153], v[182:185], v[120:123]
	v_mfma_f32_16x16x32_bf16 v[108:111], v[128:131], v[194:197], v[108:111]
	v_mfma_f32_16x16x32_bf16 v[104:107], v[150:153], v[194:197], v[104:107]
	v_mfma_f32_16x16x32_bf16 v[92:95], v[128:131], v[224:227], v[92:95]
	v_mfma_f32_16x16x32_bf16 v[88:91], v[150:153], v[224:227], v[88:91]
	v_mfma_f32_16x16x32_bf16 v[76:79], v[128:131], v[232:235], v[76:79]
	v_mfma_f32_16x16x32_bf16 v[72:75], v[150:153], v[232:235], v[72:75]
	v_mfma_f32_16x16x32_bf16 v[124:127], v[132:135], v[190:193], v[124:127]
	v_mfma_f32_16x16x32_bf16 v[120:123], v[174:177], v[190:193], v[120:123]
	v_mfma_f32_16x16x32_bf16 v[108:111], v[132:135], v[220:223], v[108:111]
	v_mfma_f32_16x16x32_bf16 v[104:107], v[174:177], v[220:223], v[104:107]
	v_mfma_f32_16x16x32_bf16 v[92:95], v[132:135], v[228:231], v[92:95]
	v_mfma_f32_16x16x32_bf16 v[88:91], v[174:177], v[228:231], v[88:91]
	v_mfma_f32_16x16x32_bf16 v[76:79], v[132:135], v[236:239], v[76:79]
	v_mfma_f32_16x16x32_bf16 v[72:75], v[174:177], v[236:239], v[72:75]
	s_barrier
	s_add_i32 s44, 0, 0x14000
	v_add_u32_e32 v154, s44, v167
	s_add_i32 s41, s41, s22
	ds_read_b128 v[240:243], v154
	ds_read_b128 v[244:247], v154 offset:1024
	ds_read_b128 v[186:189], v154 offset:2048
	ds_read_b128 v[214:217], v154 offset:3072
	v_lshl_add_u64 v[154:155], s[16:17], 0, v[140:141]
	s_mov_b32 m0, s41
	v_lshl_add_u64 v[158:159], s[16:17], 0, v[136:137]
	global_load_lds_dwordx4 v[154:155], off
	s_add_i32 m0, s41, 0x2000
	s_nop 0
	global_load_lds_dwordx4 v[158:159], off
	s_barrier
	s_waitcnt lgkmcnt(0)
	v_mfma_f32_16x16x32_bf16 v[116:119], v[240:243], v[182:185], v[116:119]
	v_mfma_f32_16x16x32_bf16 v[112:115], v[186:189], v[182:185], v[112:115]
	v_mfma_f32_16x16x32_bf16 v[100:103], v[240:243], v[194:197], v[100:103]
	v_mfma_f32_16x16x32_bf16 v[96:99], v[186:189], v[194:197], v[96:99]
	v_mfma_f32_16x16x32_bf16 v[84:87], v[240:243], v[224:227], v[84:87]
	v_mfma_f32_16x16x32_bf16 v[80:83], v[186:189], v[224:227], v[80:83]
	v_mfma_f32_16x16x32_bf16 v[68:71], v[240:243], v[232:235], v[68:71]
	v_mfma_f32_16x16x32_bf16 v[64:67], v[186:189], v[232:235], v[64:67]
	v_mfma_f32_16x16x32_bf16 v[116:119], v[244:247], v[190:193], v[116:119]
	v_mfma_f32_16x16x32_bf16 v[112:115], v[214:217], v[190:193], v[112:115]
	v_mfma_f32_16x16x32_bf16 v[100:103], v[244:247], v[220:223], v[100:103]
	v_mfma_f32_16x16x32_bf16 v[96:99], v[214:217], v[220:223], v[96:99]
	v_mfma_f32_16x16x32_bf16 v[84:87], v[244:247], v[228:231], v[84:87]
	v_mfma_f32_16x16x32_bf16 v[80:83], v[214:217], v[228:231], v[80:83]
	v_mfma_f32_16x16x32_bf16 v[68:71], v[244:247], v[236:239], v[68:71]
	v_mfma_f32_16x16x32_bf16 v[64:67], v[214:217], v[236:239], v[64:67]
	s_mov_b32 m0, s24
	v_lshl_add_u64 v[178:179], s[18:19], 0, v[142:143]
	s_barrier
	ds_read_b128 v[182:185], v219 offset:16384
	ds_read_b128 v[190:193], v219 offset:17408
	ds_read_b128 v[194:197], v219 offset:18432
	ds_read_b128 v[220:223], v219 offset:19456
	ds_read_b128 v[224:227], v219 offset:20480
	ds_read_b128 v[228:231], v219 offset:21504
	ds_read_b128 v[232:235], v219 offset:22528
	ds_read_b128 v[236:239], v219 offset:23552
	global_load_lds_dwordx4 v[178:179], off
	v_lshl_add_u64 v[248:249], s[18:19], 0, v[138:139]
	s_mov_b32 m0, s25
	s_nop 0
	global_load_lds_dwordx4 v[248:249], off
	s_barrier
	s_waitcnt lgkmcnt(0)
	v_mfma_f32_16x16x32_bf16 v[60:63], v[128:131], v[182:185], v[60:63]
	v_mfma_f32_16x16x32_bf16 v[56:59], v[150:153], v[182:185], v[56:59]
	v_mfma_f32_16x16x32_bf16 v[44:47], v[128:131], v[194:197], v[44:47]
	v_mfma_f32_16x16x32_bf16 v[40:43], v[150:153], v[194:197], v[40:43]
	v_mfma_f32_16x16x32_bf16 v[28:31], v[128:131], v[224:227], v[28:31]
	v_mfma_f32_16x16x32_bf16 v[24:27], v[150:153], v[224:227], v[24:27]
	v_mfma_f32_16x16x32_bf16 v[12:15], v[128:131], v[232:235], v[12:15]
	v_mfma_f32_16x16x32_bf16 v[8:11], v[150:153], v[232:235], v[8:11]
	v_mfma_f32_16x16x32_bf16 v[60:63], v[132:135], v[190:193], v[60:63]
	v_mfma_f32_16x16x32_bf16 v[56:59], v[174:177], v[190:193], v[56:59]
	v_mfma_f32_16x16x32_bf16 v[44:47], v[132:135], v[220:223], v[44:47]
	v_mfma_f32_16x16x32_bf16 v[40:43], v[174:177], v[220:223], v[40:43]
	v_mfma_f32_16x16x32_bf16 v[28:31], v[132:135], v[228:231], v[28:31]
	v_mfma_f32_16x16x32_bf16 v[24:27], v[174:177], v[228:231], v[24:27]
	v_mfma_f32_16x16x32_bf16 v[12:15], v[132:135], v[236:239], v[12:15]
	v_mfma_f32_16x16x32_bf16 v[8:11], v[174:177], v[236:239], v[8:11]
	s_barrier
; #define PG8_STAGE(bufoff, gbase, voff) do { _Pragma("unroll") for (int _i = 0; _i < 2; ++_i) \
;         __builtin_amdgcn_global_load_lds((const unsigned*)((const char*)(gbase) + (voff)[_i]), (LAS unsigned*)(lds + (bufoff) + ldsw + _i * 8192), 16, 0, 0); } while (0)
; #define PG8_LDA(dst, b, h) do { _Pragma("unroll") for (int m = 0; m < 4; ++m) _Pragma("unroll") for (int k = 0; k < 2; ++k) dst[m][k] = *(const LAS bf16x8*)(lds + PG8_SA(b, h) + aoff + m * 2048 + k * 1024); } while (0)
; #define PG8_LDB(dst, b, h) do { _Pragma("unroll") for (int n = 0; n < 2; ++n) _Pragma("unroll") for (int k = 0; k < 2; ++k) dst[n][k] = *(const LAS bf16x8*)(lds + PG8_SB(b, h) + boff + n * 2048 + k * 1024); } while (0)
; #define PG8_MMA(ai, bj, At, Bt) do { __builtin_amdgcn_s_setprio(1); _Pragma("unroll") for (int m = 0; m < 4; ++m) _Pragma("unroll") for (int n = 0; n < 2; ++n) _Pragma("unroll") for (int k = 0; k < 2; ++k) \
;         acc[ai][bj][m][n] = __builtin_amdgcn_mfma_f32_16x16x32_bf16(Bt[n][k], At[m][k], acc[ai][bj][m][n], 0, 0, 0); __builtin_amdgcn_s_setprio(0); } while (0)
; #define PG8_WAIT_V(n) asm volatile("s_waitcnt vmcnt(" #n ")" ::: "memory")
; #define PG8_WAIT_L(n) asm volatile("s_waitcnt lgkmcnt(" #n ")" ::: "memory")
; #define PG8_BAR __builtin_amdgcn_s_barrier()
; #define PG8_SCHED __builtin_amdgcn_sched_barrier(0)
; template <class Epi>
; DEV void gemm_phase(LAS unsigned char* lds, const Gemm g, const StaticOrder& S, const Epi& E) {
;     ...
;             PG8_STAGE(PG8_SB(0, 1), b2 + hstep, voffB);
;             PG8_WAIT_V(6); PG8_BAR; PG8_MMA(1, 1, At, B1); PG8_BAR;
;             PG8_LDB(B0, 1, 0); PG8_SCHED; PG8_LDA(At, 1, 0); PG8_STAGE(PG8_SA(0, 1), a2 + hstep, voffA);
;             PG8_WAIT_L(8); PG8_BAR; PG8_WAIT_L(0); PG8_MMA(0, 0, At, B0); PG8_BAR; PG8_SCHED;
;             PG8_LDB(B1, 1, 1); PG8_STAGE(PG8_SB(1, 0), b3, voffB);
;             PG8_BAR; PG8_WAIT_L(0); PG8_MMA(0, 1, At, B1); PG8_BAR;
;             PG8_LDA(At, 1, 1); PG8_STAGE(PG8_SA(1, 0), a3, voffA);
;             PG8_BAR; PG8_WAIT_L(0); PG8_MMA(1, 0, At, B0); PG8_BAR; PG8_SCHED;
	s_add_u32 s42, s16, 0x80000
	s_addc_u32 s43, s17, 0
	s_add_i32 s41, s44, s22
	v_lshl_add_u64 v[128:129], s[42:43], 0, v[140:141]
	s_mov_b32 m0, s41
	s_nop 0
	global_load_lds_dwordx4 v[128:129], off
	v_lshl_add_u64 v[128:129], s[42:43], 0, v[136:137]
	s_add_i32 m0, s41, 0x2000
	s_nop 0
	global_load_lds_dwordx4 v[128:129], off
	s_waitcnt vmcnt(6)
	s_barrier
	v_mfma_f32_16x16x32_bf16 v[52:55], v[240:243], v[182:185], v[52:55]
	v_mfma_f32_16x16x32_bf16 v[48:51], v[186:189], v[182:185], v[48:51]
	v_mfma_f32_16x16x32_bf16 v[36:39], v[240:243], v[194:197], v[36:39]
	v_mfma_f32_16x16x32_bf16 v[32:35], v[186:189], v[194:197], v[32:35]
	v_mfma_f32_16x16x32_bf16 v[20:23], v[240:243], v[224:227], v[20:23]
	v_mfma_f32_16x16x32_bf16 v[16:19], v[186:189], v[224:227], v[16:19]
	v_mfma_f32_16x16x32_bf16 v[4:7], v[240:243], v[232:235], v[4:7]
	v_mfma_f32_16x16x32_bf16 v[0:3], v[186:189], v[232:235], v[0:3]
	v_mfma_f32_16x16x32_bf16 v[52:55], v[244:247], v[190:193], v[52:55]
	v_mfma_f32_16x16x32_bf16 v[48:51], v[214:217], v[190:193], v[48:51]
	v_mfma_f32_16x16x32_bf16 v[36:39], v[244:247], v[220:223], v[36:39]
	v_mfma_f32_16x16x32_bf16 v[32:35], v[214:217], v[220:223], v[32:35]
	v_mfma_f32_16x16x32_bf16 v[20:23], v[244:247], v[228:231], v[20:23]
	v_mfma_f32_16x16x32_bf16 v[16:19], v[214:217], v[228:231], v[16:19]
	v_mfma_f32_16x16x32_bf16 v[4:7], v[244:247], v[236:239], v[4:7]
	v_mfma_f32_16x16x32_bf16 v[0:3], v[214:217], v[236:239], v[0:3]
	s_add_i32 s41, 0, 0x18000
	v_add_u32_e32 v156, s41, v167
	s_barrier
	ds_read_b128 v[128:131], v156
	ds_read_b128 v[132:135], v156 offset:1024
	ds_read_b128 v[150:153], v156 offset:2048
	ds_read_b128 v[174:177], v156 offset:3072
	s_add_u32 s18, s18, 0x80000
	s_addc_u32 s19, s19, 0
	s_mov_b32 m0, s26
	v_lshl_add_u64 v[232:233], s[18:19], 0, v[142:143]
	ds_read_b128 v[182:185], v219 offset:32768
	ds_read_b128 v[186:189], v219 offset:33792
	ds_read_b128 v[190:193], v219 offset:34816
	ds_read_b128 v[194:197], v219 offset:35840
	ds_read_b128 v[214:217], v219 offset:36864
	ds_read_b128 v[220:223], v219 offset:37888
	ds_read_b128 v[224:227], v219 offset:38912
	ds_read_b128 v[228:231], v219 offset:39936
	global_load_lds_dwordx4 v[232:233], off
	v_lshl_add_u64 v[232:233], s[18:19], 0, v[138:139]
	s_mov_b32 m0, s27
	s_nop 0
	global_load_lds_dwordx4 v[232:233], off
	s_waitcnt lgkmcnt(8)
	s_barrier
	s_waitcnt lgkmcnt(0)
	v_mfma_f32_16x16x32_bf16 v[124:127], v[128:131], v[182:185], v[124:127]
	v_mfma_f32_16x16x32_bf16 v[120:123], v[150:153], v[182:185], v[120:123]
	v_mfma_f32_16x16x32_bf16 v[108:111], v[128:131], v[190:193], v[108:111]
	v_mfma_f32_16x16x32_bf16 v[104:107], v[150:153], v[190:193], v[104:107]
	v_mfma_f32_16x16x32_bf16 v[92:95], v[128:131], v[214:217], v[92:95]
	v_mfma_f32_16x16x32_bf16 v[88:91], v[150:153], v[214:217], v[88:91]
	v_mfma_f32_16x16x32_bf16 v[76:79], v[128:131], v[224:227], v[76:79]
	v_mfma_f32_16x16x32_bf16 v[72:75], v[150:153], v[224:227], v[72:75]
	v_mfma_f32_16x16x32_bf16 v[124:127], v[132:135], v[186:189], v[124:127]
	v_mfma_f32_16x16x32_bf16 v[120:123], v[174:177], v[186:189], v[120:123]
	v_mfma_f32_16x16x32_bf16 v[108:111], v[132:135], v[194:197], v[108:111]
	v_mfma_f32_16x16x32_bf16 v[104:107], v[174:177], v[194:197], v[104:107]
	v_mfma_f32_16x16x32_bf16 v[92:95], v[132:135], v[220:223], v[92:95]
	v_mfma_f32_16x16x32_bf16 v[88:91], v[174:177], v[220:223], v[88:91]
	v_mfma_f32_16x16x32_bf16 v[76:79], v[132:135], v[228:231], v[76:79]
	v_mfma_f32_16x16x32_bf16 v[72:75], v[174:177], v[228:231], v[72:75]
	s_barrier
	s_add_i32 s18, 0, 0x1c000
	s_add_i32 s19, s41, s22
	v_add_u32_e32 v156, s18, v167
	v_lshl_add_u64 v[154:155], v[154:155], 0, s[2:3]
	s_mov_b32 m0, s19
	ds_read_b128 v[232:235], v156
	ds_read_b128 v[236:239], v156 offset:1024
	ds_read_b128 v[240:243], v156 offset:2048
	ds_read_b128 v[244:247], v156 offset:3072
	global_load_lds_dwordx4 v[154:155], off
	v_lshl_add_u64 v[154:155], v[158:159], 0, s[2:3]
	s_add_i32 m0, s19, 0x2000
	s_nop 0
	global_load_lds_dwordx4 v[154:155], off
	s_barrier
	s_waitcnt lgkmcnt(0)
	v_mfma_f32_16x16x32_bf16 v[116:119], v[232:235], v[182:185], v[116:119]
	v_mfma_f32_16x16x32_bf16 v[112:115], v[240:243], v[182:185], v[112:115]
	v_mfma_f32_16x16x32_bf16 v[100:103], v[232:235], v[190:193], v[100:103]
	v_mfma_f32_16x16x32_bf16 v[96:99], v[240:243], v[190:193], v[96:99]
	v_mfma_f32_16x16x32_bf16 v[84:87], v[232:235], v[214:217], v[84:87]
	v_mfma_f32_16x16x32_bf16 v[80:83], v[240:243], v[214:217], v[80:83]
	v_mfma_f32_16x16x32_bf16 v[68:71], v[232:235], v[224:227], v[68:71]
	v_mfma_f32_16x16x32_bf16 v[64:67], v[240:243], v[224:227], v[64:67]
	v_mfma_f32_16x16x32_bf16 v[116:119], v[236:239], v[186:189], v[116:119]
	v_mfma_f32_16x16x32_bf16 v[112:115], v[244:247], v[186:189], v[112:115]
	v_mfma_f32_16x16x32_bf16 v[100:103], v[236:239], v[194:197], v[100:103]
	v_mfma_f32_16x16x32_bf16 v[96:99], v[244:247], v[194:197], v[96:99]
	v_mfma_f32_16x16x32_bf16 v[84:87], v[236:239], v[220:223], v[84:87]
	v_mfma_f32_16x16x32_bf16 v[80:83], v[244:247], v[220:223], v[80:83]
	v_mfma_f32_16x16x32_bf16 v[68:71], v[236:239], v[228:231], v[68:71]
	v_mfma_f32_16x16x32_bf16 v[64:67], v[244:247], v[228:231], v[64:67]
	s_mov_b32 m0, s28
	v_lshl_add_u64 v[154:155], v[178:179], 0, s[2:3]
	s_barrier
	ds_read_b128 v[182:185], v219 offset:49152
	ds_read_b128 v[186:189], v219 offset:50176
	ds_read_b128 v[190:193], v219 offset:51200
	ds_read_b128 v[194:197], v219 offset:52224
	ds_read_b128 v[214:217], v219 offset:53248
	ds_read_b128 v[220:223], v219 offset:54272
	ds_read_b128 v[224:227], v219 offset:55296
	ds_read_b128 v[228:231], v219 offset:56320
	global_load_lds_dwordx4 v[154:155], off
	v_lshl_add_u64 v[154:155], v[248:249], 0, s[2:3]
	s_mov_b32 m0, s29
	s_nop 0
	global_load_lds_dwordx4 v[154:155], off
	s_barrier
; #define PG8_STAGE(bufoff, gbase, voff) do { _Pragma("unroll") for (int _i = 0; _i < 2; ++_i) \
;         __builtin_amdgcn_global_load_lds((const unsigned*)((const char*)(gbase) + (voff)[_i]), (LAS unsigned*)(lds + (bufoff) + ldsw + _i * 8192), 16, 0, 0); } while (0)
; #define PG8_MMA(ai, bj, At, Bt) do { __builtin_amdgcn_s_setprio(1); _Pragma("unroll") for (int m = 0; m < 4; ++m) _Pragma("unroll") for (int n = 0; n < 2; ++n) _Pragma("unroll") for (int k = 0; k < 2; ++k) \
;         acc[ai][bj][m][n] = __builtin_amdgcn_mfma_f32_16x16x32_bf16(Bt[n][k], At[m][k], acc[ai][bj][m][n], 0, 0, 0); __builtin_amdgcn_s_setprio(0); } while (0)
; #define PG8_WAIT_V(n) asm volatile("s_waitcnt vmcnt(" #n ")" ::: "memory")
; #define PG8_WAIT_L(n) asm volatile("s_waitcnt lgkmcnt(" #n ")" ::: "memory")
; #define PG8_BAR __builtin_amdgcn_s_barrier()
; #define PG8_SCHED __builtin_amdgcn_sched_barrier(0)
;     DEV void operator()(AccRef acc, const pg8::Unit& u, int wr, int wc, int fr, int fq) const { store_bf16_tile<0, false>(acc, O, ld, u.pm * 256 + wr * 64 + fr, u.pn * 256 + wc * 32 + 4 * fq, ss); }
; template <class Epi>
; DEV void gemm_phase(LAS unsigned char* lds, const Gemm g, const StaticOrder& S, const Epi& E) {
;     ...
;             PG8_BAR; PG8_WAIT_L(0); PG8_MMA(1, 0, At, B0); PG8_BAR; PG8_SCHED;
;             PG8_STAGE(PG8_SB(1, 1), b3 + hstep, voffB);
;             PG8_WAIT_V(6); PG8_BAR; PG8_MMA(1, 1, At, B1); PG8_BAR;
;         }
;     DEV void operator()(AccRef acc, const pg8::Unit& u, int wr, int wc, int fr, int fq) const {
;         const int ct = u.pn * 256, row0 = u.pm * 256 + wr * 64 + fr, cw = wc * 32 + 8 * fq;
;         if (ct < 4096) store_bf16_tile<1, true>(acc, UV, 4096, row0, ct + cw, ss);
;         else if (ct < 6144) store_bf16_tile<0, true>(acc, Z, 2048, row0, ct - 4096 + cw, ss);
;         else if (ct < 9216) store_bf16_tile<0, true>(acc, XBC, 3072, row0, ct - 6144 + cw, ss);
;         else if (wc == 0) {
; #pragma unroll
;             for (int ai = 0; ai < 2; ++ai)
; #pragma unroll
;                 for (int m = 0; m < 4; ++m) { const float rs = rowscale(ss, row0 + ai * 128 + m * 16);
; #pragma unroll
;                     for (int n = 0; n < 2; ++n) *(f32x4*)(DTR + (size_t)(row0 + ai * 128 + m * 16) * 32 + 8 * fq + 4 * n) = acc[ai][0][m][n] * rs; }
	s_waitcnt lgkmcnt(0)
	v_mfma_f32_16x16x32_bf16 v[60:63], v[128:131], v[182:185], v[60:63]
	v_mfma_f32_16x16x32_bf16 v[56:59], v[150:153], v[182:185], v[56:59]
	v_mfma_f32_16x16x32_bf16 v[44:47], v[128:131], v[190:193], v[44:47]
	v_mfma_f32_16x16x32_bf16 v[40:43], v[150:153], v[190:193], v[40:43]
	v_mfma_f32_16x16x32_bf16 v[28:31], v[128:131], v[214:217], v[28:31]
	v_mfma_f32_16x16x32_bf16 v[24:27], v[150:153], v[214:217], v[24:27]
	v_mfma_f32_16x16x32_bf16 v[12:15], v[128:131], v[224:227], v[12:15]
	v_mfma_f32_16x16x32_bf16 v[8:11], v[150:153], v[224:227], v[8:11]
	v_mfma_f32_16x16x32_bf16 v[60:63], v[132:135], v[186:189], v[60:63]
	v_mfma_f32_16x16x32_bf16 v[56:59], v[174:177], v[186:189], v[56:59]
	v_mfma_f32_16x16x32_bf16 v[44:47], v[132:135], v[194:197], v[44:47]
	v_mfma_f32_16x16x32_bf16 v[40:43], v[174:177], v[194:197], v[40:43]
	v_mfma_f32_16x16x32_bf16 v[28:31], v[132:135], v[220:223], v[28:31]
	v_mfma_f32_16x16x32_bf16 v[24:27], v[174:177], v[220:223], v[24:27]
	v_mfma_f32_16x16x32_bf16 v[12:15], v[132:135], v[228:231], v[12:15]
	v_mfma_f32_16x16x32_bf16 v[8:11], v[174:177], v[228:231], v[8:11]
	s_barrier
	s_add_u32 s16, s16, 0x80080
	s_addc_u32 s17, s17, 0
	s_add_i32 s18, s18, s22
	v_lshl_add_u64 v[128:129], s[16:17], 0, v[140:141]
	s_mov_b32 m0, s18
	s_nop 0
	global_load_lds_dwordx4 v[128:129], off
	v_lshl_add_u64 v[128:129], s[16:17], 0, v[136:137]
	s_add_i32 m0, s18, 0x2000
	s_nop 0
	global_load_lds_dwordx4 v[128:129], off
	s_waitcnt vmcnt(6)
	s_barrier
	v_mfma_f32_16x16x32_bf16 v[52:55], v[232:235], v[182:185], v[52:55]
	v_mfma_f32_16x16x32_bf16 v[48:51], v[240:243], v[182:185], v[48:51]
	v_mfma_f32_16x16x32_bf16 v[36:39], v[232:235], v[190:193], v[36:39]
	v_mfma_f32_16x16x32_bf16 v[32:35], v[240:243], v[190:193], v[32:35]
	v_mfma_f32_16x16x32_bf16 v[20:23], v[232:235], v[214:217], v[20:23]
	v_mfma_f32_16x16x32_bf16 v[16:19], v[240:243], v[214:217], v[16:19]
	v_mfma_f32_16x16x32_bf16 v[4:7], v[232:235], v[224:227], v[4:7]
	v_mfma_f32_16x16x32_bf16 v[0:3], v[240:243], v[224:227], v[0:3]
	v_mfma_f32_16x16x32_bf16 v[52:55], v[236:239], v[186:189], v[52:55]
	v_mfma_f32_16x16x32_bf16 v[48:51], v[244:247], v[186:189], v[48:51]
	v_mfma_f32_16x16x32_bf16 v[36:39], v[236:239], v[194:197], v[36:39]
	v_mfma_f32_16x16x32_bf16 v[32:35], v[244:247], v[194:197], v[32:35]
	v_mfma_f32_16x16x32_bf16 v[20:23], v[236:239], v[220:223], v[20:23]
	v_mfma_f32_16x16x32_bf16 v[16:19], v[244:247], v[220:223], v[16:19]
	v_mfma_f32_16x16x32_bf16 v[4:7], v[236:239], v[228:231], v[4:7]
	v_mfma_f32_16x16x32_bf16 v[0:3], v[244:247], v[228:231], v[0:3]
	s_add_i32 s40, s40, 2
	s_add_u32 s14, s14, 0x100
	s_addc_u32 s15, s15, 0
	s_add_u32 s36, s36, 0x100
	s_addc_u32 s37, s37, 0
	s_cmp_gt_u32 s40, 29
	s_barrier
	s_cbranch_scc0 .LBB0_588
	s_lshl_b32 s7, s34, 8
	v_lshl_add_u32 v150, s0, 8, v157
	s_cmp_gt_i32 s34, 15
	s_mov_b64 s[0:1], -1
	s_cbranch_scc0 .LBB0_601
	s_cmp_gt_u32 s34, 23
	s_cbranch_scc0 .LBB0_598
	s_cmp_gt_u32 s34, 35
	s_cbranch_scc0 .LBB0_595
	s_andn2_b64 vcc, exec, s[4:5]
	s_cbranch_vccnz .LBB0_594
	v_ashrrev_i32_e32 v151, 31, v150
	v_readlane_b32 s0, v251, 39
	v_lshlrev_b64 v[128:129], 5, v[150:151]
	v_readlane_b32 s1, v251, 40
	s_mov_b32 s9, 0x800000
	s_nop 0
	v_lshl_add_u64 v[132:133], s[0:1], 0, v[128:129]
	global_load_dwordx4 v[128:131], v[132:133], off offset:16
	s_nop 0
	global_load_dwordx4 v[132:135], v[132:133], off
	s_waitcnt vmcnt(0)
	v_mov_b32_e32 v152, v133
	v_mov_b32_e32 v153, v134
	v_mov_b32_e32 v133, v135
	v_pk_add_f32 v[132:133], v[152:153], v[132:133]
	v_mov_b32_e32 v134, v130
	v_mov_b32_e32 v135, v128
	v_mov_b32_e32 v128, v131
	v_pk_add_f32 v[128:129], v[134:135], v[128:129]
	v_add_f32_e32 v130, v132, v133
	v_add_f32_e32 v129, v130, v129
	v_add_f32_e32 v128, v128, v129
	v_fmamk_f32 v128, v128, 0x3a000000, v199
	v_cmp_gt_f32_e32 vcc, s9, v128
	v_mul_f32_e32 v129, 0x4b800000, v128
	v_lshlrev_b64 v[134:135], 7, v[150:151]
	v_cndmask_b32_e32 v128, v128, v129, vcc
	v_rsq_f32_e32 v128, v128
	v_lshl_add_u64 v[134:135], v[144:145], 0, v[134:135]
	v_or_b32_e32 v152, 16, v150
	v_ashrrev_i32_e32 v153, 31, v152
	v_mul_f32_e32 v129, 0x45800000, v128
	v_cndmask_b32_e32 v132, v128, v129, vcc
	v_pk_mul_f32 v[130:131], v[126:127], v[132:133] op_sel_hi:[1,0]
	v_pk_mul_f32 v[128:129], v[124:125], v[132:133] op_sel_hi:[1,0]
	global_store_dwordx4 v[134:135], v[128:131], off
	s_nop 1
	v_pk_mul_f32 v[130:131], v[122:123], v[132:133] op_sel_hi:[1,0]
	v_pk_mul_f32 v[128:129], v[120:121], v[132:133] op_sel_hi:[1,0]
	global_store_dwordx4 v[134:135], v[128:131], off offset:16
	s_nop 1
	v_lshlrev_b64 v[128:129], 5, v[152:153]
	v_lshl_add_u64 v[132:133], s[0:1], 0, v[128:129]
	global_load_dwordx4 v[128:131], v[132:133], off offset:16
	s_nop 0
	global_load_dwordx4 v[132:135], v[132:133], off
	s_waitcnt vmcnt(0)
	v_mov_b32_e32 v154, v133
	v_mov_b32_e32 v155, v134
	v_mov_b32_e32 v133, v135
	v_pk_add_f32 v[132:133], v[154:155], v[132:133]
	v_mov_b32_e32 v134, v130
	v_mov_b32_e32 v135, v128
	v_mov_b32_e32 v128, v131
	v_pk_add_f32 v[128:129], v[134:135], v[128:129]
	v_add_f32_e32 v130, v132, v133
	v_add_f32_e32 v129, v130, v129
	v_add_f32_e32 v128, v128, v129
	v_fmamk_f32 v128, v128, 0x3a000000, v199
	v_cmp_gt_f32_e32 vcc, s9, v128
	v_mul_f32_e32 v129, 0x4b800000, v128
	v_lshlrev_b64 v[134:135], 7, v[152:153]
	v_cndmask_b32_e32 v128, v128, v129, vcc
	v_rsq_f32_e32 v128, v128
	v_lshl_add_u64 v[134:135], v[144:145], 0, v[134:135]
	v_or_b32_e32 v152, 32, v150
	v_ashrrev_i32_e32 v153, 31, v152
	v_mul_f32_e32 v129, 0x45800000, v128
	v_cndmask_b32_e32 v132, v128, v129, vcc
	v_pk_mul_f32 v[130:131], v[110:111], v[132:133] op_sel_hi:[1,0]
	v_pk_mul_f32 v[128:129], v[108:109], v[132:133] op_sel_hi:[1,0]
	global_store_dwordx4 v[134:135], v[128:131], off
	s_nop 1
	v_pk_mul_f32 v[130:131], v[106:107], v[132:133] op_sel_hi:[1,0]
	v_pk_mul_f32 v[128:129], v[104:105], v[132:133] op_sel_hi:[1,0]
	global_store_dwordx4 v[134:135], v[128:131], off offset:16
	s_nop 1
	v_lshlrev_b64 v[128:129], 5, v[152:153]
	v_lshl_add_u64 v[132:133], s[0:1], 0, v[128:129]
	global_load_dwordx4 v[128:131], v[132:133], off offset:16
	s_nop 0
	global_load_dwordx4 v[132:135], v[132:133], off
	s_waitcnt vmcnt(0)
; DEV float rowscale(const float* ss, int row) { const f32x4 a = *(const f32x4*)(ss + (size_t)row * 8), b = *(const f32x4*)(ss + (size_t)row * 8 + 4);
;     return rsqrtf(((a[0] + a[1]) + (a[2] + a[3]) + (b[0] + b[1]) + (b[2] + b[3])) * (1.0f / 2048.0f) + EPS); }
;     DEV void operator()(AccRef acc, const pg8::Unit& u, int wr, int wc, int fr, int fq) const {
;     ...
;         else if (wc == 0) {
; #pragma unroll
;             for (int ai = 0; ai < 2; ++ai)
; #pragma unroll
;                 for (int m = 0; m < 4; ++m) { const float rs = rowscale(ss, row0 + ai * 128 + m * 16);
; #pragma unroll
;                     for (int n = 0; n < 2; ++n) *(f32x4*)(DTR + (size_t)(row0 + ai * 128 + m * 16) * 32 + 8 * fq + 4 * n) = acc[ai][0][m][n] * rs; }
	v_mov_b32_e32 v154, v133
	v_mov_b32_e32 v155, v134
	v_mov_b32_e32 v133, v135
	v_pk_add_f32 v[132:133], v[154:155], v[132:133]
	v_mov_b32_e32 v134, v130
	v_mov_b32_e32 v135, v128
	v_mov_b32_e32 v128, v131
	v_pk_add_f32 v[128:129], v[134:135], v[128:129]
	v_add_f32_e32 v130, v132, v133
	v_add_f32_e32 v129, v130, v129
	v_add_f32_e32 v128, v128, v129
	v_fmamk_f32 v128, v128, 0x3a000000, v199
	v_cmp_gt_f32_e32 vcc, s9, v128
	v_mul_f32_e32 v129, 0x4b800000, v128
	v_lshlrev_b64 v[134:135], 7, v[152:153]
	v_cndmask_b32_e32 v128, v128, v129, vcc
	v_rsq_f32_e32 v128, v128
	v_lshl_add_u64 v[134:135], v[144:145], 0, v[134:135]
	v_or_b32_e32 v152, 48, v150
	v_ashrrev_i32_e32 v153, 31, v152
	v_mul_f32_e32 v129, 0x45800000, v128
	v_cndmask_b32_e32 v132, v128, v129, vcc
	v_pk_mul_f32 v[130:131], v[94:95], v[132:133] op_sel_hi:[1,0]
	v_pk_mul_f32 v[128:129], v[92:93], v[132:133] op_sel_hi:[1,0]
	global_store_dwordx4 v[134:135], v[128:131], off
	s_nop 1
	v_pk_mul_f32 v[130:131], v[90:91], v[132:133] op_sel_hi:[1,0]
	v_pk_mul_f32 v[128:129], v[88:89], v[132:133] op_sel_hi:[1,0]
	global_store_dwordx4 v[134:135], v[128:131], off offset:16
	s_nop 1
	v_lshlrev_b64 v[128:129], 5, v[152:153]
	v_lshl_add_u64 v[132:133], s[0:1], 0, v[128:129]
	global_load_dwordx4 v[128:131], v[132:133], off offset:16
	s_nop 0
	global_load_dwordx4 v[132:135], v[132:133], off
	s_waitcnt vmcnt(0)
	v_mov_b32_e32 v154, v133
	v_mov_b32_e32 v155, v134
	v_mov_b32_e32 v133, v135
	v_pk_add_f32 v[132:133], v[154:155], v[132:133]
	v_mov_b32_e32 v134, v130
	v_mov_b32_e32 v135, v128
	v_mov_b32_e32 v128, v131
	v_pk_add_f32 v[128:129], v[134:135], v[128:129]
	v_add_f32_e32 v130, v132, v133
	v_add_f32_e32 v129, v130, v129
	v_add_f32_e32 v128, v128, v129
	v_fmamk_f32 v128, v128, 0x3a000000, v199
	v_cmp_gt_f32_e32 vcc, s9, v128
	v_mul_f32_e32 v129, 0x4b800000, v128
	v_lshlrev_b64 v[134:135], 7, v[152:153]
	v_cndmask_b32_e32 v128, v128, v129, vcc
	v_rsq_f32_e32 v128, v128
	v_lshl_add_u64 v[134:135], v[144:145], 0, v[134:135]
	v_add_u32_e32 v152, 0x80, v150
	v_ashrrev_i32_e32 v153, 31, v152
	v_mul_f32_e32 v129, 0x45800000, v128
	v_cndmask_b32_e32 v132, v128, v129, vcc
	v_pk_mul_f32 v[130:131], v[78:79], v[132:133] op_sel_hi:[1,0]
	v_pk_mul_f32 v[128:129], v[76:77], v[132:133] op_sel_hi:[1,0]
	global_store_dwordx4 v[134:135], v[128:131], off
	s_nop 1
	v_pk_mul_f32 v[130:131], v[74:75], v[132:133] op_sel_hi:[1,0]
	v_pk_mul_f32 v[128:129], v[72:73], v[132:133] op_sel_hi:[1,0]
	global_store_dwordx4 v[134:135], v[128:131], off offset:16
	s_nop 1
	v_lshlrev_b64 v[128:129], 5, v[152:153]
	v_lshl_add_u64 v[132:133], s[0:1], 0, v[128:129]
	global_load_dwordx4 v[128:131], v[132:133], off offset:16
	s_nop 0
	global_load_dwordx4 v[132:135], v[132:133], off
	s_waitcnt vmcnt(0)
	v_mov_b32_e32 v154, v133
	v_mov_b32_e32 v155, v134
	v_mov_b32_e32 v133, v135
	v_pk_add_f32 v[132:133], v[154:155], v[132:133]
	v_mov_b32_e32 v134, v130
	v_mov_b32_e32 v135, v128
	v_mov_b32_e32 v128, v131
	v_pk_add_f32 v[128:129], v[134:135], v[128:129]
	v_add_f32_e32 v130, v132, v133
	v_add_f32_e32 v129, v130, v129
	v_add_f32_e32 v128, v128, v129
	v_fmamk_f32 v128, v128, 0x3a000000, v199
	v_cmp_gt_f32_e32 vcc, s9, v128
	v_mul_f32_e32 v129, 0x4b800000, v128
	v_lshlrev_b64 v[134:135], 7, v[152:153]
	v_cndmask_b32_e32 v128, v128, v129, vcc
	v_rsq_f32_e32 v128, v128
	v_lshl_add_u64 v[134:135], v[144:145], 0, v[134:135]
	v_add_u32_e32 v152, 0x90, v150
	v_ashrrev_i32_e32 v153, 31, v152
	v_mul_f32_e32 v129, 0x45800000, v128
	v_cndmask_b32_e32 v132, v128, v129, vcc
	v_pk_mul_f32 v[130:131], v[62:63], v[132:133] op_sel_hi:[1,0]
	v_pk_mul_f32 v[128:129], v[60:61], v[132:133] op_sel_hi:[1,0]
	global_store_dwordx4 v[134:135], v[128:131], off
	s_nop 1
	v_pk_mul_f32 v[130:131], v[58:59], v[132:133] op_sel_hi:[1,0]
	v_pk_mul_f32 v[128:129], v[56:57], v[132:133] op_sel_hi:[1,0]
	global_store_dwordx4 v[134:135], v[128:131], off offset:16
	s_nop 1
	v_lshlrev_b64 v[128:129], 5, v[152:153]
	v_lshl_add_u64 v[132:133], s[0:1], 0, v[128:129]
	global_load_dwordx4 v[128:131], v[132:133], off offset:16
	s_nop 0
	global_load_dwordx4 v[132:135], v[132:133], off
	s_waitcnt vmcnt(0)
; DEV float rowscale(const float* ss, int row) { const f32x4 a = *(const f32x4*)(ss + (size_t)row * 8), b = *(const f32x4*)(ss + (size_t)row * 8 + 4);
;     return rsqrtf(((a[0] + a[1]) + (a[2] + a[3]) + (b[0] + b[1]) + (b[2] + b[3])) * (1.0f / 2048.0f) + EPS); }
;     DEV void operator()(AccRef acc, const pg8::Unit& u, int wr, int wc, int fr, int fq) const {
;     ...
;         else if (wc == 0) {
; #pragma unroll
;             for (int ai = 0; ai < 2; ++ai)
; #pragma unroll
;                 for (int m = 0; m < 4; ++m) { const float rs = rowscale(ss, row0 + ai * 128 + m * 16);
; #pragma unroll
;                     for (int n = 0; n < 2; ++n) *(f32x4*)(DTR + (size_t)(row0 + ai * 128 + m * 16) * 32 + 8 * fq + 4 * n) = acc[ai][0][m][n] * rs; }
	v_mov_b32_e32 v154, v133
	v_mov_b32_e32 v155, v134
	v_mov_b32_e32 v133, v135
	v_pk_add_f32 v[132:133], v[154:155], v[132:133]
	v_mov_b32_e32 v134, v130
	v_mov_b32_e32 v135, v128
	v_mov_b32_e32 v128, v131
	v_pk_add_f32 v[128:129], v[134:135], v[128:129]
	v_add_f32_e32 v130, v132, v133
	v_add_f32_e32 v129, v130, v129
	v_add_f32_e32 v128, v128, v129
	v_fmamk_f32 v128, v128, 0x3a000000, v199
	v_cmp_gt_f32_e32 vcc, s9, v128
	v_mul_f32_e32 v129, 0x4b800000, v128
	v_lshlrev_b64 v[134:135], 7, v[152:153]
	v_cndmask_b32_e32 v128, v128, v129, vcc
	v_rsq_f32_e32 v128, v128
	v_lshl_add_u64 v[134:135], v[144:145], 0, v[134:135]
	v_add_u32_e32 v152, 0xa0, v150
	v_ashrrev_i32_e32 v153, 31, v152
	v_mul_f32_e32 v129, 0x45800000, v128
	v_cndmask_b32_e32 v132, v128, v129, vcc
	v_pk_mul_f32 v[130:131], v[46:47], v[132:133] op_sel_hi:[1,0]
	v_pk_mul_f32 v[128:129], v[44:45], v[132:133] op_sel_hi:[1,0]
	global_store_dwordx4 v[134:135], v[128:131], off
	s_nop 1
	v_pk_mul_f32 v[130:131], v[42:43], v[132:133] op_sel_hi:[1,0]
	v_pk_mul_f32 v[128:129], v[40:41], v[132:133] op_sel_hi:[1,0]
	global_store_dwordx4 v[134:135], v[128:131], off offset:16
	s_nop 1
	v_lshlrev_b64 v[128:129], 5, v[152:153]
	v_lshl_add_u64 v[132:133], s[0:1], 0, v[128:129]
	global_load_dwordx4 v[128:131], v[132:133], off offset:16
	s_nop 0
	global_load_dwordx4 v[132:135], v[132:133], off
	s_waitcnt vmcnt(0)
	v_mov_b32_e32 v154, v133
	v_mov_b32_e32 v155, v134
	v_mov_b32_e32 v133, v135
	v_pk_add_f32 v[132:133], v[154:155], v[132:133]
	v_mov_b32_e32 v134, v130
	v_mov_b32_e32 v135, v128
	v_mov_b32_e32 v128, v131
	v_pk_add_f32 v[128:129], v[134:135], v[128:129]
	v_add_f32_e32 v130, v132, v133
	v_add_f32_e32 v129, v130, v129
	v_add_f32_e32 v128, v128, v129
	v_fmamk_f32 v128, v128, 0x3a000000, v199
	v_cmp_gt_f32_e32 vcc, s9, v128
	v_mul_f32_e32 v129, 0x4b800000, v128
	v_lshlrev_b64 v[134:135], 7, v[152:153]
	v_cndmask_b32_e32 v128, v128, v129, vcc
	v_rsq_f32_e32 v128, v128
	v_lshl_add_u64 v[134:135], v[144:145], 0, v[134:135]
	v_add_u32_e32 v152, 0xb0, v150
	v_ashrrev_i32_e32 v153, 31, v152
	v_mul_f32_e32 v129, 0x45800000, v128
	v_cndmask_b32_e32 v132, v128, v129, vcc
	v_pk_mul_f32 v[130:131], v[30:31], v[132:133] op_sel_hi:[1,0]
	v_pk_mul_f32 v[128:129], v[28:29], v[132:133] op_sel_hi:[1,0]
	global_store_dwordx4 v[134:135], v[128:131], off
	s_nop 1
	v_pk_mul_f32 v[130:131], v[26:27], v[132:133] op_sel_hi:[1,0]
	v_pk_mul_f32 v[128:129], v[24:25], v[132:133] op_sel_hi:[1,0]
	global_store_dwordx4 v[134:135], v[128:131], off offset:16
	s_nop 1
	v_lshlrev_b64 v[128:129], 5, v[152:153]
	v_lshl_add_u64 v[132:133], s[0:1], 0, v[128:129]
	global_load_dwordx4 v[128:131], v[132:133], off offset:16
	s_nop 0
	global_load_dwordx4 v[132:135], v[132:133], off
	s_waitcnt vmcnt(0)
	v_mov_b32_e32 v154, v133
	v_mov_b32_e32 v155, v134
	v_mov_b32_e32 v133, v135
	v_pk_add_f32 v[132:133], v[154:155], v[132:133]
	v_mov_b32_e32 v134, v130
	v_mov_b32_e32 v135, v128
	v_mov_b32_e32 v128, v131
	v_pk_add_f32 v[128:129], v[134:135], v[128:129]
	v_add_f32_e32 v130, v132, v133
	v_add_f32_e32 v129, v130, v129
	v_add_f32_e32 v128, v128, v129
	v_fmamk_f32 v128, v128, 0x3a000000, v199
	v_cmp_gt_f32_e32 vcc, s9, v128
	v_mul_f32_e32 v129, 0x4b800000, v128
	v_lshlrev_b64 v[134:135], 7, v[152:153]
	v_cndmask_b32_e32 v128, v128, v129, vcc
	v_rsq_f32_e32 v128, v128
	v_lshl_add_u64 v[134:135], v[144:145], 0, v[134:135]
	v_mul_f32_e32 v129, 0x45800000, v128
	v_cndmask_b32_e32 v132, v128, v129, vcc
	v_pk_mul_f32 v[130:131], v[14:15], v[132:133] op_sel_hi:[1,0]
	v_pk_mul_f32 v[128:129], v[12:13], v[132:133] op_sel_hi:[1,0]
	global_store_dwordx4 v[134:135], v[128:131], off
	s_nop 1
	v_pk_mul_f32 v[130:131], v[10:11], v[132:133] op_sel_hi:[1,0]
	v_pk_mul_f32 v[128:129], v[8:9], v[132:133] op_sel_hi:[1,0]
	global_store_dwordx4 v[134:135], v[128:131], off offset:16

; DEV int otid() { int t = (int)threadIdx.x; asm volatile("" : "+v"(t)); return t; }
; template <class Epi>
; DEV void gemm_phase(LAS unsigned char* lds, const Gemm g, const StaticOrder& S, const Epi& E) {
;     const int tid = otid(), wid = __builtin_amdgcn_readfirstlane(tid >> 6), lane = tid & 63, wr = wid >> 2, wc = wid & 3, fr = lane & 15, fq = lane >> 4;
;     const int K = g.K, nt = K / BK;
;     unsigned voffA[2], voffB[2];
; #pragma unroll
;     for (int i = 0; i < 2; ++i) { int R, C; stage_rc(tid * 16 + i * 8192, R, C); const int Rb = Epi::PERM ? ((R & ~31) + perm32(R & 31)) : R;
;         voffA[i] = (unsigned)(R * K + C) * 2u; voffB[i] = (unsigned)(Rb * K + C) * 2u; }
;     const size_t kstep = (size_t)(BK * 2);
;     const size_t hstep = (size_t)HALF * K * 2;
;     const size_t tstep = 2 * hstep;
;     const unsigned ldsw = (unsigned)wid * 1024u;
;     const int aoff = lds_byte(wr * 64 + fr, fq * 8), boff = lds_byte(wc * 32 + fr, fq * 8);
;     ...
;     Unit cur, nxt; int ui = 0;
;     if (!S.next(0, cur)) return;
;     f32x4 acc[2][2][4][2];
; #pragma unroll
;     for (int a = 0; a < 2; ++a)
; #pragma unroll
;         for (int b = 0; b < 2; ++b)
; #pragma unroll
;             for (int m = 0; m < 4; ++m)
; #pragma unroll
;                 for (int n = 0; n < 2; ++n) acc[a][b][m][n] = (f32x4){0.f, 0.f, 0.f, 0.f};
;     bf16x8 At[4][2], B0[2][2], B1[2][2];
;     const char* cA = (const char*)g.A + (size_t)cur.pm * tstep; const char* cB = (const char*)g.Bt + (size_t)cur.pn * tstep;
;     PG8_STAGE(PG8_SB(0, 0), cB, voffB); PG8_STAGE(PG8_SA(0, 0), cA, voffA); PG8_STAGE(PG8_SB(0, 1), cB + hstep, voffB); PG8_STAGE(PG8_SA(0, 1), cA + hstep, voffA);
;     if (wr == 1) PG8_BAR;
;     PG8_WAIT_V(4); PG8_BAR;
;     PG8_STAGE(PG8_SB(1, 0), cB + kstep, voffB); PG8_STAGE(PG8_SA(1, 0), cA + kstep, voffA); PG8_STAGE(PG8_SB(1, 1), cB + hstep + kstep, voffB);
;     PG8_WAIT_V(6); PG8_BAR;
; DEV void run_phase(const P& p, int ph, LAS unsigned char* lds) {
;     ...
;     case L0_DN1: case L1_DN1: case L0_DN2: case L1_DN2: {
;         const int second = (ph == L0_DN2 || ph == L1_DN2) ? 1 : 0; const int k = 2 * L + second; const bool lastp = (ph == L1_DN2);
;         run_resid_gemm(lds, ACT, (const u16*)(ws + O_WDN + k * SZ_WDN), 5632, (ph == L0_DN1) ? p.x : XW, XW, 0.5f, lastp ? nullptr : XB, lastp ? nullptr : SS + (size_t)(4 * L + (second ? 4 : 1)) * 65536, bx, G);
.LBB0_641:
	v_readlane_b32 s8, v250, 7
	s_cmp_lg_u32 s8, 23
	v_readlane_b32 s0, v254, 26
	s_cselect_b64 s[18:19], -1, 0
	s_cmp_eq_u32 s8, 23
	v_readlane_b32 s1, v254, 27
	s_cselect_b64 s[6:7], -1, 0
	s_and_b64 s[0:1], s[0:1], exec
	v_readlane_b32 s9, v250, 8
	s_cselect_b32 s4, 4, 0
	s_cmp_eq_u32 s8, 13
	s_cselect_b64 s[8:9], -1, 0
	s_and_b64 s[0:1], s[8:9], exec
	s_cselect_b32 s0, 4, 1
	s_add_i32 s4, s4, s0
	s_lshl_b32 s0, s4, 18
	s_add_u32 s16, s74, s0
	s_addc_u32 s17, s75, 0
	v_readlane_b32 s0, v254, 23
	s_cmpk_lg_i32 s0, 0x100
	s_cselect_b64 s[0:1], -1, 0
	s_or_b64 s[4:5], s[6:7], s[0:1]
	v_cndmask_b32_e64 v0, 0, 1, s[14:15]
	v_cmp_ne_u32_e64 s[0:1], 1, v0
	s_andn2_b64 vcc, exec, s[14:15]
	s_xor_b64 s[20:21], s[4:5], -1
	s_cbranch_vccnz .LBB0_735
	s_or_b64 s[6:7], s[8:9], s[6:7]
	s_waitcnt lgkmcnt(0)
	v_ashrrev_i32_e32 v1, 31, v8
	v_cndmask_b32_e64 v0, 0, 1, s[6:7]
	v_readlane_b32 s6, v254, 26
	v_lshrrev_b32_e32 v1, 26, v1
	v_readlane_b32 s7, v254, 27
	v_add_u32_e32 v1, v8, v1
	s_and_b64 s[6:7], s[6:7], exec
	v_ashrrev_i32_e32 v9, 6, v1
	v_bfe_i32 v1, v8, 27, 1
	v_readfirstlane_b32 s7, v0
	v_lshlrev_b32_e32 v0, 4, v8
	v_lshrrev_b32_e32 v1, 22, v1
	v_add_u32_e32 v1, v0, v1
	v_and_b32_e32 v1, 0xfffffc00, v1
	v_sub_u32_e32 v1, v0, v1
	v_lshrrev_b32_e32 v2, 4, v1
	v_bitop3_b32 v2, v2, v1, 32 bitop3:0x6c
	v_ashrrev_i32_e32 v1, 31, v1
	v_lshrrev_b32_e32 v1, 26, v1
	v_lshlrev_b32_e32 v3, 3, v9
	v_add_u32_e32 v1, v2, v1
	v_and_b32_e32 v3, -16, v3
	v_ashrrev_i32_e32 v11, 6, v1
	s_cselect_b32 s6, 2, 0
	v_add_u32_e32 v1, v11, v3
	v_lshlrev_b32_e32 v3, 5, v9
	s_or_b32 s6, s6, s7
	v_and_b32_e32 v10, 32, v3
	v_mul_i32_i24_e32 v3, 64, v11
	s_mul_i32 s6, s6, 0x1600000
	v_readlane_b32 s8, v251, 63
	v_sub_u32_e32 v2, v2, v3
	s_add_u32 s38, s8, s6
	v_ashrrev_i16_sdwa v2, v203, sext(v2) dst_sel:DWORD dst_unused:UNUSED_PAD src0_sel:DWORD src1_sel:BYTE_0
	v_lshlrev_b32_e32 v3, 1, v1
	v_lshrrev_b32_e32 v4, 2, v1
	v_and_b32_e32 v5, 3, v11
	s_mov_b32 s8, 0x7fffe0
	v_bfe_i32 v12, v2, 0, 16
	v_and_b32_e32 v3, 24, v3
	v_and_b32_e32 v4, 4, v4
	v_and_or_b32 v5, v1, s8, v5
	s_movk_i32 s7, 0x1600
	v_add_u32_e32 v2, v10, v12
	v_or3_b32 v3, v5, v4, v3
	v_mul_lo_u32 v1, v1, s7
	v_add_lshl_u32 v174, v2, v1, 1
	v_mul_u32_u24_e32 v1, 0x1600, v3
	v_add_u32_e32 v0, 0x2000, v0
	v_add_lshl_u32 v160, v1, v2, 1
	v_ashrrev_i32_e32 v1, 31, v0
	v_lshrrev_b32_e32 v1, 22, v1
	v_add_u32_e32 v1, v0, v1
	v_ashrrev_i32_e32 v13, 10, v1
	v_mul_i32_i24_e32 v1, 0x400, v13
	v_sub_u32_e32 v0, v0, v1
	v_lshrrev_b32_e32 v1, 4, v0
	v_bitop3_b32 v0, v1, v0, 32 bitop3:0x6c
	v_ashrrev_i32_e32 v2, 31, v0
	v_lshrrev_b32_e32 v2, 26, v2
	v_lshlrev_b32_e32 v1, 3, v13
	v_add_u32_e32 v2, v0, v2
	v_readlane_b32 s9, v252, 0
	v_and_b32_e32 v1, -16, v1
	v_ashrrev_i32_e32 v15, 6, v2
	s_addc_u32 s39, s9, 0
	s_ashr_i32 s6, s37, 6
	v_add_u32_e32 v1, v15, v1
	v_lshlrev_b32_e32 v3, 5, v13
	v_and_b32_e32 v2, 0xc0, v2
	v_and_b32_e32 v4, 3, v15
	v_and_b32_e32 v14, 32, v3
	v_sub_u32_e32 v0, v0, v2
	v_lshlrev_b32_e32 v2, 1, v1
	v_lshrrev_b32_e32 v3, 2, v1
	v_and_or_b32 v4, v1, s8, v4
	v_mul_lo_u32 v1, v1, s7
	s_ashr_i32 s7, s37, 8
	s_lshl_b32 s40, s6, 10
	s_mul_i32 s11, s22, 0x2c0000
	v_ashrrev_i16_sdwa v0, v203, sext(v0) dst_sel:DWORD dst_unused:UNUSED_PAD src0_sel:DWORD src1_sel:BYTE_0
	s_mul_hi_i32 s10, s22, 0x2c0000
	s_add_u32 s30, s38, s11
	v_bfe_i32 v16, v0, 0, 16
	v_and_b32_e32 v2, 24, v2
	v_and_b32_e32 v3, 4, v3
	s_addc_u32 s31, s39, s10
	s_add_i32 s41, s40, 0
	v_add_u32_e32 v0, v14, v16
	v_or3_b32 v2, v4, v3, v2
	s_add_i32 m0, s41, 0x10000
	v_add_lshl_u32 v176, v0, v1, 1
	v_mul_u32_u24_e32 v1, 0x1600, v2
	s_mul_i32 s9, s23, 0x2c0000
	global_load_lds_dwordx4 v160, s[30:31]
	s_add_i32 m0, s41, 0x12000
	v_readlane_b32 s10, v250, 11
	v_add_lshl_u32 v178, v1, v0, 1
	s_mul_hi_i32 s8, s23, 0x2c0000
	v_readlane_b32 s11, v250, 12
	s_add_u32 s28, s10, s9
	global_load_lds_dwordx4 v178, s[30:31]
	s_addc_u32 s29, s11, s8
	s_mov_b32 m0, s41
	s_add_i32 s42, s41, 0x2000
	global_load_lds_dwordx4 v174, s[28:29]
	s_mov_b32 m0, s42
	s_add_u32 s8, s30, 0x160000
	global_load_lds_dwordx4 v176, s[28:29]
	s_addc_u32 s9, s31, 0
	s_add_i32 m0, s41, 0x14000
	v_mov_b32_e32 v179, v161
	global_load_lds_dwordx4 v160, s[8:9]
	s_add_i32 m0, s41, 0x16000
	v_mov_b32_e32 v175, v161
	global_load_lds_dwordx4 v178, s[8:9]
	s_add_u32 s8, s28, 0x160000
	s_addc_u32 s9, s29, 0
	s_add_i32 s43, s41, 0x4000
	s_mov_b32 m0, s43
	s_add_i32 s44, s41, 0x6000
	global_load_lds_dwordx4 v174, s[8:9]
	s_mov_b32 m0, s44
	v_mov_b32_e32 v177, v161
	global_load_lds_dwordx4 v176, s[8:9]
	v_lshl_add_u64 v[6:7], s[30:31], 0, v[160:161]
	v_lshl_add_u64 v[4:5], s[30:31], 0, v[178:179]
	v_lshl_add_u64 v[2:3], s[28:29], 0, v[174:175]
	s_cmp_lg_u32 s7, 1
	v_lshl_add_u64 v[0:1], s[28:29], 0, v[176:177]
	s_cbranch_scc1 .LBB0_644
	s_barrier
	s_setprio 1

; #define PG8_STAGE(bufoff, gbase, voff) do { _Pragma("unroll") for (int _i = 0; _i < 2; ++_i) \
;         __builtin_amdgcn_global_load_lds((const unsigned*)((const char*)(gbase) + (voff)[_i]), (LAS unsigned*)(lds + (bufoff) + ldsw + _i * 8192), 16, 0, 0); } while (0)
; #define PG8_LDA(dst, b, h) do { _Pragma("unroll") for (int m = 0; m < 4; ++m) _Pragma("unroll") for (int k = 0; k < 2; ++k) dst[m][k] = *(const LAS bf16x8*)(lds + PG8_SA(b, h) + aoff + m * 2048 + k * 1024); } while (0)
; #define PG8_LDB(dst, b, h) do { _Pragma("unroll") for (int n = 0; n < 2; ++n) _Pragma("unroll") for (int k = 0; k < 2; ++k) dst[n][k] = *(const LAS bf16x8*)(lds + PG8_SB(b, h) + boff + n * 2048 + k * 1024); } while (0)
; #define PG8_MMA(ai, bj, At, Bt) do { __builtin_amdgcn_s_setprio(1); _Pragma("unroll") for (int m = 0; m < 4; ++m) _Pragma("unroll") for (int n = 0; n < 2; ++n) _Pragma("unroll") for (int k = 0; k < 2; ++k) \
;         acc[ai][bj][m][n] = __builtin_amdgcn_mfma_f32_16x16x32_bf16(Bt[n][k], At[m][k], acc[ai][bj][m][n], 0, 0, 0); __builtin_amdgcn_s_setprio(0); } while (0)
; #define PG8_WAIT_V(n) asm volatile("s_waitcnt vmcnt(" #n ")" ::: "memory")
; #define PG8_WAIT_L(n) asm volatile("s_waitcnt lgkmcnt(" #n ")" ::: "memory")
; #define PG8_BAR __builtin_amdgcn_s_barrier()
; template <class Epi>
; DEV void gemm_phase(LAS unsigned char* lds, const Gemm g, const StaticOrder& S, const Epi& E) {
;     ...
;         for (int t = 0; t < nt; t += 2) {
;             const bool last = (t == nt - 2);
;             const char* a1 = cA + (size_t)(t + 1) * kstep;
;             const char* a2 = last ? nA : cA + (size_t)(t + 2) * kstep; const char* b2 = last ? nB : cB + (size_t)(t + 2) * kstep;
;             const char* a3 = a2 + kstep; const char* b3 = b2 + kstep;
;             PG8_LDB(B0, 0, 0); PG8_SCHED; PG8_LDA(At, 0, 0); PG8_STAGE(PG8_SA(1, 1), a1 + hstep, voffA);
;             PG8_WAIT_L(8); PG8_BAR; PG8_WAIT_L(0); PG8_MMA(0, 0, At, B0); PG8_BAR; PG8_SCHED;
;             PG8_LDB(B1, 0, 1); PG8_STAGE(PG8_SB(0, 0), b2, voffB);
;             PG8_BAR; PG8_WAIT_L(0); PG8_MMA(0, 1, At, B1); PG8_BAR;
;             PG8_LDA(At, 0, 1); PG8_STAGE(PG8_SA(0, 0), a2, voffA);
;             PG8_BAR; PG8_WAIT_L(0); PG8_MMA(1, 0, At, B0); PG8_BAR; PG8_SCHED;
;             PG8_STAGE(PG8_SB(0, 1), b2 + hstep, voffB);
;             PG8_WAIT_V(6); PG8_BAR; PG8_MMA(1, 1, At, B1); PG8_BAR;
.LBB0_657:
	s_add_u32 s6, s28, 0x100
	s_addc_u32 s7, s29, 0
	s_add_i32 s55, 0, 0x10000
	v_add_u32_e32 v140, s55, v196
	ds_read_b128 v[128:131], v140
	ds_read_b128 v[132:135], v140 offset:1024
	ds_read_b128 v[136:139], v140 offset:2048
	ds_read_b128 v[140:143], v140 offset:3072
	s_cmpk_eq_i32 s54, 0x54
	s_cselect_b32 s35, s27, s7
	s_cselect_b32 s34, s26, s6
	s_cselect_b32 s31, s9, s53
	s_cselect_b32 s30, s8, s52
	v_lshl_add_u64 v[214:215], s[28:29], 0, v[180:181]
	s_add_i32 m0, s41, 0xc000
	ds_read_b128 v[144:147], v219
	ds_read_b128 v[148:151], v219 offset:1024
	ds_read_b128 v[152:155], v219 offset:2048
	ds_read_b128 v[156:159], v219 offset:3072
	ds_read_b128 v[184:187], v219 offset:4096
	ds_read_b128 v[188:191], v219 offset:5120
	ds_read_b128 v[192:195], v219 offset:6144
	ds_read_b128 v[220:223], v219 offset:7168
	global_load_lds_dwordx4 v[214:215], off
	v_lshl_add_u64 v[214:215], s[28:29], 0, v[182:183]
	s_add_i32 m0, s41, 0xe000
	s_nop 0
	global_load_lds_dwordx4 v[214:215], off
	s_waitcnt lgkmcnt(8)
	s_barrier
	s_waitcnt lgkmcnt(0)
	v_mfma_f32_16x16x32_bf16 v[124:127], v[128:131], v[144:147], v[124:127]
	v_mfma_f32_16x16x32_bf16 v[120:123], v[136:139], v[144:147], v[120:123]
	v_mfma_f32_16x16x32_bf16 v[112:115], v[128:131], v[152:155], v[112:115]
	v_mfma_f32_16x16x32_bf16 v[104:107], v[136:139], v[152:155], v[104:107]
	v_mfma_f32_16x16x32_bf16 v[92:95], v[128:131], v[184:187], v[92:95]
	v_mfma_f32_16x16x32_bf16 v[88:91], v[136:139], v[184:187], v[88:91]
	v_mfma_f32_16x16x32_bf16 v[80:83], v[128:131], v[192:195], v[80:83]
	v_mfma_f32_16x16x32_bf16 v[72:75], v[136:139], v[192:195], v[72:75]
	v_mfma_f32_16x16x32_bf16 v[124:127], v[132:135], v[148:151], v[124:127]
	v_mfma_f32_16x16x32_bf16 v[120:123], v[140:143], v[148:151], v[120:123]
	v_mfma_f32_16x16x32_bf16 v[112:115], v[132:135], v[156:159], v[112:115]
	v_mfma_f32_16x16x32_bf16 v[104:107], v[140:143], v[156:159], v[104:107]
	v_mfma_f32_16x16x32_bf16 v[92:95], v[132:135], v[188:191], v[92:95]
	v_mfma_f32_16x16x32_bf16 v[88:91], v[140:143], v[188:191], v[88:91]
	v_mfma_f32_16x16x32_bf16 v[80:83], v[132:135], v[220:223], v[80:83]
	v_mfma_f32_16x16x32_bf16 v[72:75], v[140:143], v[220:223], v[72:75]
	s_barrier
	s_add_i32 s56, 0, 0x14000
	v_add_u32_e32 v214, s56, v196
	s_add_i32 s28, s55, s40
	ds_read_b128 v[224:227], v214
	ds_read_b128 v[228:231], v214 offset:1024
	ds_read_b128 v[232:235], v214 offset:2048
	ds_read_b128 v[236:239], v214 offset:3072
	v_lshl_add_u64 v[214:215], s[30:31], 0, v[160:161]
	s_mov_b32 m0, s28
	v_lshl_add_u64 v[216:217], s[30:31], 0, v[178:179]
	global_load_lds_dwordx4 v[214:215], off
	s_add_i32 m0, s28, 0x2000
	s_nop 0
	global_load_lds_dwordx4 v[216:217], off
	s_barrier
	s_waitcnt lgkmcnt(0)
	v_mfma_f32_16x16x32_bf16 v[116:119], v[224:227], v[144:147], v[116:119]
	v_mfma_f32_16x16x32_bf16 v[108:111], v[232:235], v[144:147], v[108:111]
	v_mfma_f32_16x16x32_bf16 v[100:103], v[224:227], v[152:155], v[100:103]
	v_mfma_f32_16x16x32_bf16 v[96:99], v[232:235], v[152:155], v[96:99]
	v_mfma_f32_16x16x32_bf16 v[84:87], v[224:227], v[184:187], v[84:87]
	v_mfma_f32_16x16x32_bf16 v[76:79], v[232:235], v[184:187], v[76:79]
	v_mfma_f32_16x16x32_bf16 v[68:71], v[224:227], v[192:195], v[68:71]
	v_mfma_f32_16x16x32_bf16 v[64:67], v[232:235], v[192:195], v[64:67]
	v_mfma_f32_16x16x32_bf16 v[116:119], v[228:231], v[148:151], v[116:119]
	v_mfma_f32_16x16x32_bf16 v[108:111], v[236:239], v[148:151], v[108:111]
	v_mfma_f32_16x16x32_bf16 v[100:103], v[228:231], v[156:159], v[100:103]
	v_mfma_f32_16x16x32_bf16 v[96:99], v[236:239], v[156:159], v[96:99]
	v_mfma_f32_16x16x32_bf16 v[84:87], v[228:231], v[188:191], v[84:87]
	v_mfma_f32_16x16x32_bf16 v[76:79], v[236:239], v[188:191], v[76:79]
	v_mfma_f32_16x16x32_bf16 v[68:71], v[228:231], v[220:223], v[68:71]
	v_mfma_f32_16x16x32_bf16 v[64:67], v[236:239], v[220:223], v[64:67]
	s_mov_b32 m0, s41
	v_lshl_add_u64 v[240:241], s[34:35], 0, v[174:175]
	s_barrier
	ds_read_b128 v[144:147], v219 offset:16384
	ds_read_b128 v[148:151], v219 offset:17408
	ds_read_b128 v[152:155], v219 offset:18432
	ds_read_b128 v[156:159], v219 offset:19456
	ds_read_b128 v[184:187], v219 offset:20480
	ds_read_b128 v[188:191], v219 offset:21504
	ds_read_b128 v[192:195], v219 offset:22528
	ds_read_b128 v[220:223], v219 offset:23552
	global_load_lds_dwordx4 v[240:241], off
	v_lshl_add_u64 v[242:243], s[34:35], 0, v[176:177]
	s_mov_b32 m0, s42
	s_nop 0
	global_load_lds_dwordx4 v[242:243], off
	s_barrier
	s_waitcnt lgkmcnt(0)
	v_mfma_f32_16x16x32_bf16 v[60:63], v[128:131], v[144:147], v[60:63]
	v_mfma_f32_16x16x32_bf16 v[56:59], v[136:139], v[144:147], v[56:59]
	v_mfma_f32_16x16x32_bf16 v[48:51], v[128:131], v[152:155], v[48:51]
	v_mfma_f32_16x16x32_bf16 v[40:43], v[136:139], v[152:155], v[40:43]
	v_mfma_f32_16x16x32_bf16 v[28:31], v[128:131], v[184:187], v[28:31]
	v_mfma_f32_16x16x32_bf16 v[24:27], v[136:139], v[184:187], v[24:27]
	v_mfma_f32_16x16x32_bf16 v[16:19], v[128:131], v[192:195], v[16:19]
	v_mfma_f32_16x16x32_bf16 v[8:11], v[136:139], v[192:195], v[8:11]
	v_mfma_f32_16x16x32_bf16 v[60:63], v[132:135], v[148:151], v[60:63]
	v_mfma_f32_16x16x32_bf16 v[56:59], v[140:143], v[148:151], v[56:59]
	v_mfma_f32_16x16x32_bf16 v[48:51], v[132:135], v[156:159], v[48:51]
	v_mfma_f32_16x16x32_bf16 v[40:43], v[140:143], v[156:159], v[40:43]
	v_mfma_f32_16x16x32_bf16 v[28:31], v[132:135], v[188:191], v[28:31]
	v_mfma_f32_16x16x32_bf16 v[24:27], v[140:143], v[188:191], v[24:27]
	v_mfma_f32_16x16x32_bf16 v[16:19], v[132:135], v[220:223], v[16:19]
	v_mfma_f32_16x16x32_bf16 v[8:11], v[140:143], v[220:223], v[8:11]
	s_barrier
; #define PG8_STAGE(bufoff, gbase, voff) do { _Pragma("unroll") for (int _i = 0; _i < 2; ++_i) \
;         __builtin_amdgcn_global_load_lds((const unsigned*)((const char*)(gbase) + (voff)[_i]), (LAS unsigned*)(lds + (bufoff) + ldsw + _i * 8192), 16, 0, 0); } while (0)
; #define PG8_LDA(dst, b, h) do { _Pragma("unroll") for (int m = 0; m < 4; ++m) _Pragma("unroll") for (int k = 0; k < 2; ++k) dst[m][k] = *(const LAS bf16x8*)(lds + PG8_SA(b, h) + aoff + m * 2048 + k * 1024); } while (0)
; #define PG8_LDB(dst, b, h) do { _Pragma("unroll") for (int n = 0; n < 2; ++n) _Pragma("unroll") for (int k = 0; k < 2; ++k) dst[n][k] = *(const LAS bf16x8*)(lds + PG8_SB(b, h) + boff + n * 2048 + k * 1024); } while (0)
; #define PG8_MMA(ai, bj, At, Bt) do { __builtin_amdgcn_s_setprio(1); _Pragma("unroll") for (int m = 0; m < 4; ++m) _Pragma("unroll") for (int n = 0; n < 2; ++n) _Pragma("unroll") for (int k = 0; k < 2; ++k) \
;         acc[ai][bj][m][n] = __builtin_amdgcn_mfma_f32_16x16x32_bf16(Bt[n][k], At[m][k], acc[ai][bj][m][n], 0, 0, 0); __builtin_amdgcn_s_setprio(0); } while (0)
; #define PG8_WAIT_V(n) asm volatile("s_waitcnt vmcnt(" #n ")" ::: "memory")
; #define PG8_WAIT_L(n) asm volatile("s_waitcnt lgkmcnt(" #n ")" ::: "memory")
; #define PG8_BAR __builtin_amdgcn_s_barrier()
; #define PG8_SCHED __builtin_amdgcn_sched_barrier(0)
; template <class Epi>
; DEV void gemm_phase(LAS unsigned char* lds, const Gemm g, const StaticOrder& S, const Epi& E) {
;     ...
;             PG8_STAGE(PG8_SB(0, 1), b2 + hstep, voffB);
;             PG8_WAIT_V(6); PG8_BAR; PG8_MMA(1, 1, At, B1); PG8_BAR;
;             PG8_LDB(B0, 1, 0); PG8_SCHED; PG8_LDA(At, 1, 0); PG8_STAGE(PG8_SA(0, 1), a2 + hstep, voffA);
;             PG8_WAIT_L(8); PG8_BAR; PG8_WAIT_L(0); PG8_MMA(0, 0, At, B0); PG8_BAR; PG8_SCHED;
;             PG8_LDB(B1, 1, 1); PG8_STAGE(PG8_SB(1, 0), b3, voffB);
;             PG8_BAR; PG8_WAIT_L(0); PG8_MMA(0, 1, At, B1); PG8_BAR;
;             PG8_LDA(At, 1, 1); PG8_STAGE(PG8_SA(1, 0), a3, voffA);
;             PG8_BAR; PG8_WAIT_L(0); PG8_MMA(1, 0, At, B0); PG8_BAR; PG8_SCHED;
	s_add_u32 s28, s30, 0x160000
	s_addc_u32 s29, s31, 0
	s_add_i32 s55, s56, s40
	v_lshl_add_u64 v[128:129], s[28:29], 0, v[160:161]
	s_mov_b32 m0, s55
	s_nop 0
	global_load_lds_dwordx4 v[128:129], off
	v_lshl_add_u64 v[128:129], s[28:29], 0, v[178:179]
	s_add_i32 m0, s55, 0x2000
	s_nop 0
	global_load_lds_dwordx4 v[128:129], off
	s_waitcnt vmcnt(6)
	s_barrier
	v_mfma_f32_16x16x32_bf16 v[52:55], v[224:227], v[144:147], v[52:55]
	v_mfma_f32_16x16x32_bf16 v[44:47], v[232:235], v[144:147], v[44:47]
	v_mfma_f32_16x16x32_bf16 v[36:39], v[224:227], v[152:155], v[36:39]
	v_mfma_f32_16x16x32_bf16 v[32:35], v[232:235], v[152:155], v[32:35]
	v_mfma_f32_16x16x32_bf16 v[20:23], v[224:227], v[184:187], v[20:23]
	v_mfma_f32_16x16x32_bf16 v[12:15], v[232:235], v[184:187], v[12:15]
	v_mfma_f32_16x16x32_bf16 v[4:7], v[224:227], v[192:195], v[4:7]
	v_mfma_f32_16x16x32_bf16 v[0:3], v[232:235], v[192:195], v[0:3]
	v_mfma_f32_16x16x32_bf16 v[52:55], v[228:231], v[148:151], v[52:55]
	v_mfma_f32_16x16x32_bf16 v[44:47], v[236:239], v[148:151], v[44:47]
	v_mfma_f32_16x16x32_bf16 v[36:39], v[228:231], v[156:159], v[36:39]
	v_mfma_f32_16x16x32_bf16 v[32:35], v[236:239], v[156:159], v[32:35]
	v_mfma_f32_16x16x32_bf16 v[20:23], v[228:231], v[188:191], v[20:23]
	v_mfma_f32_16x16x32_bf16 v[12:15], v[236:239], v[188:191], v[12:15]
	v_mfma_f32_16x16x32_bf16 v[4:7], v[228:231], v[220:223], v[4:7]
	v_mfma_f32_16x16x32_bf16 v[0:3], v[236:239], v[220:223], v[0:3]
	s_add_i32 s55, 0, 0x18000
	v_add_u32_e32 v140, s55, v196
	s_barrier
	ds_read_b128 v[128:131], v140
	ds_read_b128 v[132:135], v140 offset:1024
	ds_read_b128 v[136:139], v140 offset:2048
	ds_read_b128 v[140:143], v140 offset:3072
	s_add_u32 s28, s34, 0x160000
	s_addc_u32 s29, s35, 0
	s_mov_b32 m0, s43
	v_lshl_add_u64 v[224:225], s[28:29], 0, v[174:175]
	ds_read_b128 v[144:147], v219 offset:32768
	ds_read_b128 v[148:151], v219 offset:33792
	ds_read_b128 v[152:155], v219 offset:34816
	ds_read_b128 v[156:159], v219 offset:35840
	ds_read_b128 v[184:187], v219 offset:36864
	ds_read_b128 v[188:191], v219 offset:37888
	ds_read_b128 v[192:195], v219 offset:38912
	ds_read_b128 v[220:223], v219 offset:39936
	global_load_lds_dwordx4 v[224:225], off
	v_lshl_add_u64 v[224:225], s[28:29], 0, v[176:177]
	s_mov_b32 m0, s44
	s_nop 0
	global_load_lds_dwordx4 v[224:225], off
	s_waitcnt lgkmcnt(8)
	s_barrier
	s_waitcnt lgkmcnt(0)
	v_mfma_f32_16x16x32_bf16 v[124:127], v[128:131], v[144:147], v[124:127]
	v_mfma_f32_16x16x32_bf16 v[120:123], v[136:139], v[144:147], v[120:123]
	v_mfma_f32_16x16x32_bf16 v[112:115], v[128:131], v[152:155], v[112:115]
	v_mfma_f32_16x16x32_bf16 v[104:107], v[136:139], v[152:155], v[104:107]
	v_mfma_f32_16x16x32_bf16 v[92:95], v[128:131], v[184:187], v[92:95]
	v_mfma_f32_16x16x32_bf16 v[88:91], v[136:139], v[184:187], v[88:91]
	v_mfma_f32_16x16x32_bf16 v[80:83], v[128:131], v[192:195], v[80:83]
	v_mfma_f32_16x16x32_bf16 v[72:75], v[136:139], v[192:195], v[72:75]
	v_mfma_f32_16x16x32_bf16 v[124:127], v[132:135], v[148:151], v[124:127]
	v_mfma_f32_16x16x32_bf16 v[120:123], v[140:143], v[148:151], v[120:123]
	v_mfma_f32_16x16x32_bf16 v[112:115], v[132:135], v[156:159], v[112:115]
	v_mfma_f32_16x16x32_bf16 v[104:107], v[140:143], v[156:159], v[104:107]
	v_mfma_f32_16x16x32_bf16 v[92:95], v[132:135], v[188:191], v[92:95]
	v_mfma_f32_16x16x32_bf16 v[88:91], v[140:143], v[188:191], v[88:91]
	v_mfma_f32_16x16x32_bf16 v[80:83], v[132:135], v[220:223], v[80:83]
	v_mfma_f32_16x16x32_bf16 v[72:75], v[140:143], v[220:223], v[72:75]
	s_barrier
	s_add_i32 s34, 0, 0x1c000
	s_add_i32 s28, s55, s40
	v_add_u32_e32 v236, s34, v196
	v_lshl_add_u64 v[214:215], v[214:215], 0, s[2:3]
	s_mov_b32 m0, s28
	ds_read_b128 v[224:227], v236
	ds_read_b128 v[228:231], v236 offset:1024
	ds_read_b128 v[232:235], v236 offset:2048
	ds_read_b128 v[236:239], v236 offset:3072
	global_load_lds_dwordx4 v[214:215], off
	v_lshl_add_u64 v[214:215], v[216:217], 0, s[2:3]
	s_add_i32 m0, s28, 0x2000
	s_nop 0
	global_load_lds_dwordx4 v[214:215], off
	s_barrier
	s_waitcnt lgkmcnt(0)
	v_mfma_f32_16x16x32_bf16 v[116:119], v[224:227], v[144:147], v[116:119]
	v_mfma_f32_16x16x32_bf16 v[108:111], v[232:235], v[144:147], v[108:111]
	v_mfma_f32_16x16x32_bf16 v[100:103], v[224:227], v[152:155], v[100:103]
	v_mfma_f32_16x16x32_bf16 v[96:99], v[232:235], v[152:155], v[96:99]
	v_mfma_f32_16x16x32_bf16 v[84:87], v[224:227], v[184:187], v[84:87]
	v_mfma_f32_16x16x32_bf16 v[76:79], v[232:235], v[184:187], v[76:79]
	v_mfma_f32_16x16x32_bf16 v[68:71], v[224:227], v[192:195], v[68:71]
	v_mfma_f32_16x16x32_bf16 v[64:67], v[232:235], v[192:195], v[64:67]
	v_mfma_f32_16x16x32_bf16 v[116:119], v[228:231], v[148:151], v[116:119]
	v_mfma_f32_16x16x32_bf16 v[108:111], v[236:239], v[148:151], v[108:111]
	v_mfma_f32_16x16x32_bf16 v[100:103], v[228:231], v[156:159], v[100:103]
	v_mfma_f32_16x16x32_bf16 v[96:99], v[236:239], v[156:159], v[96:99]
	v_mfma_f32_16x16x32_bf16 v[84:87], v[228:231], v[188:191], v[84:87]
	v_mfma_f32_16x16x32_bf16 v[76:79], v[236:239], v[188:191], v[76:79]
	v_mfma_f32_16x16x32_bf16 v[68:71], v[228:231], v[220:223], v[68:71]
	v_mfma_f32_16x16x32_bf16 v[64:67], v[236:239], v[220:223], v[64:67]
	s_mov_b32 m0, s45
	v_lshl_add_u64 v[214:215], v[240:241], 0, s[2:3]
	s_barrier
	ds_read_b128 v[144:147], v219 offset:49152
	ds_read_b128 v[148:151], v219 offset:50176
	ds_read_b128 v[152:155], v219 offset:51200
	ds_read_b128 v[156:159], v219 offset:52224
	ds_read_b128 v[184:187], v219 offset:53248
	ds_read_b128 v[188:191], v219 offset:54272
	ds_read_b128 v[192:195], v219 offset:55296
	ds_read_b128 v[220:223], v219 offset:56320
	global_load_lds_dwordx4 v[214:215], off
	v_lshl_add_u64 v[214:215], v[242:243], 0, s[2:3]
	s_mov_b32 m0, s46
	s_nop 0
	global_load_lds_dwordx4 v[214:215], off
	s_barrier
; DEV bf16x8 pack8(f32x4 a, f32x4 b) { u32x4 w; w.x = cvt_pk_bf16(a[0], a[1]); w.y = cvt_pk_bf16(a[2], a[3]); w.z = cvt_pk_bf16(b[0], b[1]); w.w = cvt_pk_bf16(b[2], b[3]); return __builtin_bit_cast(bf16x8, w); }
; #define PG8_WAIT_V(n) asm volatile("s_waitcnt vmcnt(" #n ")" ::: "memory")
; #define PG8_WAIT_L(n) asm volatile("s_waitcnt lgkmcnt(" #n ")" ::: "memory")
; #define PG8_BAR __builtin_amdgcn_s_barrier()
; #define PG8_SCHED __builtin_amdgcn_sched_barrier(0)
; template <class Epi>
; DEV void gemm_phase(LAS unsigned char* lds, const Gemm g, const StaticOrder& S, const Epi& E) {
;     ...
;             PG8_BAR; PG8_WAIT_L(0); PG8_MMA(1, 0, At, B0); PG8_BAR; PG8_SCHED;
;             PG8_STAGE(PG8_SB(1, 1), b3 + hstep, voffB);
;             PG8_WAIT_V(6); PG8_BAR; PG8_MMA(1, 1, At, B1); PG8_BAR;
;     DEV void operator()(AccRef acc, const pg8::Unit& u, int wr, int wc, int fr, int fq) const {
;         const int row0 = u.pm * 256 + wr * 64 + fr, col0 = u.pn * 256 + wc * 32 + 8 * fq;
; #pragma unroll
;         for (int am = 0; am < 4; ++am) { const int ai = am >> 1, m0 = (am & 1) * 2;
;             f32x4 bv[4][2][2];
; #pragma unroll
;             for (int m = m0; m < m0 + 2; ++m)
; #pragma unroll
;                 for (int bj = 0; bj < 2; ++bj)
; #pragma unroll
;                     for (int n = 0; n < 2; ++n) bv[m][bj][n] = *(const f32x4*)(base + (size_t)(row0 + ai * 128 + m * 16) * 2048 + col0 + bj * 128 + n * 4);
; #pragma unroll
;             for (int m = m0; m < m0 + 2; ++m) { const size_t off = (size_t)(row0 + ai * 128 + m * 16) * 2048 + col0; float sq = 0.f;
; #pragma unroll
;                 for (int bj = 0; bj < 2; ++bj) { const f32x4 o0 = bv[m][bj][0] + scale * acc[ai][bj][m][0], o1 = bv[m][bj][1] + scale * acc[ai][bj][m][1];
;                     *(f32x4*)(out + off + bj * 128) = o0; *(f32x4*)(out + off + bj * 128 + 4) = o1;
;                     if (xb) { *(u32x4*)(xb + off + bj * 128) = __builtin_bit_cast(u32x4, pack8(o0, o1));
;                         sq += (o0[0] * o0[0] + o0[1] * o0[1] + o0[2] * o0[2] + o0[3] * o0[3]) + (o1[0] * o1[0] + o1[1] * o1[1] + o1[2] * o1[2] + o1[3] * o1[3]); } }
;                 if (ssout) { sq += __shfl_xor(sq, 16); sq += __shfl_xor(sq, 32);
;                     if (fq == 0) { if (red) red[(ai * 128 + wr * 64 + m * 16 + fr) * 4 + wc] = sq; else atomicAdd(ssout + (size_t)(row0 + ai * 128 + m * 16) * 8 + u.pn, sq); } } }
	s_waitcnt lgkmcnt(0)
	v_mfma_f32_16x16x32_bf16 v[60:63], v[128:131], v[144:147], v[60:63]
	v_mfma_f32_16x16x32_bf16 v[56:59], v[136:139], v[144:147], v[56:59]
	v_mfma_f32_16x16x32_bf16 v[48:51], v[128:131], v[152:155], v[48:51]
	v_mfma_f32_16x16x32_bf16 v[40:43], v[136:139], v[152:155], v[40:43]
	v_mfma_f32_16x16x32_bf16 v[28:31], v[128:131], v[184:187], v[28:31]
	v_mfma_f32_16x16x32_bf16 v[24:27], v[136:139], v[184:187], v[24:27]
	v_mfma_f32_16x16x32_bf16 v[16:19], v[128:131], v[192:195], v[16:19]
	v_mfma_f32_16x16x32_bf16 v[8:11], v[136:139], v[192:195], v[8:11]
	v_mfma_f32_16x16x32_bf16 v[60:63], v[132:135], v[148:151], v[60:63]
	v_mfma_f32_16x16x32_bf16 v[56:59], v[140:143], v[148:151], v[56:59]
	v_mfma_f32_16x16x32_bf16 v[48:51], v[132:135], v[156:159], v[48:51]
	v_mfma_f32_16x16x32_bf16 v[40:43], v[140:143], v[156:159], v[40:43]
	v_mfma_f32_16x16x32_bf16 v[28:31], v[132:135], v[188:191], v[28:31]
	v_mfma_f32_16x16x32_bf16 v[24:27], v[140:143], v[188:191], v[24:27]
	v_mfma_f32_16x16x32_bf16 v[16:19], v[132:135], v[220:223], v[16:19]
	v_mfma_f32_16x16x32_bf16 v[8:11], v[140:143], v[220:223], v[8:11]
	s_barrier
	s_add_u32 s28, s30, 0x160080
	s_addc_u32 s29, s31, 0
	s_add_i32 s30, s34, s40
	v_lshl_add_u64 v[128:129], s[28:29], 0, v[160:161]
	s_mov_b32 m0, s30
	s_nop 0
	global_load_lds_dwordx4 v[128:129], off
	v_lshl_add_u64 v[128:129], s[28:29], 0, v[178:179]
	s_add_i32 m0, s30, 0x2000
	s_nop 0
	global_load_lds_dwordx4 v[128:129], off
	s_waitcnt vmcnt(6)
	s_barrier
	v_mfma_f32_16x16x32_bf16 v[52:55], v[224:227], v[144:147], v[52:55]
	v_mfma_f32_16x16x32_bf16 v[44:47], v[232:235], v[144:147], v[44:47]
	v_mfma_f32_16x16x32_bf16 v[36:39], v[224:227], v[152:155], v[36:39]
	v_mfma_f32_16x16x32_bf16 v[32:35], v[232:235], v[152:155], v[32:35]
	v_mfma_f32_16x16x32_bf16 v[20:23], v[224:227], v[184:187], v[20:23]
	v_mfma_f32_16x16x32_bf16 v[12:15], v[232:235], v[184:187], v[12:15]
	v_mfma_f32_16x16x32_bf16 v[4:7], v[224:227], v[192:195], v[4:7]
	v_mfma_f32_16x16x32_bf16 v[0:3], v[232:235], v[192:195], v[0:3]
	v_mfma_f32_16x16x32_bf16 v[52:55], v[228:231], v[148:151], v[52:55]
	v_mfma_f32_16x16x32_bf16 v[44:47], v[236:239], v[148:151], v[44:47]
	v_mfma_f32_16x16x32_bf16 v[36:39], v[228:231], v[156:159], v[36:39]
	v_mfma_f32_16x16x32_bf16 v[32:35], v[236:239], v[156:159], v[32:35]
	v_mfma_f32_16x16x32_bf16 v[20:23], v[228:231], v[188:191], v[20:23]
	v_mfma_f32_16x16x32_bf16 v[12:15], v[236:239], v[188:191], v[12:15]
	v_mfma_f32_16x16x32_bf16 v[4:7], v[228:231], v[220:223], v[4:7]
	v_mfma_f32_16x16x32_bf16 v[0:3], v[236:239], v[220:223], v[0:3]
	s_add_i32 s54, s54, 2
	s_add_u32 s52, s52, 0x100
	s_addc_u32 s53, s53, 0
	s_cmpk_gt_u32 s54, 0x55
	s_mov_b64 s[28:29], s[6:7]
	s_barrier
	s_cbranch_scc0 .LBB0_657
	v_lshl_add_u32 v186, s23, 8, v167
	v_lshl_or_b32 v184, s22, 8, v197
	v_ashrrev_i32_e32 v185, 31, v184
	v_ashrrev_i32_e32 v187, 31, v186
	v_lshl_add_u64 v[188:189], v[184:185], 2, s[24:25]
	v_lshlrev_b64 v[128:129], 13, v[186:187]
	v_or_b32_e32 v190, 16, v186
	v_lshl_add_u64 v[128:129], v[188:189], 0, v[128:129]
	v_ashrrev_i32_e32 v191, 31, v190
	global_load_dwordx4 v[152:155], v[128:129], off offset:16
	global_load_dwordx4 v[156:159], v[128:129], off
	global_load_dwordx4 v[144:147], v[128:129], off offset:528
	global_load_dwordx4 v[148:151], v[128:129], off offset:512
	v_lshlrev_b64 v[128:129], 13, v[190:191]
	v_lshl_add_u64 v[132:133], v[188:189], 0, v[128:129]
	global_load_dwordx4 v[136:139], v[132:133], off offset:16
	global_load_dwordx4 v[140:143], v[132:133], off
	global_load_dwordx4 v[128:131], v[132:133], off offset:528
	s_nop 0
	global_load_dwordx4 v[132:135], v[132:133], off offset:512
	v_lshlrev_b64 v[192:193], 11, v[186:187]
	v_lshl_add_u64 v[194:195], v[192:193], 0, v[184:185]
	s_ashr_i32 s23, s22, 31
	v_lshl_add_u64 v[192:193], v[194:195], 2, s[68:69]
	s_mov_b64 s[28:29], -1
	s_andn2_b64 vcc, exec, s[18:19]
	s_waitcnt vmcnt(0)
	v_pk_fma_f32 v[152:153], v[120:121], 0.5, v[152:153] op_sel_hi:[1,0,1]
	v_cndmask_b32_e64 v120, 0, 1, s[18:19]
	v_pk_fma_f32 v[158:159], v[126:127], 0.5, v[158:159] op_sel_hi:[1,0,1]
	v_pk_fma_f32 v[156:157], v[124:125], 0.5, v[156:157] op_sel_hi:[1,0,1]
	v_pk_fma_f32 v[154:155], v[122:123], 0.5, v[154:155] op_sel_hi:[1,0,1]
	v_cmp_ne_u32_e64 s[6:7], 1, v120
	v_pk_fma_f32 v[120:121], v[116:117], 0.5, v[148:149] op_sel_hi:[1,0,1]
	v_pk_fma_f32 v[124:125], v[108:109], 0.5, v[144:145] op_sel_hi:[1,0,1]
	global_store_dwordx4 v[192:193], v[156:159], off
	global_store_dwordx4 v[192:193], v[152:155], off offset:16
	s_cbranch_vccnz .LBB0_665
	v_mul_f32_e32 v108, v157, v157
	v_mul_f32_e32 v109, v153, v153
	v_fmac_f32_e32 v108, v156, v156
	v_fmac_f32_e32 v109, v152, v152
	v_fmac_f32_e32 v108, v158, v158
	v_fmac_f32_e32 v109, v154, v154
	v_fmac_f32_e32 v108, v159, v159
	v_fmac_f32_e32 v109, v155, v155
	v_add_f32_e32 v108, v108, v109
	v_mul_f32_e32 v109, v121, v121
	v_mul_f32_e32 v144, v125, v125
	v_pk_fma_f32 v[122:123], v[118:119], 0.5, v[150:151] op_sel_hi:[1,0,1]
	v_pk_fma_f32 v[126:127], v[110:111], 0.5, v[146:147] op_sel_hi:[1,0,1]
	v_fmac_f32_e32 v109, v120, v120
	v_fmac_f32_e32 v144, v124, v124
	v_fmac_f32_e32 v109, v122, v122
	v_fmac_f32_e32 v144, v126, v126
	v_fmac_f32_e32 v109, v123, v123
	v_fmac_f32_e32 v144, v127, v127
	v_add_f32_e32 v109, v109, v144
	v_cmp_lt_i32_e32 vcc, v208, v206
	v_add_f32_e32 v108, v108, v109
	v_readlane_b32 s28, v250, 9
	v_cndmask_b32_e32 v109, v204, v208, vcc
	v_lshlrev_b32_e32 v109, 2, v109
	ds_bpermute_b32 v109, v109, v108
	v_cmp_lt_i32_e32 vcc, v207, v206
	v_readlane_b32 s29, v250, 10
	v_cvt_pk_bf16_f32 v220, v156, v157
	v_cvt_pk_bf16_f32 v221, v158, v159
	s_waitcnt lgkmcnt(0)
	v_add_f32_e32 v108, v108, v109
	v_cndmask_b32_e32 v109, v204, v207, vcc
	v_lshlrev_b32_e32 v109, 2, v109
	ds_bpermute_b32 v109, v109, v108
	v_cvt_pk_bf16_f32 v222, v152, v153
	v_cvt_pk_bf16_f32 v223, v154, v155
	v_lshl_add_u64 v[116:117], v[194:195], 1, s[28:29]
	v_cvt_pk_bf16_f32 v152, v120, v121
	v_cvt_pk_bf16_f32 v153, v122, v123
	v_cvt_pk_bf16_f32 v154, v124, v125
	v_cvt_pk_bf16_f32 v155, v126, v127
	global_store_dwordx4 v[116:117], v[220:223], off
	global_store_dwordx4 v[192:193], v[120:123], off offset:512
	global_store_dwordx4 v[192:193], v[124:127], off offset:528
	global_store_dwordx4 v[116:117], v[152:155], off offset:256
	s_and_saveexec_b64 s[28:29], s[10:11]
	s_cbranch_execz .LBB0_664
	s_waitcnt lgkmcnt(0)
	v_add_f32_e32 v108, v108, v109
	s_andn2_b64 vcc, exec, s[20:21]
	s_mov_b64 s[30:31], -1
	s_cbranch_vccnz .LBB0_662
	s_mov_b64 s[30:31], 0
	ds_write_b32 v218, v108

; DEV int otid() { int t = (int)threadIdx.x; asm volatile("" : "+v"(t)); return t; }
; #define PG8_WAIT_V(n) asm volatile("s_waitcnt vmcnt(" #n ")" ::: "memory")
; template <class Epi>
; DEV void gemm_phase(LAS unsigned char* lds, const Gemm g, const StaticOrder& S, const Epi& E) {
;     const int tid = otid(), wid = __builtin_amdgcn_readfirstlane(tid >> 6), lane = tid & 63, wr = wid >> 2, wc = wid & 3, fr = lane & 15, fq = lane >> 4;
;     const int K = g.K, nt = K / BK;
;     unsigned voffA[2], voffB[2];
; #pragma unroll
;     for (int i = 0; i < 2; ++i) { int R, C; stage_rc(tid * 16 + i * 8192, R, C); const int Rb = Epi::PERM ? ((R & ~31) + perm32(R & 31)) : R;
;         voffA[i] = (unsigned)(R * K + C) * 2u; voffB[i] = (unsigned)(Rb * K + C) * 2u; }
;     const size_t kstep = (size_t)(BK * 2);
;     const size_t hstep = (size_t)HALF * K * 2;
;     const size_t tstep = 2 * hstep;
;     const unsigned ldsw = (unsigned)wid * 1024u;
;     const int aoff = lds_byte(wr * 64 + fr, fq * 8), boff = lds_byte(wc * 32 + fr, fq * 8);
;     ...
;     Unit cur, nxt; int ui = 0;
;     if (!S.next(0, cur)) return;
;     f32x4 acc[2][2][4][2];
; #pragma unroll
;     for (int a = 0; a < 2; ++a)
; #pragma unroll
;         for (int b = 0; b < 2; ++b)
; #pragma unroll
;             for (int m = 0; m < 4; ++m)
; #pragma unroll
;                 for (int n = 0; n < 2; ++n) acc[a][b][m][n] = (f32x4){0.f, 0.f, 0.f, 0.f};
;     bf16x8 At[4][2], B0[2][2], B1[2][2];
;     const char* cA = (const char*)g.A + (size_t)cur.pm * tstep; const char* cB = (const char*)g.Bt + (size_t)cur.pn * tstep;
;     PG8_STAGE(PG8_SB(0, 0), cB, voffB); PG8_STAGE(PG8_SA(0, 0), cA, voffA); PG8_STAGE(PG8_SB(0, 1), cB + hstep, voffB); PG8_STAGE(PG8_SA(0, 1), cA + hstep, voffA);
;     if (wr == 1) PG8_BAR;
;     PG8_WAIT_V(4); PG8_BAR;
;     PG8_STAGE(PG8_SB(1, 0), cB + kstep, voffB); PG8_STAGE(PG8_SA(1, 0), cA + kstep, voffA); PG8_STAGE(PG8_SB(1, 1), cB + hstep + kstep, voffB);
;     PG8_WAIT_V(6); PG8_BAR;
; DEV void run_phase(const P& p, int ph, LAS unsigned char* lds) {
;     ...
;     case L0_GU1: case L1_GU1: case L0_GU2: case L1_GU2: {
;         const int second = (ph == L0_GU2 || ph == L1_GU2) ? 1 : 0; const int k = 2 * L + second; EpiSwiglu E{ACT, SS + (size_t)(4 * L + (second ? 3 : 0)) * 65536};
;         run_gemm(lds, XB, (const u16*)(ws + O_WGU + k * SZ_WGU), 8192, 11264, 2048, E, bx);
.LBB0_747:
	s_nop 0
	v_readlane_b32 s0, v254, 30
	v_readlane_b32 s1, v254, 31
	s_and_b64 vcc, exec, s[0:1]
	s_cbranch_vccz .LBB0_784
	v_readlane_b32 s0, v250, 7
	v_readlane_b32 s1, v250, 8
	s_cmp_eq_u32 s0, 12
	v_readlane_b32 s0, v250, 1
	s_mov_b32 s26, s0
	v_mov_b32_e32 v8, v198
	v_readlane_b32 s8, v254, 20
	s_cselect_b64 s[6:7], -1, 0
	s_cmpk_gt_i32 s8, 0x57f
	v_readfirstlane_b32 s27, v8
	v_readlane_b32 s1, v250, 2
	s_cbranch_scc1 .LBB0_760
	v_readlane_b32 s0, v250, 7
	v_readlane_b32 s1, v250, 8
	s_cmp_eq_u32 s0, 22
	s_cselect_b64 s[0:1], -1, 0
	v_readlane_b32 s4, v254, 26
	s_or_b64 s[0:1], s[6:7], s[0:1]
	v_readlane_b32 s5, v254, 27
	v_cndmask_b32_e64 v0, 0, 1, s[0:1]
	s_and_b64 s[4:5], s[4:5], exec
	v_readfirstlane_b32 s5, v0
	v_lshlrev_b32_e32 v0, 4, v8
	s_waitcnt lgkmcnt(0)
	v_add_u32_e32 v1, 0x2000, v0
	v_ashrrev_i32_e32 v2, 31, v1
	v_lshrrev_b32_e32 v2, 22, v2
	v_add_u32_e32 v2, v1, v2
	v_ashrrev_i32_e32 v9, 10, v2
	v_mul_i32_i24_e32 v2, 0x400, v9
	v_sub_u32_e32 v1, v1, v2
	v_lshrrev_b32_e32 v2, 4, v1
	v_bitop3_b32 v1, v2, v1, 32 bitop3:0x6c
	v_ashrrev_i32_e32 v2, 31, v1
	v_lshrrev_b32_e32 v2, 26, v2
	s_cselect_b32 s4, 2, 0
	v_add_u32_e32 v2, v1, v2
	v_lshlrev_b32_e32 v3, 3, v9
	s_or_b32 s4, s4, s5
	v_ashrrev_i32_e32 v10, 6, v2
	v_and_b32_e32 v3, -16, v3
	s_mul_i32 s4, s4, 0x2c00000
	v_add_u32_e32 v3, v10, v3
	s_add_u32 s28, s90, s4
	v_and_b32_e32 v4, 3, v10
	s_mov_b32 s4, 0xfffe0
	v_lshrrev_b32_e32 v5, 2, v3
	v_lshlrev_b32_e32 v6, 1, v3
	v_and_b32_e32 v2, 0xc0, v2
	v_and_or_b32 v4, v3, s4, v4
	v_and_b32_e32 v5, 4, v5
	v_and_b32_e32 v6, 24, v6
	v_sub_u32_e32 v1, v1, v2
	v_or3_b32 v4, v4, v5, v6
	v_lshlrev_b32_e32 v5, 5, v9
	v_ashrrev_i16_sdwa v1, v203, sext(v1) dst_sel:DWORD dst_unused:UNUSED_PAD src0_sel:DWORD src1_sel:BYTE_0
	v_and_b32_e32 v5, 32, v5
	v_bfe_i32 v11, v1, 0, 16
	v_add_lshl_u32 v1, v5, v11, 1
	v_lshl_add_u32 v136, v4, 12, v1
	v_lshl_add_u32 v138, v3, 12, v1
	v_bfe_i32 v1, v8, 27, 1
	v_lshrrev_b32_e32 v1, 22, v1
	v_add_u32_e32 v1, v0, v1
	v_and_b32_e32 v1, 0xfffffc00, v1
	v_sub_u32_e32 v0, v0, v1
	v_lshrrev_b32_e32 v1, 4, v0
	v_bitop3_b32 v1, v1, v0, 32 bitop3:0x6c
	v_ashrrev_i32_e32 v0, 31, v0
	v_lshrrev_b32_e32 v0, 26, v0
	v_add_u32_e32 v0, v1, v0
	v_ashrrev_i32_e32 v12, 6, v0
	v_ashrrev_i32_e32 v0, 31, v8
	v_lshrrev_b32_e32 v0, 26, v0
	v_add_u32_e32 v0, v8, v0
	v_ashrrev_i32_e32 v13, 6, v0
	v_lshlrev_b32_e32 v0, 3, v13
	v_and_b32_e32 v0, -16, v0
	s_addc_u32 s29, s91, 0
	v_add_u32_e32 v0, v12, v0
	v_and_b32_e32 v2, 3, v12
	s_ashr_i32 s31, s8, 31
	v_and_or_b32 v2, v0, s4, v2
	s_lshr_b32 s4, s31, 29
	s_add_i32 s4, s8, s4
	s_ashr_i32 s14, s27, 6
	s_ashr_i32 s5, s4, 3
	s_and_b32 s4, s4, -8
	s_ashr_i32 s11, s27, 8
	s_lshl_b32 s30, s14, 10
	s_sub_i32 s4, s8, s4
	s_cmp_lt_i32 s4, 0
	s_movk_i32 s8, 0xb1
	s_cselect_b32 s8, s8, 0xb0
	s_mul_i32 s4, s8, s4
	s_add_i32 s4, s4, s5
	s_mul_hi_i32 s5, s4, 0x2e8ba2e9
	s_lshr_b32 s8, s5, 31
	s_ashr_i32 s5, s5, 6
	s_add_i32 s5, s5, s8
	s_lshl_b32 s8, s5, 3
	s_mulk_i32 s5, 0x160
	s_sub_i32 s4, s4, s5
	s_sext_i32_i16 s5, s4
	s_bfe_u32 s5, s5, 0x3001c
	s_add_i32 s5, s4, s5
	s_sext_i32_i16 s9, s5
	s_and_b32 s5, s5, 0xfff8
	v_lshrrev_b32_e32 v3, 2, v0
	v_lshlrev_b32_e32 v4, 1, v0
	s_sub_i32 s4, s4, s5
	v_and_b32_e32 v3, 4, v3
	v_and_b32_e32 v4, 24, v4
	s_sext_i32_i16 s4, s4
	v_or3_b32 v2, v2, v3, v4
	v_mul_i32_i24_e32 v4, 64, v12
	s_lshr_b32 s10, s9, 3
	s_add_i32 s4, s8, s4
	v_sub_u32_e32 v1, v1, v4
	s_ashr_i32 s5, s4, 31
	s_bfe_i64 s[16:17], s[10:11], 0x100000
	v_lshlrev_b32_e32 v3, 5, v13
	v_ashrrev_i16_sdwa v1, v203, sext(v1) dst_sel:DWORD dst_unused:UNUSED_PAD src0_sel:DWORD src1_sel:BYTE_0
	s_lshl_b64 s[8:9], s[4:5], 20
	s_lshl_b64 s[16:17], s[16:17], 20
	v_and_b32_e32 v3, 32, v3
	v_bfe_i32 v14, v1, 0, 16
	s_add_u32 s22, s28, s16
	v_add_lshl_u32 v1, v3, v14, 1
	s_addc_u32 s23, s29, s17
	s_add_i32 s34, s30, 0
	v_lshl_add_u32 v160, v2, 12, v1
	s_add_i32 m0, s34, 0x10000
	v_readlane_b32 s16, v250, 9
	global_load_lds_dwordx4 v160, s[22:23]
	s_add_i32 m0, s34, 0x12000
	v_readlane_b32 s17, v250, 10
	s_add_u32 s20, s16, s8
	v_lshl_add_u32 v140, v0, 12, v1
	global_load_lds_dwordx4 v136, s[22:23]
	s_addc_u32 s21, s17, s9
	s_mov_b32 m0, s34
	s_add_i32 s35, s34, 0x2000
	global_load_lds_dwordx4 v140, s[20:21]
	s_mov_b32 m0, s35
	s_add_u32 s8, s22, 0x80000
	global_load_lds_dwordx4 v138, s[20:21]
	s_addc_u32 s9, s23, 0
	s_add_i32 m0, s34, 0x14000
	v_mov_b32_e32 v137, v161
	global_load_lds_dwordx4 v160, s[8:9]
	s_add_i32 m0, s34, 0x16000
	v_mov_b32_e32 v141, v161
	global_load_lds_dwordx4 v136, s[8:9]
	s_add_u32 s8, s20, 0x80000
	s_addc_u32 s9, s21, 0
	s_add_i32 s36, s34, 0x4000
	s_mov_b32 m0, s36
	s_add_i32 s37, s34, 0x6000
	global_load_lds_dwordx4 v140, s[8:9]
	s_mov_b32 m0, s37
	v_mov_b32_e32 v139, v161
	global_load_lds_dwordx4 v138, s[8:9]
	v_lshl_add_u64 v[6:7], s[22:23], 0, v[160:161]
	v_lshl_add_u64 v[4:5], s[22:23], 0, v[136:137]
	v_lshl_add_u64 v[2:3], s[20:21], 0, v[140:141]
	s_cmp_lg_u32 s11, 1
	v_lshl_add_u64 v[0:1], s[20:21], 0, v[138:139]
	s_cbranch_scc1 .LBB0_751
	s_barrier
	s_setprio 1

; #define PG8_STAGE(bufoff, gbase, voff) do { _Pragma("unroll") for (int _i = 0; _i < 2; ++_i) \
;         __builtin_amdgcn_global_load_lds((const unsigned*)((const char*)(gbase) + (voff)[_i]), (LAS unsigned*)(lds + (bufoff) + ldsw + _i * 8192), 16, 0, 0); } while (0)
; #define PG8_LDA(dst, b, h) do { _Pragma("unroll") for (int m = 0; m < 4; ++m) _Pragma("unroll") for (int k = 0; k < 2; ++k) dst[m][k] = *(const LAS bf16x8*)(lds + PG8_SA(b, h) + aoff + m * 2048 + k * 1024); } while (0)
; #define PG8_LDB(dst, b, h) do { _Pragma("unroll") for (int n = 0; n < 2; ++n) _Pragma("unroll") for (int k = 0; k < 2; ++k) dst[n][k] = *(const LAS bf16x8*)(lds + PG8_SB(b, h) + boff + n * 2048 + k * 1024); } while (0)
; #define PG8_MMA(ai, bj, At, Bt) do { __builtin_amdgcn_s_setprio(1); _Pragma("unroll") for (int m = 0; m < 4; ++m) _Pragma("unroll") for (int n = 0; n < 2; ++n) _Pragma("unroll") for (int k = 0; k < 2; ++k) \
;         acc[ai][bj][m][n] = __builtin_amdgcn_mfma_f32_16x16x32_bf16(Bt[n][k], At[m][k], acc[ai][bj][m][n], 0, 0, 0); __builtin_amdgcn_s_setprio(0); } while (0)
; #define PG8_WAIT_V(n) asm volatile("s_waitcnt vmcnt(" #n ")" ::: "memory")
; #define PG8_WAIT_L(n) asm volatile("s_waitcnt lgkmcnt(" #n ")" ::: "memory")
; #define PG8_BAR __builtin_amdgcn_s_barrier()
; template <class Epi>
; DEV void gemm_phase(LAS unsigned char* lds, const Gemm g, const StaticOrder& S, const Epi& E) {
;     ...
;         for (int t = 0; t < nt; t += 2) {
;             const bool last = (t == nt - 2);
;             const char* a1 = cA + (size_t)(t + 1) * kstep;
;             const char* a2 = last ? nA : cA + (size_t)(t + 2) * kstep; const char* b2 = last ? nB : cB + (size_t)(t + 2) * kstep;
;             const char* a3 = a2 + kstep; const char* b3 = b2 + kstep;
;             PG8_LDB(B0, 0, 0); PG8_SCHED; PG8_LDA(At, 0, 0); PG8_STAGE(PG8_SA(1, 1), a1 + hstep, voffA);
;             PG8_WAIT_L(8); PG8_BAR; PG8_WAIT_L(0); PG8_MMA(0, 0, At, B0); PG8_BAR; PG8_SCHED;
;             PG8_LDB(B1, 0, 1); PG8_STAGE(PG8_SB(0, 0), b2, voffB);
;             PG8_BAR; PG8_WAIT_L(0); PG8_MMA(0, 1, At, B1); PG8_BAR;
;             PG8_LDA(At, 0, 1); PG8_STAGE(PG8_SA(0, 0), a2, voffA);
;             PG8_BAR; PG8_WAIT_L(0); PG8_MMA(1, 0, At, B0); PG8_BAR; PG8_SCHED;
;             PG8_STAGE(PG8_SB(0, 1), b2 + hstep, voffB);
;             PG8_WAIT_V(6); PG8_BAR; PG8_MMA(1, 1, At, B1); PG8_BAR;
.LBB0_755:
	s_add_u32 s22, s20, 0xfff80080
	s_addc_u32 s23, s21, -1
	s_add_i32 s47, 0, 0x10000
	v_add_u32_e32 v146, s47, v155
	ds_read_b128 v[128:131], v146
	ds_read_b128 v[132:135], v146 offset:1024
	ds_read_b128 v[150:153], v146 offset:2048
	ds_read_b128 v[174:177], v146 offset:3072
	s_cmp_eq_u32 s46, 28
	s_cselect_b32 s25, s5, s23
	s_cselect_b32 s24, s15, s22
	s_cselect_b32 s23, s11, s45
	s_cselect_b32 s22, s43, s44
	v_lshl_add_u64 v[146:147], s[20:21], 0, v[142:143]
	s_add_i32 m0, s34, 0xc000
	ds_read_b128 v[178:181], v167
	ds_read_b128 v[182:185], v167 offset:1024
	ds_read_b128 v[186:189], v167 offset:2048
	ds_read_b128 v[190:193], v167 offset:3072
	ds_read_b128 v[194:197], v167 offset:4096
	ds_read_b128 v[218:221], v167 offset:5120
	ds_read_b128 v[222:225], v167 offset:6144
	ds_read_b128 v[226:229], v167 offset:7168
	global_load_lds_dwordx4 v[146:147], off
	v_lshl_add_u64 v[146:147], s[20:21], 0, v[144:145]
	s_add_i32 m0, s34, 0xe000
	s_nop 0
	global_load_lds_dwordx4 v[146:147], off
	s_waitcnt lgkmcnt(8)
	s_barrier
	s_waitcnt lgkmcnt(0)
	v_mfma_f32_16x16x32_bf16 v[124:127], v[128:131], v[178:181], v[124:127]
	v_mfma_f32_16x16x32_bf16 v[116:119], v[150:153], v[178:181], v[116:119]
	v_mfma_f32_16x16x32_bf16 v[108:111], v[128:131], v[186:189], v[108:111]
	v_mfma_f32_16x16x32_bf16 v[100:103], v[150:153], v[186:189], v[100:103]
	v_mfma_f32_16x16x32_bf16 v[92:95], v[128:131], v[194:197], v[92:95]
	v_mfma_f32_16x16x32_bf16 v[84:87], v[150:153], v[194:197], v[84:87]
	v_mfma_f32_16x16x32_bf16 v[76:79], v[128:131], v[222:225], v[76:79]
	v_mfma_f32_16x16x32_bf16 v[68:71], v[150:153], v[222:225], v[68:71]
	v_mfma_f32_16x16x32_bf16 v[124:127], v[132:135], v[182:185], v[124:127]
	v_mfma_f32_16x16x32_bf16 v[116:119], v[174:177], v[182:185], v[116:119]
	v_mfma_f32_16x16x32_bf16 v[108:111], v[132:135], v[190:193], v[108:111]
	v_mfma_f32_16x16x32_bf16 v[100:103], v[174:177], v[190:193], v[100:103]
	v_mfma_f32_16x16x32_bf16 v[92:95], v[132:135], v[218:221], v[92:95]
	v_mfma_f32_16x16x32_bf16 v[84:87], v[174:177], v[218:221], v[84:87]
	v_mfma_f32_16x16x32_bf16 v[76:79], v[132:135], v[226:229], v[76:79]
	v_mfma_f32_16x16x32_bf16 v[68:71], v[174:177], v[226:229], v[68:71]
	s_barrier
	s_add_i32 s50, 0, 0x14000
	v_add_u32_e32 v146, s50, v155
	s_add_i32 s47, s47, s30
	ds_read_b128 v[230:233], v146
	ds_read_b128 v[234:237], v146 offset:1024
	ds_read_b128 v[238:241], v146 offset:2048
	ds_read_b128 v[242:245], v146 offset:3072
	v_lshl_add_u64 v[146:147], s[22:23], 0, v[160:161]
	s_mov_b32 m0, s47
	v_lshl_add_u64 v[158:159], s[22:23], 0, v[136:137]
	global_load_lds_dwordx4 v[146:147], off
	s_add_i32 m0, s47, 0x2000
	s_nop 0
	global_load_lds_dwordx4 v[158:159], off
	s_barrier
	s_waitcnt lgkmcnt(0)
	v_mfma_f32_16x16x32_bf16 v[120:123], v[230:233], v[178:181], v[120:123]
	v_mfma_f32_16x16x32_bf16 v[112:115], v[238:241], v[178:181], v[112:115]
	v_mfma_f32_16x16x32_bf16 v[104:107], v[230:233], v[186:189], v[104:107]
	v_mfma_f32_16x16x32_bf16 v[96:99], v[238:241], v[186:189], v[96:99]
	v_mfma_f32_16x16x32_bf16 v[88:91], v[230:233], v[194:197], v[88:91]
	v_mfma_f32_16x16x32_bf16 v[80:83], v[238:241], v[194:197], v[80:83]
	v_mfma_f32_16x16x32_bf16 v[72:75], v[230:233], v[222:225], v[72:75]
	v_mfma_f32_16x16x32_bf16 v[64:67], v[238:241], v[222:225], v[64:67]
	v_mfma_f32_16x16x32_bf16 v[120:123], v[234:237], v[182:185], v[120:123]
	v_mfma_f32_16x16x32_bf16 v[112:115], v[242:245], v[182:185], v[112:115]
	v_mfma_f32_16x16x32_bf16 v[104:107], v[234:237], v[190:193], v[104:107]
	v_mfma_f32_16x16x32_bf16 v[96:99], v[242:245], v[190:193], v[96:99]
	v_mfma_f32_16x16x32_bf16 v[88:91], v[234:237], v[218:221], v[88:91]
	v_mfma_f32_16x16x32_bf16 v[80:83], v[242:245], v[218:221], v[80:83]
	v_mfma_f32_16x16x32_bf16 v[72:75], v[234:237], v[226:229], v[72:75]
	v_mfma_f32_16x16x32_bf16 v[64:67], v[242:245], v[226:229], v[64:67]
	s_mov_b32 m0, s34
	v_lshl_add_u64 v[214:215], s[24:25], 0, v[140:141]
	s_barrier
	ds_read_b128 v[178:181], v167 offset:16384
	ds_read_b128 v[182:185], v167 offset:17408
	ds_read_b128 v[186:189], v167 offset:18432
	ds_read_b128 v[190:193], v167 offset:19456
	ds_read_b128 v[194:197], v167 offset:20480
	ds_read_b128 v[218:221], v167 offset:21504
	ds_read_b128 v[222:225], v167 offset:22528
	ds_read_b128 v[226:229], v167 offset:23552
	global_load_lds_dwordx4 v[214:215], off
	v_lshl_add_u64 v[216:217], s[24:25], 0, v[138:139]
	s_mov_b32 m0, s35
	s_nop 0
	global_load_lds_dwordx4 v[216:217], off
	s_barrier
	s_waitcnt lgkmcnt(0)
	v_mfma_f32_16x16x32_bf16 v[60:63], v[128:131], v[178:181], v[60:63]
	v_mfma_f32_16x16x32_bf16 v[52:55], v[150:153], v[178:181], v[52:55]
	v_mfma_f32_16x16x32_bf16 v[44:47], v[128:131], v[186:189], v[44:47]
	v_mfma_f32_16x16x32_bf16 v[36:39], v[150:153], v[186:189], v[36:39]
	v_mfma_f32_16x16x32_bf16 v[28:31], v[128:131], v[194:197], v[28:31]
	v_mfma_f32_16x16x32_bf16 v[20:23], v[150:153], v[194:197], v[20:23]
	v_mfma_f32_16x16x32_bf16 v[12:15], v[128:131], v[222:225], v[12:15]
	v_mfma_f32_16x16x32_bf16 v[4:7], v[150:153], v[222:225], v[4:7]
	v_mfma_f32_16x16x32_bf16 v[60:63], v[132:135], v[182:185], v[60:63]
	v_mfma_f32_16x16x32_bf16 v[52:55], v[174:177], v[182:185], v[52:55]
	v_mfma_f32_16x16x32_bf16 v[44:47], v[132:135], v[190:193], v[44:47]
	v_mfma_f32_16x16x32_bf16 v[36:39], v[174:177], v[190:193], v[36:39]
	v_mfma_f32_16x16x32_bf16 v[28:31], v[132:135], v[218:221], v[28:31]
	v_mfma_f32_16x16x32_bf16 v[20:23], v[174:177], v[218:221], v[20:23]
	v_mfma_f32_16x16x32_bf16 v[12:15], v[132:135], v[226:229], v[12:15]
	v_mfma_f32_16x16x32_bf16 v[4:7], v[174:177], v[226:229], v[4:7]
	s_barrier
; #define PG8_STAGE(bufoff, gbase, voff) do { _Pragma("unroll") for (int _i = 0; _i < 2; ++_i) \
;         __builtin_amdgcn_global_load_lds((const unsigned*)((const char*)(gbase) + (voff)[_i]), (LAS unsigned*)(lds + (bufoff) + ldsw + _i * 8192), 16, 0, 0); } while (0)
; #define PG8_LDA(dst, b, h) do { _Pragma("unroll") for (int m = 0; m < 4; ++m) _Pragma("unroll") for (int k = 0; k < 2; ++k) dst[m][k] = *(const LAS bf16x8*)(lds + PG8_SA(b, h) + aoff + m * 2048 + k * 1024); } while (0)
; #define PG8_LDB(dst, b, h) do { _Pragma("unroll") for (int n = 0; n < 2; ++n) _Pragma("unroll") for (int k = 0; k < 2; ++k) dst[n][k] = *(const LAS bf16x8*)(lds + PG8_SB(b, h) + boff + n * 2048 + k * 1024); } while (0)
; #define PG8_MMA(ai, bj, At, Bt) do { __builtin_amdgcn_s_setprio(1); _Pragma("unroll") for (int m = 0; m < 4; ++m) _Pragma("unroll") for (int n = 0; n < 2; ++n) _Pragma("unroll") for (int k = 0; k < 2; ++k) \
;         acc[ai][bj][m][n] = __builtin_amdgcn_mfma_f32_16x16x32_bf16(Bt[n][k], At[m][k], acc[ai][bj][m][n], 0, 0, 0); __builtin_amdgcn_s_setprio(0); } while (0)
; #define PG8_WAIT_V(n) asm volatile("s_waitcnt vmcnt(" #n ")" ::: "memory")
; #define PG8_WAIT_L(n) asm volatile("s_waitcnt lgkmcnt(" #n ")" ::: "memory")
; #define PG8_BAR __builtin_amdgcn_s_barrier()
; #define PG8_SCHED __builtin_amdgcn_sched_barrier(0)
; template <class Epi>
; DEV void gemm_phase(LAS unsigned char* lds, const Gemm g, const StaticOrder& S, const Epi& E) {
;     ...
;             PG8_STAGE(PG8_SB(0, 1), b2 + hstep, voffB);
;             PG8_WAIT_V(6); PG8_BAR; PG8_MMA(1, 1, At, B1); PG8_BAR;
;             PG8_LDB(B0, 1, 0); PG8_SCHED; PG8_LDA(At, 1, 0); PG8_STAGE(PG8_SA(0, 1), a2 + hstep, voffA);
;             PG8_WAIT_L(8); PG8_BAR; PG8_WAIT_L(0); PG8_MMA(0, 0, At, B0); PG8_BAR; PG8_SCHED;
;             PG8_LDB(B1, 1, 1); PG8_STAGE(PG8_SB(1, 0), b3, voffB);
;             PG8_BAR; PG8_WAIT_L(0); PG8_MMA(0, 1, At, B1); PG8_BAR;
;             PG8_LDA(At, 1, 1); PG8_STAGE(PG8_SA(1, 0), a3, voffA);
;             PG8_BAR; PG8_WAIT_L(0); PG8_MMA(1, 0, At, B0); PG8_BAR; PG8_SCHED;
	s_add_u32 s48, s22, 0x80000
	s_addc_u32 s49, s23, 0
	s_add_i32 s47, s50, s30
	v_lshl_add_u64 v[128:129], s[48:49], 0, v[160:161]
	s_mov_b32 m0, s47
	s_nop 0
	global_load_lds_dwordx4 v[128:129], off
	v_lshl_add_u64 v[128:129], s[48:49], 0, v[136:137]
	s_add_i32 m0, s47, 0x2000
	s_nop 0
	global_load_lds_dwordx4 v[128:129], off
	s_waitcnt vmcnt(6)
	s_barrier
	v_mfma_f32_16x16x32_bf16 v[56:59], v[230:233], v[178:181], v[56:59]
	v_mfma_f32_16x16x32_bf16 v[48:51], v[238:241], v[178:181], v[48:51]
	v_mfma_f32_16x16x32_bf16 v[40:43], v[230:233], v[186:189], v[40:43]
	v_mfma_f32_16x16x32_bf16 v[32:35], v[238:241], v[186:189], v[32:35]
	v_mfma_f32_16x16x32_bf16 v[24:27], v[230:233], v[194:197], v[24:27]
	v_mfma_f32_16x16x32_bf16 v[16:19], v[238:241], v[194:197], v[16:19]
	v_mfma_f32_16x16x32_bf16 v[8:11], v[230:233], v[222:225], v[8:11]
	v_mfma_f32_16x16x32_bf16 v[0:3], v[238:241], v[222:225], v[0:3]
	v_mfma_f32_16x16x32_bf16 v[56:59], v[234:237], v[182:185], v[56:59]
	v_mfma_f32_16x16x32_bf16 v[48:51], v[242:245], v[182:185], v[48:51]
	v_mfma_f32_16x16x32_bf16 v[40:43], v[234:237], v[190:193], v[40:43]
	v_mfma_f32_16x16x32_bf16 v[32:35], v[242:245], v[190:193], v[32:35]
	v_mfma_f32_16x16x32_bf16 v[24:27], v[234:237], v[218:221], v[24:27]
	v_mfma_f32_16x16x32_bf16 v[16:19], v[242:245], v[218:221], v[16:19]
	v_mfma_f32_16x16x32_bf16 v[8:11], v[234:237], v[226:229], v[8:11]
	v_mfma_f32_16x16x32_bf16 v[0:3], v[242:245], v[226:229], v[0:3]
	s_add_i32 s47, 0, 0x18000
	v_add_u32_e32 v148, s47, v155
	s_barrier
	ds_read_b128 v[128:131], v148
	ds_read_b128 v[132:135], v148 offset:1024
	ds_read_b128 v[150:153], v148 offset:2048
	ds_read_b128 v[174:177], v148 offset:3072
	s_add_u32 s24, s24, 0x80000
	s_addc_u32 s25, s25, 0
	s_mov_b32 m0, s36
	v_lshl_add_u64 v[230:231], s[24:25], 0, v[140:141]
	ds_read_b128 v[178:181], v167 offset:32768
	ds_read_b128 v[182:185], v167 offset:33792
	ds_read_b128 v[186:189], v167 offset:34816
	ds_read_b128 v[190:193], v167 offset:35840
	ds_read_b128 v[194:197], v167 offset:36864
	ds_read_b128 v[218:221], v167 offset:37888
	ds_read_b128 v[222:225], v167 offset:38912
	ds_read_b128 v[226:229], v167 offset:39936
	global_load_lds_dwordx4 v[230:231], off
	v_lshl_add_u64 v[230:231], s[24:25], 0, v[138:139]
	s_mov_b32 m0, s37
	s_nop 0
	global_load_lds_dwordx4 v[230:231], off
	s_waitcnt lgkmcnt(8)
	s_barrier
	s_waitcnt lgkmcnt(0)
	v_mfma_f32_16x16x32_bf16 v[124:127], v[128:131], v[178:181], v[124:127]
	v_mfma_f32_16x16x32_bf16 v[116:119], v[150:153], v[178:181], v[116:119]
	v_mfma_f32_16x16x32_bf16 v[108:111], v[128:131], v[186:189], v[108:111]
	v_mfma_f32_16x16x32_bf16 v[100:103], v[150:153], v[186:189], v[100:103]
	v_mfma_f32_16x16x32_bf16 v[92:95], v[128:131], v[194:197], v[92:95]
	v_mfma_f32_16x16x32_bf16 v[84:87], v[150:153], v[194:197], v[84:87]
	v_mfma_f32_16x16x32_bf16 v[76:79], v[128:131], v[222:225], v[76:79]
	v_mfma_f32_16x16x32_bf16 v[68:71], v[150:153], v[222:225], v[68:71]
	v_mfma_f32_16x16x32_bf16 v[124:127], v[132:135], v[182:185], v[124:127]
	v_mfma_f32_16x16x32_bf16 v[116:119], v[174:177], v[182:185], v[116:119]
	v_mfma_f32_16x16x32_bf16 v[108:111], v[132:135], v[190:193], v[108:111]
	v_mfma_f32_16x16x32_bf16 v[100:103], v[174:177], v[190:193], v[100:103]
	v_mfma_f32_16x16x32_bf16 v[92:95], v[132:135], v[218:221], v[92:95]
	v_mfma_f32_16x16x32_bf16 v[84:87], v[174:177], v[218:221], v[84:87]
	v_mfma_f32_16x16x32_bf16 v[76:79], v[132:135], v[226:229], v[76:79]
	v_mfma_f32_16x16x32_bf16 v[68:71], v[174:177], v[226:229], v[68:71]
	s_barrier
	s_add_i32 s24, 0, 0x1c000
	s_add_i32 s25, s47, s30
	v_add_u32_e32 v148, s24, v155
	v_lshl_add_u64 v[146:147], v[146:147], 0, s[2:3]
	s_mov_b32 m0, s25
	ds_read_b128 v[230:233], v148
	ds_read_b128 v[234:237], v148 offset:1024
	ds_read_b128 v[238:241], v148 offset:2048
	ds_read_b128 v[242:245], v148 offset:3072
	global_load_lds_dwordx4 v[146:147], off
	v_lshl_add_u64 v[146:147], v[158:159], 0, s[2:3]
	s_add_i32 m0, s25, 0x2000
	s_nop 0
	global_load_lds_dwordx4 v[146:147], off
	s_barrier
	s_waitcnt lgkmcnt(0)
	v_mfma_f32_16x16x32_bf16 v[120:123], v[230:233], v[178:181], v[120:123]
	v_mfma_f32_16x16x32_bf16 v[112:115], v[238:241], v[178:181], v[112:115]
	v_mfma_f32_16x16x32_bf16 v[104:107], v[230:233], v[186:189], v[104:107]
	v_mfma_f32_16x16x32_bf16 v[96:99], v[238:241], v[186:189], v[96:99]
	v_mfma_f32_16x16x32_bf16 v[88:91], v[230:233], v[194:197], v[88:91]
	v_mfma_f32_16x16x32_bf16 v[80:83], v[238:241], v[194:197], v[80:83]
	v_mfma_f32_16x16x32_bf16 v[72:75], v[230:233], v[222:225], v[72:75]
	v_mfma_f32_16x16x32_bf16 v[64:67], v[238:241], v[222:225], v[64:67]
	v_mfma_f32_16x16x32_bf16 v[120:123], v[234:237], v[182:185], v[120:123]
	v_mfma_f32_16x16x32_bf16 v[112:115], v[242:245], v[182:185], v[112:115]
	v_mfma_f32_16x16x32_bf16 v[104:107], v[234:237], v[190:193], v[104:107]
	v_mfma_f32_16x16x32_bf16 v[96:99], v[242:245], v[190:193], v[96:99]
	v_mfma_f32_16x16x32_bf16 v[88:91], v[234:237], v[218:221], v[88:91]
	v_mfma_f32_16x16x32_bf16 v[80:83], v[242:245], v[218:221], v[80:83]
	v_mfma_f32_16x16x32_bf16 v[72:75], v[234:237], v[226:229], v[72:75]
	v_mfma_f32_16x16x32_bf16 v[64:67], v[242:245], v[226:229], v[64:67]
	s_mov_b32 m0, s38
	v_lshl_add_u64 v[146:147], v[214:215], 0, s[2:3]
	s_barrier
	ds_read_b128 v[178:181], v167 offset:49152
	ds_read_b128 v[182:185], v167 offset:50176
	ds_read_b128 v[186:189], v167 offset:51200
	ds_read_b128 v[190:193], v167 offset:52224
	ds_read_b128 v[194:197], v167 offset:53248
	ds_read_b128 v[218:221], v167 offset:54272
	ds_read_b128 v[222:225], v167 offset:55296
	ds_read_b128 v[226:229], v167 offset:56320
	global_load_lds_dwordx4 v[146:147], off
	v_lshl_add_u64 v[146:147], v[216:217], 0, s[2:3]
	s_mov_b32 m0, s39
	s_nop 0
	global_load_lds_dwordx4 v[146:147], off
	s_barrier
; #define PG8_STAGE(bufoff, gbase, voff) do { _Pragma("unroll") for (int _i = 0; _i < 2; ++_i) \
;         __builtin_amdgcn_global_load_lds((const unsigned*)((const char*)(gbase) + (voff)[_i]), (LAS unsigned*)(lds + (bufoff) + ldsw + _i * 8192), 16, 0, 0); } while (0)
; #define PG8_MMA(ai, bj, At, Bt) do { __builtin_amdgcn_s_setprio(1); _Pragma("unroll") for (int m = 0; m < 4; ++m) _Pragma("unroll") for (int n = 0; n < 2; ++n) _Pragma("unroll") for (int k = 0; k < 2; ++k) \
;         acc[ai][bj][m][n] = __builtin_amdgcn_mfma_f32_16x16x32_bf16(Bt[n][k], At[m][k], acc[ai][bj][m][n], 0, 0, 0); __builtin_amdgcn_s_setprio(0); } while (0)
; #define PG8_WAIT_V(n) asm volatile("s_waitcnt vmcnt(" #n ")" ::: "memory")
; #define PG8_WAIT_L(n) asm volatile("s_waitcnt lgkmcnt(" #n ")" ::: "memory")
; #define PG8_BAR __builtin_amdgcn_s_barrier()
; #define PG8_SCHED __builtin_amdgcn_sched_barrier(0)
; template <class Epi>
; DEV void gemm_phase(LAS unsigned char* lds, const Gemm g, const StaticOrder& S, const Epi& E) {
;     ...
;             PG8_BAR; PG8_WAIT_L(0); PG8_MMA(1, 0, At, B0); PG8_BAR; PG8_SCHED;
;             PG8_STAGE(PG8_SB(1, 1), b3 + hstep, voffB);
;             PG8_WAIT_V(6); PG8_BAR; PG8_MMA(1, 1, At, B1); PG8_BAR;
;         }
;     DEV void operator()(AccRef acc, const pg8::Unit& u, int wr, int wc, int fr, int fq) const {
;         const int row0 = u.pm * 256 + wr * 64 + fr, col0 = u.pn * 128 + wc * 32 + 8 * fq;
;         float rsv[2][4];
; #pragma unroll
;         for (int ai = 0; ai < 2; ++ai)
; #pragma unroll
;             for (int m = 0; m < 4; ++m) rsv[ai][m] = rowscale(ss, row0 + ai * 128 + m * 16);
; #pragma unroll
;         for (int ai = 0; ai < 2; ++ai)
; #pragma unroll
;             for (int m = 0; m < 4; ++m) { u16* rowp = O + (size_t)(row0 + ai * 128 + m * 16) * 5632 + col0; const float rs = rsv[ai][m]; f32x4 r[2];
; #pragma unroll
;                 for (int n = 0; n < 2; ++n) { const f32x4 g = acc[ai][0][m][n] * rs, uu = acc[ai][1][m][n] * rs;
	s_waitcnt lgkmcnt(0)
	v_mfma_f32_16x16x32_bf16 v[60:63], v[128:131], v[178:181], v[60:63]
	v_mfma_f32_16x16x32_bf16 v[52:55], v[150:153], v[178:181], v[52:55]
	v_mfma_f32_16x16x32_bf16 v[44:47], v[128:131], v[186:189], v[44:47]
	v_mfma_f32_16x16x32_bf16 v[36:39], v[150:153], v[186:189], v[36:39]
	v_mfma_f32_16x16x32_bf16 v[28:31], v[128:131], v[194:197], v[28:31]
	v_mfma_f32_16x16x32_bf16 v[20:23], v[150:153], v[194:197], v[20:23]
	v_mfma_f32_16x16x32_bf16 v[12:15], v[128:131], v[222:225], v[12:15]
	v_mfma_f32_16x16x32_bf16 v[4:7], v[150:153], v[222:225], v[4:7]
	v_mfma_f32_16x16x32_bf16 v[60:63], v[132:135], v[182:185], v[60:63]
	v_mfma_f32_16x16x32_bf16 v[52:55], v[174:177], v[182:185], v[52:55]
	v_mfma_f32_16x16x32_bf16 v[44:47], v[132:135], v[190:193], v[44:47]
	v_mfma_f32_16x16x32_bf16 v[36:39], v[174:177], v[190:193], v[36:39]
	v_mfma_f32_16x16x32_bf16 v[28:31], v[132:135], v[218:221], v[28:31]
	v_mfma_f32_16x16x32_bf16 v[20:23], v[174:177], v[218:221], v[20:23]
	v_mfma_f32_16x16x32_bf16 v[12:15], v[132:135], v[226:229], v[12:15]
	v_mfma_f32_16x16x32_bf16 v[4:7], v[174:177], v[226:229], v[4:7]
	s_barrier
	s_add_u32 s22, s22, 0x80080
	s_addc_u32 s23, s23, 0
	s_add_i32 s24, s24, s30
	v_lshl_add_u64 v[128:129], s[22:23], 0, v[160:161]
	s_mov_b32 m0, s24
	s_nop 0
	global_load_lds_dwordx4 v[128:129], off
	v_lshl_add_u64 v[128:129], s[22:23], 0, v[136:137]
	s_add_i32 m0, s24, 0x2000
	s_nop 0
	global_load_lds_dwordx4 v[128:129], off
	s_waitcnt vmcnt(6)
	s_barrier
	v_mfma_f32_16x16x32_bf16 v[56:59], v[230:233], v[178:181], v[56:59]
	v_mfma_f32_16x16x32_bf16 v[48:51], v[238:241], v[178:181], v[48:51]
	v_mfma_f32_16x16x32_bf16 v[40:43], v[230:233], v[186:189], v[40:43]
	v_mfma_f32_16x16x32_bf16 v[32:35], v[238:241], v[186:189], v[32:35]
	v_mfma_f32_16x16x32_bf16 v[24:27], v[230:233], v[194:197], v[24:27]
	v_mfma_f32_16x16x32_bf16 v[16:19], v[238:241], v[194:197], v[16:19]
	v_mfma_f32_16x16x32_bf16 v[8:11], v[230:233], v[222:225], v[8:11]
	v_mfma_f32_16x16x32_bf16 v[0:3], v[238:241], v[222:225], v[0:3]
	v_mfma_f32_16x16x32_bf16 v[56:59], v[234:237], v[182:185], v[56:59]
	v_mfma_f32_16x16x32_bf16 v[48:51], v[242:245], v[182:185], v[48:51]
	v_mfma_f32_16x16x32_bf16 v[40:43], v[234:237], v[190:193], v[40:43]
	v_mfma_f32_16x16x32_bf16 v[32:35], v[242:245], v[190:193], v[32:35]
	v_mfma_f32_16x16x32_bf16 v[24:27], v[234:237], v[218:221], v[24:27]
	v_mfma_f32_16x16x32_bf16 v[16:19], v[242:245], v[218:221], v[16:19]
	v_mfma_f32_16x16x32_bf16 v[8:11], v[234:237], v[226:229], v[8:11]
	v_mfma_f32_16x16x32_bf16 v[0:3], v[242:245], v[226:229], v[0:3]
	s_add_i32 s46, s46, 2
	s_add_u32 s20, s20, 0x100
	s_addc_u32 s21, s21, 0
	s_add_u32 s44, s44, 0x100
	s_addc_u32 s45, s45, 0
	s_cmp_gt_u32 s46, 29
	s_barrier
	s_cbranch_scc0 .LBB0_755
	v_lshl_add_u32 v186, s4, 8, v149
	v_ashrrev_i32_e32 v187, 31, v186
	v_lshlrev_b64 v[146:147], 5, v[186:187]
	v_lshl_add_u64 v[146:147], s[8:9], 0, v[146:147]
	v_add_co_u32_e32 v158, vcc, 0x1000, v146
	global_load_dwordx4 v[218:221], v[146:147], off
	global_load_dwordx4 v[222:225], v[146:147], off offset:16
	v_addc_co_u32_e32 v159, vcc, 0, v147, vcc
	global_load_dwordx4 v[174:177], v[146:147], off offset:512
	global_load_dwordx4 v[230:233], v[146:147], off offset:528
	global_load_dwordx4 v[234:237], v[146:147], off offset:1024
	global_load_dwordx4 v[238:241], v[146:147], off offset:1040
	global_load_dwordx4 v[242:245], v[146:147], off offset:1536
	global_load_dwordx4 v[246:249], v[146:147], off offset:1552
	global_load_dwordx4 v[190:193], v[158:159], off
	global_load_dwordx4 v[194:197], v[158:159], off offset:16
	global_load_dwordx4 v[214:217], v[158:159], off offset:512
	global_load_dwordx4 v[132:135], v[158:159], off offset:528
	global_load_dwordx4 v[150:153], v[158:159], off offset:1024
	global_load_dwordx4 v[128:131], v[158:159], off offset:1040
	global_load_dwordx4 v[226:229], v[158:159], off offset:1536
	global_load_dwordx4 v[180:183], v[158:159], off offset:1552
	s_mov_b32 s12, 0x3a000000
	s_mov_b64 s[22:23], s[18:19]
	s_mov_b64 s[20:21], s[16:17]
	s_movk_i32 s11, 0x2c00
	v_readlane_b32 s4, v250, 11
	v_readlane_b32 s5, v250, 12
	s_waitcnt vmcnt(14)
	v_add_f32_e32 v218, v218, v219
	v_add_f32_e32 v220, v220, v221
	v_add_f32_e32 v222, v222, v223
	v_add_f32_e32 v224, v224, v225
	v_add_f32_e32 v218, v218, v220
	v_add_f32_e32 v218, v218, v222
	v_add_f32_e32 v218, v218, v224
	v_fmamk_f32 v218, v218, 0x3a000000, v199
	v_rsq_f32_e32 v184, v218
	s_waitcnt vmcnt(12)
	v_add_f32_e32 v174, v174, v175
	v_add_f32_e32 v176, v176, v177
	v_add_f32_e32 v230, v230, v231
	v_add_f32_e32 v232, v232, v233
	v_add_f32_e32 v174, v174, v176
	v_add_f32_e32 v174, v174, v230
	v_add_f32_e32 v174, v174, v232
	v_fmamk_f32 v174, v174, 0x3a000000, v199
	v_rsq_f32_e32 v176, v174
	v_pk_mul_f32 v[124:125], v[124:125], v[184:185] op_sel_hi:[1,0]
	v_pk_mul_f32 v[120:121], v[120:121], v[184:185] op_sel_hi:[1,0]
	v_pk_mul_f32 v[122:123], v[122:123], v[184:185] op_sel_hi:[1,0]
	v_pk_mul_f32 v[116:117], v[116:117], v[184:185] op_sel_hi:[1,0]
	v_pk_mul_f32 v[112:113], v[112:113], v[184:185] op_sel_hi:[1,0]
	v_pk_mul_f32 v[114:115], v[114:115], v[184:185] op_sel_hi:[1,0]
	s_waitcnt vmcnt(10)
	v_add_f32_e32 v234, v234, v235
	v_add_f32_e32 v236, v236, v237
	v_add_f32_e32 v238, v238, v239
	v_add_f32_e32 v240, v240, v241
	v_add_f32_e32 v234, v234, v236
	v_add_f32_e32 v234, v234, v238
	v_add_f32_e32 v234, v234, v240
	v_fmamk_f32 v234, v234, 0x3a000000, v199
	v_rsq_f32_e32 v178, v234
	v_pk_mul_f32 v[108:109], v[108:109], v[176:177] op_sel_hi:[1,0]
	v_pk_mul_f32 v[104:105], v[104:105], v[176:177] op_sel_hi:[1,0]
	v_pk_mul_f32 v[106:107], v[106:107], v[176:177] op_sel_hi:[1,0]
	v_pk_mul_f32 v[100:101], v[100:101], v[176:177] op_sel_hi:[1,0]
	v_pk_mul_f32 v[96:97], v[96:97], v[176:177] op_sel_hi:[1,0]
	v_pk_mul_f32 v[98:99], v[98:99], v[176:177] op_sel_hi:[1,0]
	s_waitcnt vmcnt(8)
; DEV bf16x8 pack8(f32x4 a, f32x4 b) { u32x4 w; w.x = cvt_pk_bf16(a[0], a[1]); w.y = cvt_pk_bf16(a[2], a[3]); w.z = cvt_pk_bf16(b[0], b[1]); w.w = cvt_pk_bf16(b[2], b[3]); return __builtin_bit_cast(bf16x8, w); }
; DEV float siluf(float x) { return x * __builtin_amdgcn_rcpf(1.0f + __builtin_amdgcn_exp2f(x * -1.4426950408889634f)); }
;     DEV void operator()(AccRef acc, const pg8::Unit& u, int wr, int wc, int fr, int fq) const {
;         const int row0 = u.pm * 256 + wr * 64 + fr, col0 = u.pn * 128 + wc * 32 + 8 * fq;
;         float rsv[2][4];
; #pragma unroll
;         for (int ai = 0; ai < 2; ++ai)
; #pragma unroll
;             for (int m = 0; m < 4; ++m) rsv[ai][m] = rowscale(ss, row0 + ai * 128 + m * 16);
; #pragma unroll
;         for (int ai = 0; ai < 2; ++ai)
; #pragma unroll
;             for (int m = 0; m < 4; ++m) { u16* rowp = O + (size_t)(row0 + ai * 128 + m * 16) * 5632 + col0; const float rs = rsv[ai][m]; f32x4 r[2];
; #pragma unroll
;                 for (int n = 0; n < 2; ++n) { const f32x4 g = acc[ai][0][m][n] * rs, uu = acc[ai][1][m][n] * rs;
; #pragma unroll
;                     for (int e = 0; e < 4; ++e) r[n][e] = siluf(g[e]) * uu[e]; }
;                 *(u32x4*)rowp = __builtin_bit_cast(u32x4, pack8(r[0], r[1])); }
	v_add_f32_e32 v242, v242, v243
	v_add_f32_e32 v244, v244, v245
	v_add_f32_e32 v246, v246, v247
	v_add_f32_e32 v248, v248, v249
	v_add_f32_e32 v242, v242, v244
	v_add_f32_e32 v242, v242, v246
	v_add_f32_e32 v242, v242, v248
	v_fmamk_f32 v242, v242, 0x3a000000, v199
	v_rsq_f32_e32 v154, v242
	v_pk_mul_f32 v[92:93], v[92:93], v[178:179] op_sel_hi:[1,0]
	v_pk_mul_f32 v[88:89], v[88:89], v[178:179] op_sel_hi:[1,0]
	v_pk_mul_f32 v[90:91], v[90:91], v[178:179] op_sel_hi:[1,0]
	v_pk_mul_f32 v[84:85], v[84:85], v[178:179] op_sel_hi:[1,0]
	v_pk_mul_f32 v[80:81], v[80:81], v[178:179] op_sel_hi:[1,0]
	v_pk_mul_f32 v[82:83], v[82:83], v[178:179] op_sel_hi:[1,0]
	s_waitcnt vmcnt(6)
	v_add_f32_e32 v190, v190, v191
	v_add_f32_e32 v192, v192, v193
	v_add_f32_e32 v194, v194, v195
	v_add_f32_e32 v196, v196, v197
	v_add_f32_e32 v190, v190, v192
	v_add_f32_e32 v190, v190, v194
	v_add_f32_e32 v190, v190, v196
	v_fmamk_f32 v190, v190, 0x3a000000, v199
	v_rsq_f32_e32 v156, v190
	v_pk_mul_f32 v[76:77], v[76:77], v[154:155] op_sel_hi:[1,0]
	v_pk_mul_f32 v[72:73], v[72:73], v[154:155] op_sel_hi:[1,0]
	v_pk_mul_f32 v[74:75], v[74:75], v[154:155] op_sel_hi:[1,0]
	v_pk_mul_f32 v[68:69], v[68:69], v[154:155] op_sel_hi:[1,0]
	v_pk_mul_f32 v[64:65], v[64:65], v[154:155] op_sel_hi:[1,0]
	v_pk_mul_f32 v[66:67], v[66:67], v[154:155] op_sel_hi:[1,0]
	s_waitcnt vmcnt(4)
	v_add_f32_e32 v214, v214, v215
	v_add_f32_e32 v216, v216, v217
	v_add_f32_e32 v132, v132, v133
	v_add_f32_e32 v134, v134, v135
	v_add_f32_e32 v214, v214, v216
	v_add_f32_e32 v214, v214, v132
	v_add_f32_e32 v214, v214, v134
	v_fmamk_f32 v214, v214, 0x3a000000, v199
	v_rsq_f32_e32 v148, v214
	v_pk_mul_f32 v[60:61], v[60:61], v[156:157] op_sel_hi:[1,0]
	v_pk_mul_f32 v[56:57], v[56:57], v[156:157] op_sel_hi:[1,0]
	v_pk_mul_f32 v[58:59], v[58:59], v[156:157] op_sel_hi:[1,0]
	v_pk_mul_f32 v[52:53], v[52:53], v[156:157] op_sel_hi:[1,0]
	v_pk_mul_f32 v[48:49], v[48:49], v[156:157] op_sel_hi:[1,0]
	v_pk_mul_f32 v[50:51], v[50:51], v[156:157] op_sel_hi:[1,0]
	s_waitcnt vmcnt(2)
	v_add_f32_e32 v150, v150, v151
	v_add_f32_e32 v152, v152, v153
	v_add_f32_e32 v128, v128, v129
	v_add_f32_e32 v130, v130, v131
	v_add_f32_e32 v150, v150, v152
	v_add_f32_e32 v150, v150, v128
	v_add_f32_e32 v150, v150, v130
	v_fmamk_f32 v150, v150, 0x3a000000, v199
	v_rsq_f32_e32 v130, v150
	v_pk_mul_f32 v[44:45], v[44:45], v[148:149] op_sel_hi:[1,0]
	v_pk_mul_f32 v[40:41], v[40:41], v[148:149] op_sel_hi:[1,0]
	v_pk_mul_f32 v[42:43], v[42:43], v[148:149] op_sel_hi:[1,0]
	v_pk_mul_f32 v[36:37], v[36:37], v[148:149] op_sel_hi:[1,0]
	v_pk_mul_f32 v[32:33], v[32:33], v[148:149] op_sel_hi:[1,0]
	v_pk_mul_f32 v[34:35], v[34:35], v[148:149] op_sel_hi:[1,0]
	s_waitcnt vmcnt(0)
	v_add_f32_e32 v226, v226, v227
	v_add_f32_e32 v228, v228, v229
	v_add_f32_e32 v180, v180, v181
	v_add_f32_e32 v182, v182, v183
	v_add_f32_e32 v226, v226, v228
	v_add_f32_e32 v226, v226, v180
	v_add_f32_e32 v226, v226, v182
	v_fmamk_f32 v226, v226, 0x3a000000, v199
	v_rsq_f32_e32 v128, v226
	v_pk_mul_f32 v[28:29], v[28:29], v[130:131] op_sel_hi:[1,0]
	v_or_b32_e32 v182, 16, v186
	v_ashrrev_i32_e32 v183, 31, v182
	v_or_b32_e32 v180, 32, v186
	v_ashrrev_i32_e32 v181, 31, v180
	v_or_b32_e32 v174, 48, v186
	v_ashrrev_i32_e32 v175, 31, v174
	v_add_u32_e32 v158, 0x80, v186
	v_ashrrev_i32_e32 v159, 31, v158
	v_add_u32_e32 v152, 0x90, v186
	v_ashrrev_i32_e32 v153, 31, v152
	v_add_u32_e32 v150, 0xa0, v186
	v_ashrrev_i32_e32 v151, 31, v150
	v_add_u32_e32 v146, 0xb0, v186
	v_ashrrev_i32_e32 v147, 31, v146
	v_lshl_or_b32 v134, s42, 7, v157
	v_ashrrev_i32_e32 v135, 31, v134
	s_mov_b32 s42, s10
	v_mul_f32_e32 v129, 0xbfb8aa3b, v124
	v_exp_f32_e32 v129, v129
	v_mov_b64_e32 v[132:133], s[4:5]
	v_mad_i64_i32 v[186:187], s[4:5], v186, s11, v[132:133]
	v_add_f32_e32 v129, 1.0, v129
	v_rcp_f32_e32 v188, v129
	v_mul_f32_e32 v129, 0xbfb8aa3b, v125
	v_exp_f32_e32 v129, v129
	v_pk_mul_f32 v[24:25], v[24:25], v[130:131] op_sel_hi:[1,0]
	v_pk_mul_f32 v[26:27], v[26:27], v[130:131] op_sel_hi:[1,0]
	v_pk_mul_f32 v[20:21], v[20:21], v[130:131] op_sel_hi:[1,0]
	v_add_f32_e32 v129, 1.0, v129
	v_rcp_f32_e32 v189, v129
	v_pk_mul_f32 v[16:17], v[16:17], v[130:131] op_sel_hi:[1,0]
	v_pk_mul_f32 v[18:19], v[18:19], v[130:131] op_sel_hi:[1,0]
	v_pk_mul_f32 v[12:13], v[12:13], v[128:129] op_sel_hi:[1,0]
	v_pk_mul_f32 v[124:125], v[124:125], v[188:189]
	v_pk_mul_f32 v[8:9], v[8:9], v[128:129] op_sel_hi:[1,0]
	v_pk_mul_f32 v[120:121], v[120:121], v[124:125]
	v_pk_mul_f32 v[124:125], v[126:127], v[184:185] op_sel_hi:[1,0]
	v_pk_mul_f32 v[10:11], v[10:11], v[128:129] op_sel_hi:[1,0]
	v_mul_f32_e32 v126, 0xbfb8aa3b, v124
	v_mul_f32_e32 v127, 0xbfb8aa3b, v125
	v_exp_f32_e32 v126, v126
	v_exp_f32_e32 v127, v127
	v_pk_mul_f32 v[4:5], v[4:5], v[128:129] op_sel_hi:[1,0]
	v_pk_mul_f32 v[0:1], v[0:1], v[128:129] op_sel_hi:[1,0]
	v_add_f32_e32 v126, 1.0, v126
	v_add_f32_e32 v127, 1.0, v127
	v_rcp_f32_e32 v126, v126
	v_rcp_f32_e32 v127, v127
	v_pk_mul_f32 v[2:3], v[2:3], v[128:129] op_sel_hi:[1,0]
	s_and_b64 vcc, exec, s[0:1]
	v_pk_mul_f32 v[124:125], v[124:125], v[126:127]
	s_nop 0
	v_pk_mul_f32 v[122:123], v[122:123], v[124:125]
	v_mul_f32_e32 v124, 0xbfb8aa3b, v116
	v_mul_f32_e32 v125, 0xbfb8aa3b, v117
	v_exp_f32_e32 v124, v124
	v_exp_f32_e32 v125, v125
	v_add_f32_e32 v124, 1.0, v124
	v_add_f32_e32 v125, 1.0, v125
	v_rcp_f32_e32 v124, v124
	v_rcp_f32_e32 v125, v125
	s_nop 0
	v_pk_mul_f32 v[116:117], v[116:117], v[124:125]
	s_nop 0
	v_pk_mul_f32 v[116:117], v[112:113], v[116:117]
	v_pk_mul_f32 v[112:113], v[118:119], v[184:185] op_sel_hi:[1,0]
	v_cvt_pk_bf16_f32 v116, v116, v117
	v_mul_f32_e32 v118, 0xbfb8aa3b, v112
; DEV bf16x8 pack8(f32x4 a, f32x4 b) { u32x4 w; w.x = cvt_pk_bf16(a[0], a[1]); w.y = cvt_pk_bf16(a[2], a[3]); w.z = cvt_pk_bf16(b[0], b[1]); w.w = cvt_pk_bf16(b[2], b[3]); return __builtin_bit_cast(bf16x8, w); }
; DEV float siluf(float x) { return x * __builtin_amdgcn_rcpf(1.0f + __builtin_amdgcn_exp2f(x * -1.4426950408889634f)); }
;     DEV void operator()(AccRef acc, const pg8::Unit& u, int wr, int wc, int fr, int fq) const {
;     ...
;         for (int ai = 0; ai < 2; ++ai)
; #pragma unroll
;             for (int m = 0; m < 4; ++m) { u16* rowp = O + (size_t)(row0 + ai * 128 + m * 16) * 5632 + col0; const float rs = rsv[ai][m]; f32x4 r[2];
; #pragma unroll
;                 for (int n = 0; n < 2; ++n) { const f32x4 g = acc[ai][0][m][n] * rs, uu = acc[ai][1][m][n] * rs;
; #pragma unroll
;                     for (int e = 0; e < 4; ++e) r[n][e] = siluf(g[e]) * uu[e]; }
;                 *(u32x4*)rowp = __builtin_bit_cast(u32x4, pack8(r[0], r[1])); }
	v_mul_f32_e32 v119, 0xbfb8aa3b, v113
	v_exp_f32_e32 v118, v118
	v_exp_f32_e32 v119, v119
	v_add_f32_e32 v118, 1.0, v118
	v_add_f32_e32 v119, 1.0, v119
	v_rcp_f32_e32 v118, v118
	v_rcp_f32_e32 v119, v119
	s_nop 0
	v_pk_mul_f32 v[112:113], v[112:113], v[118:119]
	s_nop 0
	v_pk_mul_f32 v[118:119], v[114:115], v[112:113]
	v_lshlrev_b64 v[112:113], 1, v[134:135]
	v_lshl_add_u64 v[124:125], v[186:187], 0, v[112:113]
	v_cvt_pk_bf16_f32 v114, v120, v121
	v_cvt_pk_bf16_f32 v115, v122, v123
	v_cvt_pk_bf16_f32 v117, v118, v119
	global_store_dwordx4 v[124:125], v[114:117], off
	s_nop 1
	v_mul_f32_e32 v116, 0xbfb8aa3b, v108
	v_mul_f32_e32 v117, 0xbfb8aa3b, v109
	v_exp_f32_e32 v116, v116
	v_exp_f32_e32 v117, v117
	v_mad_i64_i32 v[114:115], s[4:5], v182, s11, v[132:133]
	v_add_f32_e32 v116, 1.0, v116
	v_add_f32_e32 v117, 1.0, v117
	v_rcp_f32_e32 v116, v116
	v_rcp_f32_e32 v117, v117
	s_nop 0
	v_pk_mul_f32 v[108:109], v[108:109], v[116:117]
	s_nop 0
	v_pk_mul_f32 v[104:105], v[104:105], v[108:109]
	v_pk_mul_f32 v[108:109], v[110:111], v[176:177] op_sel_hi:[1,0]
	s_nop 0
	v_mul_f32_e32 v110, 0xbfb8aa3b, v108
	v_mul_f32_e32 v111, 0xbfb8aa3b, v109
	v_exp_f32_e32 v110, v110
	v_exp_f32_e32 v111, v111
	v_add_f32_e32 v110, 1.0, v110
	v_add_f32_e32 v111, 1.0, v111
	v_rcp_f32_e32 v110, v110
	v_rcp_f32_e32 v111, v111
	s_nop 0
	v_pk_mul_f32 v[108:109], v[108:109], v[110:111]
	s_nop 0
	v_pk_mul_f32 v[106:107], v[106:107], v[108:109]
	v_mul_f32_e32 v108, 0xbfb8aa3b, v100
	v_mul_f32_e32 v109, 0xbfb8aa3b, v101
	v_exp_f32_e32 v108, v108
	v_exp_f32_e32 v109, v109
	v_add_f32_e32 v108, 1.0, v108
	v_add_f32_e32 v109, 1.0, v109
	v_rcp_f32_e32 v108, v108
	v_rcp_f32_e32 v109, v109
	s_nop 0
	v_pk_mul_f32 v[100:101], v[100:101], v[108:109]
	s_nop 0
	v_pk_mul_f32 v[100:101], v[96:97], v[100:101]
	v_pk_mul_f32 v[96:97], v[102:103], v[176:177] op_sel_hi:[1,0]
	v_lshl_add_u64 v[108:109], v[114:115], 0, v[112:113]
	v_mul_f32_e32 v102, 0xbfb8aa3b, v96
	v_mul_f32_e32 v103, 0xbfb8aa3b, v97
	v_exp_f32_e32 v102, v102
	v_exp_f32_e32 v103, v103
	v_add_f32_e32 v102, 1.0, v102
	v_add_f32_e32 v103, 1.0, v103
	v_rcp_f32_e32 v102, v102
	v_rcp_f32_e32 v103, v103
	s_nop 0
	v_pk_mul_f32 v[96:97], v[96:97], v[102:103]
	s_nop 0
	v_pk_mul_f32 v[102:103], v[98:99], v[96:97]
	v_cvt_pk_bf16_f32 v96, v104, v105
	v_cvt_pk_bf16_f32 v97, v106, v107
	v_cvt_pk_bf16_f32 v98, v100, v101
	v_cvt_pk_bf16_f32 v99, v102, v103
	global_store_dwordx4 v[108:109], v[96:99], off
	s_nop 1
	v_mul_f32_e32 v98, 0xbfb8aa3b, v92
	v_mul_f32_e32 v99, 0xbfb8aa3b, v93
	v_exp_f32_e32 v98, v98
	v_exp_f32_e32 v99, v99
	v_mad_i64_i32 v[96:97], s[4:5], v180, s11, v[132:133]
	v_add_f32_e32 v98, 1.0, v98
	v_add_f32_e32 v99, 1.0, v99
	v_rcp_f32_e32 v98, v98
	v_rcp_f32_e32 v99, v99
	s_nop 0
	v_pk_mul_f32 v[92:93], v[92:93], v[98:99]
	s_nop 0
	v_pk_mul_f32 v[88:89], v[88:89], v[92:93]
	v_pk_mul_f32 v[92:93], v[94:95], v[178:179] op_sel_hi:[1,0]
	s_nop 0
	v_mul_f32_e32 v94, 0xbfb8aa3b, v92
	v_mul_f32_e32 v95, 0xbfb8aa3b, v93
	v_exp_f32_e32 v94, v94
	v_exp_f32_e32 v95, v95
	v_add_f32_e32 v94, 1.0, v94
	v_add_f32_e32 v95, 1.0, v95
	v_rcp_f32_e32 v94, v94
	v_rcp_f32_e32 v95, v95
	s_nop 0
	v_pk_mul_f32 v[92:93], v[92:93], v[94:95]
	s_nop 0
	v_pk_mul_f32 v[90:91], v[90:91], v[92:93]
	v_mul_f32_e32 v92, 0xbfb8aa3b, v84
	v_mul_f32_e32 v93, 0xbfb8aa3b, v85
	v_exp_f32_e32 v92, v92
	v_exp_f32_e32 v93, v93
	v_add_f32_e32 v92, 1.0, v92
	v_add_f32_e32 v93, 1.0, v93
	v_rcp_f32_e32 v92, v92
	v_rcp_f32_e32 v93, v93
	s_nop 0
	v_pk_mul_f32 v[84:85], v[84:85], v[92:93]
	s_nop 0
	v_pk_mul_f32 v[84:85], v[80:81], v[84:85]
	v_pk_mul_f32 v[80:81], v[86:87], v[178:179] op_sel_hi:[1,0]
	v_lshl_add_u64 v[92:93], v[96:97], 0, v[112:113]
	v_mul_f32_e32 v86, 0xbfb8aa3b, v80
	v_mul_f32_e32 v87, 0xbfb8aa3b, v81
	v_exp_f32_e32 v86, v86
	v_exp_f32_e32 v87, v87
	v_add_f32_e32 v86, 1.0, v86
	v_add_f32_e32 v87, 1.0, v87
	v_rcp_f32_e32 v86, v86
	v_rcp_f32_e32 v87, v87
	s_nop 0
	v_pk_mul_f32 v[80:81], v[80:81], v[86:87]
	s_nop 0
	v_pk_mul_f32 v[86:87], v[82:83], v[80:81]
	v_cvt_pk_bf16_f32 v80, v88, v89
	v_cvt_pk_bf16_f32 v81, v90, v91
	v_cvt_pk_bf16_f32 v82, v84, v85
	v_cvt_pk_bf16_f32 v83, v86, v87
	global_store_dwordx4 v[92:93], v[80:83], off
	s_nop 1
	v_mul_f32_e32 v82, 0xbfb8aa3b, v76
	v_mul_f32_e32 v83, 0xbfb8aa3b, v77
	v_exp_f32_e32 v82, v82
	v_exp_f32_e32 v83, v83
	v_mad_i64_i32 v[80:81], s[4:5], v174, s11, v[132:133]
	v_add_f32_e32 v82, 1.0, v82
	v_add_f32_e32 v83, 1.0, v83
	v_rcp_f32_e32 v82, v82
	v_rcp_f32_e32 v83, v83
	s_nop 0
	v_pk_mul_f32 v[76:77], v[76:77], v[82:83]
	s_nop 0
	v_pk_mul_f32 v[72:73], v[72:73], v[76:77]
	v_pk_mul_f32 v[76:77], v[78:79], v[154:155] op_sel_hi:[1,0]
	s_nop 0
	v_mul_f32_e32 v78, 0xbfb8aa3b, v76
	v_mul_f32_e32 v79, 0xbfb8aa3b, v77
	v_exp_f32_e32 v78, v78
	v_exp_f32_e32 v79, v79
	v_add_f32_e32 v78, 1.0, v78
	v_add_f32_e32 v79, 1.0, v79
	v_rcp_f32_e32 v78, v78
	v_rcp_f32_e32 v79, v79
	s_nop 0
	v_pk_mul_f32 v[76:77], v[76:77], v[78:79]
	s_nop 0
	v_pk_mul_f32 v[74:75], v[74:75], v[76:77]
	v_mul_f32_e32 v76, 0xbfb8aa3b, v68
	v_mul_f32_e32 v77, 0xbfb8aa3b, v69
	v_exp_f32_e32 v76, v76
	v_exp_f32_e32 v77, v77
	v_add_f32_e32 v76, 1.0, v76
	v_add_f32_e32 v77, 1.0, v77
	v_rcp_f32_e32 v76, v76
	v_rcp_f32_e32 v77, v77
	s_nop 0
	v_pk_mul_f32 v[68:69], v[68:69], v[76:77]
	s_nop 0
	v_pk_mul_f32 v[68:69], v[64:65], v[68:69]
	v_pk_mul_f32 v[64:65], v[70:71], v[154:155] op_sel_hi:[1,0]
	v_lshl_add_u64 v[76:77], v[80:81], 0, v[112:113]
	v_mul_f32_e32 v70, 0xbfb8aa3b, v64
	v_mul_f32_e32 v71, 0xbfb8aa3b, v65
	v_exp_f32_e32 v70, v70
	v_exp_f32_e32 v71, v71
	v_add_f32_e32 v70, 1.0, v70
	v_add_f32_e32 v71, 1.0, v71
	v_rcp_f32_e32 v70, v70
	v_rcp_f32_e32 v71, v71
; DEV bf16x8 pack8(f32x4 a, f32x4 b) { u32x4 w; w.x = cvt_pk_bf16(a[0], a[1]); w.y = cvt_pk_bf16(a[2], a[3]); w.z = cvt_pk_bf16(b[0], b[1]); w.w = cvt_pk_bf16(b[2], b[3]); return __builtin_bit_cast(bf16x8, w); }
; DEV float siluf(float x) { return x * __builtin_amdgcn_rcpf(1.0f + __builtin_amdgcn_exp2f(x * -1.4426950408889634f)); }
;     DEV void operator()(AccRef acc, const pg8::Unit& u, int wr, int wc, int fr, int fq) const {
;     ...
;         for (int ai = 0; ai < 2; ++ai)
; #pragma unroll
;             for (int m = 0; m < 4; ++m) { u16* rowp = O + (size_t)(row0 + ai * 128 + m * 16) * 5632 + col0; const float rs = rsv[ai][m]; f32x4 r[2];
; #pragma unroll
;                 for (int n = 0; n < 2; ++n) { const f32x4 g = acc[ai][0][m][n] * rs, uu = acc[ai][1][m][n] * rs;
; #pragma unroll
;                     for (int e = 0; e < 4; ++e) r[n][e] = siluf(g[e]) * uu[e]; }
;                 *(u32x4*)rowp = __builtin_bit_cast(u32x4, pack8(r[0], r[1])); }
	s_nop 0
	v_pk_mul_f32 v[64:65], v[64:65], v[70:71]
	s_nop 0
	v_pk_mul_f32 v[70:71], v[66:67], v[64:65]
	v_cvt_pk_bf16_f32 v64, v72, v73
	v_cvt_pk_bf16_f32 v65, v74, v75
	v_cvt_pk_bf16_f32 v66, v68, v69
	v_cvt_pk_bf16_f32 v67, v70, v71
	global_store_dwordx4 v[76:77], v[64:67], off
	s_nop 1
	v_mul_f32_e32 v66, 0xbfb8aa3b, v60
	v_mul_f32_e32 v67, 0xbfb8aa3b, v61
	v_exp_f32_e32 v66, v66
	v_exp_f32_e32 v67, v67
	v_mad_i64_i32 v[64:65], s[4:5], v158, s11, v[132:133]
	v_add_f32_e32 v66, 1.0, v66
	v_add_f32_e32 v67, 1.0, v67
	v_rcp_f32_e32 v66, v66
	v_rcp_f32_e32 v67, v67
	s_nop 0
	v_pk_mul_f32 v[60:61], v[60:61], v[66:67]
	s_nop 0
	v_pk_mul_f32 v[56:57], v[56:57], v[60:61]
	v_pk_mul_f32 v[60:61], v[62:63], v[156:157] op_sel_hi:[1,0]
	s_nop 0
	v_mul_f32_e32 v62, 0xbfb8aa3b, v60
	v_mul_f32_e32 v63, 0xbfb8aa3b, v61
	v_exp_f32_e32 v62, v62
	v_exp_f32_e32 v63, v63
	v_add_f32_e32 v62, 1.0, v62
	v_add_f32_e32 v63, 1.0, v63
	v_rcp_f32_e32 v62, v62
	v_rcp_f32_e32 v63, v63
	s_nop 0
	v_pk_mul_f32 v[60:61], v[60:61], v[62:63]
	s_nop 0
	v_pk_mul_f32 v[58:59], v[58:59], v[60:61]
	v_mul_f32_e32 v60, 0xbfb8aa3b, v52
	v_mul_f32_e32 v61, 0xbfb8aa3b, v53
	v_exp_f32_e32 v60, v60
	v_exp_f32_e32 v61, v61
	v_add_f32_e32 v60, 1.0, v60
	v_add_f32_e32 v61, 1.0, v61
	v_rcp_f32_e32 v60, v60
	v_rcp_f32_e32 v61, v61
	s_nop 0
	v_pk_mul_f32 v[52:53], v[52:53], v[60:61]
	s_nop 0
	v_pk_mul_f32 v[52:53], v[48:49], v[52:53]
	v_pk_mul_f32 v[48:49], v[54:55], v[156:157] op_sel_hi:[1,0]
	v_lshl_add_u64 v[60:61], v[64:65], 0, v[112:113]
	v_mul_f32_e32 v54, 0xbfb8aa3b, v48
	v_mul_f32_e32 v55, 0xbfb8aa3b, v49
	v_exp_f32_e32 v54, v54
	v_exp_f32_e32 v55, v55
	v_add_f32_e32 v54, 1.0, v54
	v_add_f32_e32 v55, 1.0, v55
	v_rcp_f32_e32 v54, v54
	v_rcp_f32_e32 v55, v55
	s_nop 0
	v_pk_mul_f32 v[48:49], v[48:49], v[54:55]
	s_nop 0
	v_pk_mul_f32 v[54:55], v[50:51], v[48:49]
	v_cvt_pk_bf16_f32 v48, v56, v57
	v_cvt_pk_bf16_f32 v49, v58, v59
	v_cvt_pk_bf16_f32 v50, v52, v53
	v_cvt_pk_bf16_f32 v51, v54, v55
	global_store_dwordx4 v[60:61], v[48:51], off
	s_nop 1
	v_mul_f32_e32 v50, 0xbfb8aa3b, v44
	v_mul_f32_e32 v51, 0xbfb8aa3b, v45
	v_exp_f32_e32 v50, v50
	v_exp_f32_e32 v51, v51
	v_mad_i64_i32 v[48:49], s[4:5], v152, s11, v[132:133]
	v_add_f32_e32 v50, 1.0, v50
	v_add_f32_e32 v51, 1.0, v51
	v_rcp_f32_e32 v50, v50
	v_rcp_f32_e32 v51, v51
	s_nop 0
	v_pk_mul_f32 v[44:45], v[44:45], v[50:51]
	s_nop 0
	v_pk_mul_f32 v[40:41], v[40:41], v[44:45]
	v_pk_mul_f32 v[44:45], v[46:47], v[148:149] op_sel_hi:[1,0]
	s_nop 0
	v_mul_f32_e32 v46, 0xbfb8aa3b, v44
	v_mul_f32_e32 v47, 0xbfb8aa3b, v45
	v_exp_f32_e32 v46, v46
	v_exp_f32_e32 v47, v47
	v_add_f32_e32 v46, 1.0, v46
	v_add_f32_e32 v47, 1.0, v47
	v_rcp_f32_e32 v46, v46
	v_rcp_f32_e32 v47, v47
	s_nop 0
	v_pk_mul_f32 v[44:45], v[44:45], v[46:47]
	s_nop 0
	v_pk_mul_f32 v[42:43], v[42:43], v[44:45]
	v_mul_f32_e32 v44, 0xbfb8aa3b, v36
	v_mul_f32_e32 v45, 0xbfb8aa3b, v37
	v_exp_f32_e32 v44, v44
	v_exp_f32_e32 v45, v45
	v_add_f32_e32 v44, 1.0, v44
	v_add_f32_e32 v45, 1.0, v45
	v_rcp_f32_e32 v44, v44
	v_rcp_f32_e32 v45, v45
	s_nop 0
	v_pk_mul_f32 v[36:37], v[36:37], v[44:45]
	s_nop 0
	v_pk_mul_f32 v[36:37], v[32:33], v[36:37]
	v_pk_mul_f32 v[32:33], v[38:39], v[148:149] op_sel_hi:[1,0]
	v_lshl_add_u64 v[44:45], v[48:49], 0, v[112:113]
	v_mul_f32_e32 v38, 0xbfb8aa3b, v32
	v_mul_f32_e32 v39, 0xbfb8aa3b, v33
	v_exp_f32_e32 v38, v38
	v_exp_f32_e32 v39, v39
	v_add_f32_e32 v38, 1.0, v38
	v_add_f32_e32 v39, 1.0, v39
	v_rcp_f32_e32 v38, v38
	v_rcp_f32_e32 v39, v39
	s_nop 0
	v_pk_mul_f32 v[32:33], v[32:33], v[38:39]
	s_nop 0
	v_pk_mul_f32 v[38:39], v[34:35], v[32:33]
	v_cvt_pk_bf16_f32 v32, v40, v41
	v_cvt_pk_bf16_f32 v33, v42, v43
; DEV float siluf(float x) { return x * __builtin_amdgcn_rcpf(1.0f + __builtin_amdgcn_exp2f(x * -1.4426950408889634f)); }
; DEV bf16x8 pack8(f32x4 a, f32x4 b) { u32x4 w; w.x = cvt_pk_bf16(a[0], a[1]); w.y = cvt_pk_bf16(a[2], a[3]); w.z = cvt_pk_bf16(b[0], b[1]); w.w = cvt_pk_bf16(b[2], b[3]); return __builtin_bit_cast(bf16x8, w); }
; #define PG8_WAIT_V(n) asm volatile("s_waitcnt vmcnt(" #n ")" ::: "memory")
; #define PG8_BAR __builtin_amdgcn_s_barrier()
; template <class Epi>
; DEV void gemm_phase(LAS unsigned char* lds, const Gemm g, const StaticOrder& S, const Epi& E) {
;     ...
;     PG8_WAIT_V(0);
;     if (wr == 0) PG8_BAR;
;     PG8_BAR;
;     DEV void operator()(AccRef acc, const pg8::Unit& u, int wr, int wc, int fr, int fq) const {
;     ...
;         for (int ai = 0; ai < 2; ++ai)
; #pragma unroll
;             for (int m = 0; m < 4; ++m) { u16* rowp = O + (size_t)(row0 + ai * 128 + m * 16) * 5632 + col0; const float rs = rsv[ai][m]; f32x4 r[2];
; #pragma unroll
;                 for (int n = 0; n < 2; ++n) { const f32x4 g = acc[ai][0][m][n] * rs, uu = acc[ai][1][m][n] * rs;
; #pragma unroll
;                     for (int e = 0; e < 4; ++e) r[n][e] = siluf(g[e]) * uu[e]; }
;                 *(u32x4*)rowp = __builtin_bit_cast(u32x4, pack8(r[0], r[1])); }
	v_cvt_pk_bf16_f32 v34, v36, v37
	v_cvt_pk_bf16_f32 v35, v38, v39
	global_store_dwordx4 v[44:45], v[32:35], off
	s_nop 1
	v_mul_f32_e32 v34, 0xbfb8aa3b, v28
	v_mul_f32_e32 v35, 0xbfb8aa3b, v29
	v_exp_f32_e32 v34, v34
	v_exp_f32_e32 v35, v35
	v_mad_i64_i32 v[32:33], s[4:5], v150, s11, v[132:133]
	v_add_f32_e32 v34, 1.0, v34
	v_add_f32_e32 v35, 1.0, v35
	v_rcp_f32_e32 v34, v34
	v_rcp_f32_e32 v35, v35
	s_nop 0
	v_pk_mul_f32 v[28:29], v[28:29], v[34:35]
	s_nop 0
	v_pk_mul_f32 v[24:25], v[24:25], v[28:29]
	v_pk_mul_f32 v[28:29], v[30:31], v[130:131] op_sel_hi:[1,0]
	s_nop 0
	v_mul_f32_e32 v30, 0xbfb8aa3b, v28
	v_mul_f32_e32 v31, 0xbfb8aa3b, v29
	v_exp_f32_e32 v30, v30
	v_exp_f32_e32 v31, v31
	v_add_f32_e32 v30, 1.0, v30
	v_add_f32_e32 v31, 1.0, v31
	v_rcp_f32_e32 v30, v30
	v_rcp_f32_e32 v31, v31
	s_nop 0
	v_pk_mul_f32 v[28:29], v[28:29], v[30:31]
	s_nop 0
	v_pk_mul_f32 v[26:27], v[26:27], v[28:29]
	v_mul_f32_e32 v28, 0xbfb8aa3b, v20
	v_mul_f32_e32 v29, 0xbfb8aa3b, v21
	v_exp_f32_e32 v28, v28
	v_exp_f32_e32 v29, v29
	v_add_f32_e32 v28, 1.0, v28
	v_add_f32_e32 v29, 1.0, v29
	v_rcp_f32_e32 v28, v28
	v_rcp_f32_e32 v29, v29
	s_nop 0
	v_pk_mul_f32 v[20:21], v[20:21], v[28:29]
	s_nop 0
	v_pk_mul_f32 v[20:21], v[16:17], v[20:21]
	v_pk_mul_f32 v[16:17], v[22:23], v[130:131] op_sel_hi:[1,0]
	v_lshl_add_u64 v[28:29], v[32:33], 0, v[112:113]
	v_mul_f32_e32 v22, 0xbfb8aa3b, v16
	v_mul_f32_e32 v23, 0xbfb8aa3b, v17
	v_exp_f32_e32 v22, v22
	v_exp_f32_e32 v23, v23
	v_add_f32_e32 v22, 1.0, v22
	v_add_f32_e32 v23, 1.0, v23
	v_rcp_f32_e32 v22, v22
	v_rcp_f32_e32 v23, v23
	s_nop 0
	v_pk_mul_f32 v[16:17], v[16:17], v[22:23]
	s_nop 0
	v_pk_mul_f32 v[22:23], v[18:19], v[16:17]
	v_cvt_pk_bf16_f32 v16, v24, v25
	v_cvt_pk_bf16_f32 v17, v26, v27
	v_cvt_pk_bf16_f32 v18, v20, v21
	v_cvt_pk_bf16_f32 v19, v22, v23
	global_store_dwordx4 v[28:29], v[16:19], off
	s_nop 1
	v_mul_f32_e32 v18, 0xbfb8aa3b, v12
	v_mul_f32_e32 v19, 0xbfb8aa3b, v13
	v_exp_f32_e32 v18, v18
	v_exp_f32_e32 v19, v19
	v_mad_i64_i32 v[16:17], s[4:5], v146, s11, v[132:133]
	v_add_f32_e32 v18, 1.0, v18
	v_add_f32_e32 v19, 1.0, v19
	v_rcp_f32_e32 v18, v18
	v_rcp_f32_e32 v19, v19
	s_mov_b32 s4, s14
	v_pk_mul_f32 v[12:13], v[12:13], v[18:19]
	s_nop 0
	v_pk_mul_f32 v[8:9], v[8:9], v[12:13]
	v_pk_mul_f32 v[12:13], v[14:15], v[128:129] op_sel_hi:[1,0]
	s_nop 0
	v_mul_f32_e32 v14, 0xbfb8aa3b, v12
	v_mul_f32_e32 v15, 0xbfb8aa3b, v13
	v_exp_f32_e32 v14, v14
	v_exp_f32_e32 v15, v15
	v_add_f32_e32 v14, 1.0, v14
	v_add_f32_e32 v15, 1.0, v15
	v_rcp_f32_e32 v14, v14
	v_rcp_f32_e32 v15, v15
	s_nop 0
	v_pk_mul_f32 v[12:13], v[12:13], v[14:15]
	s_nop 0
	v_pk_mul_f32 v[10:11], v[10:11], v[12:13]
	v_mul_f32_e32 v12, 0xbfb8aa3b, v4
	v_mul_f32_e32 v13, 0xbfb8aa3b, v5
	v_exp_f32_e32 v12, v12
	v_exp_f32_e32 v13, v13
	v_add_f32_e32 v12, 1.0, v12
	v_add_f32_e32 v13, 1.0, v13
	v_rcp_f32_e32 v12, v12
	v_rcp_f32_e32 v13, v13
	s_nop 0
	v_pk_mul_f32 v[4:5], v[4:5], v[12:13]
	s_nop 0
	v_pk_mul_f32 v[4:5], v[0:1], v[4:5]
	v_pk_mul_f32 v[0:1], v[6:7], v[128:129] op_sel_hi:[1,0]
	v_lshl_add_u64 v[12:13], v[16:17], 0, v[112:113]
	v_mul_f32_e32 v6, 0xbfb8aa3b, v0
	v_mul_f32_e32 v7, 0xbfb8aa3b, v1
	v_exp_f32_e32 v6, v6
	v_exp_f32_e32 v7, v7
	v_add_f32_e32 v6, 1.0, v6
	v_add_f32_e32 v7, 1.0, v7
	v_rcp_f32_e32 v6, v6
	v_rcp_f32_e32 v7, v7
	s_nop 0
	v_pk_mul_f32 v[0:1], v[0:1], v[6:7]
	s_nop 0
	v_pk_mul_f32 v[6:7], v[2:3], v[0:1]
	v_cvt_pk_bf16_f32 v0, v8, v9
	v_cvt_pk_bf16_f32 v1, v10, v11
	v_cvt_pk_bf16_f32 v2, v4, v5
	v_cvt_pk_bf16_f32 v3, v6, v7
	global_store_dwordx4 v[12:13], v[0:3], off
	s_cbranch_vccz .LBB0_752
	s_waitcnt vmcnt(0)
	s_cmpk_gt_u32 s27, 0xff
	s_cbranch_scc1 .LBB0_759
	s_barrier

; __global__ void __launch_bounds__(512) mega(P p) {
;     ...
;     for (int ph = p.ph0; ph < p.ph1; ++ph) {
;         run_phase(p, ph, lds);
;         if (ph + 1 < p.ph1) xcd_barrier(xb);
;     }
.LBB0_786:
	s_setprio 0
	v_readlane_b32 s0, v250, 3
	v_readlane_b32 s1, v250, 4
	s_load_dword s0, s[0:1], 0x134
	v_readlane_b32 s4, v250, 7
	v_readlane_b32 s5, v250, 8
	s_add_i32 s4, s4, 1
	v_writelane_b32 v250, s4, 7
	s_waitcnt lgkmcnt(0)
	s_cmp_ge_i32 s4, s0
	v_writelane_b32 v250, s5, 8
	s_cbranch_scc0 .LBB0_787
	s_getpc_b64 s[98:99]
